# next-tile index math in in-proj/up GEMM unit loops: runtime division by the group size (always 8 here: 128 row tiles) replaced by shift/mask; the two back-to-back s_waitcnt before each load-segment ba
# speedup vs baseline: 1.0094x; 1.0068x over previous
; #define PG8_STAGE(bufoff, gbase, voff) do { _Pragma("unroll") for (int _i = 0; _i < 2; ++_i) \
;         __builtin_amdgcn_global_load_lds((const unsigned*)((const char*)(gbase) + (voff)[_i]), (PG8_LAS unsigned*)(lds + (bufoff) + ldsw + _i * 8192), 16, 0, 0); } while (0)
; #define PG8_LDA(dst, b, h) do { _Pragma("unroll") for (int m = 0; m < 4; ++m) _Pragma("unroll") for (int k = 0; k < 2; ++k) dst[m][k] = *(const PG8_LAS bf16x8*)(lds + PG8_SA(b, h) + aoff + m * 2048 + k * 1024); } while (0)
; #define PG8_LDB(dst, b, h) do { _Pragma("unroll") for (int n = 0; n < 2; ++n) _Pragma("unroll") for (int k = 0; k < 2; ++k) dst[n][k] = *(const PG8_LAS bf16x8*)(lds + PG8_SB(b, h) + boff + n * 2048 + k * 1024); } while (0)
; #define PG8_BAR __builtin_amdgcn_s_barrier()
;     __host__ __device__ bool next(int i, Unit& u) const {
;         const long L = (long)i * G + c; if (L >= nwg) return false;
;         int wgid = (int)L; { const int q = nwg / NXCD, r = nwg % NXCD, xcd = wgid % NXCD, off = wgid / NXCD; wgid = (xcd < r ? xcd * (q + 1) : r * (q + 1) + (xcd - r) * q) + off; }
;         const int nig = WGM * nN, gid = wgid / nig, fm = gid * WGM, gsz = (nM - fm) < WGM ? (nM - fm) : WGM;
;         u.pm = fm + ((wgid % nig) % gsz); u.pn = (wgid % nig) / gsz; return true;
; template <class Epi, class Sched, bool ALIGN_EPI = false, bool SP2 = false>
; __device__ __forceinline__ void gemm_phase(PG8_LAS unsigned char* lds, const Gemm g, const Sched& S, const Epi& E) {
;     ...
;         const bool has_next = S.next(ui + 1, nxt);
;         const char* nA = has_next ? (const char*)g.A + (size_t)nxt.pm * tstep : cA; const char* nB = has_next ? (const char*)g.Bt + (size_t)nxt.pn * tstep : cB;
;         for (int t = 0; t < nt; t += 2) {
;             const bool last = (t == nt - 2);
;             const char* a1 = cA + (size_t)(t + 1) * kstep;
;             const char* a2 = last ? nA : cA + (size_t)(t + 2) * kstep; const char* b2 = last ? nB : cB + (size_t)(t + 2) * kstep;
;             const char* a3 = a2 + kstep; const char* b3 = b2 + kstep;
;             if (last && has_next) S.a_ready(nxt);
;             if constexpr (SP2) {
;             PG8_LDB(B0, 0, 0); PG8_LDB(B1, 0, 1); PG8_SCHED; PG8_LDA(At, 0, 0); PG8_STAGE(PG8_SA(1, 1), a1 + hstep, voffA);
;             PG8_WAIT_V(8); PG8_WAIT_L(0); PG8_BAR; PG8_MMA(0, 0, At, B0); PG8_MMA(0, 1, At, B1); PG8_BAR; PG8_SCHED;
.LBB0_298:
	s_lshl_b32 s4, s22, 8
	s_ashr_i32 s5, s4, 31
	v_lshl_add_u64 v[242:243], s[4:5], 2, v[146:147]
	global_load_dwordx4 v[246:249], v[242:243], off offset:16
	s_nop 0
	global_load_dwordx4 v[242:245], v[242:243], off
	s_add_i32 s43, s43, 1
	s_mul_i32 s4, s43, s42
	s_mul_hi_u32 s5, s43, s30
	s_add_i32 s5, s5, s4
	s_mul_i32 s4, s43, s30
	s_add_u32 s16, s4, s31
	s_addc_u32 s17, s5, s36
	v_mov_b64_e32 v[2:3], 0x580
	v_cmp_lt_i64_e64 s[4:5], s[16:17], v[2:3]
	v_mov_b64_e32 v[2:3], 0x57f
	v_cmp_gt_i64_e32 vcc, s[16:17], v[2:3]
	s_cbranch_vccnz .LBB0_300
	s_ashr_i32 s10, s16, 31
	s_lshr_b32 s10, s10, 29
	s_add_i32 s10, s16, s10
	s_ashr_i32 s11, s10, 3
	s_and_b32 s10, s10, -8
	s_sub_i32 s10, s16, s10
	s_cmp_lt_i32 s10, 0
	s_cselect_b32 s12, s51, 0xb0
	s_mul_i32 s10, s10, s12
	s_add_i32 s10, s10, s11
	s_mul_hi_i32 s11, s10, 0x2e8ba2e9
	s_lshr_b32 s12, s11, 31
	s_ashr_i32 s11, s11, 4
	s_add_i32 s11, s11, s12
	s_lshl_b32 s12, s11, 3
	s_mulk_i32 s11, 0x58
	s_sub_i32 s11, s10, s11
	s_lshr_b32 s10, s11, 3
	s_and_b32 s11, s11, 7
	s_add_i32 s12, s12, s11
.LBB0_300:
	s_ashr_i32 s13, s12, 31
	s_lshl_b64 s[16:17], s[12:13], 19
	s_add_u32 s16, s0, s16
	s_addc_u32 s17, s1, s17
	s_and_b64 s[18:19], s[4:5], exec
	s_cselect_b32 s13, s17, s25
	s_cselect_b32 s21, s16, s24
	s_ashr_i32 s11, s10, 31
	s_lshl_b64 s[18:19], s[10:11], 19
	s_add_u32 s18, s33, s18
	s_addc_u32 s19, s34, s19
	s_and_b64 s[28:29], s[4:5], exec
	s_cselect_b32 s11, s19, s27
	s_cselect_b32 s44, s18, s26
	s_add_u32 s24, s24, 0x40080
	s_addc_u32 s25, s25, 0
	s_add_u32 s45, s26, 0x100
	s_addc_u32 s46, s27, 0
	s_mov_b32 s47, -2
	s_add_u32 s26, s24, 0xfffc0080
	s_addc_u32 s27, s25, -1
	s_add_i32 s48, 0, 0x10000
	s_cmp_eq_u32 s47, 12
	s_cselect_b32 s29, s13, s27
	s_cselect_b32 s28, s21, s26
	v_add_u32_e32 v154, s48, v156
	s_cselect_b32 s27, s11, s46
	s_cselect_b32 s26, s44, s45
	s_add_i32 s50, 0, 0x14000
	ds_read_b128 v[94:97], v154
	ds_read_b128 v[134:137], v154 offset:1024
	ds_read_b128 v[158:161], v154 offset:2048
	ds_read_b128 v[162:165], v154 offset:3072
	v_add_u32_e32 v154, s50, v156
	ds_read_b128 v[166:169], v154
	ds_read_b128 v[170:173], v154 offset:1024
	ds_read_b128 v[174:177], v154 offset:2048
	ds_read_b128 v[186:189], v154 offset:3072
	v_lshl_add_u64 v[154:155], s[24:25], 0, v[150:151]
	s_add_i32 m0, s23, 0xc000
	ds_read_b128 v[190:193], v157
	ds_read_b128 v[194:197], v157 offset:1024
	ds_read_b128 v[198:201], v157 offset:2048
	ds_read_b128 v[202:205], v157 offset:3072
	ds_read_b128 v[206:209], v157 offset:4096
	ds_read_b128 v[210:213], v157 offset:5120
	ds_read_b128 v[214:217], v157 offset:6144
	ds_read_b128 v[218:221], v157 offset:7168
	global_load_lds_dwordx4 v[154:155], off
	v_lshl_add_u64 v[154:155], s[24:25], 0, v[152:153]
	s_add_i32 m0, s23, 0xe000
	s_nop 0
	global_load_lds_dwordx4 v[154:155], off
	s_waitcnt vmcnt(8) lgkmcnt(0)
	s_barrier
	s_setprio 1
	v_mfma_f32_16x16x32_bf16 v[130:133], v[94:97], v[190:193], 0
	v_mfma_f32_16x16x32_bf16 v[126:129], v[158:161], v[190:193], 0
	v_mfma_f32_16x16x32_bf16 v[114:117], v[94:97], v[198:201], 0
	v_mfma_f32_16x16x32_bf16 v[110:113], v[158:161], v[198:201], 0
	v_mfma_f32_16x16x32_bf16 v[98:101], v[94:97], v[206:209], 0
	v_mfma_f32_16x16x32_bf16 v[90:93], v[158:161], v[206:209], 0
	v_mfma_f32_16x16x32_bf16 v[78:81], v[94:97], v[214:217], 0
	v_mfma_f32_16x16x32_bf16 v[74:77], v[158:161], v[214:217], 0
	v_mfma_f32_16x16x32_bf16 v[130:133], v[134:137], v[194:197], v[130:133]
	v_mfma_f32_16x16x32_bf16 v[126:129], v[162:165], v[194:197], v[126:129]
	v_mfma_f32_16x16x32_bf16 v[114:117], v[134:137], v[202:205], v[114:117]
	v_mfma_f32_16x16x32_bf16 v[110:113], v[162:165], v[202:205], v[110:113]
	v_mfma_f32_16x16x32_bf16 v[98:101], v[134:137], v[210:213], v[98:101]
	v_mfma_f32_16x16x32_bf16 v[90:93], v[162:165], v[210:213], v[90:93]
	v_mfma_f32_16x16x32_bf16 v[78:81], v[134:137], v[218:221], v[78:81]
	v_mfma_f32_16x16x32_bf16 v[74:77], v[162:165], v[218:221], v[74:77]
	s_setprio 0
	s_setprio 1
	v_mfma_f32_16x16x32_bf16 v[122:125], v[166:169], v[190:193], 0
	v_mfma_f32_16x16x32_bf16 v[118:121], v[174:177], v[190:193], 0
	v_mfma_f32_16x16x32_bf16 v[106:109], v[166:169], v[198:201], 0
	v_mfma_f32_16x16x32_bf16 v[102:105], v[174:177], v[198:201], 0
	v_mfma_f32_16x16x32_bf16 v[86:89], v[166:169], v[206:209], 0
	v_mfma_f32_16x16x32_bf16 v[82:85], v[174:177], v[206:209], 0
	v_mfma_f32_16x16x32_bf16 v[70:73], v[166:169], v[214:217], 0
	v_mfma_f32_16x16x32_bf16 v[66:69], v[174:177], v[214:217], 0
	v_mfma_f32_16x16x32_bf16 v[122:125], v[170:173], v[194:197], v[122:125]
	v_mfma_f32_16x16x32_bf16 v[118:121], v[186:189], v[194:197], v[118:121]
	v_mfma_f32_16x16x32_bf16 v[106:109], v[170:173], v[202:205], v[106:109]
	v_mfma_f32_16x16x32_bf16 v[102:105], v[186:189], v[202:205], v[102:105]
	v_mfma_f32_16x16x32_bf16 v[86:89], v[170:173], v[210:213], v[86:89]
	v_mfma_f32_16x16x32_bf16 v[82:85], v[186:189], v[210:213], v[82:85]
	v_mfma_f32_16x16x32_bf16 v[70:73], v[170:173], v[218:221], v[70:73]
	v_mfma_f32_16x16x32_bf16 v[66:69], v[186:189], v[218:221], v[66:69]
	s_setprio 0
	s_barrier
; #define PG8_STAGE(bufoff, gbase, voff) do { _Pragma("unroll") for (int _i = 0; _i < 2; ++_i) \
;         __builtin_amdgcn_global_load_lds((const unsigned*)((const char*)(gbase) + (voff)[_i]), (PG8_LAS unsigned*)(lds + (bufoff) + ldsw + _i * 8192), 16, 0, 0); } while (0)
; #define PG8_LDA(dst, b, h) do { _Pragma("unroll") for (int m = 0; m < 4; ++m) _Pragma("unroll") for (int k = 0; k < 2; ++k) dst[m][k] = *(const PG8_LAS bf16x8*)(lds + PG8_SA(b, h) + aoff + m * 2048 + k * 1024); } while (0)
; #define PG8_LDB(dst, b, h) do { _Pragma("unroll") for (int n = 0; n < 2; ++n) _Pragma("unroll") for (int k = 0; k < 2; ++k) dst[n][k] = *(const PG8_LAS bf16x8*)(lds + PG8_SB(b, h) + boff + n * 2048 + k * 1024); } while (0)
; #define PG8_MMA(ai, bj, At, Bt) do { __builtin_amdgcn_s_setprio(1); _Pragma("unroll") for (int m = 0; m < 4; ++m) _Pragma("unroll") for (int n = 0; n < 2; ++n) _Pragma("unroll") for (int k = 0; k < 2; ++k) \
;         acc[ai][bj][m][n] = __builtin_amdgcn_mfma_f32_16x16x32_bf16(Bt[n][k], At[m][k], acc[ai][bj][m][n], 0, 0, 0); __builtin_amdgcn_s_setprio(0); } while (0)
; #define PG8_WAIT_V(n) asm volatile("s_waitcnt vmcnt(" #n ")" ::: "memory")
; #define PG8_WAIT_L(n) asm volatile("s_waitcnt lgkmcnt(" #n ")" ::: "memory")
; #define PG8_BAR __builtin_amdgcn_s_barrier()
; #define PG8_SCHED __builtin_amdgcn_sched_barrier(0)
; template <class Epi, class Sched, bool ALIGN_EPI = false, bool SP2 = false>
; __device__ __forceinline__ void gemm_phase(PG8_LAS unsigned char* lds, const Gemm g, const Sched& S, const Epi& E) {
;     ...
;             PG8_LDA(At, 0, 1); PG8_STAGE(PG8_SB(0, 0), b2, voffB); PG8_STAGE(PG8_SB(0, 1), b2 + hstep, voffB); PG8_STAGE(PG8_SA(0, 0), a2, voffA);
;             PG8_WAIT_V(8); PG8_WAIT_L(0); PG8_BAR; PG8_MMA(1, 0, At, B0); PG8_MMA(1, 1, At, B1); PG8_BAR; PG8_SCHED;
;             PG8_LDB(B0, 1, 0); PG8_LDB(B1, 1, 1); PG8_SCHED; PG8_LDA(At, 1, 0); PG8_STAGE(PG8_SA(0, 1), a2 + hstep, voffA);
;             PG8_WAIT_V(8); PG8_WAIT_L(0); PG8_BAR; PG8_MMA(0, 0, At, B0); PG8_MMA(0, 1, At, B1); PG8_BAR; PG8_SCHED;
	s_add_i32 s48, s48, s35
	v_lshl_add_u64 v[154:155], s[26:27], 0, v[142:143]
	s_mov_b32 m0, s48
	ds_read_b128 v[190:193], v157 offset:16384
	ds_read_b128 v[194:197], v157 offset:17408
	ds_read_b128 v[198:201], v157 offset:18432
	ds_read_b128 v[202:205], v157 offset:19456
	ds_read_b128 v[206:209], v157 offset:20480
	ds_read_b128 v[210:213], v157 offset:21504
	ds_read_b128 v[214:217], v157 offset:22528
	ds_read_b128 v[218:221], v157 offset:23552
	global_load_lds_dwordx4 v[154:155], off
	s_add_i32 m0, s48, 0x2000
	s_add_u32 s48, s26, 0x40000
	v_lshl_add_u64 v[180:181], s[26:27], 0, v[138:139]
	s_addc_u32 s49, s27, 0
	s_add_i32 s50, s50, s35
	global_load_lds_dwordx4 v[180:181], off
	v_lshl_add_u64 v[182:183], s[48:49], 0, v[142:143]
	s_mov_b32 m0, s50
	v_lshl_add_u64 v[222:223], s[28:29], 0, v[140:141]
	global_load_lds_dwordx4 v[182:183], off
	v_lshl_add_u64 v[182:183], s[48:49], 0, v[138:139]
	s_add_i32 m0, s50, 0x2000
	s_nop 0
	global_load_lds_dwordx4 v[182:183], off
	v_lshl_add_u64 v[182:183], s[28:29], 0, v[144:145]
	s_mov_b32 m0, s23
	s_nop 0
	global_load_lds_dwordx4 v[182:183], off
	s_mov_b32 m0, s37
	s_nop 0
	global_load_lds_dwordx4 v[222:223], off
	s_waitcnt vmcnt(8) lgkmcnt(0)
	s_barrier
	s_setprio 1
	v_mfma_f32_16x16x32_bf16 v[62:65], v[94:97], v[190:193], 0
	v_mfma_f32_16x16x32_bf16 v[58:61], v[158:161], v[190:193], 0
	v_mfma_f32_16x16x32_bf16 v[50:53], v[94:97], v[198:201], 0
	v_mfma_f32_16x16x32_bf16 v[42:45], v[158:161], v[198:201], 0
	v_mfma_f32_16x16x32_bf16 v[34:37], v[94:97], v[206:209], 0
	v_mfma_f32_16x16x32_bf16 v[26:29], v[158:161], v[206:209], 0
	v_mfma_f32_16x16x32_bf16 v[18:21], v[94:97], v[214:217], 0
	v_mfma_f32_16x16x32_bf16 v[10:13], v[158:161], v[214:217], 0
	v_mfma_f32_16x16x32_bf16 v[62:65], v[134:137], v[194:197], v[62:65]
	v_mfma_f32_16x16x32_bf16 v[58:61], v[162:165], v[194:197], v[58:61]
	v_mfma_f32_16x16x32_bf16 v[50:53], v[134:137], v[202:205], v[50:53]
	v_mfma_f32_16x16x32_bf16 v[42:45], v[162:165], v[202:205], v[42:45]
	v_mfma_f32_16x16x32_bf16 v[34:37], v[134:137], v[210:213], v[34:37]
	v_mfma_f32_16x16x32_bf16 v[26:29], v[162:165], v[210:213], v[26:29]
	v_mfma_f32_16x16x32_bf16 v[18:21], v[134:137], v[218:221], v[18:21]
	v_mfma_f32_16x16x32_bf16 v[10:13], v[162:165], v[218:221], v[10:13]
	s_setprio 0
	s_setprio 1
	v_mfma_f32_16x16x32_bf16 v[54:57], v[166:169], v[190:193], 0
	v_mfma_f32_16x16x32_bf16 v[46:49], v[174:177], v[190:193], 0
	v_mfma_f32_16x16x32_bf16 v[38:41], v[166:169], v[198:201], 0
	v_mfma_f32_16x16x32_bf16 v[30:33], v[174:177], v[198:201], 0
	v_mfma_f32_16x16x32_bf16 v[22:25], v[166:169], v[206:209], 0
	v_mfma_f32_16x16x32_bf16 v[14:17], v[174:177], v[206:209], 0
	v_mfma_f32_16x16x32_bf16 v[6:9], v[166:169], v[214:217], 0
	v_mfma_f32_16x16x32_bf16 v[2:5], v[174:177], v[214:217], 0
	v_mfma_f32_16x16x32_bf16 v[54:57], v[170:173], v[194:197], v[54:57]
	v_mfma_f32_16x16x32_bf16 v[46:49], v[186:189], v[194:197], v[46:49]
	v_mfma_f32_16x16x32_bf16 v[38:41], v[170:173], v[202:205], v[38:41]
	v_mfma_f32_16x16x32_bf16 v[30:33], v[186:189], v[202:205], v[30:33]
	v_mfma_f32_16x16x32_bf16 v[22:25], v[170:173], v[210:213], v[22:25]
	v_mfma_f32_16x16x32_bf16 v[14:17], v[186:189], v[210:213], v[14:17]
	v_mfma_f32_16x16x32_bf16 v[6:9], v[170:173], v[218:221], v[6:9]
	v_mfma_f32_16x16x32_bf16 v[2:5], v[186:189], v[218:221], v[2:5]
	s_setprio 0
	s_barrier
	s_add_i32 s48, 0, 0x18000
	s_add_i32 s49, 0, 0x1c000
	v_add_u32_e32 v162, s48, v156
	v_add_u32_e32 v179, s49, v156
	ds_read_b128 v[94:97], v162
	ds_read_b128 v[134:137], v162 offset:1024
	ds_read_b128 v[158:161], v162 offset:2048
	ds_read_b128 v[162:165], v162 offset:3072
	ds_read_b128 v[166:169], v179
	ds_read_b128 v[170:173], v179 offset:1024
	ds_read_b128 v[174:177], v179 offset:2048
	ds_read_b128 v[186:189], v179 offset:3072
	s_add_u32 s28, s28, 0x40000
	s_addc_u32 s29, s29, 0
	s_mov_b32 m0, s38
	v_lshl_add_u64 v[240:241], s[28:29], 0, v[144:145]
	ds_read_b128 v[190:193], v157 offset:32768
	ds_read_b128 v[194:197], v157 offset:33792
	ds_read_b128 v[198:201], v157 offset:34816
	ds_read_b128 v[202:205], v157 offset:35840
	ds_read_b128 v[206:209], v157 offset:36864
	ds_read_b128 v[210:213], v157 offset:37888
	ds_read_b128 v[214:217], v157 offset:38912
	ds_read_b128 v[218:221], v157 offset:39936
	global_load_lds_dwordx4 v[240:241], off
	v_lshl_add_u64 v[240:241], s[28:29], 0, v[140:141]
	s_mov_b32 m0, s39
	s_nop 0
	global_load_lds_dwordx4 v[240:241], off
	s_waitcnt vmcnt(8) lgkmcnt(0)
	s_barrier
	s_setprio 1
	v_mfma_f32_16x16x32_bf16 v[130:133], v[94:97], v[190:193], v[130:133]
	v_mfma_f32_16x16x32_bf16 v[126:129], v[158:161], v[190:193], v[126:129]
	v_mfma_f32_16x16x32_bf16 v[114:117], v[94:97], v[198:201], v[114:117]
	v_mfma_f32_16x16x32_bf16 v[110:113], v[158:161], v[198:201], v[110:113]
	v_mfma_f32_16x16x32_bf16 v[98:101], v[94:97], v[206:209], v[98:101]
	v_mfma_f32_16x16x32_bf16 v[90:93], v[158:161], v[206:209], v[90:93]
	v_mfma_f32_16x16x32_bf16 v[78:81], v[94:97], v[214:217], v[78:81]
	v_mfma_f32_16x16x32_bf16 v[74:77], v[158:161], v[214:217], v[74:77]
	v_mfma_f32_16x16x32_bf16 v[130:133], v[134:137], v[194:197], v[130:133]
	v_mfma_f32_16x16x32_bf16 v[126:129], v[162:165], v[194:197], v[126:129]
	v_mfma_f32_16x16x32_bf16 v[114:117], v[134:137], v[202:205], v[114:117]
	v_mfma_f32_16x16x32_bf16 v[110:113], v[162:165], v[202:205], v[110:113]
	v_mfma_f32_16x16x32_bf16 v[98:101], v[134:137], v[210:213], v[98:101]
	v_mfma_f32_16x16x32_bf16 v[90:93], v[162:165], v[210:213], v[90:93]
	v_mfma_f32_16x16x32_bf16 v[78:81], v[134:137], v[218:221], v[78:81]
	v_mfma_f32_16x16x32_bf16 v[74:77], v[162:165], v[218:221], v[74:77]
	s_setprio 0
	s_setprio 1
	v_mfma_f32_16x16x32_bf16 v[122:125], v[166:169], v[190:193], v[122:125]
	v_mfma_f32_16x16x32_bf16 v[118:121], v[174:177], v[190:193], v[118:121]
	v_mfma_f32_16x16x32_bf16 v[106:109], v[166:169], v[198:201], v[106:109]
	v_mfma_f32_16x16x32_bf16 v[102:105], v[174:177], v[198:201], v[102:105]
	v_mfma_f32_16x16x32_bf16 v[86:89], v[166:169], v[206:209], v[86:89]
	v_mfma_f32_16x16x32_bf16 v[82:85], v[174:177], v[206:209], v[82:85]
	v_mfma_f32_16x16x32_bf16 v[70:73], v[166:169], v[214:217], v[70:73]
	v_mfma_f32_16x16x32_bf16 v[66:69], v[174:177], v[214:217], v[66:69]
	v_mfma_f32_16x16x32_bf16 v[122:125], v[170:173], v[194:197], v[122:125]
	v_mfma_f32_16x16x32_bf16 v[118:121], v[186:189], v[194:197], v[118:121]
	v_mfma_f32_16x16x32_bf16 v[106:109], v[170:173], v[202:205], v[106:109]
	v_mfma_f32_16x16x32_bf16 v[102:105], v[186:189], v[202:205], v[102:105]
	v_mfma_f32_16x16x32_bf16 v[86:89], v[170:173], v[210:213], v[86:89]
	v_mfma_f32_16x16x32_bf16 v[82:85], v[186:189], v[210:213], v[82:85]
	v_mfma_f32_16x16x32_bf16 v[70:73], v[170:173], v[218:221], v[70:73]
	v_mfma_f32_16x16x32_bf16 v[66:69], v[186:189], v[218:221], v[66:69]
	s_setprio 0
	s_barrier
; #define PG8_STAGE(bufoff, gbase, voff) do { _Pragma("unroll") for (int _i = 0; _i < 2; ++_i) \
;         __builtin_amdgcn_global_load_lds((const unsigned*)((const char*)(gbase) + (voff)[_i]), (PG8_LAS unsigned*)(lds + (bufoff) + ldsw + _i * 8192), 16, 0, 0); } while (0)
; #define PG8_LDA(dst, b, h) do { _Pragma("unroll") for (int m = 0; m < 4; ++m) _Pragma("unroll") for (int k = 0; k < 2; ++k) dst[m][k] = *(const PG8_LAS bf16x8*)(lds + PG8_SA(b, h) + aoff + m * 2048 + k * 1024); } while (0)
; #define PG8_LDB(dst, b, h) do { _Pragma("unroll") for (int n = 0; n < 2; ++n) _Pragma("unroll") for (int k = 0; k < 2; ++k) dst[n][k] = *(const PG8_LAS bf16x8*)(lds + PG8_SB(b, h) + boff + n * 2048 + k * 1024); } while (0)
; #define PG8_MMA(ai, bj, At, Bt) do { __builtin_amdgcn_s_setprio(1); _Pragma("unroll") for (int m = 0; m < 4; ++m) _Pragma("unroll") for (int n = 0; n < 2; ++n) _Pragma("unroll") for (int k = 0; k < 2; ++k) \
;         acc[ai][bj][m][n] = __builtin_amdgcn_mfma_f32_16x16x32_bf16(Bt[n][k], At[m][k], acc[ai][bj][m][n], 0, 0, 0); __builtin_amdgcn_s_setprio(0); } while (0)
; #define PG8_WAIT_V(n) asm volatile("s_waitcnt vmcnt(" #n ")" ::: "memory")
; #define PG8_WAIT_L(n) asm volatile("s_waitcnt lgkmcnt(" #n ")" ::: "memory")
; #define PG8_BAR __builtin_amdgcn_s_barrier()
; #define PG8_SCHED __builtin_amdgcn_sched_barrier(0)
; template <class Epi, class Sched, bool ALIGN_EPI = false, bool SP2 = false>
; __device__ __forceinline__ void gemm_phase(PG8_LAS unsigned char* lds, const Gemm g, const Sched& S, const Epi& E) {
;     ...
;             PG8_LDB(B0, 0, 0); PG8_LDB(B1, 0, 1); PG8_SCHED; PG8_LDA(At, 0, 0); PG8_STAGE(PG8_SA(1, 1), a1 + hstep, voffA);
;             PG8_WAIT_V(8); PG8_WAIT_L(0); PG8_BAR; PG8_MMA(0, 0, At, B0); PG8_MMA(0, 1, At, B1); PG8_BAR; PG8_SCHED;
;     ...
;             PG8_LDA(At, 1, 1); PG8_STAGE(PG8_SB(1, 0), b3, voffB); PG8_STAGE(PG8_SB(1, 1), b3 + hstep, voffB); PG8_STAGE(PG8_SA(1, 0), a3, voffA);
;             PG8_WAIT_V(8); PG8_WAIT_L(0); PG8_BAR; PG8_MMA(1, 0, At, B0); PG8_MMA(1, 1, At, B1); PG8_BAR; PG8_SCHED;
	s_add_i32 s28, s48, s35
	v_lshl_add_u64 v[154:155], v[154:155], 0, s[80:81]
	s_mov_b32 m0, s28
	ds_read_b128 v[190:193], v157 offset:49152
	ds_read_b128 v[194:197], v157 offset:50176
	ds_read_b128 v[198:201], v157 offset:51200
	ds_read_b128 v[202:205], v157 offset:52224
	ds_read_b128 v[206:209], v157 offset:53248
	ds_read_b128 v[210:213], v157 offset:54272
	ds_read_b128 v[214:217], v157 offset:55296
	ds_read_b128 v[218:221], v157 offset:56320
	global_load_lds_dwordx4 v[154:155], off
	s_add_i32 m0, s28, 0x2000
	s_add_u32 s26, s26, 0x40080
	v_lshl_add_u64 v[154:155], v[180:181], 0, s[80:81]
	s_addc_u32 s27, s27, 0
	s_add_i32 s28, s49, s35
	global_load_lds_dwordx4 v[154:155], off
	v_lshl_add_u64 v[154:155], s[26:27], 0, v[142:143]
	s_mov_b32 m0, s28
	s_nop 0
	global_load_lds_dwordx4 v[154:155], off
	v_lshl_add_u64 v[154:155], s[26:27], 0, v[138:139]
	s_add_i32 m0, s28, 0x2000
	s_nop 0
	global_load_lds_dwordx4 v[154:155], off
	v_lshl_add_u64 v[154:155], v[182:183], 0, s[80:81]
	s_mov_b32 m0, s40
	s_nop 0
	global_load_lds_dwordx4 v[154:155], off
	v_lshl_add_u64 v[154:155], v[222:223], 0, s[80:81]
	s_mov_b32 m0, s41
	s_nop 0
	global_load_lds_dwordx4 v[154:155], off
	s_waitcnt vmcnt(8) lgkmcnt(0)
	s_barrier
	s_setprio 1
	v_mfma_f32_16x16x32_bf16 v[62:65], v[94:97], v[190:193], v[62:65]
	v_mfma_f32_16x16x32_bf16 v[58:61], v[158:161], v[190:193], v[58:61]
	v_mfma_f32_16x16x32_bf16 v[50:53], v[94:97], v[198:201], v[50:53]
	v_mfma_f32_16x16x32_bf16 v[42:45], v[158:161], v[198:201], v[42:45]
	v_mfma_f32_16x16x32_bf16 v[34:37], v[94:97], v[206:209], v[34:37]
	v_mfma_f32_16x16x32_bf16 v[26:29], v[158:161], v[206:209], v[26:29]
	v_mfma_f32_16x16x32_bf16 v[18:21], v[94:97], v[214:217], v[18:21]
	v_mfma_f32_16x16x32_bf16 v[10:13], v[158:161], v[214:217], v[10:13]
	v_mfma_f32_16x16x32_bf16 v[62:65], v[134:137], v[194:197], v[62:65]
	v_mfma_f32_16x16x32_bf16 v[58:61], v[162:165], v[194:197], v[58:61]
	v_mfma_f32_16x16x32_bf16 v[50:53], v[134:137], v[202:205], v[50:53]
	v_mfma_f32_16x16x32_bf16 v[42:45], v[162:165], v[202:205], v[42:45]
	v_mfma_f32_16x16x32_bf16 v[34:37], v[134:137], v[210:213], v[34:37]
	v_mfma_f32_16x16x32_bf16 v[26:29], v[162:165], v[210:213], v[26:29]
	v_mfma_f32_16x16x32_bf16 v[18:21], v[134:137], v[218:221], v[18:21]
	v_mfma_f32_16x16x32_bf16 v[10:13], v[162:165], v[218:221], v[10:13]
	s_setprio 0
	s_setprio 1
	v_mfma_f32_16x16x32_bf16 v[54:57], v[166:169], v[190:193], v[54:57]
	v_mfma_f32_16x16x32_bf16 v[46:49], v[174:177], v[190:193], v[46:49]
	v_mfma_f32_16x16x32_bf16 v[38:41], v[166:169], v[198:201], v[38:41]
	v_mfma_f32_16x16x32_bf16 v[30:33], v[174:177], v[198:201], v[30:33]
	v_mfma_f32_16x16x32_bf16 v[22:25], v[166:169], v[206:209], v[22:25]
	v_mfma_f32_16x16x32_bf16 v[14:17], v[174:177], v[206:209], v[14:17]
	v_mfma_f32_16x16x32_bf16 v[6:9], v[166:169], v[214:217], v[6:9]
	v_mfma_f32_16x16x32_bf16 v[2:5], v[174:177], v[214:217], v[2:5]
	v_mfma_f32_16x16x32_bf16 v[54:57], v[170:173], v[194:197], v[54:57]
	v_mfma_f32_16x16x32_bf16 v[46:49], v[186:189], v[194:197], v[46:49]
	v_mfma_f32_16x16x32_bf16 v[38:41], v[170:173], v[202:205], v[38:41]
	v_mfma_f32_16x16x32_bf16 v[30:33], v[186:189], v[202:205], v[30:33]
	v_mfma_f32_16x16x32_bf16 v[22:25], v[170:173], v[210:213], v[22:25]
	v_mfma_f32_16x16x32_bf16 v[14:17], v[186:189], v[210:213], v[14:17]
	v_mfma_f32_16x16x32_bf16 v[6:9], v[170:173], v[218:221], v[6:9]
	v_mfma_f32_16x16x32_bf16 v[2:5], v[186:189], v[218:221], v[2:5]
	s_setprio 0
	s_barrier
	s_add_i32 s47, s47, 2
	s_add_u32 s24, s24, 0x100
	s_addc_u32 s25, s25, 0
	s_add_u32 s45, s45, 0x100
	s_addc_u32 s46, s46, 0
	s_cmp_gt_u32 s47, 13
	s_branch .LBB0_301
.LBB0_301:
	s_add_u32 s26, s24, 0xfffc0080
	s_addc_u32 s27, s25, -1
	s_add_i32 s48, 0, 0x10000
	s_cmp_eq_u32 s47, 12
	s_cselect_b32 s29, s13, s27
	s_cselect_b32 s28, s21, s26
	v_add_u32_e32 v154, s48, v156
	s_cselect_b32 s27, s11, s46
	s_cselect_b32 s26, s44, s45
	s_add_i32 s50, 0, 0x14000
	ds_read_b128 v[94:97], v154
	ds_read_b128 v[134:137], v154 offset:1024
	ds_read_b128 v[158:161], v154 offset:2048
	ds_read_b128 v[162:165], v154 offset:3072
	v_add_u32_e32 v154, s50, v156
	ds_read_b128 v[166:169], v154
	ds_read_b128 v[170:173], v154 offset:1024
	ds_read_b128 v[174:177], v154 offset:2048
	ds_read_b128 v[186:189], v154 offset:3072
	v_lshl_add_u64 v[154:155], s[24:25], 0, v[150:151]
	s_add_i32 m0, s23, 0xc000
	ds_read_b128 v[190:193], v157
	ds_read_b128 v[194:197], v157 offset:1024
	ds_read_b128 v[198:201], v157 offset:2048
	ds_read_b128 v[202:205], v157 offset:3072
	ds_read_b128 v[206:209], v157 offset:4096
	ds_read_b128 v[210:213], v157 offset:5120
	ds_read_b128 v[214:217], v157 offset:6144
	ds_read_b128 v[218:221], v157 offset:7168
	global_load_lds_dwordx4 v[154:155], off
	v_lshl_add_u64 v[154:155], s[24:25], 0, v[152:153]
	s_add_i32 m0, s23, 0xe000
	s_nop 0
	global_load_lds_dwordx4 v[154:155], off
	s_waitcnt vmcnt(8) lgkmcnt(0)
	s_barrier
; #define PG8_STAGE(bufoff, gbase, voff) do { _Pragma("unroll") for (int _i = 0; _i < 2; ++_i) \
;         __builtin_amdgcn_global_load_lds((const unsigned*)((const char*)(gbase) + (voff)[_i]), (PG8_LAS unsigned*)(lds + (bufoff) + ldsw + _i * 8192), 16, 0, 0); } while (0)
; #define PG8_LDA(dst, b, h) do { _Pragma("unroll") for (int m = 0; m < 4; ++m) _Pragma("unroll") for (int k = 0; k < 2; ++k) dst[m][k] = *(const PG8_LAS bf16x8*)(lds + PG8_SA(b, h) + aoff + m * 2048 + k * 1024); } while (0)
; #define PG8_MMA(ai, bj, At, Bt) do { __builtin_amdgcn_s_setprio(1); _Pragma("unroll") for (int m = 0; m < 4; ++m) _Pragma("unroll") for (int n = 0; n < 2; ++n) _Pragma("unroll") for (int k = 0; k < 2; ++k) \
;         acc[ai][bj][m][n] = __builtin_amdgcn_mfma_f32_16x16x32_bf16(Bt[n][k], At[m][k], acc[ai][bj][m][n], 0, 0, 0); __builtin_amdgcn_s_setprio(0); } while (0)
; #define PG8_WAIT_V(n) asm volatile("s_waitcnt vmcnt(" #n ")" ::: "memory")
; #define PG8_WAIT_L(n) asm volatile("s_waitcnt lgkmcnt(" #n ")" ::: "memory")
; #define PG8_BAR __builtin_amdgcn_s_barrier()
; #define PG8_SCHED __builtin_amdgcn_sched_barrier(0)
; template <class Epi, class Sched, bool ALIGN_EPI = false, bool SP2 = false>
; __device__ __forceinline__ void gemm_phase(PG8_LAS unsigned char* lds, const Gemm g, const Sched& S, const Epi& E) {
;     ...
;             PG8_WAIT_V(8); PG8_WAIT_L(0); PG8_BAR; PG8_MMA(0, 0, At, B0); PG8_MMA(0, 1, At, B1); PG8_BAR; PG8_SCHED;
;             PG8_LDA(At, 0, 1); PG8_STAGE(PG8_SB(0, 0), b2, voffB); PG8_STAGE(PG8_SB(0, 1), b2 + hstep, voffB); PG8_STAGE(PG8_SA(0, 0), a2, voffA);
;             PG8_WAIT_V(8); PG8_WAIT_L(0); PG8_BAR; PG8_MMA(1, 0, At, B0); PG8_MMA(1, 1, At, B1); PG8_BAR; PG8_SCHED;
	s_setprio 1
	v_mfma_f32_16x16x32_bf16 v[130:133], v[94:97], v[190:193], v[130:133]
	v_mfma_f32_16x16x32_bf16 v[126:129], v[158:161], v[190:193], v[126:129]
	v_mfma_f32_16x16x32_bf16 v[114:117], v[94:97], v[198:201], v[114:117]
	v_mfma_f32_16x16x32_bf16 v[110:113], v[158:161], v[198:201], v[110:113]
	v_mfma_f32_16x16x32_bf16 v[98:101], v[94:97], v[206:209], v[98:101]
	v_mfma_f32_16x16x32_bf16 v[90:93], v[158:161], v[206:209], v[90:93]
	v_mfma_f32_16x16x32_bf16 v[78:81], v[94:97], v[214:217], v[78:81]
	v_mfma_f32_16x16x32_bf16 v[74:77], v[158:161], v[214:217], v[74:77]
	v_mfma_f32_16x16x32_bf16 v[130:133], v[134:137], v[194:197], v[130:133]
	v_mfma_f32_16x16x32_bf16 v[126:129], v[162:165], v[194:197], v[126:129]
	v_mfma_f32_16x16x32_bf16 v[114:117], v[134:137], v[202:205], v[114:117]
	v_mfma_f32_16x16x32_bf16 v[110:113], v[162:165], v[202:205], v[110:113]
	v_mfma_f32_16x16x32_bf16 v[98:101], v[134:137], v[210:213], v[98:101]
	v_mfma_f32_16x16x32_bf16 v[90:93], v[162:165], v[210:213], v[90:93]
	v_mfma_f32_16x16x32_bf16 v[78:81], v[134:137], v[218:221], v[78:81]
	v_mfma_f32_16x16x32_bf16 v[74:77], v[162:165], v[218:221], v[74:77]
	s_setprio 0
	s_setprio 1
	v_mfma_f32_16x16x32_bf16 v[122:125], v[166:169], v[190:193], v[122:125]
	v_mfma_f32_16x16x32_bf16 v[118:121], v[174:177], v[190:193], v[118:121]
	v_mfma_f32_16x16x32_bf16 v[106:109], v[166:169], v[198:201], v[106:109]
	v_mfma_f32_16x16x32_bf16 v[102:105], v[174:177], v[198:201], v[102:105]
	v_mfma_f32_16x16x32_bf16 v[86:89], v[166:169], v[206:209], v[86:89]
	v_mfma_f32_16x16x32_bf16 v[82:85], v[174:177], v[206:209], v[82:85]
	v_mfma_f32_16x16x32_bf16 v[70:73], v[166:169], v[214:217], v[70:73]
	v_mfma_f32_16x16x32_bf16 v[66:69], v[174:177], v[214:217], v[66:69]
	v_mfma_f32_16x16x32_bf16 v[122:125], v[170:173], v[194:197], v[122:125]
	v_mfma_f32_16x16x32_bf16 v[118:121], v[186:189], v[194:197], v[118:121]
	v_mfma_f32_16x16x32_bf16 v[106:109], v[170:173], v[202:205], v[106:109]
	v_mfma_f32_16x16x32_bf16 v[102:105], v[186:189], v[202:205], v[102:105]
	v_mfma_f32_16x16x32_bf16 v[86:89], v[170:173], v[210:213], v[86:89]
	v_mfma_f32_16x16x32_bf16 v[82:85], v[186:189], v[210:213], v[82:85]
	v_mfma_f32_16x16x32_bf16 v[70:73], v[170:173], v[218:221], v[70:73]
	v_mfma_f32_16x16x32_bf16 v[66:69], v[186:189], v[218:221], v[66:69]
	s_setprio 0
	s_barrier
	s_add_i32 s48, s48, s35
	v_lshl_add_u64 v[154:155], s[26:27], 0, v[142:143]
	s_mov_b32 m0, s48
	ds_read_b128 v[190:193], v157 offset:16384
	ds_read_b128 v[194:197], v157 offset:17408
	ds_read_b128 v[198:201], v157 offset:18432
	ds_read_b128 v[202:205], v157 offset:19456
	ds_read_b128 v[206:209], v157 offset:20480
	ds_read_b128 v[210:213], v157 offset:21504
	ds_read_b128 v[214:217], v157 offset:22528
	ds_read_b128 v[218:221], v157 offset:23552
	global_load_lds_dwordx4 v[154:155], off
	s_add_i32 m0, s48, 0x2000
	s_add_u32 s48, s26, 0x40000
	v_lshl_add_u64 v[180:181], s[26:27], 0, v[138:139]
	s_addc_u32 s49, s27, 0
	s_add_i32 s50, s50, s35
	global_load_lds_dwordx4 v[180:181], off
	v_lshl_add_u64 v[182:183], s[48:49], 0, v[142:143]
	s_mov_b32 m0, s50
	v_lshl_add_u64 v[222:223], s[28:29], 0, v[140:141]
	global_load_lds_dwordx4 v[182:183], off
	v_lshl_add_u64 v[182:183], s[48:49], 0, v[138:139]
	s_add_i32 m0, s50, 0x2000
	s_nop 0
	global_load_lds_dwordx4 v[182:183], off
	v_lshl_add_u64 v[182:183], s[28:29], 0, v[144:145]
	s_mov_b32 m0, s23
	s_nop 0
	global_load_lds_dwordx4 v[182:183], off
	s_mov_b32 m0, s37
	s_nop 0
	global_load_lds_dwordx4 v[222:223], off
	s_waitcnt vmcnt(8) lgkmcnt(0)
	s_barrier
	s_setprio 1
	v_mfma_f32_16x16x32_bf16 v[62:65], v[94:97], v[190:193], v[62:65]
	v_mfma_f32_16x16x32_bf16 v[58:61], v[158:161], v[190:193], v[58:61]
	v_mfma_f32_16x16x32_bf16 v[50:53], v[94:97], v[198:201], v[50:53]
	v_mfma_f32_16x16x32_bf16 v[42:45], v[158:161], v[198:201], v[42:45]
	v_mfma_f32_16x16x32_bf16 v[34:37], v[94:97], v[206:209], v[34:37]
	v_mfma_f32_16x16x32_bf16 v[26:29], v[158:161], v[206:209], v[26:29]
	v_mfma_f32_16x16x32_bf16 v[18:21], v[94:97], v[214:217], v[18:21]
	v_mfma_f32_16x16x32_bf16 v[10:13], v[158:161], v[214:217], v[10:13]
	v_mfma_f32_16x16x32_bf16 v[62:65], v[134:137], v[194:197], v[62:65]
	v_mfma_f32_16x16x32_bf16 v[58:61], v[162:165], v[194:197], v[58:61]
	v_mfma_f32_16x16x32_bf16 v[50:53], v[134:137], v[202:205], v[50:53]
	v_mfma_f32_16x16x32_bf16 v[42:45], v[162:165], v[202:205], v[42:45]
	v_mfma_f32_16x16x32_bf16 v[34:37], v[134:137], v[210:213], v[34:37]
	v_mfma_f32_16x16x32_bf16 v[26:29], v[162:165], v[210:213], v[26:29]
	v_mfma_f32_16x16x32_bf16 v[18:21], v[134:137], v[218:221], v[18:21]
	v_mfma_f32_16x16x32_bf16 v[10:13], v[162:165], v[218:221], v[10:13]
	s_setprio 0
	s_setprio 1
	v_mfma_f32_16x16x32_bf16 v[54:57], v[166:169], v[190:193], v[54:57]
	v_mfma_f32_16x16x32_bf16 v[46:49], v[174:177], v[190:193], v[46:49]
	v_mfma_f32_16x16x32_bf16 v[38:41], v[166:169], v[198:201], v[38:41]
	v_mfma_f32_16x16x32_bf16 v[30:33], v[174:177], v[198:201], v[30:33]
	v_mfma_f32_16x16x32_bf16 v[22:25], v[166:169], v[206:209], v[22:25]
	v_mfma_f32_16x16x32_bf16 v[14:17], v[174:177], v[206:209], v[14:17]
	v_mfma_f32_16x16x32_bf16 v[6:9], v[166:169], v[214:217], v[6:9]
	v_mfma_f32_16x16x32_bf16 v[2:5], v[174:177], v[214:217], v[2:5]
	v_mfma_f32_16x16x32_bf16 v[54:57], v[170:173], v[194:197], v[54:57]
	v_mfma_f32_16x16x32_bf16 v[46:49], v[186:189], v[194:197], v[46:49]
	v_mfma_f32_16x16x32_bf16 v[38:41], v[170:173], v[202:205], v[38:41]
	v_mfma_f32_16x16x32_bf16 v[30:33], v[186:189], v[202:205], v[30:33]
	v_mfma_f32_16x16x32_bf16 v[22:25], v[170:173], v[210:213], v[22:25]
	v_mfma_f32_16x16x32_bf16 v[14:17], v[186:189], v[210:213], v[14:17]
	v_mfma_f32_16x16x32_bf16 v[6:9], v[170:173], v[218:221], v[6:9]
	v_mfma_f32_16x16x32_bf16 v[2:5], v[186:189], v[218:221], v[2:5]
	s_setprio 0
	s_barrier
; #define PG8_STAGE(bufoff, gbase, voff) do { _Pragma("unroll") for (int _i = 0; _i < 2; ++_i) \
;         __builtin_amdgcn_global_load_lds((const unsigned*)((const char*)(gbase) + (voff)[_i]), (PG8_LAS unsigned*)(lds + (bufoff) + ldsw + _i * 8192), 16, 0, 0); } while (0)
; #define PG8_LDA(dst, b, h) do { _Pragma("unroll") for (int m = 0; m < 4; ++m) _Pragma("unroll") for (int k = 0; k < 2; ++k) dst[m][k] = *(const PG8_LAS bf16x8*)(lds + PG8_SA(b, h) + aoff + m * 2048 + k * 1024); } while (0)
; #define PG8_LDB(dst, b, h) do { _Pragma("unroll") for (int n = 0; n < 2; ++n) _Pragma("unroll") for (int k = 0; k < 2; ++k) dst[n][k] = *(const PG8_LAS bf16x8*)(lds + PG8_SB(b, h) + boff + n * 2048 + k * 1024); } while (0)
; #define PG8_MMA(ai, bj, At, Bt) do { __builtin_amdgcn_s_setprio(1); _Pragma("unroll") for (int m = 0; m < 4; ++m) _Pragma("unroll") for (int n = 0; n < 2; ++n) _Pragma("unroll") for (int k = 0; k < 2; ++k) \
;         acc[ai][bj][m][n] = __builtin_amdgcn_mfma_f32_16x16x32_bf16(Bt[n][k], At[m][k], acc[ai][bj][m][n], 0, 0, 0); __builtin_amdgcn_s_setprio(0); } while (0)
; #define PG8_WAIT_V(n) asm volatile("s_waitcnt vmcnt(" #n ")" ::: "memory")
; #define PG8_WAIT_L(n) asm volatile("s_waitcnt lgkmcnt(" #n ")" ::: "memory")
; #define PG8_BAR __builtin_amdgcn_s_barrier()
; #define PG8_SCHED __builtin_amdgcn_sched_barrier(0)
; template <class Epi, class Sched, bool ALIGN_EPI = false, bool SP2 = false>
; __device__ __forceinline__ void gemm_phase(PG8_LAS unsigned char* lds, const Gemm g, const Sched& S, const Epi& E) {
;     ...
;             PG8_LDB(B0, 1, 0); PG8_LDB(B1, 1, 1); PG8_SCHED; PG8_LDA(At, 1, 0); PG8_STAGE(PG8_SA(0, 1), a2 + hstep, voffA);
;             PG8_WAIT_V(8); PG8_WAIT_L(0); PG8_BAR; PG8_MMA(0, 0, At, B0); PG8_MMA(0, 1, At, B1); PG8_BAR; PG8_SCHED;
	s_add_i32 s48, 0, 0x18000
	s_add_i32 s49, 0, 0x1c000
	v_add_u32_e32 v162, s48, v156
	v_add_u32_e32 v179, s49, v156
	ds_read_b128 v[94:97], v162
	ds_read_b128 v[134:137], v162 offset:1024
	ds_read_b128 v[158:161], v162 offset:2048
	ds_read_b128 v[162:165], v162 offset:3072
	ds_read_b128 v[166:169], v179
	ds_read_b128 v[170:173], v179 offset:1024
	ds_read_b128 v[174:177], v179 offset:2048
	ds_read_b128 v[186:189], v179 offset:3072
	s_add_u32 s28, s28, 0x40000
	s_addc_u32 s29, s29, 0
	s_mov_b32 m0, s38
	v_lshl_add_u64 v[240:241], s[28:29], 0, v[144:145]
	ds_read_b128 v[190:193], v157 offset:32768
	ds_read_b128 v[194:197], v157 offset:33792
	ds_read_b128 v[198:201], v157 offset:34816
	ds_read_b128 v[202:205], v157 offset:35840
	ds_read_b128 v[206:209], v157 offset:36864
	ds_read_b128 v[210:213], v157 offset:37888
	ds_read_b128 v[214:217], v157 offset:38912
	ds_read_b128 v[218:221], v157 offset:39936
	global_load_lds_dwordx4 v[240:241], off
	v_lshl_add_u64 v[240:241], s[28:29], 0, v[140:141]
	s_mov_b32 m0, s39
	s_nop 0
	global_load_lds_dwordx4 v[240:241], off
	s_waitcnt vmcnt(8) lgkmcnt(0)
	s_barrier
	s_setprio 1
	v_mfma_f32_16x16x32_bf16 v[130:133], v[94:97], v[190:193], v[130:133]
	v_mfma_f32_16x16x32_bf16 v[126:129], v[158:161], v[190:193], v[126:129]
	v_mfma_f32_16x16x32_bf16 v[114:117], v[94:97], v[198:201], v[114:117]
	v_mfma_f32_16x16x32_bf16 v[110:113], v[158:161], v[198:201], v[110:113]
	v_mfma_f32_16x16x32_bf16 v[98:101], v[94:97], v[206:209], v[98:101]
	v_mfma_f32_16x16x32_bf16 v[90:93], v[158:161], v[206:209], v[90:93]
	v_mfma_f32_16x16x32_bf16 v[78:81], v[94:97], v[214:217], v[78:81]
	v_mfma_f32_16x16x32_bf16 v[74:77], v[158:161], v[214:217], v[74:77]
	v_mfma_f32_16x16x32_bf16 v[130:133], v[134:137], v[194:197], v[130:133]
	v_mfma_f32_16x16x32_bf16 v[126:129], v[162:165], v[194:197], v[126:129]
	v_mfma_f32_16x16x32_bf16 v[114:117], v[134:137], v[202:205], v[114:117]
	v_mfma_f32_16x16x32_bf16 v[110:113], v[162:165], v[202:205], v[110:113]
	v_mfma_f32_16x16x32_bf16 v[98:101], v[134:137], v[210:213], v[98:101]
	v_mfma_f32_16x16x32_bf16 v[90:93], v[162:165], v[210:213], v[90:93]
	v_mfma_f32_16x16x32_bf16 v[78:81], v[134:137], v[218:221], v[78:81]
	v_mfma_f32_16x16x32_bf16 v[74:77], v[162:165], v[218:221], v[74:77]
	s_setprio 0
	s_setprio 1
	v_mfma_f32_16x16x32_bf16 v[122:125], v[166:169], v[190:193], v[122:125]
	v_mfma_f32_16x16x32_bf16 v[118:121], v[174:177], v[190:193], v[118:121]
	v_mfma_f32_16x16x32_bf16 v[106:109], v[166:169], v[198:201], v[106:109]
	v_mfma_f32_16x16x32_bf16 v[102:105], v[174:177], v[198:201], v[102:105]
	v_mfma_f32_16x16x32_bf16 v[86:89], v[166:169], v[206:209], v[86:89]
	v_mfma_f32_16x16x32_bf16 v[82:85], v[174:177], v[206:209], v[82:85]
	v_mfma_f32_16x16x32_bf16 v[70:73], v[166:169], v[214:217], v[70:73]
	v_mfma_f32_16x16x32_bf16 v[66:69], v[174:177], v[214:217], v[66:69]
	v_mfma_f32_16x16x32_bf16 v[122:125], v[170:173], v[194:197], v[122:125]
	v_mfma_f32_16x16x32_bf16 v[118:121], v[186:189], v[194:197], v[118:121]
	v_mfma_f32_16x16x32_bf16 v[106:109], v[170:173], v[202:205], v[106:109]
	v_mfma_f32_16x16x32_bf16 v[102:105], v[186:189], v[202:205], v[102:105]
	v_mfma_f32_16x16x32_bf16 v[86:89], v[170:173], v[210:213], v[86:89]
	v_mfma_f32_16x16x32_bf16 v[82:85], v[186:189], v[210:213], v[82:85]
	v_mfma_f32_16x16x32_bf16 v[70:73], v[170:173], v[218:221], v[70:73]
	v_mfma_f32_16x16x32_bf16 v[66:69], v[186:189], v[218:221], v[66:69]
	s_setprio 0
	s_barrier
; #define PG8_STAGE(bufoff, gbase, voff) do { _Pragma("unroll") for (int _i = 0; _i < 2; ++_i) \
;         __builtin_amdgcn_global_load_lds((const unsigned*)((const char*)(gbase) + (voff)[_i]), (PG8_LAS unsigned*)(lds + (bufoff) + ldsw + _i * 8192), 16, 0, 0); } while (0)
; #define PG8_LDA(dst, b, h) do { _Pragma("unroll") for (int m = 0; m < 4; ++m) _Pragma("unroll") for (int k = 0; k < 2; ++k) dst[m][k] = *(const PG8_LAS bf16x8*)(lds + PG8_SA(b, h) + aoff + m * 2048 + k * 1024); } while (0)
; #define PG8_MMA(ai, bj, At, Bt) do { __builtin_amdgcn_s_setprio(1); _Pragma("unroll") for (int m = 0; m < 4; ++m) _Pragma("unroll") for (int n = 0; n < 2; ++n) _Pragma("unroll") for (int k = 0; k < 2; ++k) \
;         acc[ai][bj][m][n] = __builtin_amdgcn_mfma_f32_16x16x32_bf16(Bt[n][k], At[m][k], acc[ai][bj][m][n], 0, 0, 0); __builtin_amdgcn_s_setprio(0); } while (0)
; #define PG8_WAIT_V(n) asm volatile("s_waitcnt vmcnt(" #n ")" ::: "memory")
; #define PG8_WAIT_L(n) asm volatile("s_waitcnt lgkmcnt(" #n ")" ::: "memory")
; #define PG8_BAR __builtin_amdgcn_s_barrier()
; #define PG8_SCHED __builtin_amdgcn_sched_barrier(0)
; template <class Epi, class Sched, bool ALIGN_EPI = false, bool SP2 = false>
; __device__ __forceinline__ void gemm_phase(PG8_LAS unsigned char* lds, const Gemm g, const Sched& S, const Epi& E) {
;     ...
;             PG8_LDA(At, 1, 1); PG8_STAGE(PG8_SB(1, 0), b3, voffB); PG8_STAGE(PG8_SB(1, 1), b3 + hstep, voffB); PG8_STAGE(PG8_SA(1, 0), a3, voffA);
;             PG8_WAIT_V(8); PG8_WAIT_L(0); PG8_BAR; PG8_MMA(1, 0, At, B0); PG8_MMA(1, 1, At, B1); PG8_BAR; PG8_SCHED;
;     ...
;         if constexpr (ALIGN_EPI) { if (wr == 0) PG8_BAR; }
	s_add_i32 s28, s48, s35
	v_lshl_add_u64 v[154:155], v[154:155], 0, s[80:81]
	s_mov_b32 m0, s28
	ds_read_b128 v[190:193], v157 offset:49152
	ds_read_b128 v[194:197], v157 offset:50176
	ds_read_b128 v[198:201], v157 offset:51200
	ds_read_b128 v[202:205], v157 offset:52224
	ds_read_b128 v[206:209], v157 offset:53248
	ds_read_b128 v[210:213], v157 offset:54272
	ds_read_b128 v[214:217], v157 offset:55296
	ds_read_b128 v[218:221], v157 offset:56320
	global_load_lds_dwordx4 v[154:155], off
	s_add_i32 m0, s28, 0x2000
	s_add_u32 s26, s26, 0x40080
	v_lshl_add_u64 v[154:155], v[180:181], 0, s[80:81]
	s_addc_u32 s27, s27, 0
	s_add_i32 s28, s49, s35
	global_load_lds_dwordx4 v[154:155], off
	v_lshl_add_u64 v[154:155], s[26:27], 0, v[142:143]
	s_mov_b32 m0, s28
	s_nop 0
	global_load_lds_dwordx4 v[154:155], off
	v_lshl_add_u64 v[154:155], s[26:27], 0, v[138:139]
	s_add_i32 m0, s28, 0x2000
	s_nop 0
	global_load_lds_dwordx4 v[154:155], off
	v_lshl_add_u64 v[154:155], v[182:183], 0, s[80:81]
	s_mov_b32 m0, s40
	s_nop 0
	global_load_lds_dwordx4 v[154:155], off
	v_lshl_add_u64 v[154:155], v[222:223], 0, s[80:81]
	s_mov_b32 m0, s41
	s_nop 0
	global_load_lds_dwordx4 v[154:155], off
	s_waitcnt vmcnt(8) lgkmcnt(0)
	s_barrier
	s_setprio 1
	v_mfma_f32_16x16x32_bf16 v[62:65], v[94:97], v[190:193], v[62:65]
	v_mfma_f32_16x16x32_bf16 v[58:61], v[158:161], v[190:193], v[58:61]
	v_mfma_f32_16x16x32_bf16 v[50:53], v[94:97], v[198:201], v[50:53]
	v_mfma_f32_16x16x32_bf16 v[42:45], v[158:161], v[198:201], v[42:45]
	v_mfma_f32_16x16x32_bf16 v[34:37], v[94:97], v[206:209], v[34:37]
	v_mfma_f32_16x16x32_bf16 v[26:29], v[158:161], v[206:209], v[26:29]
	v_mfma_f32_16x16x32_bf16 v[18:21], v[94:97], v[214:217], v[18:21]
	v_mfma_f32_16x16x32_bf16 v[10:13], v[158:161], v[214:217], v[10:13]
	v_mfma_f32_16x16x32_bf16 v[62:65], v[134:137], v[194:197], v[62:65]
	v_mfma_f32_16x16x32_bf16 v[58:61], v[162:165], v[194:197], v[58:61]
	v_mfma_f32_16x16x32_bf16 v[50:53], v[134:137], v[202:205], v[50:53]
	v_mfma_f32_16x16x32_bf16 v[42:45], v[162:165], v[202:205], v[42:45]
	v_mfma_f32_16x16x32_bf16 v[34:37], v[134:137], v[210:213], v[34:37]
	v_mfma_f32_16x16x32_bf16 v[26:29], v[162:165], v[210:213], v[26:29]
	v_mfma_f32_16x16x32_bf16 v[18:21], v[134:137], v[218:221], v[18:21]
	v_mfma_f32_16x16x32_bf16 v[10:13], v[162:165], v[218:221], v[10:13]
	s_setprio 0
	s_setprio 1
	v_mfma_f32_16x16x32_bf16 v[54:57], v[166:169], v[190:193], v[54:57]
	v_mfma_f32_16x16x32_bf16 v[46:49], v[174:177], v[190:193], v[46:49]
	v_mfma_f32_16x16x32_bf16 v[38:41], v[166:169], v[198:201], v[38:41]
	v_mfma_f32_16x16x32_bf16 v[30:33], v[174:177], v[198:201], v[30:33]
	v_mfma_f32_16x16x32_bf16 v[22:25], v[166:169], v[206:209], v[22:25]
	v_mfma_f32_16x16x32_bf16 v[14:17], v[174:177], v[206:209], v[14:17]
	v_mfma_f32_16x16x32_bf16 v[6:9], v[166:169], v[214:217], v[6:9]
	v_mfma_f32_16x16x32_bf16 v[2:5], v[174:177], v[214:217], v[2:5]
	v_mfma_f32_16x16x32_bf16 v[54:57], v[170:173], v[194:197], v[54:57]
	v_mfma_f32_16x16x32_bf16 v[46:49], v[186:189], v[194:197], v[46:49]
	v_mfma_f32_16x16x32_bf16 v[38:41], v[170:173], v[202:205], v[38:41]
	v_mfma_f32_16x16x32_bf16 v[30:33], v[186:189], v[202:205], v[30:33]
	v_mfma_f32_16x16x32_bf16 v[22:25], v[170:173], v[210:213], v[22:25]
	v_mfma_f32_16x16x32_bf16 v[14:17], v[186:189], v[210:213], v[14:17]
	v_mfma_f32_16x16x32_bf16 v[6:9], v[170:173], v[218:221], v[6:9]
	v_mfma_f32_16x16x32_bf16 v[2:5], v[186:189], v[218:221], v[2:5]
	s_setprio 0
	s_barrier
	s_add_i32 s47, s47, 2
	s_add_u32 s24, s24, 0x100
	s_addc_u32 s25, s25, 0
	s_add_u32 s45, s45, 0x100
	s_addc_u32 s46, s46, 0
	s_cmp_gt_u32 s47, 13
	s_cbranch_scc0 .LBB0_301
	s_and_b64 vcc, exec, s[8:9]
	s_cbranch_vccz .LBB0_304
	s_barrier

; #define PG8_STAGE(bufoff, gbase, voff) do { _Pragma("unroll") for (int _i = 0; _i < 2; ++_i) \
;         __builtin_amdgcn_global_load_lds((const unsigned*)((const char*)(gbase) + (voff)[_i]), (PG8_LAS unsigned*)(lds + (bufoff) + ldsw + _i * 8192), 16, 0, 0); } while (0)
; #define PG8_LDA(dst, b, h) do { _Pragma("unroll") for (int m = 0; m < 4; ++m) _Pragma("unroll") for (int k = 0; k < 2; ++k) dst[m][k] = *(const PG8_LAS bf16x8*)(lds + PG8_SA(b, h) + aoff + m * 2048 + k * 1024); } while (0)
; #define PG8_LDB(dst, b, h) do { _Pragma("unroll") for (int n = 0; n < 2; ++n) _Pragma("unroll") for (int k = 0; k < 2; ++k) dst[n][k] = *(const PG8_LAS bf16x8*)(lds + PG8_SB(b, h) + boff + n * 2048 + k * 1024); } while (0)
; #define PG8_BAR __builtin_amdgcn_s_barrier()
;     __host__ __device__ bool next(int i, Unit& u) const {
;         const long L = (long)i * G + c; if (L >= nwg) return false;
;         int wgid = (int)L; { const int q = nwg / NXCD, r = nwg % NXCD, xcd = wgid % NXCD, off = wgid / NXCD; wgid = (xcd < r ? xcd * (q + 1) : r * (q + 1) + (xcd - r) * q) + off; }
;         const int nig = WGM * nN, gid = wgid / nig, fm = gid * WGM, gsz = (nM - fm) < WGM ? (nM - fm) : WGM;
;         u.pm = fm + ((wgid % nig) % gsz); u.pn = (wgid % nig) / gsz; return true;
; template <class Epi, class Sched, bool ALIGN_EPI = false, bool SP2 = false>
; __device__ __forceinline__ void gemm_phase(PG8_LAS unsigned char* lds, const Gemm g, const Sched& S, const Epi& E) {
;     ...
;         const bool has_next = S.next(ui + 1, nxt);
;         const char* nA = has_next ? (const char*)g.A + (size_t)nxt.pm * tstep : cA; const char* nB = has_next ? (const char*)g.Bt + (size_t)nxt.pn * tstep : cB;
;         for (int t = 0; t < nt; t += 2) {
;             const bool last = (t == nt - 2);
;             const char* a1 = cA + (size_t)(t + 1) * kstep;
;             const char* a2 = last ? nA : cA + (size_t)(t + 2) * kstep; const char* b2 = last ? nB : cB + (size_t)(t + 2) * kstep;
;             const char* a3 = a2 + kstep; const char* b3 = b2 + kstep;
;             if (last && has_next) S.a_ready(nxt);
;             if constexpr (SP2) {
;             PG8_LDB(B0, 0, 0); PG8_LDB(B1, 0, 1); PG8_SCHED; PG8_LDA(At, 0, 0); PG8_STAGE(PG8_SA(1, 1), a1 + hstep, voffA);
;             PG8_WAIT_V(8); PG8_WAIT_L(0); PG8_BAR; PG8_MMA(0, 0, At, B0); PG8_MMA(0, 1, At, B1); PG8_BAR; PG8_SCHED;
.LBB0_315:
	s_lshl_b32 s4, s22, 8
	s_ashr_i32 s5, s4, 31
	v_lshl_add_u64 v[242:243], s[4:5], 2, v[146:147]
	global_load_dwordx4 v[246:249], v[242:243], off offset:16
	s_nop 0
	global_load_dwordx4 v[242:245], v[242:243], off
	s_add_i32 s43, s43, 1
	s_mul_i32 s4, s43, s42
	s_mul_hi_u32 s5, s43, s30
	s_add_i32 s5, s5, s4
	s_mul_i32 s4, s43, s30
	s_add_u32 s16, s4, s31
	s_addc_u32 s17, s5, s36
	v_mov_b64_e32 v[2:3], 0x700
	v_cmp_lt_i64_e64 s[4:5], s[16:17], v[2:3]
	v_mov_b64_e32 v[2:3], 0x6ff
	v_cmp_gt_i64_e32 vcc, s[16:17], v[2:3]
	s_cbranch_vccnz .LBB0_317
	s_ashr_i32 s10, s16, 31
	s_lshr_b32 s10, s10, 29
	s_add_i32 s10, s16, s10
	s_ashr_i32 s11, s10, 3
	s_and_b32 s10, s10, -8
	s_sub_i32 s10, s16, s10
	s_cmp_lt_i32 s10, 0
	s_cselect_b32 s12, s51, 0xe0
	s_mul_i32 s10, s10, s12
	s_add_i32 s10, s10, s11
	s_mul_hi_i32 s11, s10, 0x92492493
	s_add_i32 s11, s11, s10
	s_lshr_b32 s12, s11, 31
	s_ashr_i32 s11, s11, 6
	s_add_i32 s11, s11, s12
	s_lshl_b32 s12, s11, 3
	s_mulk_i32 s11, 0x70
	s_sub_i32 s11, s10, s11
	s_lshr_b32 s10, s11, 3
	s_and_b32 s11, s11, 7
	s_add_i32 s12, s12, s11
.LBB0_317:
	s_ashr_i32 s13, s12, 31
	s_lshl_b64 s[16:17], s[12:13], 19
	s_add_u32 s16, s8, s16
	s_addc_u32 s17, s9, s17
	s_and_b64 s[18:19], s[4:5], exec
	s_cselect_b32 s13, s17, s25
	s_cselect_b32 s21, s16, s24
	s_ashr_i32 s11, s10, 31
	s_lshl_b64 s[18:19], s[10:11], 19
	s_add_u32 s18, s33, s18
	s_addc_u32 s19, s34, s19
	s_and_b64 s[28:29], s[4:5], exec
	s_cselect_b32 s11, s19, s27
	s_cselect_b32 s44, s18, s26
	s_add_u32 s24, s24, 0x40080
	s_addc_u32 s25, s25, 0
	s_add_u32 s45, s26, 0x100
	s_addc_u32 s46, s27, 0
	s_mov_b32 s47, -2
	s_add_u32 s26, s24, 0xfffc0080
	s_addc_u32 s27, s25, -1
	s_add_i32 s48, 0, 0x10000
	s_cmp_eq_u32 s47, 12
	s_cselect_b32 s29, s13, s27
	s_cselect_b32 s28, s21, s26
	v_add_u32_e32 v154, s48, v156
	s_cselect_b32 s27, s11, s46
	s_cselect_b32 s26, s44, s45
	s_add_i32 s50, 0, 0x14000
	ds_read_b128 v[94:97], v154
	ds_read_b128 v[134:137], v154 offset:1024
	ds_read_b128 v[158:161], v154 offset:2048
	ds_read_b128 v[162:165], v154 offset:3072
	v_add_u32_e32 v154, s50, v156
	ds_read_b128 v[166:169], v154
	ds_read_b128 v[170:173], v154 offset:1024
	ds_read_b128 v[174:177], v154 offset:2048
	ds_read_b128 v[186:189], v154 offset:3072
	v_lshl_add_u64 v[154:155], s[24:25], 0, v[150:151]
	s_add_i32 m0, s23, 0xc000
	ds_read_b128 v[190:193], v157
	ds_read_b128 v[194:197], v157 offset:1024
	ds_read_b128 v[198:201], v157 offset:2048
	ds_read_b128 v[202:205], v157 offset:3072
	ds_read_b128 v[206:209], v157 offset:4096
	ds_read_b128 v[210:213], v157 offset:5120
	ds_read_b128 v[214:217], v157 offset:6144
	ds_read_b128 v[218:221], v157 offset:7168
	global_load_lds_dwordx4 v[154:155], off
	v_lshl_add_u64 v[154:155], s[24:25], 0, v[152:153]
	s_add_i32 m0, s23, 0xe000
	s_nop 0
	global_load_lds_dwordx4 v[154:155], off
	s_waitcnt vmcnt(8) lgkmcnt(0)
	s_barrier
	s_setprio 1
	v_mfma_f32_16x16x32_bf16 v[130:133], v[94:97], v[190:193], 0
	v_mfma_f32_16x16x32_bf16 v[126:129], v[158:161], v[190:193], 0
	v_mfma_f32_16x16x32_bf16 v[114:117], v[94:97], v[198:201], 0
	v_mfma_f32_16x16x32_bf16 v[110:113], v[158:161], v[198:201], 0
	v_mfma_f32_16x16x32_bf16 v[98:101], v[94:97], v[206:209], 0
	v_mfma_f32_16x16x32_bf16 v[90:93], v[158:161], v[206:209], 0
	v_mfma_f32_16x16x32_bf16 v[78:81], v[94:97], v[214:217], 0
	v_mfma_f32_16x16x32_bf16 v[74:77], v[158:161], v[214:217], 0
	v_mfma_f32_16x16x32_bf16 v[130:133], v[134:137], v[194:197], v[130:133]
	v_mfma_f32_16x16x32_bf16 v[126:129], v[162:165], v[194:197], v[126:129]
	v_mfma_f32_16x16x32_bf16 v[114:117], v[134:137], v[202:205], v[114:117]
	v_mfma_f32_16x16x32_bf16 v[110:113], v[162:165], v[202:205], v[110:113]
	v_mfma_f32_16x16x32_bf16 v[98:101], v[134:137], v[210:213], v[98:101]
	v_mfma_f32_16x16x32_bf16 v[90:93], v[162:165], v[210:213], v[90:93]
	v_mfma_f32_16x16x32_bf16 v[78:81], v[134:137], v[218:221], v[78:81]
	v_mfma_f32_16x16x32_bf16 v[74:77], v[162:165], v[218:221], v[74:77]
	s_setprio 0
	s_setprio 1
	v_mfma_f32_16x16x32_bf16 v[122:125], v[166:169], v[190:193], 0
	v_mfma_f32_16x16x32_bf16 v[118:121], v[174:177], v[190:193], 0
	v_mfma_f32_16x16x32_bf16 v[106:109], v[166:169], v[198:201], 0
	v_mfma_f32_16x16x32_bf16 v[102:105], v[174:177], v[198:201], 0
	v_mfma_f32_16x16x32_bf16 v[86:89], v[166:169], v[206:209], 0
	v_mfma_f32_16x16x32_bf16 v[82:85], v[174:177], v[206:209], 0
	v_mfma_f32_16x16x32_bf16 v[70:73], v[166:169], v[214:217], 0
	v_mfma_f32_16x16x32_bf16 v[66:69], v[174:177], v[214:217], 0
	v_mfma_f32_16x16x32_bf16 v[122:125], v[170:173], v[194:197], v[122:125]
	v_mfma_f32_16x16x32_bf16 v[118:121], v[186:189], v[194:197], v[118:121]
	v_mfma_f32_16x16x32_bf16 v[106:109], v[170:173], v[202:205], v[106:109]
	v_mfma_f32_16x16x32_bf16 v[102:105], v[186:189], v[202:205], v[102:105]
	v_mfma_f32_16x16x32_bf16 v[86:89], v[170:173], v[210:213], v[86:89]
	v_mfma_f32_16x16x32_bf16 v[82:85], v[186:189], v[210:213], v[82:85]
	v_mfma_f32_16x16x32_bf16 v[70:73], v[170:173], v[218:221], v[70:73]
	v_mfma_f32_16x16x32_bf16 v[66:69], v[186:189], v[218:221], v[66:69]
	s_setprio 0
	s_barrier
; #define PG8_STAGE(bufoff, gbase, voff) do { _Pragma("unroll") for (int _i = 0; _i < 2; ++_i) \
;         __builtin_amdgcn_global_load_lds((const unsigned*)((const char*)(gbase) + (voff)[_i]), (PG8_LAS unsigned*)(lds + (bufoff) + ldsw + _i * 8192), 16, 0, 0); } while (0)
; #define PG8_LDA(dst, b, h) do { _Pragma("unroll") for (int m = 0; m < 4; ++m) _Pragma("unroll") for (int k = 0; k < 2; ++k) dst[m][k] = *(const PG8_LAS bf16x8*)(lds + PG8_SA(b, h) + aoff + m * 2048 + k * 1024); } while (0)
; #define PG8_LDB(dst, b, h) do { _Pragma("unroll") for (int n = 0; n < 2; ++n) _Pragma("unroll") for (int k = 0; k < 2; ++k) dst[n][k] = *(const PG8_LAS bf16x8*)(lds + PG8_SB(b, h) + boff + n * 2048 + k * 1024); } while (0)
; #define PG8_MMA(ai, bj, At, Bt) do { __builtin_amdgcn_s_setprio(1); _Pragma("unroll") for (int m = 0; m < 4; ++m) _Pragma("unroll") for (int n = 0; n < 2; ++n) _Pragma("unroll") for (int k = 0; k < 2; ++k) \
;         acc[ai][bj][m][n] = __builtin_amdgcn_mfma_f32_16x16x32_bf16(Bt[n][k], At[m][k], acc[ai][bj][m][n], 0, 0, 0); __builtin_amdgcn_s_setprio(0); } while (0)
; #define PG8_WAIT_V(n) asm volatile("s_waitcnt vmcnt(" #n ")" ::: "memory")
; #define PG8_WAIT_L(n) asm volatile("s_waitcnt lgkmcnt(" #n ")" ::: "memory")
; #define PG8_BAR __builtin_amdgcn_s_barrier()
; #define PG8_SCHED __builtin_amdgcn_sched_barrier(0)
; template <class Epi, class Sched, bool ALIGN_EPI = false, bool SP2 = false>
; __device__ __forceinline__ void gemm_phase(PG8_LAS unsigned char* lds, const Gemm g, const Sched& S, const Epi& E) {
;     ...
;             PG8_LDA(At, 0, 1); PG8_STAGE(PG8_SB(0, 0), b2, voffB); PG8_STAGE(PG8_SB(0, 1), b2 + hstep, voffB); PG8_STAGE(PG8_SA(0, 0), a2, voffA);
;             PG8_WAIT_V(8); PG8_WAIT_L(0); PG8_BAR; PG8_MMA(1, 0, At, B0); PG8_MMA(1, 1, At, B1); PG8_BAR; PG8_SCHED;
;             PG8_LDB(B0, 1, 0); PG8_LDB(B1, 1, 1); PG8_SCHED; PG8_LDA(At, 1, 0); PG8_STAGE(PG8_SA(0, 1), a2 + hstep, voffA);
;             PG8_WAIT_V(8); PG8_WAIT_L(0); PG8_BAR; PG8_MMA(0, 0, At, B0); PG8_MMA(0, 1, At, B1); PG8_BAR; PG8_SCHED;
	s_add_i32 s48, s48, s35
	v_lshl_add_u64 v[154:155], s[26:27], 0, v[142:143]
	s_mov_b32 m0, s48
	ds_read_b128 v[190:193], v157 offset:16384
	ds_read_b128 v[194:197], v157 offset:17408
	ds_read_b128 v[198:201], v157 offset:18432
	ds_read_b128 v[202:205], v157 offset:19456
	ds_read_b128 v[206:209], v157 offset:20480
	ds_read_b128 v[210:213], v157 offset:21504
	ds_read_b128 v[214:217], v157 offset:22528
	ds_read_b128 v[218:221], v157 offset:23552
	global_load_lds_dwordx4 v[154:155], off
	s_add_i32 m0, s48, 0x2000
	s_add_u32 s48, s26, 0x40000
	v_lshl_add_u64 v[180:181], s[26:27], 0, v[138:139]
	s_addc_u32 s49, s27, 0
	s_add_i32 s50, s50, s35
	global_load_lds_dwordx4 v[180:181], off
	v_lshl_add_u64 v[182:183], s[48:49], 0, v[142:143]
	s_mov_b32 m0, s50
	v_lshl_add_u64 v[222:223], s[28:29], 0, v[140:141]
	global_load_lds_dwordx4 v[182:183], off
	v_lshl_add_u64 v[182:183], s[48:49], 0, v[138:139]
	s_add_i32 m0, s50, 0x2000
	s_nop 0
	global_load_lds_dwordx4 v[182:183], off
	v_lshl_add_u64 v[182:183], s[28:29], 0, v[144:145]
	s_mov_b32 m0, s23
	s_nop 0
	global_load_lds_dwordx4 v[182:183], off
	s_mov_b32 m0, s37
	s_nop 0
	global_load_lds_dwordx4 v[222:223], off
	s_waitcnt vmcnt(8) lgkmcnt(0)
	s_barrier
	s_setprio 1
	v_mfma_f32_16x16x32_bf16 v[62:65], v[94:97], v[190:193], 0
	v_mfma_f32_16x16x32_bf16 v[58:61], v[158:161], v[190:193], 0
	v_mfma_f32_16x16x32_bf16 v[50:53], v[94:97], v[198:201], 0
	v_mfma_f32_16x16x32_bf16 v[42:45], v[158:161], v[198:201], 0
	v_mfma_f32_16x16x32_bf16 v[34:37], v[94:97], v[206:209], 0
	v_mfma_f32_16x16x32_bf16 v[26:29], v[158:161], v[206:209], 0
	v_mfma_f32_16x16x32_bf16 v[18:21], v[94:97], v[214:217], 0
	v_mfma_f32_16x16x32_bf16 v[10:13], v[158:161], v[214:217], 0
	v_mfma_f32_16x16x32_bf16 v[62:65], v[134:137], v[194:197], v[62:65]
	v_mfma_f32_16x16x32_bf16 v[58:61], v[162:165], v[194:197], v[58:61]
	v_mfma_f32_16x16x32_bf16 v[50:53], v[134:137], v[202:205], v[50:53]
	v_mfma_f32_16x16x32_bf16 v[42:45], v[162:165], v[202:205], v[42:45]
	v_mfma_f32_16x16x32_bf16 v[34:37], v[134:137], v[210:213], v[34:37]
	v_mfma_f32_16x16x32_bf16 v[26:29], v[162:165], v[210:213], v[26:29]
	v_mfma_f32_16x16x32_bf16 v[18:21], v[134:137], v[218:221], v[18:21]
	v_mfma_f32_16x16x32_bf16 v[10:13], v[162:165], v[218:221], v[10:13]
	s_setprio 0
	s_setprio 1
	v_mfma_f32_16x16x32_bf16 v[54:57], v[166:169], v[190:193], 0
	v_mfma_f32_16x16x32_bf16 v[46:49], v[174:177], v[190:193], 0
	v_mfma_f32_16x16x32_bf16 v[38:41], v[166:169], v[198:201], 0
	v_mfma_f32_16x16x32_bf16 v[30:33], v[174:177], v[198:201], 0
	v_mfma_f32_16x16x32_bf16 v[22:25], v[166:169], v[206:209], 0
	v_mfma_f32_16x16x32_bf16 v[14:17], v[174:177], v[206:209], 0
	v_mfma_f32_16x16x32_bf16 v[6:9], v[166:169], v[214:217], 0
	v_mfma_f32_16x16x32_bf16 v[2:5], v[174:177], v[214:217], 0
	v_mfma_f32_16x16x32_bf16 v[54:57], v[170:173], v[194:197], v[54:57]
	v_mfma_f32_16x16x32_bf16 v[46:49], v[186:189], v[194:197], v[46:49]
	v_mfma_f32_16x16x32_bf16 v[38:41], v[170:173], v[202:205], v[38:41]
	v_mfma_f32_16x16x32_bf16 v[30:33], v[186:189], v[202:205], v[30:33]
	v_mfma_f32_16x16x32_bf16 v[22:25], v[170:173], v[210:213], v[22:25]
	v_mfma_f32_16x16x32_bf16 v[14:17], v[186:189], v[210:213], v[14:17]
	v_mfma_f32_16x16x32_bf16 v[6:9], v[170:173], v[218:221], v[6:9]
	v_mfma_f32_16x16x32_bf16 v[2:5], v[186:189], v[218:221], v[2:5]
	s_setprio 0
	s_barrier
	s_add_i32 s48, 0, 0x18000
	s_add_i32 s49, 0, 0x1c000
	v_add_u32_e32 v162, s48, v156
	v_add_u32_e32 v179, s49, v156
	ds_read_b128 v[94:97], v162
	ds_read_b128 v[134:137], v162 offset:1024
	ds_read_b128 v[158:161], v162 offset:2048
	ds_read_b128 v[162:165], v162 offset:3072
	ds_read_b128 v[166:169], v179
	ds_read_b128 v[170:173], v179 offset:1024
	ds_read_b128 v[174:177], v179 offset:2048
	ds_read_b128 v[186:189], v179 offset:3072
	s_add_u32 s28, s28, 0x40000
	s_addc_u32 s29, s29, 0
	s_mov_b32 m0, s38
	v_lshl_add_u64 v[240:241], s[28:29], 0, v[144:145]
	ds_read_b128 v[190:193], v157 offset:32768
	ds_read_b128 v[194:197], v157 offset:33792
	ds_read_b128 v[198:201], v157 offset:34816
	ds_read_b128 v[202:205], v157 offset:35840
	ds_read_b128 v[206:209], v157 offset:36864
	ds_read_b128 v[210:213], v157 offset:37888
	ds_read_b128 v[214:217], v157 offset:38912
	ds_read_b128 v[218:221], v157 offset:39936
	global_load_lds_dwordx4 v[240:241], off
	v_lshl_add_u64 v[240:241], s[28:29], 0, v[140:141]
	s_mov_b32 m0, s39
	s_nop 0
	global_load_lds_dwordx4 v[240:241], off
	s_waitcnt vmcnt(8) lgkmcnt(0)
	s_barrier
	s_setprio 1
	v_mfma_f32_16x16x32_bf16 v[130:133], v[94:97], v[190:193], v[130:133]
	v_mfma_f32_16x16x32_bf16 v[126:129], v[158:161], v[190:193], v[126:129]
	v_mfma_f32_16x16x32_bf16 v[114:117], v[94:97], v[198:201], v[114:117]
	v_mfma_f32_16x16x32_bf16 v[110:113], v[158:161], v[198:201], v[110:113]
	v_mfma_f32_16x16x32_bf16 v[98:101], v[94:97], v[206:209], v[98:101]
	v_mfma_f32_16x16x32_bf16 v[90:93], v[158:161], v[206:209], v[90:93]
	v_mfma_f32_16x16x32_bf16 v[78:81], v[94:97], v[214:217], v[78:81]
	v_mfma_f32_16x16x32_bf16 v[74:77], v[158:161], v[214:217], v[74:77]
	v_mfma_f32_16x16x32_bf16 v[130:133], v[134:137], v[194:197], v[130:133]
	v_mfma_f32_16x16x32_bf16 v[126:129], v[162:165], v[194:197], v[126:129]
	v_mfma_f32_16x16x32_bf16 v[114:117], v[134:137], v[202:205], v[114:117]
	v_mfma_f32_16x16x32_bf16 v[110:113], v[162:165], v[202:205], v[110:113]
	v_mfma_f32_16x16x32_bf16 v[98:101], v[134:137], v[210:213], v[98:101]
	v_mfma_f32_16x16x32_bf16 v[90:93], v[162:165], v[210:213], v[90:93]
	v_mfma_f32_16x16x32_bf16 v[78:81], v[134:137], v[218:221], v[78:81]
	v_mfma_f32_16x16x32_bf16 v[74:77], v[162:165], v[218:221], v[74:77]
	s_setprio 0
	s_setprio 1
	v_mfma_f32_16x16x32_bf16 v[122:125], v[166:169], v[190:193], v[122:125]
	v_mfma_f32_16x16x32_bf16 v[118:121], v[174:177], v[190:193], v[118:121]
	v_mfma_f32_16x16x32_bf16 v[106:109], v[166:169], v[198:201], v[106:109]
	v_mfma_f32_16x16x32_bf16 v[102:105], v[174:177], v[198:201], v[102:105]
	v_mfma_f32_16x16x32_bf16 v[86:89], v[166:169], v[206:209], v[86:89]
	v_mfma_f32_16x16x32_bf16 v[82:85], v[174:177], v[206:209], v[82:85]
	v_mfma_f32_16x16x32_bf16 v[70:73], v[166:169], v[214:217], v[70:73]
	v_mfma_f32_16x16x32_bf16 v[66:69], v[174:177], v[214:217], v[66:69]
	v_mfma_f32_16x16x32_bf16 v[122:125], v[170:173], v[194:197], v[122:125]
	v_mfma_f32_16x16x32_bf16 v[118:121], v[186:189], v[194:197], v[118:121]
	v_mfma_f32_16x16x32_bf16 v[106:109], v[170:173], v[202:205], v[106:109]
	v_mfma_f32_16x16x32_bf16 v[102:105], v[186:189], v[202:205], v[102:105]
	v_mfma_f32_16x16x32_bf16 v[86:89], v[170:173], v[210:213], v[86:89]
	v_mfma_f32_16x16x32_bf16 v[82:85], v[186:189], v[210:213], v[82:85]
	v_mfma_f32_16x16x32_bf16 v[70:73], v[170:173], v[218:221], v[70:73]
	v_mfma_f32_16x16x32_bf16 v[66:69], v[186:189], v[218:221], v[66:69]
	s_setprio 0
	s_barrier
; #define PG8_STAGE(bufoff, gbase, voff) do { _Pragma("unroll") for (int _i = 0; _i < 2; ++_i) \
;         __builtin_amdgcn_global_load_lds((const unsigned*)((const char*)(gbase) + (voff)[_i]), (PG8_LAS unsigned*)(lds + (bufoff) + ldsw + _i * 8192), 16, 0, 0); } while (0)
; #define PG8_LDA(dst, b, h) do { _Pragma("unroll") for (int m = 0; m < 4; ++m) _Pragma("unroll") for (int k = 0; k < 2; ++k) dst[m][k] = *(const PG8_LAS bf16x8*)(lds + PG8_SA(b, h) + aoff + m * 2048 + k * 1024); } while (0)
; #define PG8_LDB(dst, b, h) do { _Pragma("unroll") for (int n = 0; n < 2; ++n) _Pragma("unroll") for (int k = 0; k < 2; ++k) dst[n][k] = *(const PG8_LAS bf16x8*)(lds + PG8_SB(b, h) + boff + n * 2048 + k * 1024); } while (0)
; #define PG8_MMA(ai, bj, At, Bt) do { __builtin_amdgcn_s_setprio(1); _Pragma("unroll") for (int m = 0; m < 4; ++m) _Pragma("unroll") for (int n = 0; n < 2; ++n) _Pragma("unroll") for (int k = 0; k < 2; ++k) \
;         acc[ai][bj][m][n] = __builtin_amdgcn_mfma_f32_16x16x32_bf16(Bt[n][k], At[m][k], acc[ai][bj][m][n], 0, 0, 0); __builtin_amdgcn_s_setprio(0); } while (0)
; #define PG8_WAIT_V(n) asm volatile("s_waitcnt vmcnt(" #n ")" ::: "memory")
; template <class Epi, class Sched, bool ALIGN_EPI = false, bool SP2 = false>
; __device__ __forceinline__ void gemm_phase(PG8_LAS unsigned char* lds, const Gemm g, const Sched& S, const Epi& E) {
;     ...
;             PG8_LDB(B0, 0, 0); PG8_LDB(B1, 0, 1); PG8_SCHED; PG8_LDA(At, 0, 0); PG8_STAGE(PG8_SA(1, 1), a1 + hstep, voffA);
;             PG8_WAIT_V(8); PG8_WAIT_L(0); PG8_BAR; PG8_MMA(0, 0, At, B0); PG8_MMA(0, 1, At, B1); PG8_BAR; PG8_SCHED;
;             PG8_LDA(At, 0, 1); PG8_STAGE(PG8_SB(0, 0), b2, voffB); PG8_STAGE(PG8_SB(0, 1), b2 + hstep, voffB); PG8_STAGE(PG8_SA(0, 0), a2, voffA);
;             PG8_WAIT_V(8); PG8_WAIT_L(0); PG8_BAR; PG8_MMA(1, 0, At, B0); PG8_MMA(1, 1, At, B1); PG8_BAR; PG8_SCHED;
;             PG8_LDB(B0, 1, 0); PG8_LDB(B1, 1, 1); PG8_SCHED; PG8_LDA(At, 1, 0); PG8_STAGE(PG8_SA(0, 1), a2 + hstep, voffA);
;             PG8_WAIT_V(8); PG8_WAIT_L(0); PG8_BAR; PG8_MMA(0, 0, At, B0); PG8_MMA(0, 1, At, B1); PG8_BAR; PG8_SCHED;
;             PG8_LDA(At, 1, 1); PG8_STAGE(PG8_SB(1, 0), b3, voffB); PG8_STAGE(PG8_SB(1, 1), b3 + hstep, voffB); PG8_STAGE(PG8_SA(1, 0), a3, voffA);
;             PG8_WAIT_V(8); PG8_WAIT_L(0); PG8_BAR; PG8_MMA(1, 0, At, B0); PG8_MMA(1, 1, At, B1); PG8_BAR; PG8_SCHED;
	s_add_i32 s28, s48, s35
	v_lshl_add_u64 v[154:155], v[154:155], 0, s[80:81]
	s_mov_b32 m0, s28
	ds_read_b128 v[190:193], v157 offset:49152
	ds_read_b128 v[194:197], v157 offset:50176
	ds_read_b128 v[198:201], v157 offset:51200
	ds_read_b128 v[202:205], v157 offset:52224
	ds_read_b128 v[206:209], v157 offset:53248
	ds_read_b128 v[210:213], v157 offset:54272
	ds_read_b128 v[214:217], v157 offset:55296
	ds_read_b128 v[218:221], v157 offset:56320
	global_load_lds_dwordx4 v[154:155], off
	s_add_i32 m0, s28, 0x2000
	s_add_u32 s26, s26, 0x40080
	v_lshl_add_u64 v[154:155], v[180:181], 0, s[80:81]
	s_addc_u32 s27, s27, 0
	s_add_i32 s28, s49, s35
	global_load_lds_dwordx4 v[154:155], off
	v_lshl_add_u64 v[154:155], s[26:27], 0, v[142:143]
	s_mov_b32 m0, s28
	s_nop 0
	global_load_lds_dwordx4 v[154:155], off
	v_lshl_add_u64 v[154:155], s[26:27], 0, v[138:139]
	s_add_i32 m0, s28, 0x2000
	s_nop 0
	global_load_lds_dwordx4 v[154:155], off
	v_lshl_add_u64 v[154:155], v[182:183], 0, s[80:81]
	s_mov_b32 m0, s40
	s_nop 0
	global_load_lds_dwordx4 v[154:155], off
	v_lshl_add_u64 v[154:155], v[222:223], 0, s[80:81]
	s_mov_b32 m0, s41
	s_nop 0
	global_load_lds_dwordx4 v[154:155], off
	s_waitcnt vmcnt(8) lgkmcnt(0)
	s_barrier
	s_setprio 1
	v_mfma_f32_16x16x32_bf16 v[62:65], v[94:97], v[190:193], v[62:65]
	v_mfma_f32_16x16x32_bf16 v[58:61], v[158:161], v[190:193], v[58:61]
	v_mfma_f32_16x16x32_bf16 v[50:53], v[94:97], v[198:201], v[50:53]
	v_mfma_f32_16x16x32_bf16 v[42:45], v[158:161], v[198:201], v[42:45]
	v_mfma_f32_16x16x32_bf16 v[34:37], v[94:97], v[206:209], v[34:37]
	v_mfma_f32_16x16x32_bf16 v[26:29], v[158:161], v[206:209], v[26:29]
	v_mfma_f32_16x16x32_bf16 v[18:21], v[94:97], v[214:217], v[18:21]
	v_mfma_f32_16x16x32_bf16 v[10:13], v[158:161], v[214:217], v[10:13]
	v_mfma_f32_16x16x32_bf16 v[62:65], v[134:137], v[194:197], v[62:65]
	v_mfma_f32_16x16x32_bf16 v[58:61], v[162:165], v[194:197], v[58:61]
	v_mfma_f32_16x16x32_bf16 v[50:53], v[134:137], v[202:205], v[50:53]
	v_mfma_f32_16x16x32_bf16 v[42:45], v[162:165], v[202:205], v[42:45]
	v_mfma_f32_16x16x32_bf16 v[34:37], v[134:137], v[210:213], v[34:37]
	v_mfma_f32_16x16x32_bf16 v[26:29], v[162:165], v[210:213], v[26:29]
	v_mfma_f32_16x16x32_bf16 v[18:21], v[134:137], v[218:221], v[18:21]
	v_mfma_f32_16x16x32_bf16 v[10:13], v[162:165], v[218:221], v[10:13]
	s_setprio 0
	s_setprio 1
	v_mfma_f32_16x16x32_bf16 v[54:57], v[166:169], v[190:193], v[54:57]
	v_mfma_f32_16x16x32_bf16 v[46:49], v[174:177], v[190:193], v[46:49]
	v_mfma_f32_16x16x32_bf16 v[38:41], v[166:169], v[198:201], v[38:41]
	v_mfma_f32_16x16x32_bf16 v[30:33], v[174:177], v[198:201], v[30:33]
	v_mfma_f32_16x16x32_bf16 v[22:25], v[166:169], v[206:209], v[22:25]
	v_mfma_f32_16x16x32_bf16 v[14:17], v[174:177], v[206:209], v[14:17]
	v_mfma_f32_16x16x32_bf16 v[6:9], v[166:169], v[214:217], v[6:9]
	v_mfma_f32_16x16x32_bf16 v[2:5], v[174:177], v[214:217], v[2:5]
	v_mfma_f32_16x16x32_bf16 v[54:57], v[170:173], v[194:197], v[54:57]
	v_mfma_f32_16x16x32_bf16 v[46:49], v[186:189], v[194:197], v[46:49]
	v_mfma_f32_16x16x32_bf16 v[38:41], v[170:173], v[202:205], v[38:41]
	v_mfma_f32_16x16x32_bf16 v[30:33], v[186:189], v[202:205], v[30:33]
	v_mfma_f32_16x16x32_bf16 v[22:25], v[170:173], v[210:213], v[22:25]
	v_mfma_f32_16x16x32_bf16 v[14:17], v[186:189], v[210:213], v[14:17]
	v_mfma_f32_16x16x32_bf16 v[6:9], v[170:173], v[218:221], v[6:9]
	v_mfma_f32_16x16x32_bf16 v[2:5], v[186:189], v[218:221], v[2:5]
	s_setprio 0
	s_barrier
	s_add_i32 s47, s47, 2
	s_add_u32 s24, s24, 0x100
	s_addc_u32 s25, s25, 0
	s_add_u32 s45, s45, 0x100
	s_addc_u32 s46, s46, 0
	s_cmp_gt_u32 s47, 13
	s_branch .LBB0_318
.LBB0_318:
	s_add_u32 s26, s24, 0xfffc0080
	s_addc_u32 s27, s25, -1
	s_add_i32 s48, 0, 0x10000
	s_cmp_eq_u32 s47, 12
	s_cselect_b32 s29, s13, s27
	s_cselect_b32 s28, s21, s26
	v_add_u32_e32 v154, s48, v156
	s_cselect_b32 s27, s11, s46
	s_cselect_b32 s26, s44, s45
	s_add_i32 s50, 0, 0x14000
	ds_read_b128 v[94:97], v154
	ds_read_b128 v[134:137], v154 offset:1024
	ds_read_b128 v[158:161], v154 offset:2048
	ds_read_b128 v[162:165], v154 offset:3072
	v_add_u32_e32 v154, s50, v156
	ds_read_b128 v[166:169], v154
	ds_read_b128 v[170:173], v154 offset:1024
	ds_read_b128 v[174:177], v154 offset:2048
	ds_read_b128 v[186:189], v154 offset:3072
	v_lshl_add_u64 v[154:155], s[24:25], 0, v[150:151]
	s_add_i32 m0, s23, 0xc000
	ds_read_b128 v[190:193], v157
	ds_read_b128 v[194:197], v157 offset:1024
	ds_read_b128 v[198:201], v157 offset:2048
	ds_read_b128 v[202:205], v157 offset:3072
	ds_read_b128 v[206:209], v157 offset:4096
	ds_read_b128 v[210:213], v157 offset:5120
	ds_read_b128 v[214:217], v157 offset:6144
	ds_read_b128 v[218:221], v157 offset:7168
	global_load_lds_dwordx4 v[154:155], off
	v_lshl_add_u64 v[154:155], s[24:25], 0, v[152:153]
	s_add_i32 m0, s23, 0xe000
	s_nop 0
	global_load_lds_dwordx4 v[154:155], off
	s_waitcnt vmcnt(8) lgkmcnt(0)
	s_barrier
; #define PG8_STAGE(bufoff, gbase, voff) do { _Pragma("unroll") for (int _i = 0; _i < 2; ++_i) \
;         __builtin_amdgcn_global_load_lds((const unsigned*)((const char*)(gbase) + (voff)[_i]), (PG8_LAS unsigned*)(lds + (bufoff) + ldsw + _i * 8192), 16, 0, 0); } while (0)
; #define PG8_LDA(dst, b, h) do { _Pragma("unroll") for (int m = 0; m < 4; ++m) _Pragma("unroll") for (int k = 0; k < 2; ++k) dst[m][k] = *(const PG8_LAS bf16x8*)(lds + PG8_SA(b, h) + aoff + m * 2048 + k * 1024); } while (0)
; #define PG8_LDB(dst, b, h) do { _Pragma("unroll") for (int n = 0; n < 2; ++n) _Pragma("unroll") for (int k = 0; k < 2; ++k) dst[n][k] = *(const PG8_LAS bf16x8*)(lds + PG8_SB(b, h) + boff + n * 2048 + k * 1024); } while (0)
; #define PG8_MMA(ai, bj, At, Bt) do { __builtin_amdgcn_s_setprio(1); _Pragma("unroll") for (int m = 0; m < 4; ++m) _Pragma("unroll") for (int n = 0; n < 2; ++n) _Pragma("unroll") for (int k = 0; k < 2; ++k) \
;         acc[ai][bj][m][n] = __builtin_amdgcn_mfma_f32_16x16x32_bf16(Bt[n][k], At[m][k], acc[ai][bj][m][n], 0, 0, 0); __builtin_amdgcn_s_setprio(0); } while (0)
; #define PG8_WAIT_V(n) asm volatile("s_waitcnt vmcnt(" #n ")" ::: "memory")
; #define PG8_WAIT_L(n) asm volatile("s_waitcnt lgkmcnt(" #n ")" ::: "memory")
; #define PG8_BAR __builtin_amdgcn_s_barrier()
; #define PG8_SCHED __builtin_amdgcn_sched_barrier(0)
; template <class Epi, class Sched, bool ALIGN_EPI = false, bool SP2 = false>
; __device__ __forceinline__ void gemm_phase(PG8_LAS unsigned char* lds, const Gemm g, const Sched& S, const Epi& E) {
;     ...
;             PG8_WAIT_V(8); PG8_WAIT_L(0); PG8_BAR; PG8_MMA(0, 0, At, B0); PG8_MMA(0, 1, At, B1); PG8_BAR; PG8_SCHED;
;             PG8_LDA(At, 0, 1); PG8_STAGE(PG8_SB(0, 0), b2, voffB); PG8_STAGE(PG8_SB(0, 1), b2 + hstep, voffB); PG8_STAGE(PG8_SA(0, 0), a2, voffA);
;             PG8_WAIT_V(8); PG8_WAIT_L(0); PG8_BAR; PG8_MMA(1, 0, At, B0); PG8_MMA(1, 1, At, B1); PG8_BAR; PG8_SCHED;
;             PG8_LDB(B0, 1, 0); PG8_LDB(B1, 1, 1); PG8_SCHED; PG8_LDA(At, 1, 0); PG8_STAGE(PG8_SA(0, 1), a2 + hstep, voffA);
	s_setprio 1
	v_mfma_f32_16x16x32_bf16 v[130:133], v[94:97], v[190:193], v[130:133]
	v_mfma_f32_16x16x32_bf16 v[126:129], v[158:161], v[190:193], v[126:129]
	v_mfma_f32_16x16x32_bf16 v[114:117], v[94:97], v[198:201], v[114:117]
	v_mfma_f32_16x16x32_bf16 v[110:113], v[158:161], v[198:201], v[110:113]
	v_mfma_f32_16x16x32_bf16 v[98:101], v[94:97], v[206:209], v[98:101]
	v_mfma_f32_16x16x32_bf16 v[90:93], v[158:161], v[206:209], v[90:93]
	v_mfma_f32_16x16x32_bf16 v[78:81], v[94:97], v[214:217], v[78:81]
	v_mfma_f32_16x16x32_bf16 v[74:77], v[158:161], v[214:217], v[74:77]
	v_mfma_f32_16x16x32_bf16 v[130:133], v[134:137], v[194:197], v[130:133]
	v_mfma_f32_16x16x32_bf16 v[126:129], v[162:165], v[194:197], v[126:129]
	v_mfma_f32_16x16x32_bf16 v[114:117], v[134:137], v[202:205], v[114:117]
	v_mfma_f32_16x16x32_bf16 v[110:113], v[162:165], v[202:205], v[110:113]
	v_mfma_f32_16x16x32_bf16 v[98:101], v[134:137], v[210:213], v[98:101]
	v_mfma_f32_16x16x32_bf16 v[90:93], v[162:165], v[210:213], v[90:93]
	v_mfma_f32_16x16x32_bf16 v[78:81], v[134:137], v[218:221], v[78:81]
	v_mfma_f32_16x16x32_bf16 v[74:77], v[162:165], v[218:221], v[74:77]
	s_setprio 0
	s_setprio 1
	v_mfma_f32_16x16x32_bf16 v[122:125], v[166:169], v[190:193], v[122:125]
	v_mfma_f32_16x16x32_bf16 v[118:121], v[174:177], v[190:193], v[118:121]
	v_mfma_f32_16x16x32_bf16 v[106:109], v[166:169], v[198:201], v[106:109]
	v_mfma_f32_16x16x32_bf16 v[102:105], v[174:177], v[198:201], v[102:105]
	v_mfma_f32_16x16x32_bf16 v[86:89], v[166:169], v[206:209], v[86:89]
	v_mfma_f32_16x16x32_bf16 v[82:85], v[174:177], v[206:209], v[82:85]
	v_mfma_f32_16x16x32_bf16 v[70:73], v[166:169], v[214:217], v[70:73]
	v_mfma_f32_16x16x32_bf16 v[66:69], v[174:177], v[214:217], v[66:69]
	v_mfma_f32_16x16x32_bf16 v[122:125], v[170:173], v[194:197], v[122:125]
	v_mfma_f32_16x16x32_bf16 v[118:121], v[186:189], v[194:197], v[118:121]
	v_mfma_f32_16x16x32_bf16 v[106:109], v[170:173], v[202:205], v[106:109]
	v_mfma_f32_16x16x32_bf16 v[102:105], v[186:189], v[202:205], v[102:105]
	v_mfma_f32_16x16x32_bf16 v[86:89], v[170:173], v[210:213], v[86:89]
	v_mfma_f32_16x16x32_bf16 v[82:85], v[186:189], v[210:213], v[82:85]
	v_mfma_f32_16x16x32_bf16 v[70:73], v[170:173], v[218:221], v[70:73]
	v_mfma_f32_16x16x32_bf16 v[66:69], v[186:189], v[218:221], v[66:69]
	s_setprio 0
	s_barrier
	s_add_i32 s48, s48, s35
	v_lshl_add_u64 v[154:155], s[26:27], 0, v[142:143]
	s_mov_b32 m0, s48
	ds_read_b128 v[190:193], v157 offset:16384
	ds_read_b128 v[194:197], v157 offset:17408
	ds_read_b128 v[198:201], v157 offset:18432
	ds_read_b128 v[202:205], v157 offset:19456
	ds_read_b128 v[206:209], v157 offset:20480
	ds_read_b128 v[210:213], v157 offset:21504
	ds_read_b128 v[214:217], v157 offset:22528
	ds_read_b128 v[218:221], v157 offset:23552
	global_load_lds_dwordx4 v[154:155], off
	s_add_i32 m0, s48, 0x2000
	s_add_u32 s48, s26, 0x40000
	v_lshl_add_u64 v[180:181], s[26:27], 0, v[138:139]
	s_addc_u32 s49, s27, 0
	s_add_i32 s50, s50, s35
	global_load_lds_dwordx4 v[180:181], off
	v_lshl_add_u64 v[182:183], s[48:49], 0, v[142:143]
	s_mov_b32 m0, s50
	v_lshl_add_u64 v[222:223], s[28:29], 0, v[140:141]
	global_load_lds_dwordx4 v[182:183], off
	v_lshl_add_u64 v[182:183], s[48:49], 0, v[138:139]
	s_add_i32 m0, s50, 0x2000
	s_nop 0
	global_load_lds_dwordx4 v[182:183], off
	v_lshl_add_u64 v[182:183], s[28:29], 0, v[144:145]
	s_mov_b32 m0, s23
	s_nop 0
	global_load_lds_dwordx4 v[182:183], off
	s_mov_b32 m0, s37
	s_nop 0
	global_load_lds_dwordx4 v[222:223], off
	s_waitcnt vmcnt(8) lgkmcnt(0)
	s_barrier
	s_setprio 1
	v_mfma_f32_16x16x32_bf16 v[62:65], v[94:97], v[190:193], v[62:65]
	v_mfma_f32_16x16x32_bf16 v[58:61], v[158:161], v[190:193], v[58:61]
	v_mfma_f32_16x16x32_bf16 v[50:53], v[94:97], v[198:201], v[50:53]
	v_mfma_f32_16x16x32_bf16 v[42:45], v[158:161], v[198:201], v[42:45]
	v_mfma_f32_16x16x32_bf16 v[34:37], v[94:97], v[206:209], v[34:37]
	v_mfma_f32_16x16x32_bf16 v[26:29], v[158:161], v[206:209], v[26:29]
	v_mfma_f32_16x16x32_bf16 v[18:21], v[94:97], v[214:217], v[18:21]
	v_mfma_f32_16x16x32_bf16 v[10:13], v[158:161], v[214:217], v[10:13]
	v_mfma_f32_16x16x32_bf16 v[62:65], v[134:137], v[194:197], v[62:65]
	v_mfma_f32_16x16x32_bf16 v[58:61], v[162:165], v[194:197], v[58:61]
	v_mfma_f32_16x16x32_bf16 v[50:53], v[134:137], v[202:205], v[50:53]
	v_mfma_f32_16x16x32_bf16 v[42:45], v[162:165], v[202:205], v[42:45]
	v_mfma_f32_16x16x32_bf16 v[34:37], v[134:137], v[210:213], v[34:37]
	v_mfma_f32_16x16x32_bf16 v[26:29], v[162:165], v[210:213], v[26:29]
	v_mfma_f32_16x16x32_bf16 v[18:21], v[134:137], v[218:221], v[18:21]
	v_mfma_f32_16x16x32_bf16 v[10:13], v[162:165], v[218:221], v[10:13]
	s_setprio 0
	s_setprio 1
	v_mfma_f32_16x16x32_bf16 v[54:57], v[166:169], v[190:193], v[54:57]
	v_mfma_f32_16x16x32_bf16 v[46:49], v[174:177], v[190:193], v[46:49]
	v_mfma_f32_16x16x32_bf16 v[38:41], v[166:169], v[198:201], v[38:41]
	v_mfma_f32_16x16x32_bf16 v[30:33], v[174:177], v[198:201], v[30:33]
	v_mfma_f32_16x16x32_bf16 v[22:25], v[166:169], v[206:209], v[22:25]
	v_mfma_f32_16x16x32_bf16 v[14:17], v[174:177], v[206:209], v[14:17]
	v_mfma_f32_16x16x32_bf16 v[6:9], v[166:169], v[214:217], v[6:9]
	v_mfma_f32_16x16x32_bf16 v[2:5], v[174:177], v[214:217], v[2:5]
	v_mfma_f32_16x16x32_bf16 v[54:57], v[170:173], v[194:197], v[54:57]
	v_mfma_f32_16x16x32_bf16 v[46:49], v[186:189], v[194:197], v[46:49]
	v_mfma_f32_16x16x32_bf16 v[38:41], v[170:173], v[202:205], v[38:41]
	v_mfma_f32_16x16x32_bf16 v[30:33], v[186:189], v[202:205], v[30:33]
	v_mfma_f32_16x16x32_bf16 v[22:25], v[170:173], v[210:213], v[22:25]
	v_mfma_f32_16x16x32_bf16 v[14:17], v[186:189], v[210:213], v[14:17]
	v_mfma_f32_16x16x32_bf16 v[6:9], v[170:173], v[218:221], v[6:9]
	v_mfma_f32_16x16x32_bf16 v[2:5], v[186:189], v[218:221], v[2:5]
	s_setprio 0
	s_barrier
; #define PG8_STAGE(bufoff, gbase, voff) do { _Pragma("unroll") for (int _i = 0; _i < 2; ++_i) \
;         __builtin_amdgcn_global_load_lds((const unsigned*)((const char*)(gbase) + (voff)[_i]), (PG8_LAS unsigned*)(lds + (bufoff) + ldsw + _i * 8192), 16, 0, 0); } while (0)
; #define PG8_LDA(dst, b, h) do { _Pragma("unroll") for (int m = 0; m < 4; ++m) _Pragma("unroll") for (int k = 0; k < 2; ++k) dst[m][k] = *(const PG8_LAS bf16x8*)(lds + PG8_SA(b, h) + aoff + m * 2048 + k * 1024); } while (0)
; #define PG8_LDB(dst, b, h) do { _Pragma("unroll") for (int n = 0; n < 2; ++n) _Pragma("unroll") for (int k = 0; k < 2; ++k) dst[n][k] = *(const PG8_LAS bf16x8*)(lds + PG8_SB(b, h) + boff + n * 2048 + k * 1024); } while (0)
; #define PG8_MMA(ai, bj, At, Bt) do { __builtin_amdgcn_s_setprio(1); _Pragma("unroll") for (int m = 0; m < 4; ++m) _Pragma("unroll") for (int n = 0; n < 2; ++n) _Pragma("unroll") for (int k = 0; k < 2; ++k) \
;         acc[ai][bj][m][n] = __builtin_amdgcn_mfma_f32_16x16x32_bf16(Bt[n][k], At[m][k], acc[ai][bj][m][n], 0, 0, 0); __builtin_amdgcn_s_setprio(0); } while (0)
; #define PG8_WAIT_V(n) asm volatile("s_waitcnt vmcnt(" #n ")" ::: "memory")
; #define PG8_WAIT_L(n) asm volatile("s_waitcnt lgkmcnt(" #n ")" ::: "memory")
; #define PG8_BAR __builtin_amdgcn_s_barrier()
; #define PG8_SCHED __builtin_amdgcn_sched_barrier(0)
; template <class Epi, class Sched, bool ALIGN_EPI = false, bool SP2 = false>
; __device__ __forceinline__ void gemm_phase(PG8_LAS unsigned char* lds, const Gemm g, const Sched& S, const Epi& E) {
;     ...
;             PG8_LDB(B0, 1, 0); PG8_LDB(B1, 1, 1); PG8_SCHED; PG8_LDA(At, 1, 0); PG8_STAGE(PG8_SA(0, 1), a2 + hstep, voffA);
;             PG8_WAIT_V(8); PG8_WAIT_L(0); PG8_BAR; PG8_MMA(0, 0, At, B0); PG8_MMA(0, 1, At, B1); PG8_BAR; PG8_SCHED;
	s_add_i32 s48, 0, 0x18000
	s_add_i32 s49, 0, 0x1c000
	v_add_u32_e32 v162, s48, v156
	v_add_u32_e32 v179, s49, v156
	ds_read_b128 v[94:97], v162
	ds_read_b128 v[134:137], v162 offset:1024
	ds_read_b128 v[158:161], v162 offset:2048
	ds_read_b128 v[162:165], v162 offset:3072
	ds_read_b128 v[166:169], v179
	ds_read_b128 v[170:173], v179 offset:1024
	ds_read_b128 v[174:177], v179 offset:2048
	ds_read_b128 v[186:189], v179 offset:3072
	s_add_u32 s28, s28, 0x40000
	s_addc_u32 s29, s29, 0
	s_mov_b32 m0, s38
	v_lshl_add_u64 v[240:241], s[28:29], 0, v[144:145]
	ds_read_b128 v[190:193], v157 offset:32768
	ds_read_b128 v[194:197], v157 offset:33792
	ds_read_b128 v[198:201], v157 offset:34816
	ds_read_b128 v[202:205], v157 offset:35840
	ds_read_b128 v[206:209], v157 offset:36864
	ds_read_b128 v[210:213], v157 offset:37888
	ds_read_b128 v[214:217], v157 offset:38912
	ds_read_b128 v[218:221], v157 offset:39936
	global_load_lds_dwordx4 v[240:241], off
	v_lshl_add_u64 v[240:241], s[28:29], 0, v[140:141]
	s_mov_b32 m0, s39
	s_nop 0
	global_load_lds_dwordx4 v[240:241], off
	s_waitcnt vmcnt(8) lgkmcnt(0)
	s_barrier
	s_setprio 1
	v_mfma_f32_16x16x32_bf16 v[130:133], v[94:97], v[190:193], v[130:133]
	v_mfma_f32_16x16x32_bf16 v[126:129], v[158:161], v[190:193], v[126:129]
	v_mfma_f32_16x16x32_bf16 v[114:117], v[94:97], v[198:201], v[114:117]
	v_mfma_f32_16x16x32_bf16 v[110:113], v[158:161], v[198:201], v[110:113]
	v_mfma_f32_16x16x32_bf16 v[98:101], v[94:97], v[206:209], v[98:101]
	v_mfma_f32_16x16x32_bf16 v[90:93], v[158:161], v[206:209], v[90:93]
	v_mfma_f32_16x16x32_bf16 v[78:81], v[94:97], v[214:217], v[78:81]
	v_mfma_f32_16x16x32_bf16 v[74:77], v[158:161], v[214:217], v[74:77]
	v_mfma_f32_16x16x32_bf16 v[130:133], v[134:137], v[194:197], v[130:133]
	v_mfma_f32_16x16x32_bf16 v[126:129], v[162:165], v[194:197], v[126:129]
	v_mfma_f32_16x16x32_bf16 v[114:117], v[134:137], v[202:205], v[114:117]
	v_mfma_f32_16x16x32_bf16 v[110:113], v[162:165], v[202:205], v[110:113]
	v_mfma_f32_16x16x32_bf16 v[98:101], v[134:137], v[210:213], v[98:101]
	v_mfma_f32_16x16x32_bf16 v[90:93], v[162:165], v[210:213], v[90:93]
	v_mfma_f32_16x16x32_bf16 v[78:81], v[134:137], v[218:221], v[78:81]
	v_mfma_f32_16x16x32_bf16 v[74:77], v[162:165], v[218:221], v[74:77]
	s_setprio 0
	s_setprio 1
	v_mfma_f32_16x16x32_bf16 v[122:125], v[166:169], v[190:193], v[122:125]
	v_mfma_f32_16x16x32_bf16 v[118:121], v[174:177], v[190:193], v[118:121]
	v_mfma_f32_16x16x32_bf16 v[106:109], v[166:169], v[198:201], v[106:109]
	v_mfma_f32_16x16x32_bf16 v[102:105], v[174:177], v[198:201], v[102:105]
	v_mfma_f32_16x16x32_bf16 v[86:89], v[166:169], v[206:209], v[86:89]
	v_mfma_f32_16x16x32_bf16 v[82:85], v[174:177], v[206:209], v[82:85]
	v_mfma_f32_16x16x32_bf16 v[70:73], v[166:169], v[214:217], v[70:73]
	v_mfma_f32_16x16x32_bf16 v[66:69], v[174:177], v[214:217], v[66:69]
	v_mfma_f32_16x16x32_bf16 v[122:125], v[170:173], v[194:197], v[122:125]
	v_mfma_f32_16x16x32_bf16 v[118:121], v[186:189], v[194:197], v[118:121]
	v_mfma_f32_16x16x32_bf16 v[106:109], v[170:173], v[202:205], v[106:109]
	v_mfma_f32_16x16x32_bf16 v[102:105], v[186:189], v[202:205], v[102:105]
	v_mfma_f32_16x16x32_bf16 v[86:89], v[170:173], v[210:213], v[86:89]
	v_mfma_f32_16x16x32_bf16 v[82:85], v[186:189], v[210:213], v[82:85]
	v_mfma_f32_16x16x32_bf16 v[70:73], v[170:173], v[218:221], v[70:73]
	v_mfma_f32_16x16x32_bf16 v[66:69], v[186:189], v[218:221], v[66:69]
	s_setprio 0
	s_barrier
; #define PG8_STAGE(bufoff, gbase, voff) do { _Pragma("unroll") for (int _i = 0; _i < 2; ++_i) \
;         __builtin_amdgcn_global_load_lds((const unsigned*)((const char*)(gbase) + (voff)[_i]), (PG8_LAS unsigned*)(lds + (bufoff) + ldsw + _i * 8192), 16, 0, 0); } while (0)
; #define PG8_LDA(dst, b, h) do { _Pragma("unroll") for (int m = 0; m < 4; ++m) _Pragma("unroll") for (int k = 0; k < 2; ++k) dst[m][k] = *(const PG8_LAS bf16x8*)(lds + PG8_SA(b, h) + aoff + m * 2048 + k * 1024); } while (0)
; #define PG8_MMA(ai, bj, At, Bt) do { __builtin_amdgcn_s_setprio(1); _Pragma("unroll") for (int m = 0; m < 4; ++m) _Pragma("unroll") for (int n = 0; n < 2; ++n) _Pragma("unroll") for (int k = 0; k < 2; ++k) \
;         acc[ai][bj][m][n] = __builtin_amdgcn_mfma_f32_16x16x32_bf16(Bt[n][k], At[m][k], acc[ai][bj][m][n], 0, 0, 0); __builtin_amdgcn_s_setprio(0); } while (0)
; #define PG8_WAIT_V(n) asm volatile("s_waitcnt vmcnt(" #n ")" ::: "memory")
; #define PG8_WAIT_L(n) asm volatile("s_waitcnt lgkmcnt(" #n ")" ::: "memory")
; #define PG8_BAR __builtin_amdgcn_s_barrier()
; #define PG8_SCHED __builtin_amdgcn_sched_barrier(0)
; template <class Epi, class Sched, bool ALIGN_EPI = false, bool SP2 = false>
; __device__ __forceinline__ void gemm_phase(PG8_LAS unsigned char* lds, const Gemm g, const Sched& S, const Epi& E) {
;     ...
;             PG8_LDA(At, 1, 1); PG8_STAGE(PG8_SB(1, 0), b3, voffB); PG8_STAGE(PG8_SB(1, 1), b3 + hstep, voffB); PG8_STAGE(PG8_SA(1, 0), a3, voffA);
;             PG8_WAIT_V(8); PG8_WAIT_L(0); PG8_BAR; PG8_MMA(1, 0, At, B0); PG8_MMA(1, 1, At, B1); PG8_BAR; PG8_SCHED;
;     ...
;         if constexpr (ALIGN_EPI) { if (wr == 0) PG8_BAR; }
	s_add_i32 s28, s48, s35
	v_lshl_add_u64 v[154:155], v[154:155], 0, s[80:81]
	s_mov_b32 m0, s28
	ds_read_b128 v[190:193], v157 offset:49152
	ds_read_b128 v[194:197], v157 offset:50176
	ds_read_b128 v[198:201], v157 offset:51200
	ds_read_b128 v[202:205], v157 offset:52224
	ds_read_b128 v[206:209], v157 offset:53248
	ds_read_b128 v[210:213], v157 offset:54272
	ds_read_b128 v[214:217], v157 offset:55296
	ds_read_b128 v[218:221], v157 offset:56320
	global_load_lds_dwordx4 v[154:155], off
	s_add_i32 m0, s28, 0x2000
	s_add_u32 s26, s26, 0x40080
	v_lshl_add_u64 v[154:155], v[180:181], 0, s[80:81]
	s_addc_u32 s27, s27, 0
	s_add_i32 s28, s49, s35
	global_load_lds_dwordx4 v[154:155], off
	v_lshl_add_u64 v[154:155], s[26:27], 0, v[142:143]
	s_mov_b32 m0, s28
	s_nop 0
	global_load_lds_dwordx4 v[154:155], off
	v_lshl_add_u64 v[154:155], s[26:27], 0, v[138:139]
	s_add_i32 m0, s28, 0x2000
	s_nop 0
	global_load_lds_dwordx4 v[154:155], off
	v_lshl_add_u64 v[154:155], v[182:183], 0, s[80:81]
	s_mov_b32 m0, s40
	s_nop 0
	global_load_lds_dwordx4 v[154:155], off
	v_lshl_add_u64 v[154:155], v[222:223], 0, s[80:81]
	s_mov_b32 m0, s41
	s_nop 0
	global_load_lds_dwordx4 v[154:155], off
	s_waitcnt vmcnt(8) lgkmcnt(0)
	s_barrier
	s_setprio 1
	v_mfma_f32_16x16x32_bf16 v[62:65], v[94:97], v[190:193], v[62:65]
	v_mfma_f32_16x16x32_bf16 v[58:61], v[158:161], v[190:193], v[58:61]
	v_mfma_f32_16x16x32_bf16 v[50:53], v[94:97], v[198:201], v[50:53]
	v_mfma_f32_16x16x32_bf16 v[42:45], v[158:161], v[198:201], v[42:45]
	v_mfma_f32_16x16x32_bf16 v[34:37], v[94:97], v[206:209], v[34:37]
	v_mfma_f32_16x16x32_bf16 v[26:29], v[158:161], v[206:209], v[26:29]
	v_mfma_f32_16x16x32_bf16 v[18:21], v[94:97], v[214:217], v[18:21]
	v_mfma_f32_16x16x32_bf16 v[10:13], v[158:161], v[214:217], v[10:13]
	v_mfma_f32_16x16x32_bf16 v[62:65], v[134:137], v[194:197], v[62:65]
	v_mfma_f32_16x16x32_bf16 v[58:61], v[162:165], v[194:197], v[58:61]
	v_mfma_f32_16x16x32_bf16 v[50:53], v[134:137], v[202:205], v[50:53]
	v_mfma_f32_16x16x32_bf16 v[42:45], v[162:165], v[202:205], v[42:45]
	v_mfma_f32_16x16x32_bf16 v[34:37], v[134:137], v[210:213], v[34:37]
	v_mfma_f32_16x16x32_bf16 v[26:29], v[162:165], v[210:213], v[26:29]
	v_mfma_f32_16x16x32_bf16 v[18:21], v[134:137], v[218:221], v[18:21]
	v_mfma_f32_16x16x32_bf16 v[10:13], v[162:165], v[218:221], v[10:13]
	s_setprio 0
	s_setprio 1
	v_mfma_f32_16x16x32_bf16 v[54:57], v[166:169], v[190:193], v[54:57]
	v_mfma_f32_16x16x32_bf16 v[46:49], v[174:177], v[190:193], v[46:49]
	v_mfma_f32_16x16x32_bf16 v[38:41], v[166:169], v[198:201], v[38:41]
	v_mfma_f32_16x16x32_bf16 v[30:33], v[174:177], v[198:201], v[30:33]
	v_mfma_f32_16x16x32_bf16 v[22:25], v[166:169], v[206:209], v[22:25]
	v_mfma_f32_16x16x32_bf16 v[14:17], v[174:177], v[206:209], v[14:17]
	v_mfma_f32_16x16x32_bf16 v[6:9], v[166:169], v[214:217], v[6:9]
	v_mfma_f32_16x16x32_bf16 v[2:5], v[174:177], v[214:217], v[2:5]
	v_mfma_f32_16x16x32_bf16 v[54:57], v[170:173], v[194:197], v[54:57]
	v_mfma_f32_16x16x32_bf16 v[46:49], v[186:189], v[194:197], v[46:49]
	v_mfma_f32_16x16x32_bf16 v[38:41], v[170:173], v[202:205], v[38:41]
	v_mfma_f32_16x16x32_bf16 v[30:33], v[186:189], v[202:205], v[30:33]
	v_mfma_f32_16x16x32_bf16 v[22:25], v[170:173], v[210:213], v[22:25]
	v_mfma_f32_16x16x32_bf16 v[14:17], v[186:189], v[210:213], v[14:17]
	v_mfma_f32_16x16x32_bf16 v[6:9], v[170:173], v[218:221], v[6:9]
	v_mfma_f32_16x16x32_bf16 v[2:5], v[186:189], v[218:221], v[2:5]
	s_setprio 0
	s_barrier
	s_add_i32 s47, s47, 2
	s_add_u32 s24, s24, 0x100
	s_addc_u32 s25, s25, 0
	s_add_u32 s45, s45, 0x100
	s_addc_u32 s46, s46, 0
	s_cmp_gt_u32 s47, 13
	s_cbranch_scc0 .LBB0_318
	s_and_b64 vcc, exec, s[6:7]
	s_cbranch_vccz .LBB0_321
	s_barrier

; #define PG8_STAGE(bufoff, gbase, voff) do { _Pragma("unroll") for (int _i = 0; _i < 2; ++_i) \
;         __builtin_amdgcn_global_load_lds((const unsigned*)((const char*)(gbase) + (voff)[_i]), (PG8_LAS unsigned*)(lds + (bufoff) + ldsw + _i * 8192), 16, 0, 0); } while (0)
; #define PG8_LDA(dst, b, h) do { _Pragma("unroll") for (int m = 0; m < 4; ++m) _Pragma("unroll") for (int k = 0; k < 2; ++k) dst[m][k] = *(const PG8_LAS bf16x8*)(lds + PG8_SA(b, h) + aoff + m * 2048 + k * 1024); } while (0)
; #define PG8_LDB(dst, b, h) do { _Pragma("unroll") for (int n = 0; n < 2; ++n) _Pragma("unroll") for (int k = 0; k < 2; ++k) dst[n][k] = *(const PG8_LAS bf16x8*)(lds + PG8_SB(b, h) + boff + n * 2048 + k * 1024); } while (0)
; #define PG8_WAIT_V(n) asm volatile("s_waitcnt vmcnt(" #n ")" ::: "memory")
; #define PG8_WAIT_L(n) asm volatile("s_waitcnt lgkmcnt(" #n ")" ::: "memory")
; #define PG8_BAR __builtin_amdgcn_s_barrier()
; #define PG8_SCHED __builtin_amdgcn_sched_barrier(0)
; template <class Epi, class Sched, bool ALIGN_EPI = false, bool SP2 = false>
; __device__ __forceinline__ void gemm_phase(PG8_LAS unsigned char* lds, const Gemm g, const Sched& S, const Epi& E) {
;     ...
;     for (;;) {
;         const bool has_next = S.next(ui + 1, nxt);
;         const char* nA = has_next ? (const char*)g.A + (size_t)nxt.pm * tstep : cA; const char* nB = has_next ? (const char*)g.Bt + (size_t)nxt.pn * tstep : cB;
;         for (int t = 0; t < nt; t += 2) {
;             const bool last = (t == nt - 2);
;             const char* a1 = cA + (size_t)(t + 1) * kstep;
;             const char* a2 = last ? nA : cA + (size_t)(t + 2) * kstep; const char* b2 = last ? nB : cB + (size_t)(t + 2) * kstep;
;             const char* a3 = a2 + kstep; const char* b3 = b2 + kstep;
;             if (last && has_next) S.a_ready(nxt);
;             if constexpr (SP2) {
;             PG8_LDB(B0, 0, 0); PG8_LDB(B1, 0, 1); PG8_SCHED; PG8_LDA(At, 0, 0); PG8_STAGE(PG8_SA(1, 1), a1 + hstep, voffA);
;             PG8_WAIT_V(8); PG8_WAIT_L(0); PG8_BAR; PG8_MMA(0, 0, At, B0); PG8_MMA(0, 1, At, B1); PG8_BAR; PG8_SCHED;
;             PG8_LDA(At, 0, 1); PG8_STAGE(PG8_SB(0, 0), b2, voffB); PG8_STAGE(PG8_SB(0, 1), b2 + hstep, voffB); PG8_STAGE(PG8_SA(0, 0), a2, voffA);
;             PG8_WAIT_V(8); PG8_WAIT_L(0); PG8_BAR; PG8_MMA(1, 0, At, B0); PG8_MMA(1, 1, At, B1); PG8_BAR; PG8_SCHED;
.LBB0_1061:
	s_ashr_i32 s23, s22, 31
	s_lshl_b64 s[24:25], s[22:23], 19
	s_add_u32 s24, s42, s24
	s_addc_u32 s25, s43, s25
	s_and_b64 s[26:27], s[6:7], exec
	s_cselect_b32 s23, s25, s35
	s_cselect_b32 s29, s24, s34
	s_ashr_i32 s21, s20, 31
	s_lshl_b64 s[26:27], s[20:21], 19
	s_add_u32 s26, s40, s26
	s_addc_u32 s27, s41, s27
	s_and_b64 s[38:39], s[6:7], exec
	s_cselect_b32 s21, s27, s37
	s_cselect_b32 s31, s26, s36
	s_add_u32 s34, s34, 0x40080
	s_addc_u32 s35, s35, 0
	s_add_u32 s56, s36, 0x100
	s_addc_u32 s57, s37, 0
	s_mov_b32 s58, -2
	s_waitcnt lgkmcnt(0)
	s_add_u32 s36, s34, 0xfffc0080
	s_addc_u32 s37, s35, -1
	s_add_i32 s59, 0, 0x10000
	s_cmp_eq_u32 s58, 12
	s_cselect_b32 s39, s23, s37
	s_cselect_b32 s38, s29, s36
	s_cselect_b32 s37, s21, s57
	s_cselect_b32 s36, s31, s56
	s_add_i32 s62, 0, 0x14000
	v_add_u32_e32 v142, s59, v179
	v_add_u32_e32 v170, s62, v179
	ds_read_b128 v[130:133], v142
	ds_read_b128 v[134:137], v142 offset:1024
	ds_read_b128 v[138:141], v142 offset:2048
	ds_read_b128 v[142:145], v142 offset:3072
	ds_read_b128 v[146:149], v170
	ds_read_b128 v[150:153], v170 offset:1024
	ds_read_b128 v[166:169], v170 offset:2048
	ds_read_b128 v[170:173], v170 offset:3072
	v_lshl_add_u64 v[212:213], s[34:35], 0, v[162:163]
	s_add_i32 m0, s46, 0xc000
	ds_read_b128 v[174:177], v187
	ds_read_b128 v[180:183], v187 offset:1024
	ds_read_b128 v[188:191], v187 offset:2048
	ds_read_b128 v[192:195], v187 offset:3072
	ds_read_b128 v[196:199], v187 offset:4096
	ds_read_b128 v[200:203], v187 offset:5120
	ds_read_b128 v[204:207], v187 offset:6144
	ds_read_b128 v[208:211], v187 offset:7168
	global_load_lds_dwordx4 v[212:213], off
	v_lshl_add_u64 v[212:213], s[34:35], 0, v[164:165]
	s_add_i32 m0, s46, 0xe000
	s_nop 0
	global_load_lds_dwordx4 v[212:213], off
	s_waitcnt vmcnt(8) lgkmcnt(0)
	s_barrier
	s_setprio 1
	v_mfma_f32_16x16x32_bf16 v[126:129], v[130:133], v[174:177], 0
	v_mfma_f32_16x16x32_bf16 v[122:125], v[138:141], v[174:177], 0
	v_mfma_f32_16x16x32_bf16 v[110:113], v[130:133], v[188:191], 0
	v_mfma_f32_16x16x32_bf16 v[106:109], v[138:141], v[188:191], 0
	v_mfma_f32_16x16x32_bf16 v[94:97], v[130:133], v[196:199], 0
	v_mfma_f32_16x16x32_bf16 v[90:93], v[138:141], v[196:199], 0
	v_mfma_f32_16x16x32_bf16 v[78:81], v[130:133], v[204:207], 0
	v_mfma_f32_16x16x32_bf16 v[74:77], v[138:141], v[204:207], 0
	v_mfma_f32_16x16x32_bf16 v[126:129], v[134:137], v[180:183], v[126:129]
	v_mfma_f32_16x16x32_bf16 v[122:125], v[142:145], v[180:183], v[122:125]
	v_mfma_f32_16x16x32_bf16 v[110:113], v[134:137], v[192:195], v[110:113]
	v_mfma_f32_16x16x32_bf16 v[106:109], v[142:145], v[192:195], v[106:109]
	v_mfma_f32_16x16x32_bf16 v[94:97], v[134:137], v[200:203], v[94:97]
	v_mfma_f32_16x16x32_bf16 v[90:93], v[142:145], v[200:203], v[90:93]
	v_mfma_f32_16x16x32_bf16 v[78:81], v[134:137], v[208:211], v[78:81]
	v_mfma_f32_16x16x32_bf16 v[74:77], v[142:145], v[208:211], v[74:77]
	s_setprio 0
	s_setprio 1
	v_mfma_f32_16x16x32_bf16 v[118:121], v[146:149], v[174:177], 0
	v_mfma_f32_16x16x32_bf16 v[114:117], v[166:169], v[174:177], 0
	v_mfma_f32_16x16x32_bf16 v[102:105], v[146:149], v[188:191], 0
	v_mfma_f32_16x16x32_bf16 v[98:101], v[166:169], v[188:191], 0
	v_mfma_f32_16x16x32_bf16 v[86:89], v[146:149], v[196:199], 0
	v_mfma_f32_16x16x32_bf16 v[82:85], v[166:169], v[196:199], 0
	v_mfma_f32_16x16x32_bf16 v[70:73], v[146:149], v[204:207], 0
	v_mfma_f32_16x16x32_bf16 v[66:69], v[166:169], v[204:207], 0
	v_mfma_f32_16x16x32_bf16 v[118:121], v[150:153], v[180:183], v[118:121]
	v_mfma_f32_16x16x32_bf16 v[114:117], v[170:173], v[180:183], v[114:117]
	v_mfma_f32_16x16x32_bf16 v[102:105], v[150:153], v[192:195], v[102:105]
	v_mfma_f32_16x16x32_bf16 v[98:101], v[170:173], v[192:195], v[98:101]
	v_mfma_f32_16x16x32_bf16 v[86:89], v[150:153], v[200:203], v[86:89]
	v_mfma_f32_16x16x32_bf16 v[82:85], v[170:173], v[200:203], v[82:85]
	v_mfma_f32_16x16x32_bf16 v[70:73], v[150:153], v[208:211], v[70:73]
	v_mfma_f32_16x16x32_bf16 v[66:69], v[170:173], v[208:211], v[66:69]
	s_setprio 0
	s_barrier
	s_add_i32 s59, s59, s33
	v_lshl_add_u64 v[212:213], s[36:37], 0, v[156:157]
	s_mov_b32 m0, s59
	ds_read_b128 v[174:177], v187 offset:16384
	ds_read_b128 v[180:183], v187 offset:17408
	ds_read_b128 v[188:191], v187 offset:18432
	ds_read_b128 v[192:195], v187 offset:19456
	ds_read_b128 v[196:199], v187 offset:20480
	ds_read_b128 v[200:203], v187 offset:21504
	ds_read_b128 v[204:207], v187 offset:22528
	ds_read_b128 v[208:211], v187 offset:23552
	global_load_lds_dwordx4 v[212:213], off
	s_add_i32 m0, s59, 0x2000
	s_add_u32 s60, s36, 0x40000
	v_lshl_add_u64 v[214:215], s[36:37], 0, v[160:161]
	s_addc_u32 s61, s37, 0
	s_add_i32 s59, s62, s33
	global_load_lds_dwordx4 v[214:215], off
	v_lshl_add_u64 v[216:217], s[60:61], 0, v[156:157]
	s_mov_b32 m0, s59
	v_lshl_add_u64 v[218:219], s[38:39], 0, v[158:159]
	global_load_lds_dwordx4 v[216:217], off
	v_lshl_add_u64 v[216:217], s[60:61], 0, v[160:161]
	s_add_i32 m0, s59, 0x2000
	s_nop 0
	global_load_lds_dwordx4 v[216:217], off
	v_lshl_add_u64 v[216:217], s[38:39], 0, v[154:155]
	s_mov_b32 m0, s46
	s_nop 0
	global_load_lds_dwordx4 v[216:217], off
	s_mov_b32 m0, s47
	s_nop 0
	global_load_lds_dwordx4 v[218:219], off
	s_waitcnt vmcnt(8) lgkmcnt(0)
	s_barrier
; #define PG8_STAGE(bufoff, gbase, voff) do { _Pragma("unroll") for (int _i = 0; _i < 2; ++_i) \
;         __builtin_amdgcn_global_load_lds((const unsigned*)((const char*)(gbase) + (voff)[_i]), (PG8_LAS unsigned*)(lds + (bufoff) + ldsw + _i * 8192), 16, 0, 0); } while (0)
; #define PG8_LDA(dst, b, h) do { _Pragma("unroll") for (int m = 0; m < 4; ++m) _Pragma("unroll") for (int k = 0; k < 2; ++k) dst[m][k] = *(const PG8_LAS bf16x8*)(lds + PG8_SA(b, h) + aoff + m * 2048 + k * 1024); } while (0)
; #define PG8_LDB(dst, b, h) do { _Pragma("unroll") for (int n = 0; n < 2; ++n) _Pragma("unroll") for (int k = 0; k < 2; ++k) dst[n][k] = *(const PG8_LAS bf16x8*)(lds + PG8_SB(b, h) + boff + n * 2048 + k * 1024); } while (0)
; #define PG8_MMA(ai, bj, At, Bt) do { __builtin_amdgcn_s_setprio(1); _Pragma("unroll") for (int m = 0; m < 4; ++m) _Pragma("unroll") for (int n = 0; n < 2; ++n) _Pragma("unroll") for (int k = 0; k < 2; ++k) \
;         acc[ai][bj][m][n] = __builtin_amdgcn_mfma_f32_16x16x32_bf16(Bt[n][k], At[m][k], acc[ai][bj][m][n], 0, 0, 0); __builtin_amdgcn_s_setprio(0); } while (0)
; #define PG8_WAIT_V(n) asm volatile("s_waitcnt vmcnt(" #n ")" ::: "memory")
; #define PG8_WAIT_L(n) asm volatile("s_waitcnt lgkmcnt(" #n ")" ::: "memory")
; #define PG8_BAR __builtin_amdgcn_s_barrier()
; #define PG8_SCHED __builtin_amdgcn_sched_barrier(0)
; template <class Epi, class Sched, bool ALIGN_EPI = false, bool SP2 = false>
; __device__ __forceinline__ void gemm_phase(PG8_LAS unsigned char* lds, const Gemm g, const Sched& S, const Epi& E) {
;     ...
;             PG8_WAIT_V(8); PG8_WAIT_L(0); PG8_BAR; PG8_MMA(1, 0, At, B0); PG8_MMA(1, 1, At, B1); PG8_BAR; PG8_SCHED;
;             PG8_LDB(B0, 1, 0); PG8_LDB(B1, 1, 1); PG8_SCHED; PG8_LDA(At, 1, 0); PG8_STAGE(PG8_SA(0, 1), a2 + hstep, voffA);
;             PG8_WAIT_V(8); PG8_WAIT_L(0); PG8_BAR; PG8_MMA(0, 0, At, B0); PG8_MMA(0, 1, At, B1); PG8_BAR; PG8_SCHED;
	s_setprio 1
	v_mfma_f32_16x16x32_bf16 v[62:65], v[130:133], v[174:177], 0
	v_mfma_f32_16x16x32_bf16 v[58:61], v[138:141], v[174:177], 0
	v_mfma_f32_16x16x32_bf16 v[46:49], v[130:133], v[188:191], 0
	v_mfma_f32_16x16x32_bf16 v[42:45], v[138:141], v[188:191], 0
	v_mfma_f32_16x16x32_bf16 v[30:33], v[130:133], v[196:199], 0
	v_mfma_f32_16x16x32_bf16 v[26:29], v[138:141], v[196:199], 0
	v_mfma_f32_16x16x32_bf16 v[14:17], v[130:133], v[204:207], 0
	v_mfma_f32_16x16x32_bf16 v[10:13], v[138:141], v[204:207], 0
	v_mfma_f32_16x16x32_bf16 v[62:65], v[134:137], v[180:183], v[62:65]
	v_mfma_f32_16x16x32_bf16 v[58:61], v[142:145], v[180:183], v[58:61]
	v_mfma_f32_16x16x32_bf16 v[46:49], v[134:137], v[192:195], v[46:49]
	v_mfma_f32_16x16x32_bf16 v[42:45], v[142:145], v[192:195], v[42:45]
	v_mfma_f32_16x16x32_bf16 v[30:33], v[134:137], v[200:203], v[30:33]
	v_mfma_f32_16x16x32_bf16 v[26:29], v[142:145], v[200:203], v[26:29]
	v_mfma_f32_16x16x32_bf16 v[14:17], v[134:137], v[208:211], v[14:17]
	v_mfma_f32_16x16x32_bf16 v[10:13], v[142:145], v[208:211], v[10:13]
	s_setprio 0
	s_setprio 1
	v_mfma_f32_16x16x32_bf16 v[54:57], v[146:149], v[174:177], 0
	v_mfma_f32_16x16x32_bf16 v[50:53], v[166:169], v[174:177], 0
	v_mfma_f32_16x16x32_bf16 v[38:41], v[146:149], v[188:191], 0
	v_mfma_f32_16x16x32_bf16 v[34:37], v[166:169], v[188:191], 0
	v_mfma_f32_16x16x32_bf16 v[22:25], v[146:149], v[196:199], 0
	v_mfma_f32_16x16x32_bf16 v[18:21], v[166:169], v[196:199], 0
	v_mfma_f32_16x16x32_bf16 v[6:9], v[146:149], v[204:207], 0
	v_mfma_f32_16x16x32_bf16 v[2:5], v[166:169], v[204:207], 0
	v_mfma_f32_16x16x32_bf16 v[54:57], v[150:153], v[180:183], v[54:57]
	v_mfma_f32_16x16x32_bf16 v[50:53], v[170:173], v[180:183], v[50:53]
	v_mfma_f32_16x16x32_bf16 v[38:41], v[150:153], v[192:195], v[38:41]
	v_mfma_f32_16x16x32_bf16 v[34:37], v[170:173], v[192:195], v[34:37]
	v_mfma_f32_16x16x32_bf16 v[22:25], v[150:153], v[200:203], v[22:25]
	v_mfma_f32_16x16x32_bf16 v[18:21], v[170:173], v[200:203], v[18:21]
	v_mfma_f32_16x16x32_bf16 v[6:9], v[150:153], v[208:211], v[6:9]
	v_mfma_f32_16x16x32_bf16 v[2:5], v[170:173], v[208:211], v[2:5]
	s_setprio 0
	s_barrier
	s_add_i32 s59, 0, 0x18000
	s_add_i32 s60, 0, 0x1c000
	v_add_u32_e32 v142, s59, v179
	v_add_u32_e32 v170, s60, v179
	ds_read_b128 v[130:133], v142
	ds_read_b128 v[134:137], v142 offset:1024
	ds_read_b128 v[138:141], v142 offset:2048
	ds_read_b128 v[142:145], v142 offset:3072
	ds_read_b128 v[146:149], v170
	ds_read_b128 v[150:153], v170 offset:1024
	ds_read_b128 v[166:169], v170 offset:2048
	ds_read_b128 v[170:173], v170 offset:3072
	s_add_u32 s38, s38, 0x40000
	s_addc_u32 s39, s39, 0
	s_mov_b32 m0, s48
	v_lshl_add_u64 v[220:221], s[38:39], 0, v[154:155]
	ds_read_b128 v[174:177], v187 offset:32768
	ds_read_b128 v[180:183], v187 offset:33792
	ds_read_b128 v[188:191], v187 offset:34816
	ds_read_b128 v[192:195], v187 offset:35840
	ds_read_b128 v[196:199], v187 offset:36864
	ds_read_b128 v[200:203], v187 offset:37888
	ds_read_b128 v[204:207], v187 offset:38912
	ds_read_b128 v[208:211], v187 offset:39936
	global_load_lds_dwordx4 v[220:221], off
	v_lshl_add_u64 v[220:221], s[38:39], 0, v[158:159]
	s_mov_b32 m0, s49
	s_nop 0
	global_load_lds_dwordx4 v[220:221], off
	s_waitcnt vmcnt(8) lgkmcnt(0)
	s_barrier
	s_setprio 1
	v_mfma_f32_16x16x32_bf16 v[126:129], v[130:133], v[174:177], v[126:129]
	v_mfma_f32_16x16x32_bf16 v[122:125], v[138:141], v[174:177], v[122:125]
	v_mfma_f32_16x16x32_bf16 v[110:113], v[130:133], v[188:191], v[110:113]
	v_mfma_f32_16x16x32_bf16 v[106:109], v[138:141], v[188:191], v[106:109]
	v_mfma_f32_16x16x32_bf16 v[94:97], v[130:133], v[196:199], v[94:97]
	v_mfma_f32_16x16x32_bf16 v[90:93], v[138:141], v[196:199], v[90:93]
	v_mfma_f32_16x16x32_bf16 v[78:81], v[130:133], v[204:207], v[78:81]
	v_mfma_f32_16x16x32_bf16 v[74:77], v[138:141], v[204:207], v[74:77]
	v_mfma_f32_16x16x32_bf16 v[126:129], v[134:137], v[180:183], v[126:129]
	v_mfma_f32_16x16x32_bf16 v[122:125], v[142:145], v[180:183], v[122:125]
	v_mfma_f32_16x16x32_bf16 v[110:113], v[134:137], v[192:195], v[110:113]
	v_mfma_f32_16x16x32_bf16 v[106:109], v[142:145], v[192:195], v[106:109]
	v_mfma_f32_16x16x32_bf16 v[94:97], v[134:137], v[200:203], v[94:97]
	v_mfma_f32_16x16x32_bf16 v[90:93], v[142:145], v[200:203], v[90:93]
	v_mfma_f32_16x16x32_bf16 v[78:81], v[134:137], v[208:211], v[78:81]
	v_mfma_f32_16x16x32_bf16 v[74:77], v[142:145], v[208:211], v[74:77]
	s_setprio 0
	s_setprio 1
	v_mfma_f32_16x16x32_bf16 v[118:121], v[146:149], v[174:177], v[118:121]
	v_mfma_f32_16x16x32_bf16 v[114:117], v[166:169], v[174:177], v[114:117]
	v_mfma_f32_16x16x32_bf16 v[102:105], v[146:149], v[188:191], v[102:105]
	v_mfma_f32_16x16x32_bf16 v[98:101], v[166:169], v[188:191], v[98:101]
	v_mfma_f32_16x16x32_bf16 v[86:89], v[146:149], v[196:199], v[86:89]
	v_mfma_f32_16x16x32_bf16 v[82:85], v[166:169], v[196:199], v[82:85]
	v_mfma_f32_16x16x32_bf16 v[70:73], v[146:149], v[204:207], v[70:73]
	v_mfma_f32_16x16x32_bf16 v[66:69], v[166:169], v[204:207], v[66:69]
	v_mfma_f32_16x16x32_bf16 v[118:121], v[150:153], v[180:183], v[118:121]
	v_mfma_f32_16x16x32_bf16 v[114:117], v[170:173], v[180:183], v[114:117]
	v_mfma_f32_16x16x32_bf16 v[102:105], v[150:153], v[192:195], v[102:105]
	v_mfma_f32_16x16x32_bf16 v[98:101], v[170:173], v[192:195], v[98:101]
	v_mfma_f32_16x16x32_bf16 v[86:89], v[150:153], v[200:203], v[86:89]
	v_mfma_f32_16x16x32_bf16 v[82:85], v[170:173], v[200:203], v[82:85]
	v_mfma_f32_16x16x32_bf16 v[70:73], v[150:153], v[208:211], v[70:73]
	v_mfma_f32_16x16x32_bf16 v[66:69], v[170:173], v[208:211], v[66:69]
	s_setprio 0
	s_barrier
; #define PG8_STAGE(bufoff, gbase, voff) do { _Pragma("unroll") for (int _i = 0; _i < 2; ++_i) \
;         __builtin_amdgcn_global_load_lds((const unsigned*)((const char*)(gbase) + (voff)[_i]), (PG8_LAS unsigned*)(lds + (bufoff) + ldsw + _i * 8192), 16, 0, 0); } while (0)
; #define PG8_LDA(dst, b, h) do { _Pragma("unroll") for (int m = 0; m < 4; ++m) _Pragma("unroll") for (int k = 0; k < 2; ++k) dst[m][k] = *(const PG8_LAS bf16x8*)(lds + PG8_SA(b, h) + aoff + m * 2048 + k * 1024); } while (0)
; #define PG8_LDB(dst, b, h) do { _Pragma("unroll") for (int n = 0; n < 2; ++n) _Pragma("unroll") for (int k = 0; k < 2; ++k) dst[n][k] = *(const PG8_LAS bf16x8*)(lds + PG8_SB(b, h) + boff + n * 2048 + k * 1024); } while (0)
; template <class Epi, class Sched, bool ALIGN_EPI = false, bool SP2 = false>
; __device__ __forceinline__ void gemm_phase(PG8_LAS unsigned char* lds, const Gemm g, const Sched& S, const Epi& E) {
;     ...
;         for (int t = 0; t < nt; t += 2) {
;             const bool last = (t == nt - 2);
;             const char* a1 = cA + (size_t)(t + 1) * kstep;
;             const char* a2 = last ? nA : cA + (size_t)(t + 2) * kstep; const char* b2 = last ? nB : cB + (size_t)(t + 2) * kstep;
;             const char* a3 = a2 + kstep; const char* b3 = b2 + kstep;
;             if (last && has_next) S.a_ready(nxt);
;             if constexpr (SP2) {
;             PG8_LDB(B0, 0, 0); PG8_LDB(B1, 0, 1); PG8_SCHED; PG8_LDA(At, 0, 0); PG8_STAGE(PG8_SA(1, 1), a1 + hstep, voffA);
;             PG8_WAIT_V(8); PG8_WAIT_L(0); PG8_BAR; PG8_MMA(0, 0, At, B0); PG8_MMA(0, 1, At, B1); PG8_BAR; PG8_SCHED;
;             PG8_LDA(At, 0, 1); PG8_STAGE(PG8_SB(0, 0), b2, voffB); PG8_STAGE(PG8_SB(0, 1), b2 + hstep, voffB); PG8_STAGE(PG8_SA(0, 0), a2, voffA);
;             PG8_WAIT_V(8); PG8_WAIT_L(0); PG8_BAR; PG8_MMA(1, 0, At, B0); PG8_MMA(1, 1, At, B1); PG8_BAR; PG8_SCHED;
;             PG8_LDB(B0, 1, 0); PG8_LDB(B1, 1, 1); PG8_SCHED; PG8_LDA(At, 1, 0); PG8_STAGE(PG8_SA(0, 1), a2 + hstep, voffA);
;             PG8_WAIT_V(8); PG8_WAIT_L(0); PG8_BAR; PG8_MMA(0, 0, At, B0); PG8_MMA(0, 1, At, B1); PG8_BAR; PG8_SCHED;
;             PG8_LDA(At, 1, 1); PG8_STAGE(PG8_SB(1, 0), b3, voffB); PG8_STAGE(PG8_SB(1, 1), b3 + hstep, voffB); PG8_STAGE(PG8_SA(1, 0), a3, voffA);
;             PG8_WAIT_V(8); PG8_WAIT_L(0); PG8_BAR; PG8_MMA(1, 0, At, B0); PG8_MMA(1, 1, At, B1); PG8_BAR; PG8_SCHED;
	s_add_i32 s38, s59, s33
	v_lshl_add_u64 v[212:213], v[212:213], 0, s[80:81]
	s_mov_b32 m0, s38
	ds_read_b128 v[174:177], v187 offset:49152
	ds_read_b128 v[180:183], v187 offset:50176
	ds_read_b128 v[188:191], v187 offset:51200
	ds_read_b128 v[192:195], v187 offset:52224
	ds_read_b128 v[196:199], v187 offset:53248
	ds_read_b128 v[200:203], v187 offset:54272
	ds_read_b128 v[204:207], v187 offset:55296
	ds_read_b128 v[208:211], v187 offset:56320
	global_load_lds_dwordx4 v[212:213], off
	s_add_i32 m0, s38, 0x2000
	s_add_u32 s36, s36, 0x40080
	v_lshl_add_u64 v[212:213], v[214:215], 0, s[80:81]
	s_addc_u32 s37, s37, 0
	s_add_i32 s38, s60, s33
	global_load_lds_dwordx4 v[212:213], off
	v_lshl_add_u64 v[212:213], s[36:37], 0, v[156:157]
	s_mov_b32 m0, s38
	s_nop 0
	global_load_lds_dwordx4 v[212:213], off
	v_lshl_add_u64 v[212:213], s[36:37], 0, v[160:161]
	s_add_i32 m0, s38, 0x2000
	s_nop 0
	global_load_lds_dwordx4 v[212:213], off
	v_lshl_add_u64 v[212:213], v[216:217], 0, s[80:81]
	s_mov_b32 m0, s51
	s_nop 0
	global_load_lds_dwordx4 v[212:213], off
	v_lshl_add_u64 v[212:213], v[218:219], 0, s[80:81]
	s_mov_b32 m0, s52
	s_nop 0
	global_load_lds_dwordx4 v[212:213], off
	s_waitcnt vmcnt(8) lgkmcnt(0)
	s_barrier
	s_setprio 1
	v_mfma_f32_16x16x32_bf16 v[62:65], v[130:133], v[174:177], v[62:65]
	v_mfma_f32_16x16x32_bf16 v[58:61], v[138:141], v[174:177], v[58:61]
	v_mfma_f32_16x16x32_bf16 v[46:49], v[130:133], v[188:191], v[46:49]
	v_mfma_f32_16x16x32_bf16 v[42:45], v[138:141], v[188:191], v[42:45]
	v_mfma_f32_16x16x32_bf16 v[30:33], v[130:133], v[196:199], v[30:33]
	v_mfma_f32_16x16x32_bf16 v[26:29], v[138:141], v[196:199], v[26:29]
	v_mfma_f32_16x16x32_bf16 v[14:17], v[130:133], v[204:207], v[14:17]
	v_mfma_f32_16x16x32_bf16 v[10:13], v[138:141], v[204:207], v[10:13]
	v_mfma_f32_16x16x32_bf16 v[62:65], v[134:137], v[180:183], v[62:65]
	v_mfma_f32_16x16x32_bf16 v[58:61], v[142:145], v[180:183], v[58:61]
	v_mfma_f32_16x16x32_bf16 v[46:49], v[134:137], v[192:195], v[46:49]
	v_mfma_f32_16x16x32_bf16 v[42:45], v[142:145], v[192:195], v[42:45]
	v_mfma_f32_16x16x32_bf16 v[30:33], v[134:137], v[200:203], v[30:33]
	v_mfma_f32_16x16x32_bf16 v[26:29], v[142:145], v[200:203], v[26:29]
	v_mfma_f32_16x16x32_bf16 v[14:17], v[134:137], v[208:211], v[14:17]
	v_mfma_f32_16x16x32_bf16 v[10:13], v[142:145], v[208:211], v[10:13]
	s_setprio 0
	s_setprio 1
	v_mfma_f32_16x16x32_bf16 v[54:57], v[146:149], v[174:177], v[54:57]
	v_mfma_f32_16x16x32_bf16 v[50:53], v[166:169], v[174:177], v[50:53]
	v_mfma_f32_16x16x32_bf16 v[38:41], v[146:149], v[188:191], v[38:41]
	v_mfma_f32_16x16x32_bf16 v[34:37], v[166:169], v[188:191], v[34:37]
	v_mfma_f32_16x16x32_bf16 v[22:25], v[146:149], v[196:199], v[22:25]
	v_mfma_f32_16x16x32_bf16 v[18:21], v[166:169], v[196:199], v[18:21]
	v_mfma_f32_16x16x32_bf16 v[6:9], v[146:149], v[204:207], v[6:9]
	v_mfma_f32_16x16x32_bf16 v[2:5], v[166:169], v[204:207], v[2:5]
	v_mfma_f32_16x16x32_bf16 v[54:57], v[150:153], v[180:183], v[54:57]
	v_mfma_f32_16x16x32_bf16 v[50:53], v[170:173], v[180:183], v[50:53]
	v_mfma_f32_16x16x32_bf16 v[38:41], v[150:153], v[192:195], v[38:41]
	v_mfma_f32_16x16x32_bf16 v[34:37], v[170:173], v[192:195], v[34:37]
	v_mfma_f32_16x16x32_bf16 v[22:25], v[150:153], v[200:203], v[22:25]
	v_mfma_f32_16x16x32_bf16 v[18:21], v[170:173], v[200:203], v[18:21]
	v_mfma_f32_16x16x32_bf16 v[6:9], v[150:153], v[208:211], v[6:9]
	v_mfma_f32_16x16x32_bf16 v[2:5], v[170:173], v[208:211], v[2:5]
	s_setprio 0
	s_barrier
	s_add_i32 s58, s58, 2
	s_add_u32 s34, s34, 0x100
	s_addc_u32 s35, s35, 0
	s_add_u32 s56, s56, 0x100
	s_addc_u32 s57, s57, 0
	s_cmp_gt_u32 s58, 13
	s_branch .LBB0_1062
.LBB0_1062:
	s_add_u32 s36, s34, 0xfffc0080
	s_addc_u32 s37, s35, -1
	s_add_i32 s59, 0, 0x10000
	s_cmp_eq_u32 s58, 12
	s_cselect_b32 s39, s23, s37
	s_cselect_b32 s38, s29, s36
	s_cselect_b32 s37, s21, s57
	s_cselect_b32 s36, s31, s56
	s_add_i32 s62, 0, 0x14000
	v_add_u32_e32 v142, s59, v179
	v_add_u32_e32 v170, s62, v179
	ds_read_b128 v[130:133], v142
	ds_read_b128 v[134:137], v142 offset:1024
	ds_read_b128 v[138:141], v142 offset:2048
	ds_read_b128 v[142:145], v142 offset:3072
	ds_read_b128 v[146:149], v170
	ds_read_b128 v[150:153], v170 offset:1024
	ds_read_b128 v[166:169], v170 offset:2048
	ds_read_b128 v[170:173], v170 offset:3072
	v_lshl_add_u64 v[212:213], s[34:35], 0, v[162:163]
	s_add_i32 m0, s46, 0xc000
	ds_read_b128 v[174:177], v187
	ds_read_b128 v[180:183], v187 offset:1024
	ds_read_b128 v[188:191], v187 offset:2048
	ds_read_b128 v[192:195], v187 offset:3072
	ds_read_b128 v[196:199], v187 offset:4096
	ds_read_b128 v[200:203], v187 offset:5120
	ds_read_b128 v[204:207], v187 offset:6144
	ds_read_b128 v[208:211], v187 offset:7168
	global_load_lds_dwordx4 v[212:213], off
	v_lshl_add_u64 v[212:213], s[34:35], 0, v[164:165]
	s_add_i32 m0, s46, 0xe000
	s_nop 0
	global_load_lds_dwordx4 v[212:213], off
	s_waitcnt vmcnt(8) lgkmcnt(0)
	s_barrier
; #define PG8_STAGE(bufoff, gbase, voff) do { _Pragma("unroll") for (int _i = 0; _i < 2; ++_i) \
;         __builtin_amdgcn_global_load_lds((const unsigned*)((const char*)(gbase) + (voff)[_i]), (PG8_LAS unsigned*)(lds + (bufoff) + ldsw + _i * 8192), 16, 0, 0); } while (0)
; #define PG8_LDA(dst, b, h) do { _Pragma("unroll") for (int m = 0; m < 4; ++m) _Pragma("unroll") for (int k = 0; k < 2; ++k) dst[m][k] = *(const PG8_LAS bf16x8*)(lds + PG8_SA(b, h) + aoff + m * 2048 + k * 1024); } while (0)
; #define PG8_MMA(ai, bj, At, Bt) do { __builtin_amdgcn_s_setprio(1); _Pragma("unroll") for (int m = 0; m < 4; ++m) _Pragma("unroll") for (int n = 0; n < 2; ++n) _Pragma("unroll") for (int k = 0; k < 2; ++k) \
;         acc[ai][bj][m][n] = __builtin_amdgcn_mfma_f32_16x16x32_bf16(Bt[n][k], At[m][k], acc[ai][bj][m][n], 0, 0, 0); __builtin_amdgcn_s_setprio(0); } while (0)
; #define PG8_WAIT_V(n) asm volatile("s_waitcnt vmcnt(" #n ")" ::: "memory")
; #define PG8_WAIT_L(n) asm volatile("s_waitcnt lgkmcnt(" #n ")" ::: "memory")
; #define PG8_BAR __builtin_amdgcn_s_barrier()
; #define PG8_SCHED __builtin_amdgcn_sched_barrier(0)
; template <class Epi, class Sched, bool ALIGN_EPI = false, bool SP2 = false>
; __device__ __forceinline__ void gemm_phase(PG8_LAS unsigned char* lds, const Gemm g, const Sched& S, const Epi& E) {
;     ...
;             PG8_WAIT_V(8); PG8_WAIT_L(0); PG8_BAR; PG8_MMA(0, 0, At, B0); PG8_MMA(0, 1, At, B1); PG8_BAR; PG8_SCHED;
;             PG8_LDA(At, 0, 1); PG8_STAGE(PG8_SB(0, 0), b2, voffB); PG8_STAGE(PG8_SB(0, 1), b2 + hstep, voffB); PG8_STAGE(PG8_SA(0, 0), a2, voffA);
;             PG8_WAIT_V(8); PG8_WAIT_L(0); PG8_BAR; PG8_MMA(1, 0, At, B0); PG8_MMA(1, 1, At, B1); PG8_BAR; PG8_SCHED;
	s_setprio 1
	v_mfma_f32_16x16x32_bf16 v[126:129], v[130:133], v[174:177], v[126:129]
	v_mfma_f32_16x16x32_bf16 v[122:125], v[138:141], v[174:177], v[122:125]
	v_mfma_f32_16x16x32_bf16 v[110:113], v[130:133], v[188:191], v[110:113]
	v_mfma_f32_16x16x32_bf16 v[106:109], v[138:141], v[188:191], v[106:109]
	v_mfma_f32_16x16x32_bf16 v[94:97], v[130:133], v[196:199], v[94:97]
	v_mfma_f32_16x16x32_bf16 v[90:93], v[138:141], v[196:199], v[90:93]
	v_mfma_f32_16x16x32_bf16 v[78:81], v[130:133], v[204:207], v[78:81]
	v_mfma_f32_16x16x32_bf16 v[74:77], v[138:141], v[204:207], v[74:77]
	v_mfma_f32_16x16x32_bf16 v[126:129], v[134:137], v[180:183], v[126:129]
	v_mfma_f32_16x16x32_bf16 v[122:125], v[142:145], v[180:183], v[122:125]
	v_mfma_f32_16x16x32_bf16 v[110:113], v[134:137], v[192:195], v[110:113]
	v_mfma_f32_16x16x32_bf16 v[106:109], v[142:145], v[192:195], v[106:109]
	v_mfma_f32_16x16x32_bf16 v[94:97], v[134:137], v[200:203], v[94:97]
	v_mfma_f32_16x16x32_bf16 v[90:93], v[142:145], v[200:203], v[90:93]
	v_mfma_f32_16x16x32_bf16 v[78:81], v[134:137], v[208:211], v[78:81]
	v_mfma_f32_16x16x32_bf16 v[74:77], v[142:145], v[208:211], v[74:77]
	s_setprio 0
	s_setprio 1
	v_mfma_f32_16x16x32_bf16 v[118:121], v[146:149], v[174:177], v[118:121]
	v_mfma_f32_16x16x32_bf16 v[114:117], v[166:169], v[174:177], v[114:117]
	v_mfma_f32_16x16x32_bf16 v[102:105], v[146:149], v[188:191], v[102:105]
	v_mfma_f32_16x16x32_bf16 v[98:101], v[166:169], v[188:191], v[98:101]
	v_mfma_f32_16x16x32_bf16 v[86:89], v[146:149], v[196:199], v[86:89]
	v_mfma_f32_16x16x32_bf16 v[82:85], v[166:169], v[196:199], v[82:85]
	v_mfma_f32_16x16x32_bf16 v[70:73], v[146:149], v[204:207], v[70:73]
	v_mfma_f32_16x16x32_bf16 v[66:69], v[166:169], v[204:207], v[66:69]
	v_mfma_f32_16x16x32_bf16 v[118:121], v[150:153], v[180:183], v[118:121]
	v_mfma_f32_16x16x32_bf16 v[114:117], v[170:173], v[180:183], v[114:117]
	v_mfma_f32_16x16x32_bf16 v[102:105], v[150:153], v[192:195], v[102:105]
	v_mfma_f32_16x16x32_bf16 v[98:101], v[170:173], v[192:195], v[98:101]
	v_mfma_f32_16x16x32_bf16 v[86:89], v[150:153], v[200:203], v[86:89]
	v_mfma_f32_16x16x32_bf16 v[82:85], v[170:173], v[200:203], v[82:85]
	v_mfma_f32_16x16x32_bf16 v[70:73], v[150:153], v[208:211], v[70:73]
	v_mfma_f32_16x16x32_bf16 v[66:69], v[170:173], v[208:211], v[66:69]
	s_setprio 0
	s_barrier
	s_add_i32 s59, s59, s33
	v_lshl_add_u64 v[212:213], s[36:37], 0, v[156:157]
	s_mov_b32 m0, s59
	ds_read_b128 v[174:177], v187 offset:16384
	ds_read_b128 v[180:183], v187 offset:17408
	ds_read_b128 v[188:191], v187 offset:18432
	ds_read_b128 v[192:195], v187 offset:19456
	ds_read_b128 v[196:199], v187 offset:20480
	ds_read_b128 v[200:203], v187 offset:21504
	ds_read_b128 v[204:207], v187 offset:22528
	ds_read_b128 v[208:211], v187 offset:23552
	global_load_lds_dwordx4 v[212:213], off
	s_add_i32 m0, s59, 0x2000
	s_add_u32 s60, s36, 0x40000
	v_lshl_add_u64 v[214:215], s[36:37], 0, v[160:161]
	s_addc_u32 s61, s37, 0
	s_add_i32 s59, s62, s33
	global_load_lds_dwordx4 v[214:215], off
	v_lshl_add_u64 v[216:217], s[60:61], 0, v[156:157]
	s_mov_b32 m0, s59
	v_lshl_add_u64 v[218:219], s[38:39], 0, v[158:159]
	global_load_lds_dwordx4 v[216:217], off
	v_lshl_add_u64 v[216:217], s[60:61], 0, v[160:161]
	s_add_i32 m0, s59, 0x2000
	s_nop 0
	global_load_lds_dwordx4 v[216:217], off
	v_lshl_add_u64 v[216:217], s[38:39], 0, v[154:155]
	s_mov_b32 m0, s46
	s_nop 0
	global_load_lds_dwordx4 v[216:217], off
	s_mov_b32 m0, s47
	s_nop 0
	global_load_lds_dwordx4 v[218:219], off
	s_waitcnt vmcnt(8) lgkmcnt(0)
	s_barrier
	s_setprio 1
	v_mfma_f32_16x16x32_bf16 v[62:65], v[130:133], v[174:177], v[62:65]
	v_mfma_f32_16x16x32_bf16 v[58:61], v[138:141], v[174:177], v[58:61]
	v_mfma_f32_16x16x32_bf16 v[46:49], v[130:133], v[188:191], v[46:49]
	v_mfma_f32_16x16x32_bf16 v[42:45], v[138:141], v[188:191], v[42:45]
	v_mfma_f32_16x16x32_bf16 v[30:33], v[130:133], v[196:199], v[30:33]
	v_mfma_f32_16x16x32_bf16 v[26:29], v[138:141], v[196:199], v[26:29]
	v_mfma_f32_16x16x32_bf16 v[14:17], v[130:133], v[204:207], v[14:17]
	v_mfma_f32_16x16x32_bf16 v[10:13], v[138:141], v[204:207], v[10:13]
	v_mfma_f32_16x16x32_bf16 v[62:65], v[134:137], v[180:183], v[62:65]
	v_mfma_f32_16x16x32_bf16 v[58:61], v[142:145], v[180:183], v[58:61]
	v_mfma_f32_16x16x32_bf16 v[46:49], v[134:137], v[192:195], v[46:49]
	v_mfma_f32_16x16x32_bf16 v[42:45], v[142:145], v[192:195], v[42:45]
	v_mfma_f32_16x16x32_bf16 v[30:33], v[134:137], v[200:203], v[30:33]
	v_mfma_f32_16x16x32_bf16 v[26:29], v[142:145], v[200:203], v[26:29]
	v_mfma_f32_16x16x32_bf16 v[14:17], v[134:137], v[208:211], v[14:17]
	v_mfma_f32_16x16x32_bf16 v[10:13], v[142:145], v[208:211], v[10:13]
	s_setprio 0
	s_setprio 1
	v_mfma_f32_16x16x32_bf16 v[54:57], v[146:149], v[174:177], v[54:57]
	v_mfma_f32_16x16x32_bf16 v[50:53], v[166:169], v[174:177], v[50:53]
	v_mfma_f32_16x16x32_bf16 v[38:41], v[146:149], v[188:191], v[38:41]
	v_mfma_f32_16x16x32_bf16 v[34:37], v[166:169], v[188:191], v[34:37]
	v_mfma_f32_16x16x32_bf16 v[22:25], v[146:149], v[196:199], v[22:25]
	v_mfma_f32_16x16x32_bf16 v[18:21], v[166:169], v[196:199], v[18:21]
	v_mfma_f32_16x16x32_bf16 v[6:9], v[146:149], v[204:207], v[6:9]
	v_mfma_f32_16x16x32_bf16 v[2:5], v[166:169], v[204:207], v[2:5]
	v_mfma_f32_16x16x32_bf16 v[54:57], v[150:153], v[180:183], v[54:57]
	v_mfma_f32_16x16x32_bf16 v[50:53], v[170:173], v[180:183], v[50:53]
	v_mfma_f32_16x16x32_bf16 v[38:41], v[150:153], v[192:195], v[38:41]
	v_mfma_f32_16x16x32_bf16 v[34:37], v[170:173], v[192:195], v[34:37]
	v_mfma_f32_16x16x32_bf16 v[22:25], v[150:153], v[200:203], v[22:25]
	v_mfma_f32_16x16x32_bf16 v[18:21], v[170:173], v[200:203], v[18:21]
	v_mfma_f32_16x16x32_bf16 v[6:9], v[150:153], v[208:211], v[6:9]
	v_mfma_f32_16x16x32_bf16 v[2:5], v[170:173], v[208:211], v[2:5]
	s_setprio 0
	s_barrier
; #define PG8_STAGE(bufoff, gbase, voff) do { _Pragma("unroll") for (int _i = 0; _i < 2; ++_i) \
;         __builtin_amdgcn_global_load_lds((const unsigned*)((const char*)(gbase) + (voff)[_i]), (PG8_LAS unsigned*)(lds + (bufoff) + ldsw + _i * 8192), 16, 0, 0); } while (0)
; #define PG8_LDA(dst, b, h) do { _Pragma("unroll") for (int m = 0; m < 4; ++m) _Pragma("unroll") for (int k = 0; k < 2; ++k) dst[m][k] = *(const PG8_LAS bf16x8*)(lds + PG8_SA(b, h) + aoff + m * 2048 + k * 1024); } while (0)
; #define PG8_LDB(dst, b, h) do { _Pragma("unroll") for (int n = 0; n < 2; ++n) _Pragma("unroll") for (int k = 0; k < 2; ++k) dst[n][k] = *(const PG8_LAS bf16x8*)(lds + PG8_SB(b, h) + boff + n * 2048 + k * 1024); } while (0)
; #define PG8_MMA(ai, bj, At, Bt) do { __builtin_amdgcn_s_setprio(1); _Pragma("unroll") for (int m = 0; m < 4; ++m) _Pragma("unroll") for (int n = 0; n < 2; ++n) _Pragma("unroll") for (int k = 0; k < 2; ++k) \
;         acc[ai][bj][m][n] = __builtin_amdgcn_mfma_f32_16x16x32_bf16(Bt[n][k], At[m][k], acc[ai][bj][m][n], 0, 0, 0); __builtin_amdgcn_s_setprio(0); } while (0)
; #define PG8_WAIT_V(n) asm volatile("s_waitcnt vmcnt(" #n ")" ::: "memory")
; #define PG8_WAIT_L(n) asm volatile("s_waitcnt lgkmcnt(" #n ")" ::: "memory")
; #define PG8_BAR __builtin_amdgcn_s_barrier()
; #define PG8_SCHED __builtin_amdgcn_sched_barrier(0)
; template <class Epi, class Sched, bool ALIGN_EPI = false, bool SP2 = false>
; __device__ __forceinline__ void gemm_phase(PG8_LAS unsigned char* lds, const Gemm g, const Sched& S, const Epi& E) {
;     ...
;             PG8_LDB(B0, 1, 0); PG8_LDB(B1, 1, 1); PG8_SCHED; PG8_LDA(At, 1, 0); PG8_STAGE(PG8_SA(0, 1), a2 + hstep, voffA);
;             PG8_WAIT_V(8); PG8_WAIT_L(0); PG8_BAR; PG8_MMA(0, 0, At, B0); PG8_MMA(0, 1, At, B1); PG8_BAR; PG8_SCHED;
	s_add_i32 s59, 0, 0x18000
	s_add_i32 s60, 0, 0x1c000
	v_add_u32_e32 v142, s59, v179
	v_add_u32_e32 v170, s60, v179
	ds_read_b128 v[130:133], v142
	ds_read_b128 v[134:137], v142 offset:1024
	ds_read_b128 v[138:141], v142 offset:2048
	ds_read_b128 v[142:145], v142 offset:3072
	ds_read_b128 v[146:149], v170
	ds_read_b128 v[150:153], v170 offset:1024
	ds_read_b128 v[166:169], v170 offset:2048
	ds_read_b128 v[170:173], v170 offset:3072
	s_add_u32 s38, s38, 0x40000
	s_addc_u32 s39, s39, 0
	s_mov_b32 m0, s48
	v_lshl_add_u64 v[220:221], s[38:39], 0, v[154:155]
	ds_read_b128 v[174:177], v187 offset:32768
	ds_read_b128 v[180:183], v187 offset:33792
	ds_read_b128 v[188:191], v187 offset:34816
	ds_read_b128 v[192:195], v187 offset:35840
	ds_read_b128 v[196:199], v187 offset:36864
	ds_read_b128 v[200:203], v187 offset:37888
	ds_read_b128 v[204:207], v187 offset:38912
	ds_read_b128 v[208:211], v187 offset:39936
	global_load_lds_dwordx4 v[220:221], off
	v_lshl_add_u64 v[220:221], s[38:39], 0, v[158:159]
	s_mov_b32 m0, s49
	s_nop 0
	global_load_lds_dwordx4 v[220:221], off
	s_waitcnt vmcnt(8) lgkmcnt(0)
	s_barrier
	s_setprio 1
	v_mfma_f32_16x16x32_bf16 v[126:129], v[130:133], v[174:177], v[126:129]
	v_mfma_f32_16x16x32_bf16 v[122:125], v[138:141], v[174:177], v[122:125]
	v_mfma_f32_16x16x32_bf16 v[110:113], v[130:133], v[188:191], v[110:113]
	v_mfma_f32_16x16x32_bf16 v[106:109], v[138:141], v[188:191], v[106:109]
	v_mfma_f32_16x16x32_bf16 v[94:97], v[130:133], v[196:199], v[94:97]
	v_mfma_f32_16x16x32_bf16 v[90:93], v[138:141], v[196:199], v[90:93]
	v_mfma_f32_16x16x32_bf16 v[78:81], v[130:133], v[204:207], v[78:81]
	v_mfma_f32_16x16x32_bf16 v[74:77], v[138:141], v[204:207], v[74:77]
	v_mfma_f32_16x16x32_bf16 v[126:129], v[134:137], v[180:183], v[126:129]
	v_mfma_f32_16x16x32_bf16 v[122:125], v[142:145], v[180:183], v[122:125]
	v_mfma_f32_16x16x32_bf16 v[110:113], v[134:137], v[192:195], v[110:113]
	v_mfma_f32_16x16x32_bf16 v[106:109], v[142:145], v[192:195], v[106:109]
	v_mfma_f32_16x16x32_bf16 v[94:97], v[134:137], v[200:203], v[94:97]
	v_mfma_f32_16x16x32_bf16 v[90:93], v[142:145], v[200:203], v[90:93]
	v_mfma_f32_16x16x32_bf16 v[78:81], v[134:137], v[208:211], v[78:81]
	v_mfma_f32_16x16x32_bf16 v[74:77], v[142:145], v[208:211], v[74:77]
	s_setprio 0
	s_setprio 1
	v_mfma_f32_16x16x32_bf16 v[118:121], v[146:149], v[174:177], v[118:121]
	v_mfma_f32_16x16x32_bf16 v[114:117], v[166:169], v[174:177], v[114:117]
	v_mfma_f32_16x16x32_bf16 v[102:105], v[146:149], v[188:191], v[102:105]
	v_mfma_f32_16x16x32_bf16 v[98:101], v[166:169], v[188:191], v[98:101]
	v_mfma_f32_16x16x32_bf16 v[86:89], v[146:149], v[196:199], v[86:89]
	v_mfma_f32_16x16x32_bf16 v[82:85], v[166:169], v[196:199], v[82:85]
	v_mfma_f32_16x16x32_bf16 v[70:73], v[146:149], v[204:207], v[70:73]
	v_mfma_f32_16x16x32_bf16 v[66:69], v[166:169], v[204:207], v[66:69]
	v_mfma_f32_16x16x32_bf16 v[118:121], v[150:153], v[180:183], v[118:121]
	v_mfma_f32_16x16x32_bf16 v[114:117], v[170:173], v[180:183], v[114:117]
	v_mfma_f32_16x16x32_bf16 v[102:105], v[150:153], v[192:195], v[102:105]
	v_mfma_f32_16x16x32_bf16 v[98:101], v[170:173], v[192:195], v[98:101]
	v_mfma_f32_16x16x32_bf16 v[86:89], v[150:153], v[200:203], v[86:89]
	v_mfma_f32_16x16x32_bf16 v[82:85], v[170:173], v[200:203], v[82:85]
	v_mfma_f32_16x16x32_bf16 v[70:73], v[150:153], v[208:211], v[70:73]
	v_mfma_f32_16x16x32_bf16 v[66:69], v[170:173], v[208:211], v[66:69]
	s_setprio 0
	s_barrier
; #define PG8_STAGE(bufoff, gbase, voff) do { _Pragma("unroll") for (int _i = 0; _i < 2; ++_i) \
;         __builtin_amdgcn_global_load_lds((const unsigned*)((const char*)(gbase) + (voff)[_i]), (PG8_LAS unsigned*)(lds + (bufoff) + ldsw + _i * 8192), 16, 0, 0); } while (0)
; #define PG8_LDA(dst, b, h) do { _Pragma("unroll") for (int m = 0; m < 4; ++m) _Pragma("unroll") for (int k = 0; k < 2; ++k) dst[m][k] = *(const PG8_LAS bf16x8*)(lds + PG8_SA(b, h) + aoff + m * 2048 + k * 1024); } while (0)
; #define PG8_MMA(ai, bj, At, Bt) do { __builtin_amdgcn_s_setprio(1); _Pragma("unroll") for (int m = 0; m < 4; ++m) _Pragma("unroll") for (int n = 0; n < 2; ++n) _Pragma("unroll") for (int k = 0; k < 2; ++k) \
;         acc[ai][bj][m][n] = __builtin_amdgcn_mfma_f32_16x16x32_bf16(Bt[n][k], At[m][k], acc[ai][bj][m][n], 0, 0, 0); __builtin_amdgcn_s_setprio(0); } while (0)
; #define PG8_WAIT_V(n) asm volatile("s_waitcnt vmcnt(" #n ")" ::: "memory")
; #define PG8_WAIT_L(n) asm volatile("s_waitcnt lgkmcnt(" #n ")" ::: "memory")
; #define PG8_BAR __builtin_amdgcn_s_barrier()
; #define PG8_SCHED __builtin_amdgcn_sched_barrier(0)
; template <class Epi, class Sched, bool ALIGN_EPI = false, bool SP2 = false>
; __device__ __forceinline__ void gemm_phase(PG8_LAS unsigned char* lds, const Gemm g, const Sched& S, const Epi& E) {
;     ...
;             PG8_LDA(At, 1, 1); PG8_STAGE(PG8_SB(1, 0), b3, voffB); PG8_STAGE(PG8_SB(1, 1), b3 + hstep, voffB); PG8_STAGE(PG8_SA(1, 0), a3, voffA);
;             PG8_WAIT_V(8); PG8_WAIT_L(0); PG8_BAR; PG8_MMA(1, 0, At, B0); PG8_MMA(1, 1, At, B1); PG8_BAR; PG8_SCHED;
;     ...
;         if constexpr (ALIGN_EPI) { if (wr == 0) PG8_BAR; }
	s_add_i32 s38, s59, s33
	v_lshl_add_u64 v[212:213], v[212:213], 0, s[80:81]
	s_mov_b32 m0, s38
	ds_read_b128 v[174:177], v187 offset:49152
	ds_read_b128 v[180:183], v187 offset:50176
	ds_read_b128 v[188:191], v187 offset:51200
	ds_read_b128 v[192:195], v187 offset:52224
	ds_read_b128 v[196:199], v187 offset:53248
	ds_read_b128 v[200:203], v187 offset:54272
	ds_read_b128 v[204:207], v187 offset:55296
	ds_read_b128 v[208:211], v187 offset:56320
	global_load_lds_dwordx4 v[212:213], off
	s_add_i32 m0, s38, 0x2000
	s_add_u32 s36, s36, 0x40080
	v_lshl_add_u64 v[212:213], v[214:215], 0, s[80:81]
	s_addc_u32 s37, s37, 0
	s_add_i32 s38, s60, s33
	global_load_lds_dwordx4 v[212:213], off
	v_lshl_add_u64 v[212:213], s[36:37], 0, v[156:157]
	s_mov_b32 m0, s38
	s_nop 0
	global_load_lds_dwordx4 v[212:213], off
	v_lshl_add_u64 v[212:213], s[36:37], 0, v[160:161]
	s_add_i32 m0, s38, 0x2000
	s_nop 0
	global_load_lds_dwordx4 v[212:213], off
	v_lshl_add_u64 v[212:213], v[216:217], 0, s[80:81]
	s_mov_b32 m0, s51
	s_nop 0
	global_load_lds_dwordx4 v[212:213], off
	v_lshl_add_u64 v[212:213], v[218:219], 0, s[80:81]
	s_mov_b32 m0, s52
	s_nop 0
	global_load_lds_dwordx4 v[212:213], off
	s_waitcnt vmcnt(8) lgkmcnt(0)
	s_barrier
	s_setprio 1
	v_mfma_f32_16x16x32_bf16 v[62:65], v[130:133], v[174:177], v[62:65]
	v_mfma_f32_16x16x32_bf16 v[58:61], v[138:141], v[174:177], v[58:61]
	v_mfma_f32_16x16x32_bf16 v[46:49], v[130:133], v[188:191], v[46:49]
	v_mfma_f32_16x16x32_bf16 v[42:45], v[138:141], v[188:191], v[42:45]
	v_mfma_f32_16x16x32_bf16 v[30:33], v[130:133], v[196:199], v[30:33]
	v_mfma_f32_16x16x32_bf16 v[26:29], v[138:141], v[196:199], v[26:29]
	v_mfma_f32_16x16x32_bf16 v[14:17], v[130:133], v[204:207], v[14:17]
	v_mfma_f32_16x16x32_bf16 v[10:13], v[138:141], v[204:207], v[10:13]
	v_mfma_f32_16x16x32_bf16 v[62:65], v[134:137], v[180:183], v[62:65]
	v_mfma_f32_16x16x32_bf16 v[58:61], v[142:145], v[180:183], v[58:61]
	v_mfma_f32_16x16x32_bf16 v[46:49], v[134:137], v[192:195], v[46:49]
	v_mfma_f32_16x16x32_bf16 v[42:45], v[142:145], v[192:195], v[42:45]
	v_mfma_f32_16x16x32_bf16 v[30:33], v[134:137], v[200:203], v[30:33]
	v_mfma_f32_16x16x32_bf16 v[26:29], v[142:145], v[200:203], v[26:29]
	v_mfma_f32_16x16x32_bf16 v[14:17], v[134:137], v[208:211], v[14:17]
	v_mfma_f32_16x16x32_bf16 v[10:13], v[142:145], v[208:211], v[10:13]
	s_setprio 0
	s_setprio 1
	v_mfma_f32_16x16x32_bf16 v[54:57], v[146:149], v[174:177], v[54:57]
	v_mfma_f32_16x16x32_bf16 v[50:53], v[166:169], v[174:177], v[50:53]
	v_mfma_f32_16x16x32_bf16 v[38:41], v[146:149], v[188:191], v[38:41]
	v_mfma_f32_16x16x32_bf16 v[34:37], v[166:169], v[188:191], v[34:37]
	v_mfma_f32_16x16x32_bf16 v[22:25], v[146:149], v[196:199], v[22:25]
	v_mfma_f32_16x16x32_bf16 v[18:21], v[166:169], v[196:199], v[18:21]
	v_mfma_f32_16x16x32_bf16 v[6:9], v[146:149], v[204:207], v[6:9]
	v_mfma_f32_16x16x32_bf16 v[2:5], v[166:169], v[204:207], v[2:5]
	v_mfma_f32_16x16x32_bf16 v[54:57], v[150:153], v[180:183], v[54:57]
	v_mfma_f32_16x16x32_bf16 v[50:53], v[170:173], v[180:183], v[50:53]
	v_mfma_f32_16x16x32_bf16 v[38:41], v[150:153], v[192:195], v[38:41]
	v_mfma_f32_16x16x32_bf16 v[34:37], v[170:173], v[192:195], v[34:37]
	v_mfma_f32_16x16x32_bf16 v[22:25], v[150:153], v[200:203], v[22:25]
	v_mfma_f32_16x16x32_bf16 v[18:21], v[170:173], v[200:203], v[18:21]
	v_mfma_f32_16x16x32_bf16 v[6:9], v[150:153], v[208:211], v[6:9]
	v_mfma_f32_16x16x32_bf16 v[2:5], v[170:173], v[208:211], v[2:5]
	s_setprio 0
	s_barrier
	s_add_i32 s58, s58, 2
	s_add_u32 s34, s34, 0x100
	s_addc_u32 s35, s35, 0
	s_add_u32 s56, s56, 0x100
	s_addc_u32 s57, s57, 0
	s_cmp_gt_u32 s58, 13
	s_cbranch_scc0 .LBB0_1062
	s_and_b64 vcc, exec, s[18:19]
	s_cbranch_vccz .LBB0_1065
	s_barrier

; #define PG8_STAGE(bufoff, gbase, voff) do { _Pragma("unroll") for (int _i = 0; _i < 2; ++_i) \
;         __builtin_amdgcn_global_load_lds((const unsigned*)((const char*)(gbase) + (voff)[_i]), (PG8_LAS unsigned*)(lds + (bufoff) + ldsw + _i * 8192), 16, 0, 0); } while (0)
; #define PG8_LDA(dst, b, h) do { _Pragma("unroll") for (int m = 0; m < 4; ++m) _Pragma("unroll") for (int k = 0; k < 2; ++k) dst[m][k] = *(const PG8_LAS bf16x8*)(lds + PG8_SA(b, h) + aoff + m * 2048 + k * 1024); } while (0)
; #define PG8_LDB(dst, b, h) do { _Pragma("unroll") for (int n = 0; n < 2; ++n) _Pragma("unroll") for (int k = 0; k < 2; ++k) dst[n][k] = *(const PG8_LAS bf16x8*)(lds + PG8_SB(b, h) + boff + n * 2048 + k * 1024); } while (0)
; #define PG8_WAIT_V(n) asm volatile("s_waitcnt vmcnt(" #n ")" ::: "memory")
; #define PG8_WAIT_L(n) asm volatile("s_waitcnt lgkmcnt(" #n ")" ::: "memory")
; #define PG8_BAR __builtin_amdgcn_s_barrier()
; #define PG8_SCHED __builtin_amdgcn_sched_barrier(0)
; template <class Epi, class Sched, bool ALIGN_EPI = false, bool SP2 = false>
; __device__ __forceinline__ void gemm_phase(PG8_LAS unsigned char* lds, const Gemm g, const Sched& S, const Epi& E) {
;     ...
;     for (;;) {
;         const bool has_next = S.next(ui + 1, nxt);
;         const char* nA = has_next ? (const char*)g.A + (size_t)nxt.pm * tstep : cA; const char* nB = has_next ? (const char*)g.Bt + (size_t)nxt.pn * tstep : cB;
;         for (int t = 0; t < nt; t += 2) {
;             const bool last = (t == nt - 2);
;             const char* a1 = cA + (size_t)(t + 1) * kstep;
;             const char* a2 = last ? nA : cA + (size_t)(t + 2) * kstep; const char* b2 = last ? nB : cB + (size_t)(t + 2) * kstep;
;             const char* a3 = a2 + kstep; const char* b3 = b2 + kstep;
;             if (last && has_next) S.a_ready(nxt);
;             if constexpr (SP2) {
;             PG8_LDB(B0, 0, 0); PG8_LDB(B1, 0, 1); PG8_SCHED; PG8_LDA(At, 0, 0); PG8_STAGE(PG8_SA(1, 1), a1 + hstep, voffA);
;             PG8_WAIT_V(8); PG8_WAIT_L(0); PG8_BAR; PG8_MMA(0, 0, At, B0); PG8_MMA(0, 1, At, B1); PG8_BAR; PG8_SCHED;
;             PG8_LDA(At, 0, 1); PG8_STAGE(PG8_SB(0, 0), b2, voffB); PG8_STAGE(PG8_SB(0, 1), b2 + hstep, voffB); PG8_STAGE(PG8_SA(0, 0), a2, voffA);
;             PG8_WAIT_V(8); PG8_WAIT_L(0); PG8_BAR; PG8_MMA(1, 0, At, B0); PG8_MMA(1, 1, At, B1); PG8_BAR; PG8_SCHED;
.LBB0_1105:
	s_ashr_i32 s19, s18, 31
	s_lshl_b64 s[20:21], s[18:19], 19
	s_add_u32 s20, s42, s20
	s_addc_u32 s21, s43, s21
	s_and_b64 s[22:23], s[6:7], exec
	s_cselect_b32 s19, s21, s29
	s_cselect_b32 s25, s20, s28
	s_ashr_i32 s17, s16, 31
	s_lshl_b64 s[22:23], s[16:17], 19
	s_add_u32 s22, s40, s22
	s_addc_u32 s23, s41, s23
	s_and_b64 s[34:35], s[6:7], exec
	s_cselect_b32 s17, s23, s31
	s_cselect_b32 s27, s22, s30
	s_add_u32 s28, s28, 0x40080
	s_addc_u32 s29, s29, 0
	s_add_u32 s52, s30, 0x100
	s_addc_u32 s53, s31, 0
	s_mov_b32 s54, -2
	s_waitcnt lgkmcnt(0)
	s_add_u32 s30, s28, 0xfffc0080
	s_addc_u32 s31, s29, -1
	s_add_i32 s55, 0, 0x10000
	s_cmp_eq_u32 s54, 12
	s_cselect_b32 s35, s19, s31
	s_cselect_b32 s34, s25, s30
	s_cselect_b32 s31, s17, s53
	s_cselect_b32 s30, s27, s52
	s_add_i32 s58, 0, 0x14000
	v_add_u32_e32 v142, s55, v179
	v_add_u32_e32 v158, s58, v179
	ds_read_b128 v[130:133], v142
	ds_read_b128 v[134:137], v142 offset:1024
	ds_read_b128 v[138:141], v142 offset:2048
	ds_read_b128 v[142:145], v142 offset:3072
	ds_read_b128 v[146:149], v158
	ds_read_b128 v[150:153], v158 offset:1024
	ds_read_b128 v[154:157], v158 offset:2048
	ds_read_b128 v[158:161], v158 offset:3072
	v_lshl_add_u64 v[212:213], s[28:29], 0, v[194:195]
	s_add_i32 m0, s36, 0xc000
	ds_read_b128 v[162:165], v211
	ds_read_b128 v[166:169], v211 offset:1024
	ds_read_b128 v[170:173], v211 offset:2048
	ds_read_b128 v[174:177], v211 offset:3072
	ds_read_b128 v[180:183], v211 offset:4096
	ds_read_b128 v[198:201], v211 offset:5120
	ds_read_b128 v[202:205], v211 offset:6144
	ds_read_b128 v[206:209], v211 offset:7168
	global_load_lds_dwordx4 v[212:213], off
	v_lshl_add_u64 v[212:213], s[28:29], 0, v[196:197]
	s_add_i32 m0, s36, 0xe000
	s_nop 0
	global_load_lds_dwordx4 v[212:213], off
	s_waitcnt vmcnt(8) lgkmcnt(0)
	s_barrier
	s_setprio 1
	v_mfma_f32_16x16x32_bf16 v[126:129], v[130:133], v[162:165], 0
	v_mfma_f32_16x16x32_bf16 v[122:125], v[138:141], v[162:165], 0
	v_mfma_f32_16x16x32_bf16 v[110:113], v[130:133], v[170:173], 0
	v_mfma_f32_16x16x32_bf16 v[106:109], v[138:141], v[170:173], 0
	v_mfma_f32_16x16x32_bf16 v[94:97], v[130:133], v[180:183], 0
	v_mfma_f32_16x16x32_bf16 v[90:93], v[138:141], v[180:183], 0
	v_mfma_f32_16x16x32_bf16 v[78:81], v[130:133], v[202:205], 0
	v_mfma_f32_16x16x32_bf16 v[74:77], v[138:141], v[202:205], 0
	v_mfma_f32_16x16x32_bf16 v[126:129], v[134:137], v[166:169], v[126:129]
	v_mfma_f32_16x16x32_bf16 v[122:125], v[142:145], v[166:169], v[122:125]
	v_mfma_f32_16x16x32_bf16 v[110:113], v[134:137], v[174:177], v[110:113]
	v_mfma_f32_16x16x32_bf16 v[106:109], v[142:145], v[174:177], v[106:109]
	v_mfma_f32_16x16x32_bf16 v[94:97], v[134:137], v[198:201], v[94:97]
	v_mfma_f32_16x16x32_bf16 v[90:93], v[142:145], v[198:201], v[90:93]
	v_mfma_f32_16x16x32_bf16 v[78:81], v[134:137], v[206:209], v[78:81]
	v_mfma_f32_16x16x32_bf16 v[74:77], v[142:145], v[206:209], v[74:77]
	s_setprio 0
	s_setprio 1
	v_mfma_f32_16x16x32_bf16 v[118:121], v[146:149], v[162:165], 0
	v_mfma_f32_16x16x32_bf16 v[114:117], v[154:157], v[162:165], 0
	v_mfma_f32_16x16x32_bf16 v[102:105], v[146:149], v[170:173], 0
	v_mfma_f32_16x16x32_bf16 v[98:101], v[154:157], v[170:173], 0
	v_mfma_f32_16x16x32_bf16 v[86:89], v[146:149], v[180:183], 0
	v_mfma_f32_16x16x32_bf16 v[82:85], v[154:157], v[180:183], 0
	v_mfma_f32_16x16x32_bf16 v[70:73], v[146:149], v[202:205], 0
	v_mfma_f32_16x16x32_bf16 v[66:69], v[154:157], v[202:205], 0
	v_mfma_f32_16x16x32_bf16 v[118:121], v[150:153], v[166:169], v[118:121]
	v_mfma_f32_16x16x32_bf16 v[114:117], v[158:161], v[166:169], v[114:117]
	v_mfma_f32_16x16x32_bf16 v[102:105], v[150:153], v[174:177], v[102:105]
	v_mfma_f32_16x16x32_bf16 v[98:101], v[158:161], v[174:177], v[98:101]
	v_mfma_f32_16x16x32_bf16 v[86:89], v[150:153], v[198:201], v[86:89]
	v_mfma_f32_16x16x32_bf16 v[82:85], v[158:161], v[198:201], v[82:85]
	v_mfma_f32_16x16x32_bf16 v[70:73], v[150:153], v[206:209], v[70:73]
	v_mfma_f32_16x16x32_bf16 v[66:69], v[158:161], v[206:209], v[66:69]
	s_setprio 0
	s_barrier
	s_add_i32 s55, s55, s33
	v_lshl_add_u64 v[212:213], s[30:31], 0, v[188:189]
	s_mov_b32 m0, s55
	ds_read_b128 v[162:165], v211 offset:16384
	ds_read_b128 v[166:169], v211 offset:17408
	ds_read_b128 v[170:173], v211 offset:18432
	ds_read_b128 v[174:177], v211 offset:19456
	ds_read_b128 v[180:183], v211 offset:20480
	ds_read_b128 v[198:201], v211 offset:21504
	ds_read_b128 v[202:205], v211 offset:22528
	ds_read_b128 v[206:209], v211 offset:23552
	global_load_lds_dwordx4 v[212:213], off
	s_add_i32 m0, s55, 0x2000
	s_add_u32 s56, s30, 0x40000
	v_lshl_add_u64 v[214:215], s[30:31], 0, v[192:193]
	s_addc_u32 s57, s31, 0
	s_add_i32 s55, s58, s33
	global_load_lds_dwordx4 v[214:215], off
	v_lshl_add_u64 v[216:217], s[56:57], 0, v[188:189]
	s_mov_b32 m0, s55
	v_lshl_add_u64 v[218:219], s[34:35], 0, v[190:191]
	global_load_lds_dwordx4 v[216:217], off
	v_lshl_add_u64 v[216:217], s[56:57], 0, v[192:193]
	s_add_i32 m0, s55, 0x2000
	s_nop 0
	global_load_lds_dwordx4 v[216:217], off
	v_lshl_add_u64 v[216:217], s[34:35], 0, v[186:187]
	s_mov_b32 m0, s36
	s_nop 0
	global_load_lds_dwordx4 v[216:217], off
	s_mov_b32 m0, s37
	s_nop 0
	global_load_lds_dwordx4 v[218:219], off
	s_waitcnt vmcnt(8) lgkmcnt(0)
	s_barrier
; #define PG8_STAGE(bufoff, gbase, voff) do { _Pragma("unroll") for (int _i = 0; _i < 2; ++_i) \
;         __builtin_amdgcn_global_load_lds((const unsigned*)((const char*)(gbase) + (voff)[_i]), (PG8_LAS unsigned*)(lds + (bufoff) + ldsw + _i * 8192), 16, 0, 0); } while (0)
; #define PG8_LDA(dst, b, h) do { _Pragma("unroll") for (int m = 0; m < 4; ++m) _Pragma("unroll") for (int k = 0; k < 2; ++k) dst[m][k] = *(const PG8_LAS bf16x8*)(lds + PG8_SA(b, h) + aoff + m * 2048 + k * 1024); } while (0)
; #define PG8_LDB(dst, b, h) do { _Pragma("unroll") for (int n = 0; n < 2; ++n) _Pragma("unroll") for (int k = 0; k < 2; ++k) dst[n][k] = *(const PG8_LAS bf16x8*)(lds + PG8_SB(b, h) + boff + n * 2048 + k * 1024); } while (0)
; #define PG8_MMA(ai, bj, At, Bt) do { __builtin_amdgcn_s_setprio(1); _Pragma("unroll") for (int m = 0; m < 4; ++m) _Pragma("unroll") for (int n = 0; n < 2; ++n) _Pragma("unroll") for (int k = 0; k < 2; ++k) \
;         acc[ai][bj][m][n] = __builtin_amdgcn_mfma_f32_16x16x32_bf16(Bt[n][k], At[m][k], acc[ai][bj][m][n], 0, 0, 0); __builtin_amdgcn_s_setprio(0); } while (0)
; #define PG8_WAIT_V(n) asm volatile("s_waitcnt vmcnt(" #n ")" ::: "memory")
; #define PG8_WAIT_L(n) asm volatile("s_waitcnt lgkmcnt(" #n ")" ::: "memory")
; #define PG8_BAR __builtin_amdgcn_s_barrier()
; #define PG8_SCHED __builtin_amdgcn_sched_barrier(0)
; template <class Epi, class Sched, bool ALIGN_EPI = false, bool SP2 = false>
; __device__ __forceinline__ void gemm_phase(PG8_LAS unsigned char* lds, const Gemm g, const Sched& S, const Epi& E) {
;     ...
;             PG8_WAIT_V(8); PG8_WAIT_L(0); PG8_BAR; PG8_MMA(1, 0, At, B0); PG8_MMA(1, 1, At, B1); PG8_BAR; PG8_SCHED;
;             PG8_LDB(B0, 1, 0); PG8_LDB(B1, 1, 1); PG8_SCHED; PG8_LDA(At, 1, 0); PG8_STAGE(PG8_SA(0, 1), a2 + hstep, voffA);
;             PG8_WAIT_V(8); PG8_WAIT_L(0); PG8_BAR; PG8_MMA(0, 0, At, B0); PG8_MMA(0, 1, At, B1); PG8_BAR; PG8_SCHED;
	s_setprio 1
	v_mfma_f32_16x16x32_bf16 v[62:65], v[130:133], v[162:165], 0
	v_mfma_f32_16x16x32_bf16 v[58:61], v[138:141], v[162:165], 0
	v_mfma_f32_16x16x32_bf16 v[46:49], v[130:133], v[170:173], 0
	v_mfma_f32_16x16x32_bf16 v[42:45], v[138:141], v[170:173], 0
	v_mfma_f32_16x16x32_bf16 v[30:33], v[130:133], v[180:183], 0
	v_mfma_f32_16x16x32_bf16 v[26:29], v[138:141], v[180:183], 0
	v_mfma_f32_16x16x32_bf16 v[14:17], v[130:133], v[202:205], 0
	v_mfma_f32_16x16x32_bf16 v[10:13], v[138:141], v[202:205], 0
	v_mfma_f32_16x16x32_bf16 v[62:65], v[134:137], v[166:169], v[62:65]
	v_mfma_f32_16x16x32_bf16 v[58:61], v[142:145], v[166:169], v[58:61]
	v_mfma_f32_16x16x32_bf16 v[46:49], v[134:137], v[174:177], v[46:49]
	v_mfma_f32_16x16x32_bf16 v[42:45], v[142:145], v[174:177], v[42:45]
	v_mfma_f32_16x16x32_bf16 v[30:33], v[134:137], v[198:201], v[30:33]
	v_mfma_f32_16x16x32_bf16 v[26:29], v[142:145], v[198:201], v[26:29]
	v_mfma_f32_16x16x32_bf16 v[14:17], v[134:137], v[206:209], v[14:17]
	v_mfma_f32_16x16x32_bf16 v[10:13], v[142:145], v[206:209], v[10:13]
	s_setprio 0
	s_setprio 1
	v_mfma_f32_16x16x32_bf16 v[54:57], v[146:149], v[162:165], 0
	v_mfma_f32_16x16x32_bf16 v[50:53], v[154:157], v[162:165], 0
	v_mfma_f32_16x16x32_bf16 v[38:41], v[146:149], v[170:173], 0
	v_mfma_f32_16x16x32_bf16 v[34:37], v[154:157], v[170:173], 0
	v_mfma_f32_16x16x32_bf16 v[22:25], v[146:149], v[180:183], 0
	v_mfma_f32_16x16x32_bf16 v[18:21], v[154:157], v[180:183], 0
	v_mfma_f32_16x16x32_bf16 v[6:9], v[146:149], v[202:205], 0
	v_mfma_f32_16x16x32_bf16 v[2:5], v[154:157], v[202:205], 0
	v_mfma_f32_16x16x32_bf16 v[54:57], v[150:153], v[166:169], v[54:57]
	v_mfma_f32_16x16x32_bf16 v[50:53], v[158:161], v[166:169], v[50:53]
	v_mfma_f32_16x16x32_bf16 v[38:41], v[150:153], v[174:177], v[38:41]
	v_mfma_f32_16x16x32_bf16 v[34:37], v[158:161], v[174:177], v[34:37]
	v_mfma_f32_16x16x32_bf16 v[22:25], v[150:153], v[198:201], v[22:25]
	v_mfma_f32_16x16x32_bf16 v[18:21], v[158:161], v[198:201], v[18:21]
	v_mfma_f32_16x16x32_bf16 v[6:9], v[150:153], v[206:209], v[6:9]
	v_mfma_f32_16x16x32_bf16 v[2:5], v[158:161], v[206:209], v[2:5]
	s_setprio 0
	s_barrier
	s_add_i32 s55, 0, 0x18000
	s_add_i32 s56, 0, 0x1c000
	v_add_u32_e32 v142, s55, v179
	v_add_u32_e32 v158, s56, v179
	ds_read_b128 v[130:133], v142
	ds_read_b128 v[134:137], v142 offset:1024
	ds_read_b128 v[138:141], v142 offset:2048
	ds_read_b128 v[142:145], v142 offset:3072
	ds_read_b128 v[146:149], v158
	ds_read_b128 v[150:153], v158 offset:1024
	ds_read_b128 v[154:157], v158 offset:2048
	ds_read_b128 v[158:161], v158 offset:3072
	s_add_u32 s34, s34, 0x40000
	s_addc_u32 s35, s35, 0
	s_mov_b32 m0, s38
	v_lshl_add_u64 v[220:221], s[34:35], 0, v[186:187]
	ds_read_b128 v[162:165], v211 offset:32768
	ds_read_b128 v[166:169], v211 offset:33792
	ds_read_b128 v[170:173], v211 offset:34816
	ds_read_b128 v[174:177], v211 offset:35840
	ds_read_b128 v[180:183], v211 offset:36864
	ds_read_b128 v[198:201], v211 offset:37888
	ds_read_b128 v[202:205], v211 offset:38912
	ds_read_b128 v[206:209], v211 offset:39936
	global_load_lds_dwordx4 v[220:221], off
	v_lshl_add_u64 v[220:221], s[34:35], 0, v[190:191]
	s_mov_b32 m0, s39
	s_nop 0
	global_load_lds_dwordx4 v[220:221], off
	s_waitcnt vmcnt(8) lgkmcnt(0)
	s_barrier
	s_setprio 1
	v_mfma_f32_16x16x32_bf16 v[126:129], v[130:133], v[162:165], v[126:129]
	v_mfma_f32_16x16x32_bf16 v[122:125], v[138:141], v[162:165], v[122:125]
	v_mfma_f32_16x16x32_bf16 v[110:113], v[130:133], v[170:173], v[110:113]
	v_mfma_f32_16x16x32_bf16 v[106:109], v[138:141], v[170:173], v[106:109]
	v_mfma_f32_16x16x32_bf16 v[94:97], v[130:133], v[180:183], v[94:97]
	v_mfma_f32_16x16x32_bf16 v[90:93], v[138:141], v[180:183], v[90:93]
	v_mfma_f32_16x16x32_bf16 v[78:81], v[130:133], v[202:205], v[78:81]
	v_mfma_f32_16x16x32_bf16 v[74:77], v[138:141], v[202:205], v[74:77]
	v_mfma_f32_16x16x32_bf16 v[126:129], v[134:137], v[166:169], v[126:129]
	v_mfma_f32_16x16x32_bf16 v[122:125], v[142:145], v[166:169], v[122:125]
	v_mfma_f32_16x16x32_bf16 v[110:113], v[134:137], v[174:177], v[110:113]
	v_mfma_f32_16x16x32_bf16 v[106:109], v[142:145], v[174:177], v[106:109]
	v_mfma_f32_16x16x32_bf16 v[94:97], v[134:137], v[198:201], v[94:97]
	v_mfma_f32_16x16x32_bf16 v[90:93], v[142:145], v[198:201], v[90:93]
	v_mfma_f32_16x16x32_bf16 v[78:81], v[134:137], v[206:209], v[78:81]
	v_mfma_f32_16x16x32_bf16 v[74:77], v[142:145], v[206:209], v[74:77]
	s_setprio 0
	s_setprio 1
	v_mfma_f32_16x16x32_bf16 v[118:121], v[146:149], v[162:165], v[118:121]
	v_mfma_f32_16x16x32_bf16 v[114:117], v[154:157], v[162:165], v[114:117]
	v_mfma_f32_16x16x32_bf16 v[102:105], v[146:149], v[170:173], v[102:105]
	v_mfma_f32_16x16x32_bf16 v[98:101], v[154:157], v[170:173], v[98:101]
	v_mfma_f32_16x16x32_bf16 v[86:89], v[146:149], v[180:183], v[86:89]
	v_mfma_f32_16x16x32_bf16 v[82:85], v[154:157], v[180:183], v[82:85]
	v_mfma_f32_16x16x32_bf16 v[70:73], v[146:149], v[202:205], v[70:73]
	v_mfma_f32_16x16x32_bf16 v[66:69], v[154:157], v[202:205], v[66:69]
	v_mfma_f32_16x16x32_bf16 v[118:121], v[150:153], v[166:169], v[118:121]
	v_mfma_f32_16x16x32_bf16 v[114:117], v[158:161], v[166:169], v[114:117]
	v_mfma_f32_16x16x32_bf16 v[102:105], v[150:153], v[174:177], v[102:105]
	v_mfma_f32_16x16x32_bf16 v[98:101], v[158:161], v[174:177], v[98:101]
	v_mfma_f32_16x16x32_bf16 v[86:89], v[150:153], v[198:201], v[86:89]
	v_mfma_f32_16x16x32_bf16 v[82:85], v[158:161], v[198:201], v[82:85]
	v_mfma_f32_16x16x32_bf16 v[70:73], v[150:153], v[206:209], v[70:73]
	v_mfma_f32_16x16x32_bf16 v[66:69], v[158:161], v[206:209], v[66:69]
	s_setprio 0
	s_barrier
; #define PG8_STAGE(bufoff, gbase, voff) do { _Pragma("unroll") for (int _i = 0; _i < 2; ++_i) \
;         __builtin_amdgcn_global_load_lds((const unsigned*)((const char*)(gbase) + (voff)[_i]), (PG8_LAS unsigned*)(lds + (bufoff) + ldsw + _i * 8192), 16, 0, 0); } while (0)
; #define PG8_LDA(dst, b, h) do { _Pragma("unroll") for (int m = 0; m < 4; ++m) _Pragma("unroll") for (int k = 0; k < 2; ++k) dst[m][k] = *(const PG8_LAS bf16x8*)(lds + PG8_SA(b, h) + aoff + m * 2048 + k * 1024); } while (0)
; #define PG8_LDB(dst, b, h) do { _Pragma("unroll") for (int n = 0; n < 2; ++n) _Pragma("unroll") for (int k = 0; k < 2; ++k) dst[n][k] = *(const PG8_LAS bf16x8*)(lds + PG8_SB(b, h) + boff + n * 2048 + k * 1024); } while (0)
; template <class Epi, class Sched, bool ALIGN_EPI = false, bool SP2 = false>
; __device__ __forceinline__ void gemm_phase(PG8_LAS unsigned char* lds, const Gemm g, const Sched& S, const Epi& E) {
;     ...
;         for (int t = 0; t < nt; t += 2) {
;             const bool last = (t == nt - 2);
;             const char* a1 = cA + (size_t)(t + 1) * kstep;
;             const char* a2 = last ? nA : cA + (size_t)(t + 2) * kstep; const char* b2 = last ? nB : cB + (size_t)(t + 2) * kstep;
;             const char* a3 = a2 + kstep; const char* b3 = b2 + kstep;
;             if (last && has_next) S.a_ready(nxt);
;             if constexpr (SP2) {
;             PG8_LDB(B0, 0, 0); PG8_LDB(B1, 0, 1); PG8_SCHED; PG8_LDA(At, 0, 0); PG8_STAGE(PG8_SA(1, 1), a1 + hstep, voffA);
;             PG8_WAIT_V(8); PG8_WAIT_L(0); PG8_BAR; PG8_MMA(0, 0, At, B0); PG8_MMA(0, 1, At, B1); PG8_BAR; PG8_SCHED;
;             PG8_LDA(At, 0, 1); PG8_STAGE(PG8_SB(0, 0), b2, voffB); PG8_STAGE(PG8_SB(0, 1), b2 + hstep, voffB); PG8_STAGE(PG8_SA(0, 0), a2, voffA);
;             PG8_WAIT_V(8); PG8_WAIT_L(0); PG8_BAR; PG8_MMA(1, 0, At, B0); PG8_MMA(1, 1, At, B1); PG8_BAR; PG8_SCHED;
;             PG8_LDB(B0, 1, 0); PG8_LDB(B1, 1, 1); PG8_SCHED; PG8_LDA(At, 1, 0); PG8_STAGE(PG8_SA(0, 1), a2 + hstep, voffA);
;             PG8_WAIT_V(8); PG8_WAIT_L(0); PG8_BAR; PG8_MMA(0, 0, At, B0); PG8_MMA(0, 1, At, B1); PG8_BAR; PG8_SCHED;
;             PG8_LDA(At, 1, 1); PG8_STAGE(PG8_SB(1, 0), b3, voffB); PG8_STAGE(PG8_SB(1, 1), b3 + hstep, voffB); PG8_STAGE(PG8_SA(1, 0), a3, voffA);
;             PG8_WAIT_V(8); PG8_WAIT_L(0); PG8_BAR; PG8_MMA(1, 0, At, B0); PG8_MMA(1, 1, At, B1); PG8_BAR; PG8_SCHED;
	s_add_i32 s34, s55, s33
	v_lshl_add_u64 v[212:213], v[212:213], 0, s[80:81]
	s_mov_b32 m0, s34
	ds_read_b128 v[162:165], v211 offset:49152
	ds_read_b128 v[166:169], v211 offset:50176
	ds_read_b128 v[170:173], v211 offset:51200
	ds_read_b128 v[174:177], v211 offset:52224
	ds_read_b128 v[180:183], v211 offset:53248
	ds_read_b128 v[198:201], v211 offset:54272
	ds_read_b128 v[202:205], v211 offset:55296
	ds_read_b128 v[206:209], v211 offset:56320
	global_load_lds_dwordx4 v[212:213], off
	s_add_i32 m0, s34, 0x2000
	s_add_u32 s30, s30, 0x40080
	v_lshl_add_u64 v[212:213], v[214:215], 0, s[80:81]
	s_addc_u32 s31, s31, 0
	s_add_i32 s34, s56, s33
	global_load_lds_dwordx4 v[212:213], off
	v_lshl_add_u64 v[212:213], s[30:31], 0, v[188:189]
	s_mov_b32 m0, s34
	s_nop 0
	global_load_lds_dwordx4 v[212:213], off
	v_lshl_add_u64 v[212:213], s[30:31], 0, v[192:193]
	s_add_i32 m0, s34, 0x2000
	s_nop 0
	global_load_lds_dwordx4 v[212:213], off
	v_lshl_add_u64 v[212:213], v[216:217], 0, s[80:81]
	s_mov_b32 m0, s47
	s_nop 0
	global_load_lds_dwordx4 v[212:213], off
	v_lshl_add_u64 v[212:213], v[218:219], 0, s[80:81]
	s_mov_b32 m0, s48
	s_nop 0
	global_load_lds_dwordx4 v[212:213], off
	s_waitcnt vmcnt(8) lgkmcnt(0)
	s_barrier
	s_setprio 1
	v_mfma_f32_16x16x32_bf16 v[62:65], v[130:133], v[162:165], v[62:65]
	v_mfma_f32_16x16x32_bf16 v[58:61], v[138:141], v[162:165], v[58:61]
	v_mfma_f32_16x16x32_bf16 v[46:49], v[130:133], v[170:173], v[46:49]
	v_mfma_f32_16x16x32_bf16 v[42:45], v[138:141], v[170:173], v[42:45]
	v_mfma_f32_16x16x32_bf16 v[30:33], v[130:133], v[180:183], v[30:33]
	v_mfma_f32_16x16x32_bf16 v[26:29], v[138:141], v[180:183], v[26:29]
	v_mfma_f32_16x16x32_bf16 v[14:17], v[130:133], v[202:205], v[14:17]
	v_mfma_f32_16x16x32_bf16 v[10:13], v[138:141], v[202:205], v[10:13]
	v_mfma_f32_16x16x32_bf16 v[62:65], v[134:137], v[166:169], v[62:65]
	v_mfma_f32_16x16x32_bf16 v[58:61], v[142:145], v[166:169], v[58:61]
	v_mfma_f32_16x16x32_bf16 v[46:49], v[134:137], v[174:177], v[46:49]
	v_mfma_f32_16x16x32_bf16 v[42:45], v[142:145], v[174:177], v[42:45]
	v_mfma_f32_16x16x32_bf16 v[30:33], v[134:137], v[198:201], v[30:33]
	v_mfma_f32_16x16x32_bf16 v[26:29], v[142:145], v[198:201], v[26:29]
	v_mfma_f32_16x16x32_bf16 v[14:17], v[134:137], v[206:209], v[14:17]
	v_mfma_f32_16x16x32_bf16 v[10:13], v[142:145], v[206:209], v[10:13]
	s_setprio 0
	s_setprio 1
	v_mfma_f32_16x16x32_bf16 v[54:57], v[146:149], v[162:165], v[54:57]
	v_mfma_f32_16x16x32_bf16 v[50:53], v[154:157], v[162:165], v[50:53]
	v_mfma_f32_16x16x32_bf16 v[38:41], v[146:149], v[170:173], v[38:41]
	v_mfma_f32_16x16x32_bf16 v[34:37], v[154:157], v[170:173], v[34:37]
	v_mfma_f32_16x16x32_bf16 v[22:25], v[146:149], v[180:183], v[22:25]
	v_mfma_f32_16x16x32_bf16 v[18:21], v[154:157], v[180:183], v[18:21]
	v_mfma_f32_16x16x32_bf16 v[6:9], v[146:149], v[202:205], v[6:9]
	v_mfma_f32_16x16x32_bf16 v[2:5], v[154:157], v[202:205], v[2:5]
	v_mfma_f32_16x16x32_bf16 v[54:57], v[150:153], v[166:169], v[54:57]
	v_mfma_f32_16x16x32_bf16 v[50:53], v[158:161], v[166:169], v[50:53]
	v_mfma_f32_16x16x32_bf16 v[38:41], v[150:153], v[174:177], v[38:41]
	v_mfma_f32_16x16x32_bf16 v[34:37], v[158:161], v[174:177], v[34:37]
	v_mfma_f32_16x16x32_bf16 v[22:25], v[150:153], v[198:201], v[22:25]
	v_mfma_f32_16x16x32_bf16 v[18:21], v[158:161], v[198:201], v[18:21]
	v_mfma_f32_16x16x32_bf16 v[6:9], v[150:153], v[206:209], v[6:9]
	v_mfma_f32_16x16x32_bf16 v[2:5], v[158:161], v[206:209], v[2:5]
	s_setprio 0
	s_barrier
	s_add_i32 s54, s54, 2
	s_add_u32 s28, s28, 0x100
	s_addc_u32 s29, s29, 0
	s_add_u32 s52, s52, 0x100
	s_addc_u32 s53, s53, 0
	s_cmp_gt_u32 s54, 13
	s_branch .LBB0_1106
.LBB0_1106:
	s_add_u32 s30, s28, 0xfffc0080
	s_addc_u32 s31, s29, -1
	s_add_i32 s55, 0, 0x10000
	s_cmp_eq_u32 s54, 12
	s_cselect_b32 s35, s19, s31
	s_cselect_b32 s34, s25, s30
	s_cselect_b32 s31, s17, s53
	s_cselect_b32 s30, s27, s52
	s_add_i32 s58, 0, 0x14000
	v_add_u32_e32 v142, s55, v179
	v_add_u32_e32 v158, s58, v179
	ds_read_b128 v[130:133], v142
	ds_read_b128 v[134:137], v142 offset:1024
	ds_read_b128 v[138:141], v142 offset:2048
	ds_read_b128 v[142:145], v142 offset:3072
	ds_read_b128 v[146:149], v158
	ds_read_b128 v[150:153], v158 offset:1024
	ds_read_b128 v[154:157], v158 offset:2048
	ds_read_b128 v[158:161], v158 offset:3072
	v_lshl_add_u64 v[212:213], s[28:29], 0, v[194:195]
	s_add_i32 m0, s36, 0xc000
	ds_read_b128 v[162:165], v211
	ds_read_b128 v[166:169], v211 offset:1024
	ds_read_b128 v[170:173], v211 offset:2048
	ds_read_b128 v[174:177], v211 offset:3072
	ds_read_b128 v[180:183], v211 offset:4096
	ds_read_b128 v[198:201], v211 offset:5120
	ds_read_b128 v[202:205], v211 offset:6144
	ds_read_b128 v[206:209], v211 offset:7168
	global_load_lds_dwordx4 v[212:213], off
	v_lshl_add_u64 v[212:213], s[28:29], 0, v[196:197]
	s_add_i32 m0, s36, 0xe000
	s_nop 0
	global_load_lds_dwordx4 v[212:213], off
	s_waitcnt vmcnt(8) lgkmcnt(0)
	s_barrier
; #define PG8_STAGE(bufoff, gbase, voff) do { _Pragma("unroll") for (int _i = 0; _i < 2; ++_i) \
;         __builtin_amdgcn_global_load_lds((const unsigned*)((const char*)(gbase) + (voff)[_i]), (PG8_LAS unsigned*)(lds + (bufoff) + ldsw + _i * 8192), 16, 0, 0); } while (0)
; #define PG8_LDA(dst, b, h) do { _Pragma("unroll") for (int m = 0; m < 4; ++m) _Pragma("unroll") for (int k = 0; k < 2; ++k) dst[m][k] = *(const PG8_LAS bf16x8*)(lds + PG8_SA(b, h) + aoff + m * 2048 + k * 1024); } while (0)
; #define PG8_MMA(ai, bj, At, Bt) do { __builtin_amdgcn_s_setprio(1); _Pragma("unroll") for (int m = 0; m < 4; ++m) _Pragma("unroll") for (int n = 0; n < 2; ++n) _Pragma("unroll") for (int k = 0; k < 2; ++k) \
;         acc[ai][bj][m][n] = __builtin_amdgcn_mfma_f32_16x16x32_bf16(Bt[n][k], At[m][k], acc[ai][bj][m][n], 0, 0, 0); __builtin_amdgcn_s_setprio(0); } while (0)
; #define PG8_WAIT_V(n) asm volatile("s_waitcnt vmcnt(" #n ")" ::: "memory")
; #define PG8_WAIT_L(n) asm volatile("s_waitcnt lgkmcnt(" #n ")" ::: "memory")
; #define PG8_BAR __builtin_amdgcn_s_barrier()
; #define PG8_SCHED __builtin_amdgcn_sched_barrier(0)
; template <class Epi, class Sched, bool ALIGN_EPI = false, bool SP2 = false>
; __device__ __forceinline__ void gemm_phase(PG8_LAS unsigned char* lds, const Gemm g, const Sched& S, const Epi& E) {
;     ...
;             PG8_WAIT_V(8); PG8_WAIT_L(0); PG8_BAR; PG8_MMA(0, 0, At, B0); PG8_MMA(0, 1, At, B1); PG8_BAR; PG8_SCHED;
;             PG8_LDA(At, 0, 1); PG8_STAGE(PG8_SB(0, 0), b2, voffB); PG8_STAGE(PG8_SB(0, 1), b2 + hstep, voffB); PG8_STAGE(PG8_SA(0, 0), a2, voffA);
;             PG8_WAIT_V(8); PG8_WAIT_L(0); PG8_BAR; PG8_MMA(1, 0, At, B0); PG8_MMA(1, 1, At, B1); PG8_BAR; PG8_SCHED;
	s_setprio 1
	v_mfma_f32_16x16x32_bf16 v[126:129], v[130:133], v[162:165], v[126:129]
	v_mfma_f32_16x16x32_bf16 v[122:125], v[138:141], v[162:165], v[122:125]
	v_mfma_f32_16x16x32_bf16 v[110:113], v[130:133], v[170:173], v[110:113]
	v_mfma_f32_16x16x32_bf16 v[106:109], v[138:141], v[170:173], v[106:109]
	v_mfma_f32_16x16x32_bf16 v[94:97], v[130:133], v[180:183], v[94:97]
	v_mfma_f32_16x16x32_bf16 v[90:93], v[138:141], v[180:183], v[90:93]
	v_mfma_f32_16x16x32_bf16 v[78:81], v[130:133], v[202:205], v[78:81]
	v_mfma_f32_16x16x32_bf16 v[74:77], v[138:141], v[202:205], v[74:77]
	v_mfma_f32_16x16x32_bf16 v[126:129], v[134:137], v[166:169], v[126:129]
	v_mfma_f32_16x16x32_bf16 v[122:125], v[142:145], v[166:169], v[122:125]
	v_mfma_f32_16x16x32_bf16 v[110:113], v[134:137], v[174:177], v[110:113]
	v_mfma_f32_16x16x32_bf16 v[106:109], v[142:145], v[174:177], v[106:109]
	v_mfma_f32_16x16x32_bf16 v[94:97], v[134:137], v[198:201], v[94:97]
	v_mfma_f32_16x16x32_bf16 v[90:93], v[142:145], v[198:201], v[90:93]
	v_mfma_f32_16x16x32_bf16 v[78:81], v[134:137], v[206:209], v[78:81]
	v_mfma_f32_16x16x32_bf16 v[74:77], v[142:145], v[206:209], v[74:77]
	s_setprio 0
	s_setprio 1
	v_mfma_f32_16x16x32_bf16 v[118:121], v[146:149], v[162:165], v[118:121]
	v_mfma_f32_16x16x32_bf16 v[114:117], v[154:157], v[162:165], v[114:117]
	v_mfma_f32_16x16x32_bf16 v[102:105], v[146:149], v[170:173], v[102:105]
	v_mfma_f32_16x16x32_bf16 v[98:101], v[154:157], v[170:173], v[98:101]
	v_mfma_f32_16x16x32_bf16 v[86:89], v[146:149], v[180:183], v[86:89]
	v_mfma_f32_16x16x32_bf16 v[82:85], v[154:157], v[180:183], v[82:85]
	v_mfma_f32_16x16x32_bf16 v[70:73], v[146:149], v[202:205], v[70:73]
	v_mfma_f32_16x16x32_bf16 v[66:69], v[154:157], v[202:205], v[66:69]
	v_mfma_f32_16x16x32_bf16 v[118:121], v[150:153], v[166:169], v[118:121]
	v_mfma_f32_16x16x32_bf16 v[114:117], v[158:161], v[166:169], v[114:117]
	v_mfma_f32_16x16x32_bf16 v[102:105], v[150:153], v[174:177], v[102:105]
	v_mfma_f32_16x16x32_bf16 v[98:101], v[158:161], v[174:177], v[98:101]
	v_mfma_f32_16x16x32_bf16 v[86:89], v[150:153], v[198:201], v[86:89]
	v_mfma_f32_16x16x32_bf16 v[82:85], v[158:161], v[198:201], v[82:85]
	v_mfma_f32_16x16x32_bf16 v[70:73], v[150:153], v[206:209], v[70:73]
	v_mfma_f32_16x16x32_bf16 v[66:69], v[158:161], v[206:209], v[66:69]
	s_setprio 0
	s_barrier
	s_add_i32 s55, s55, s33
	v_lshl_add_u64 v[212:213], s[30:31], 0, v[188:189]
	s_mov_b32 m0, s55
	ds_read_b128 v[162:165], v211 offset:16384
	ds_read_b128 v[166:169], v211 offset:17408
	ds_read_b128 v[170:173], v211 offset:18432
	ds_read_b128 v[174:177], v211 offset:19456
	ds_read_b128 v[180:183], v211 offset:20480
	ds_read_b128 v[198:201], v211 offset:21504
	ds_read_b128 v[202:205], v211 offset:22528
	ds_read_b128 v[206:209], v211 offset:23552
	global_load_lds_dwordx4 v[212:213], off
	s_add_i32 m0, s55, 0x2000
	s_add_u32 s56, s30, 0x40000
	v_lshl_add_u64 v[214:215], s[30:31], 0, v[192:193]
	s_addc_u32 s57, s31, 0
	s_add_i32 s55, s58, s33
	global_load_lds_dwordx4 v[214:215], off
	v_lshl_add_u64 v[216:217], s[56:57], 0, v[188:189]
	s_mov_b32 m0, s55
	v_lshl_add_u64 v[218:219], s[34:35], 0, v[190:191]
	global_load_lds_dwordx4 v[216:217], off
	v_lshl_add_u64 v[216:217], s[56:57], 0, v[192:193]
	s_add_i32 m0, s55, 0x2000
	s_nop 0
	global_load_lds_dwordx4 v[216:217], off
	v_lshl_add_u64 v[216:217], s[34:35], 0, v[186:187]
	s_mov_b32 m0, s36
	s_nop 0
	global_load_lds_dwordx4 v[216:217], off
	s_mov_b32 m0, s37
	s_nop 0
	global_load_lds_dwordx4 v[218:219], off
	s_waitcnt vmcnt(8) lgkmcnt(0)
	s_barrier
	s_setprio 1
	v_mfma_f32_16x16x32_bf16 v[62:65], v[130:133], v[162:165], v[62:65]
	v_mfma_f32_16x16x32_bf16 v[58:61], v[138:141], v[162:165], v[58:61]
	v_mfma_f32_16x16x32_bf16 v[46:49], v[130:133], v[170:173], v[46:49]
	v_mfma_f32_16x16x32_bf16 v[42:45], v[138:141], v[170:173], v[42:45]
	v_mfma_f32_16x16x32_bf16 v[30:33], v[130:133], v[180:183], v[30:33]
	v_mfma_f32_16x16x32_bf16 v[26:29], v[138:141], v[180:183], v[26:29]
	v_mfma_f32_16x16x32_bf16 v[14:17], v[130:133], v[202:205], v[14:17]
	v_mfma_f32_16x16x32_bf16 v[10:13], v[138:141], v[202:205], v[10:13]
	v_mfma_f32_16x16x32_bf16 v[62:65], v[134:137], v[166:169], v[62:65]
	v_mfma_f32_16x16x32_bf16 v[58:61], v[142:145], v[166:169], v[58:61]
	v_mfma_f32_16x16x32_bf16 v[46:49], v[134:137], v[174:177], v[46:49]
	v_mfma_f32_16x16x32_bf16 v[42:45], v[142:145], v[174:177], v[42:45]
	v_mfma_f32_16x16x32_bf16 v[30:33], v[134:137], v[198:201], v[30:33]
	v_mfma_f32_16x16x32_bf16 v[26:29], v[142:145], v[198:201], v[26:29]
	v_mfma_f32_16x16x32_bf16 v[14:17], v[134:137], v[206:209], v[14:17]
	v_mfma_f32_16x16x32_bf16 v[10:13], v[142:145], v[206:209], v[10:13]
	s_setprio 0
	s_setprio 1
	v_mfma_f32_16x16x32_bf16 v[54:57], v[146:149], v[162:165], v[54:57]
	v_mfma_f32_16x16x32_bf16 v[50:53], v[154:157], v[162:165], v[50:53]
	v_mfma_f32_16x16x32_bf16 v[38:41], v[146:149], v[170:173], v[38:41]
	v_mfma_f32_16x16x32_bf16 v[34:37], v[154:157], v[170:173], v[34:37]
	v_mfma_f32_16x16x32_bf16 v[22:25], v[146:149], v[180:183], v[22:25]
	v_mfma_f32_16x16x32_bf16 v[18:21], v[154:157], v[180:183], v[18:21]
	v_mfma_f32_16x16x32_bf16 v[6:9], v[146:149], v[202:205], v[6:9]
	v_mfma_f32_16x16x32_bf16 v[2:5], v[154:157], v[202:205], v[2:5]
	v_mfma_f32_16x16x32_bf16 v[54:57], v[150:153], v[166:169], v[54:57]
	v_mfma_f32_16x16x32_bf16 v[50:53], v[158:161], v[166:169], v[50:53]
	v_mfma_f32_16x16x32_bf16 v[38:41], v[150:153], v[174:177], v[38:41]
	v_mfma_f32_16x16x32_bf16 v[34:37], v[158:161], v[174:177], v[34:37]
	v_mfma_f32_16x16x32_bf16 v[22:25], v[150:153], v[198:201], v[22:25]
	v_mfma_f32_16x16x32_bf16 v[18:21], v[158:161], v[198:201], v[18:21]
	v_mfma_f32_16x16x32_bf16 v[6:9], v[150:153], v[206:209], v[6:9]
	v_mfma_f32_16x16x32_bf16 v[2:5], v[158:161], v[206:209], v[2:5]
	s_setprio 0
	s_barrier
; #define PG8_STAGE(bufoff, gbase, voff) do { _Pragma("unroll") for (int _i = 0; _i < 2; ++_i) \
;         __builtin_amdgcn_global_load_lds((const unsigned*)((const char*)(gbase) + (voff)[_i]), (PG8_LAS unsigned*)(lds + (bufoff) + ldsw + _i * 8192), 16, 0, 0); } while (0)
; #define PG8_LDA(dst, b, h) do { _Pragma("unroll") for (int m = 0; m < 4; ++m) _Pragma("unroll") for (int k = 0; k < 2; ++k) dst[m][k] = *(const PG8_LAS bf16x8*)(lds + PG8_SA(b, h) + aoff + m * 2048 + k * 1024); } while (0)
; #define PG8_LDB(dst, b, h) do { _Pragma("unroll") for (int n = 0; n < 2; ++n) _Pragma("unroll") for (int k = 0; k < 2; ++k) dst[n][k] = *(const PG8_LAS bf16x8*)(lds + PG8_SB(b, h) + boff + n * 2048 + k * 1024); } while (0)
; #define PG8_MMA(ai, bj, At, Bt) do { __builtin_amdgcn_s_setprio(1); _Pragma("unroll") for (int m = 0; m < 4; ++m) _Pragma("unroll") for (int n = 0; n < 2; ++n) _Pragma("unroll") for (int k = 0; k < 2; ++k) \
;         acc[ai][bj][m][n] = __builtin_amdgcn_mfma_f32_16x16x32_bf16(Bt[n][k], At[m][k], acc[ai][bj][m][n], 0, 0, 0); __builtin_amdgcn_s_setprio(0); } while (0)
; #define PG8_WAIT_V(n) asm volatile("s_waitcnt vmcnt(" #n ")" ::: "memory")
; #define PG8_WAIT_L(n) asm volatile("s_waitcnt lgkmcnt(" #n ")" ::: "memory")
; #define PG8_BAR __builtin_amdgcn_s_barrier()
; #define PG8_SCHED __builtin_amdgcn_sched_barrier(0)
; template <class Epi, class Sched, bool ALIGN_EPI = false, bool SP2 = false>
; __device__ __forceinline__ void gemm_phase(PG8_LAS unsigned char* lds, const Gemm g, const Sched& S, const Epi& E) {
;     ...
;             PG8_LDB(B0, 1, 0); PG8_LDB(B1, 1, 1); PG8_SCHED; PG8_LDA(At, 1, 0); PG8_STAGE(PG8_SA(0, 1), a2 + hstep, voffA);
;             PG8_WAIT_V(8); PG8_WAIT_L(0); PG8_BAR; PG8_MMA(0, 0, At, B0); PG8_MMA(0, 1, At, B1); PG8_BAR; PG8_SCHED;
	s_add_i32 s55, 0, 0x18000
	s_add_i32 s56, 0, 0x1c000
	v_add_u32_e32 v142, s55, v179
	v_add_u32_e32 v158, s56, v179
	ds_read_b128 v[130:133], v142
	ds_read_b128 v[134:137], v142 offset:1024
	ds_read_b128 v[138:141], v142 offset:2048
	ds_read_b128 v[142:145], v142 offset:3072
	ds_read_b128 v[146:149], v158
	ds_read_b128 v[150:153], v158 offset:1024
	ds_read_b128 v[154:157], v158 offset:2048
	ds_read_b128 v[158:161], v158 offset:3072
	s_add_u32 s34, s34, 0x40000
	s_addc_u32 s35, s35, 0
	s_mov_b32 m0, s38
	v_lshl_add_u64 v[220:221], s[34:35], 0, v[186:187]
	ds_read_b128 v[162:165], v211 offset:32768
	ds_read_b128 v[166:169], v211 offset:33792
	ds_read_b128 v[170:173], v211 offset:34816
	ds_read_b128 v[174:177], v211 offset:35840
	ds_read_b128 v[180:183], v211 offset:36864
	ds_read_b128 v[198:201], v211 offset:37888
	ds_read_b128 v[202:205], v211 offset:38912
	ds_read_b128 v[206:209], v211 offset:39936
	global_load_lds_dwordx4 v[220:221], off
	v_lshl_add_u64 v[220:221], s[34:35], 0, v[190:191]
	s_mov_b32 m0, s39
	s_nop 0
	global_load_lds_dwordx4 v[220:221], off
	s_waitcnt vmcnt(8) lgkmcnt(0)
	s_barrier
	s_setprio 1
	v_mfma_f32_16x16x32_bf16 v[126:129], v[130:133], v[162:165], v[126:129]
	v_mfma_f32_16x16x32_bf16 v[122:125], v[138:141], v[162:165], v[122:125]
	v_mfma_f32_16x16x32_bf16 v[110:113], v[130:133], v[170:173], v[110:113]
	v_mfma_f32_16x16x32_bf16 v[106:109], v[138:141], v[170:173], v[106:109]
	v_mfma_f32_16x16x32_bf16 v[94:97], v[130:133], v[180:183], v[94:97]
	v_mfma_f32_16x16x32_bf16 v[90:93], v[138:141], v[180:183], v[90:93]
	v_mfma_f32_16x16x32_bf16 v[78:81], v[130:133], v[202:205], v[78:81]
	v_mfma_f32_16x16x32_bf16 v[74:77], v[138:141], v[202:205], v[74:77]
	v_mfma_f32_16x16x32_bf16 v[126:129], v[134:137], v[166:169], v[126:129]
	v_mfma_f32_16x16x32_bf16 v[122:125], v[142:145], v[166:169], v[122:125]
	v_mfma_f32_16x16x32_bf16 v[110:113], v[134:137], v[174:177], v[110:113]
	v_mfma_f32_16x16x32_bf16 v[106:109], v[142:145], v[174:177], v[106:109]
	v_mfma_f32_16x16x32_bf16 v[94:97], v[134:137], v[198:201], v[94:97]
	v_mfma_f32_16x16x32_bf16 v[90:93], v[142:145], v[198:201], v[90:93]
	v_mfma_f32_16x16x32_bf16 v[78:81], v[134:137], v[206:209], v[78:81]
	v_mfma_f32_16x16x32_bf16 v[74:77], v[142:145], v[206:209], v[74:77]
	s_setprio 0
	s_setprio 1
	v_mfma_f32_16x16x32_bf16 v[118:121], v[146:149], v[162:165], v[118:121]
	v_mfma_f32_16x16x32_bf16 v[114:117], v[154:157], v[162:165], v[114:117]
	v_mfma_f32_16x16x32_bf16 v[102:105], v[146:149], v[170:173], v[102:105]
	v_mfma_f32_16x16x32_bf16 v[98:101], v[154:157], v[170:173], v[98:101]
	v_mfma_f32_16x16x32_bf16 v[86:89], v[146:149], v[180:183], v[86:89]
	v_mfma_f32_16x16x32_bf16 v[82:85], v[154:157], v[180:183], v[82:85]
	v_mfma_f32_16x16x32_bf16 v[70:73], v[146:149], v[202:205], v[70:73]
	v_mfma_f32_16x16x32_bf16 v[66:69], v[154:157], v[202:205], v[66:69]
	v_mfma_f32_16x16x32_bf16 v[118:121], v[150:153], v[166:169], v[118:121]
	v_mfma_f32_16x16x32_bf16 v[114:117], v[158:161], v[166:169], v[114:117]
	v_mfma_f32_16x16x32_bf16 v[102:105], v[150:153], v[174:177], v[102:105]
	v_mfma_f32_16x16x32_bf16 v[98:101], v[158:161], v[174:177], v[98:101]
	v_mfma_f32_16x16x32_bf16 v[86:89], v[150:153], v[198:201], v[86:89]
	v_mfma_f32_16x16x32_bf16 v[82:85], v[158:161], v[198:201], v[82:85]
	v_mfma_f32_16x16x32_bf16 v[70:73], v[150:153], v[206:209], v[70:73]
	v_mfma_f32_16x16x32_bf16 v[66:69], v[158:161], v[206:209], v[66:69]
	s_setprio 0
	s_barrier
; #define PG8_STAGE(bufoff, gbase, voff) do { _Pragma("unroll") for (int _i = 0; _i < 2; ++_i) \
;         __builtin_amdgcn_global_load_lds((const unsigned*)((const char*)(gbase) + (voff)[_i]), (PG8_LAS unsigned*)(lds + (bufoff) + ldsw + _i * 8192), 16, 0, 0); } while (0)
; #define PG8_LDA(dst, b, h) do { _Pragma("unroll") for (int m = 0; m < 4; ++m) _Pragma("unroll") for (int k = 0; k < 2; ++k) dst[m][k] = *(const PG8_LAS bf16x8*)(lds + PG8_SA(b, h) + aoff + m * 2048 + k * 1024); } while (0)
; #define PG8_MMA(ai, bj, At, Bt) do { __builtin_amdgcn_s_setprio(1); _Pragma("unroll") for (int m = 0; m < 4; ++m) _Pragma("unroll") for (int n = 0; n < 2; ++n) _Pragma("unroll") for (int k = 0; k < 2; ++k) \
;         acc[ai][bj][m][n] = __builtin_amdgcn_mfma_f32_16x16x32_bf16(Bt[n][k], At[m][k], acc[ai][bj][m][n], 0, 0, 0); __builtin_amdgcn_s_setprio(0); } while (0)
; #define PG8_WAIT_V(n) asm volatile("s_waitcnt vmcnt(" #n ")" ::: "memory")
; #define PG8_WAIT_L(n) asm volatile("s_waitcnt lgkmcnt(" #n ")" ::: "memory")
; #define PG8_BAR __builtin_amdgcn_s_barrier()
; #define PG8_SCHED __builtin_amdgcn_sched_barrier(0)
; template <class Epi, class Sched, bool ALIGN_EPI = false, bool SP2 = false>
; __device__ __forceinline__ void gemm_phase(PG8_LAS unsigned char* lds, const Gemm g, const Sched& S, const Epi& E) {
;     ...
;             PG8_LDA(At, 1, 1); PG8_STAGE(PG8_SB(1, 0), b3, voffB); PG8_STAGE(PG8_SB(1, 1), b3 + hstep, voffB); PG8_STAGE(PG8_SA(1, 0), a3, voffA);
;             PG8_WAIT_V(8); PG8_WAIT_L(0); PG8_BAR; PG8_MMA(1, 0, At, B0); PG8_MMA(1, 1, At, B1); PG8_BAR; PG8_SCHED;
;     ...
;         if constexpr (ALIGN_EPI) { if (wr == 0) PG8_BAR; }
	s_add_i32 s34, s55, s33
	v_lshl_add_u64 v[212:213], v[212:213], 0, s[80:81]
	s_mov_b32 m0, s34
	ds_read_b128 v[162:165], v211 offset:49152
	ds_read_b128 v[166:169], v211 offset:50176
	ds_read_b128 v[170:173], v211 offset:51200
	ds_read_b128 v[174:177], v211 offset:52224
	ds_read_b128 v[180:183], v211 offset:53248
	ds_read_b128 v[198:201], v211 offset:54272
	ds_read_b128 v[202:205], v211 offset:55296
	ds_read_b128 v[206:209], v211 offset:56320
	global_load_lds_dwordx4 v[212:213], off
	s_add_i32 m0, s34, 0x2000
	s_add_u32 s30, s30, 0x40080
	v_lshl_add_u64 v[212:213], v[214:215], 0, s[80:81]
	s_addc_u32 s31, s31, 0
	s_add_i32 s34, s56, s33
	global_load_lds_dwordx4 v[212:213], off
	v_lshl_add_u64 v[212:213], s[30:31], 0, v[188:189]
	s_mov_b32 m0, s34
	s_nop 0
	global_load_lds_dwordx4 v[212:213], off
	v_lshl_add_u64 v[212:213], s[30:31], 0, v[192:193]
	s_add_i32 m0, s34, 0x2000
	s_nop 0
	global_load_lds_dwordx4 v[212:213], off
	v_lshl_add_u64 v[212:213], v[216:217], 0, s[80:81]
	s_mov_b32 m0, s47
	s_nop 0
	global_load_lds_dwordx4 v[212:213], off
	v_lshl_add_u64 v[212:213], v[218:219], 0, s[80:81]
	s_mov_b32 m0, s48
	s_nop 0
	global_load_lds_dwordx4 v[212:213], off
	s_waitcnt vmcnt(8) lgkmcnt(0)
	s_barrier
	s_setprio 1
	v_mfma_f32_16x16x32_bf16 v[62:65], v[130:133], v[162:165], v[62:65]
	v_mfma_f32_16x16x32_bf16 v[58:61], v[138:141], v[162:165], v[58:61]
	v_mfma_f32_16x16x32_bf16 v[46:49], v[130:133], v[170:173], v[46:49]
	v_mfma_f32_16x16x32_bf16 v[42:45], v[138:141], v[170:173], v[42:45]
	v_mfma_f32_16x16x32_bf16 v[30:33], v[130:133], v[180:183], v[30:33]
	v_mfma_f32_16x16x32_bf16 v[26:29], v[138:141], v[180:183], v[26:29]
	v_mfma_f32_16x16x32_bf16 v[14:17], v[130:133], v[202:205], v[14:17]
	v_mfma_f32_16x16x32_bf16 v[10:13], v[138:141], v[202:205], v[10:13]
	v_mfma_f32_16x16x32_bf16 v[62:65], v[134:137], v[166:169], v[62:65]
	v_mfma_f32_16x16x32_bf16 v[58:61], v[142:145], v[166:169], v[58:61]
	v_mfma_f32_16x16x32_bf16 v[46:49], v[134:137], v[174:177], v[46:49]
	v_mfma_f32_16x16x32_bf16 v[42:45], v[142:145], v[174:177], v[42:45]
	v_mfma_f32_16x16x32_bf16 v[30:33], v[134:137], v[198:201], v[30:33]
	v_mfma_f32_16x16x32_bf16 v[26:29], v[142:145], v[198:201], v[26:29]
	v_mfma_f32_16x16x32_bf16 v[14:17], v[134:137], v[206:209], v[14:17]
	v_mfma_f32_16x16x32_bf16 v[10:13], v[142:145], v[206:209], v[10:13]
	s_setprio 0
	s_setprio 1
	v_mfma_f32_16x16x32_bf16 v[54:57], v[146:149], v[162:165], v[54:57]
	v_mfma_f32_16x16x32_bf16 v[50:53], v[154:157], v[162:165], v[50:53]
	v_mfma_f32_16x16x32_bf16 v[38:41], v[146:149], v[170:173], v[38:41]
	v_mfma_f32_16x16x32_bf16 v[34:37], v[154:157], v[170:173], v[34:37]
	v_mfma_f32_16x16x32_bf16 v[22:25], v[146:149], v[180:183], v[22:25]
	v_mfma_f32_16x16x32_bf16 v[18:21], v[154:157], v[180:183], v[18:21]
	v_mfma_f32_16x16x32_bf16 v[6:9], v[146:149], v[202:205], v[6:9]
	v_mfma_f32_16x16x32_bf16 v[2:5], v[154:157], v[202:205], v[2:5]
	v_mfma_f32_16x16x32_bf16 v[54:57], v[150:153], v[166:169], v[54:57]
	v_mfma_f32_16x16x32_bf16 v[50:53], v[158:161], v[166:169], v[50:53]
	v_mfma_f32_16x16x32_bf16 v[38:41], v[150:153], v[174:177], v[38:41]
	v_mfma_f32_16x16x32_bf16 v[34:37], v[158:161], v[174:177], v[34:37]
	v_mfma_f32_16x16x32_bf16 v[22:25], v[150:153], v[198:201], v[22:25]
	v_mfma_f32_16x16x32_bf16 v[18:21], v[158:161], v[198:201], v[18:21]
	v_mfma_f32_16x16x32_bf16 v[6:9], v[150:153], v[206:209], v[6:9]
	v_mfma_f32_16x16x32_bf16 v[2:5], v[158:161], v[206:209], v[2:5]
	s_setprio 0
	s_barrier
	s_add_i32 s54, s54, 2
	s_add_u32 s28, s28, 0x100
	s_addc_u32 s29, s29, 0
	s_add_u32 s52, s52, 0x100
	s_addc_u32 s53, s53, 0
	s_cmp_gt_u32 s54, 13
	s_cbranch_scc0 .LBB0_1106
	s_and_b64 vcc, exec, s[14:15]
	s_cbranch_vccz .LBB0_1109
	s_barrier

; #define PG8_STAGE(bufoff, gbase, voff) do { _Pragma("unroll") for (int _i = 0; _i < 2; ++_i) \
;         __builtin_amdgcn_global_load_lds((const unsigned*)((const char*)(gbase) + (voff)[_i]), (PG8_LAS unsigned*)(lds + (bufoff) + ldsw + _i * 8192), 16, 0, 0); } while (0)
; #define PG8_LDA(dst, b, h) do { _Pragma("unroll") for (int m = 0; m < 4; ++m) _Pragma("unroll") for (int k = 0; k < 2; ++k) dst[m][k] = *(const PG8_LAS bf16x8*)(lds + PG8_SA(b, h) + aoff + m * 2048 + k * 1024); } while (0)
; #define PG8_LDB(dst, b, h) do { _Pragma("unroll") for (int n = 0; n < 2; ++n) _Pragma("unroll") for (int k = 0; k < 2; ++k) dst[n][k] = *(const PG8_LAS bf16x8*)(lds + PG8_SB(b, h) + boff + n * 2048 + k * 1024); } while (0)
; #define PG8_BAR __builtin_amdgcn_s_barrier()
;     __host__ __device__ bool next(int i, Unit& u) const {
;         const long L = (long)i * G + c; if (L >= nwg) return false;
;         int wgid = (int)L; { const int q = nwg / NXCD, r = nwg % NXCD, xcd = wgid % NXCD, off = wgid / NXCD; wgid = (xcd < r ? xcd * (q + 1) : r * (q + 1) + (xcd - r) * q) + off; }
;         const int nig = WGM * nN, gid = wgid / nig, fm = gid * WGM, gsz = (nM - fm) < WGM ? (nM - fm) : WGM;
;         u.pm = fm + ((wgid % nig) % gsz); u.pn = (wgid % nig) / gsz; return true;
; template <class Epi, class Sched, bool ALIGN_EPI = false, bool SP2 = false>
; __device__ __forceinline__ void gemm_phase(PG8_LAS unsigned char* lds, const Gemm g, const Sched& S, const Epi& E) {
;     ...
;         const bool has_next = S.next(ui + 1, nxt);
;         const char* nA = has_next ? (const char*)g.A + (size_t)nxt.pm * tstep : cA; const char* nB = has_next ? (const char*)g.Bt + (size_t)nxt.pn * tstep : cB;
;         for (int t = 0; t < nt; t += 2) {
;             const bool last = (t == nt - 2);
;             const char* a1 = cA + (size_t)(t + 1) * kstep;
;             const char* a2 = last ? nA : cA + (size_t)(t + 2) * kstep; const char* b2 = last ? nB : cB + (size_t)(t + 2) * kstep;
;             const char* a3 = a2 + kstep; const char* b3 = b2 + kstep;
;             if (last && has_next) S.a_ready(nxt);
;             if constexpr (SP2) {
;             PG8_LDB(B0, 0, 0); PG8_LDB(B1, 0, 1); PG8_SCHED; PG8_LDA(At, 0, 0); PG8_STAGE(PG8_SA(1, 1), a1 + hstep, voffA);
;             PG8_WAIT_V(8); PG8_WAIT_L(0); PG8_BAR; PG8_MMA(0, 0, At, B0); PG8_MMA(0, 1, At, B1); PG8_BAR; PG8_SCHED;
.LBB0_1246:
	s_lshl_b32 s4, s22, 8
	s_ashr_i32 s5, s4, 31
	v_lshl_add_u64 v[242:243], s[4:5], 2, v[146:147]
	global_load_dwordx4 v[246:249], v[242:243], off offset:16
	s_nop 0
	global_load_dwordx4 v[242:245], v[242:243], off
	s_add_i32 s44, s44, 1
	s_mul_i32 s4, s44, s43
	s_mul_hi_u32 s5, s44, s30
	s_add_i32 s5, s5, s4
	s_mul_i32 s4, s44, s30
	s_add_u32 s18, s4, s31
	s_addc_u32 s19, s5, s37
	v_mov_b64_e32 v[2:3], 0xb00
	v_cmp_lt_i64_e64 s[4:5], s[18:19], v[2:3]
	v_mov_b64_e32 v[2:3], 0xaff
	v_cmp_gt_i64_e32 vcc, s[18:19], v[2:3]
	s_cbranch_vccnz .LBB0_1248
	s_ashr_i32 s14, s18, 31
	s_lshr_b32 s14, s14, 29
	s_add_i32 s14, s18, s14
	s_ashr_i32 s15, s14, 3
	s_and_b32 s14, s14, -8
	s_sub_i32 s14, s18, s14
	s_cmp_lt_i32 s14, 0
	s_cselect_b32 s16, s55, 0x160
	s_mul_i32 s14, s14, s16
	s_add_i32 s14, s14, s15
	s_mul_hi_i32 s15, s14, 0x2e8ba2e9
	s_lshr_b32 s16, s15, 31
	s_ashr_i32 s15, s15, 5
	s_add_i32 s15, s15, s16
	s_lshl_b32 s16, s15, 3
	s_mulk_i32 s15, 0xb0
	s_sub_i32 s15, s14, s15
	s_lshr_b32 s14, s15, 3
	s_and_b32 s15, s15, 7
	s_add_i32 s16, s16, s15
.LBB0_1248:
	s_ashr_i32 s17, s16, 31
	s_lshl_b64 s[18:19], s[16:17], 19
	s_add_u32 s18, s0, s18
	s_addc_u32 s19, s1, s19
	s_and_b64 s[20:21], s[4:5], exec
	s_cselect_b32 s17, s19, s25
	s_cselect_b32 s45, s18, s24
	s_ashr_i32 s15, s14, 31
	s_lshl_b64 s[20:21], s[14:15], 19
	s_add_u32 s20, s34, s20
	s_addc_u32 s21, s35, s21
	s_and_b64 s[28:29], s[4:5], exec
	s_cselect_b32 s15, s21, s27
	s_cselect_b32 s46, s20, s26
	s_add_u32 s24, s24, 0x40080
	s_addc_u32 s25, s25, 0
	s_add_u32 s47, s26, 0x100
	s_addc_u32 s48, s27, 0
	s_mov_b32 s49, -2
	s_add_u32 s26, s24, 0xfffc0080
	s_addc_u32 s27, s25, -1
	s_add_i32 s50, 0, 0x10000
	s_cmp_eq_u32 s49, 12
	s_cselect_b32 s29, s17, s27
	s_cselect_b32 s28, s45, s26
	v_add_u32_e32 v156, s50, v158
	s_cselect_b32 s27, s15, s48
	s_cselect_b32 s26, s46, s47
	s_add_i32 s52, 0, 0x14000
	ds_read_b128 v[66:69], v156
	ds_read_b128 v[118:121], v156 offset:1024
	ds_read_b128 v[152:155], v156 offset:2048
	ds_read_b128 v[162:165], v156 offset:3072
	v_add_u32_e32 v156, s52, v158
	ds_read_b128 v[166:169], v156
	ds_read_b128 v[170:173], v156 offset:1024
	ds_read_b128 v[174:177], v156 offset:2048
	ds_read_b128 v[180:183], v156 offset:3072
	v_lshl_add_u64 v[156:157], s[24:25], 0, v[148:149]
	s_add_i32 m0, s33, 0xc000
	ds_read_b128 v[186:189], v160
	ds_read_b128 v[190:193], v160 offset:1024
	ds_read_b128 v[194:197], v160 offset:2048
	ds_read_b128 v[198:201], v160 offset:3072
	ds_read_b128 v[202:205], v160 offset:4096
	ds_read_b128 v[206:209], v160 offset:5120
	ds_read_b128 v[210:213], v160 offset:6144
	ds_read_b128 v[214:217], v160 offset:7168
	global_load_lds_dwordx4 v[156:157], off
	v_lshl_add_u64 v[156:157], s[24:25], 0, v[150:151]
	s_add_i32 m0, s33, 0xe000
	s_nop 0
	global_load_lds_dwordx4 v[156:157], off
	s_waitcnt vmcnt(8) lgkmcnt(0)
	s_barrier
	s_setprio 1
	v_mfma_f32_16x16x32_bf16 v[134:137], v[66:69], v[186:189], 0
	v_mfma_f32_16x16x32_bf16 v[126:129], v[152:155], v[186:189], 0
	v_mfma_f32_16x16x32_bf16 v[114:117], v[66:69], v[194:197], 0
	v_mfma_f32_16x16x32_bf16 v[110:113], v[152:155], v[194:197], 0
	v_mfma_f32_16x16x32_bf16 v[98:101], v[66:69], v[202:205], 0
	v_mfma_f32_16x16x32_bf16 v[94:97], v[152:155], v[202:205], 0
	v_mfma_f32_16x16x32_bf16 v[82:85], v[66:69], v[210:213], 0
	v_mfma_f32_16x16x32_bf16 v[78:81], v[152:155], v[210:213], 0
	v_mfma_f32_16x16x32_bf16 v[134:137], v[118:121], v[190:193], v[134:137]
	v_mfma_f32_16x16x32_bf16 v[126:129], v[162:165], v[190:193], v[126:129]
	v_mfma_f32_16x16x32_bf16 v[114:117], v[118:121], v[198:201], v[114:117]
	v_mfma_f32_16x16x32_bf16 v[110:113], v[162:165], v[198:201], v[110:113]
	v_mfma_f32_16x16x32_bf16 v[98:101], v[118:121], v[206:209], v[98:101]
	v_mfma_f32_16x16x32_bf16 v[94:97], v[162:165], v[206:209], v[94:97]
	v_mfma_f32_16x16x32_bf16 v[82:85], v[118:121], v[214:217], v[82:85]
	v_mfma_f32_16x16x32_bf16 v[78:81], v[162:165], v[214:217], v[78:81]
	s_setprio 0
	s_setprio 1
	v_mfma_f32_16x16x32_bf16 v[130:133], v[166:169], v[186:189], 0
	v_mfma_f32_16x16x32_bf16 v[122:125], v[174:177], v[186:189], 0
	v_mfma_f32_16x16x32_bf16 v[106:109], v[166:169], v[194:197], 0
	v_mfma_f32_16x16x32_bf16 v[102:105], v[174:177], v[194:197], 0
	v_mfma_f32_16x16x32_bf16 v[90:93], v[166:169], v[202:205], 0
	v_mfma_f32_16x16x32_bf16 v[86:89], v[174:177], v[202:205], 0
	v_mfma_f32_16x16x32_bf16 v[74:77], v[166:169], v[210:213], 0
	v_mfma_f32_16x16x32_bf16 v[70:73], v[174:177], v[210:213], 0
	v_mfma_f32_16x16x32_bf16 v[130:133], v[170:173], v[190:193], v[130:133]
	v_mfma_f32_16x16x32_bf16 v[122:125], v[180:183], v[190:193], v[122:125]
	v_mfma_f32_16x16x32_bf16 v[106:109], v[170:173], v[198:201], v[106:109]
	v_mfma_f32_16x16x32_bf16 v[102:105], v[180:183], v[198:201], v[102:105]
	v_mfma_f32_16x16x32_bf16 v[90:93], v[170:173], v[206:209], v[90:93]
	v_mfma_f32_16x16x32_bf16 v[86:89], v[180:183], v[206:209], v[86:89]
	v_mfma_f32_16x16x32_bf16 v[74:77], v[170:173], v[214:217], v[74:77]
	v_mfma_f32_16x16x32_bf16 v[70:73], v[180:183], v[214:217], v[70:73]
	s_setprio 0
	s_barrier
; #define PG8_STAGE(bufoff, gbase, voff) do { _Pragma("unroll") for (int _i = 0; _i < 2; ++_i) \
;         __builtin_amdgcn_global_load_lds((const unsigned*)((const char*)(gbase) + (voff)[_i]), (PG8_LAS unsigned*)(lds + (bufoff) + ldsw + _i * 8192), 16, 0, 0); } while (0)
; #define PG8_LDA(dst, b, h) do { _Pragma("unroll") for (int m = 0; m < 4; ++m) _Pragma("unroll") for (int k = 0; k < 2; ++k) dst[m][k] = *(const PG8_LAS bf16x8*)(lds + PG8_SA(b, h) + aoff + m * 2048 + k * 1024); } while (0)
; #define PG8_LDB(dst, b, h) do { _Pragma("unroll") for (int n = 0; n < 2; ++n) _Pragma("unroll") for (int k = 0; k < 2; ++k) dst[n][k] = *(const PG8_LAS bf16x8*)(lds + PG8_SB(b, h) + boff + n * 2048 + k * 1024); } while (0)
; #define PG8_MMA(ai, bj, At, Bt) do { __builtin_amdgcn_s_setprio(1); _Pragma("unroll") for (int m = 0; m < 4; ++m) _Pragma("unroll") for (int n = 0; n < 2; ++n) _Pragma("unroll") for (int k = 0; k < 2; ++k) \
;         acc[ai][bj][m][n] = __builtin_amdgcn_mfma_f32_16x16x32_bf16(Bt[n][k], At[m][k], acc[ai][bj][m][n], 0, 0, 0); __builtin_amdgcn_s_setprio(0); } while (0)
; #define PG8_WAIT_V(n) asm volatile("s_waitcnt vmcnt(" #n ")" ::: "memory")
; #define PG8_WAIT_L(n) asm volatile("s_waitcnt lgkmcnt(" #n ")" ::: "memory")
; #define PG8_BAR __builtin_amdgcn_s_barrier()
; #define PG8_SCHED __builtin_amdgcn_sched_barrier(0)
; template <class Epi, class Sched, bool ALIGN_EPI = false, bool SP2 = false>
; __device__ __forceinline__ void gemm_phase(PG8_LAS unsigned char* lds, const Gemm g, const Sched& S, const Epi& E) {
;     ...
;             PG8_LDA(At, 0, 1); PG8_STAGE(PG8_SB(0, 0), b2, voffB); PG8_STAGE(PG8_SB(0, 1), b2 + hstep, voffB); PG8_STAGE(PG8_SA(0, 0), a2, voffA);
;             PG8_WAIT_V(8); PG8_WAIT_L(0); PG8_BAR; PG8_MMA(1, 0, At, B0); PG8_MMA(1, 1, At, B1); PG8_BAR; PG8_SCHED;
;             PG8_LDB(B0, 1, 0); PG8_LDB(B1, 1, 1); PG8_SCHED; PG8_LDA(At, 1, 0); PG8_STAGE(PG8_SA(0, 1), a2 + hstep, voffA);
;             PG8_WAIT_V(8); PG8_WAIT_L(0); PG8_BAR; PG8_MMA(0, 0, At, B0); PG8_MMA(0, 1, At, B1); PG8_BAR; PG8_SCHED;
	s_add_i32 s50, s50, s36
	v_lshl_add_u64 v[156:157], s[26:27], 0, v[142:143]
	s_mov_b32 m0, s50
	ds_read_b128 v[186:189], v160 offset:16384
	ds_read_b128 v[190:193], v160 offset:17408
	ds_read_b128 v[194:197], v160 offset:18432
	ds_read_b128 v[198:201], v160 offset:19456
	ds_read_b128 v[202:205], v160 offset:20480
	ds_read_b128 v[206:209], v160 offset:21504
	ds_read_b128 v[210:213], v160 offset:22528
	ds_read_b128 v[214:217], v160 offset:23552
	global_load_lds_dwordx4 v[156:157], off
	s_add_i32 m0, s50, 0x2000
	s_add_u32 s50, s26, 0x40000
	v_lshl_add_u64 v[218:219], s[26:27], 0, v[138:139]
	s_addc_u32 s51, s27, 0
	s_add_i32 s52, s52, s36
	global_load_lds_dwordx4 v[218:219], off
	v_lshl_add_u64 v[220:221], s[50:51], 0, v[142:143]
	s_mov_b32 m0, s52
	v_lshl_add_u64 v[222:223], s[28:29], 0, v[140:141]
	global_load_lds_dwordx4 v[220:221], off
	v_lshl_add_u64 v[220:221], s[50:51], 0, v[138:139]
	s_add_i32 m0, s52, 0x2000
	s_nop 0
	global_load_lds_dwordx4 v[220:221], off
	v_lshl_add_u64 v[220:221], s[28:29], 0, v[144:145]
	s_mov_b32 m0, s33
	s_nop 0
	global_load_lds_dwordx4 v[220:221], off
	s_mov_b32 m0, s38
	s_nop 0
	global_load_lds_dwordx4 v[222:223], off
	s_waitcnt vmcnt(8) lgkmcnt(0)
	s_barrier
	s_setprio 1
	v_mfma_f32_16x16x32_bf16 v[62:65], v[66:69], v[186:189], 0
	v_mfma_f32_16x16x32_bf16 v[58:61], v[152:155], v[186:189], 0
	v_mfma_f32_16x16x32_bf16 v[46:49], v[66:69], v[194:197], 0
	v_mfma_f32_16x16x32_bf16 v[42:45], v[152:155], v[194:197], 0
	v_mfma_f32_16x16x32_bf16 v[30:33], v[66:69], v[202:205], 0
	v_mfma_f32_16x16x32_bf16 v[26:29], v[152:155], v[202:205], 0
	v_mfma_f32_16x16x32_bf16 v[14:17], v[66:69], v[210:213], 0
	v_mfma_f32_16x16x32_bf16 v[10:13], v[152:155], v[210:213], 0
	v_mfma_f32_16x16x32_bf16 v[62:65], v[118:121], v[190:193], v[62:65]
	v_mfma_f32_16x16x32_bf16 v[58:61], v[162:165], v[190:193], v[58:61]
	v_mfma_f32_16x16x32_bf16 v[46:49], v[118:121], v[198:201], v[46:49]
	v_mfma_f32_16x16x32_bf16 v[42:45], v[162:165], v[198:201], v[42:45]
	v_mfma_f32_16x16x32_bf16 v[30:33], v[118:121], v[206:209], v[30:33]
	v_mfma_f32_16x16x32_bf16 v[26:29], v[162:165], v[206:209], v[26:29]
	v_mfma_f32_16x16x32_bf16 v[14:17], v[118:121], v[214:217], v[14:17]
	v_mfma_f32_16x16x32_bf16 v[10:13], v[162:165], v[214:217], v[10:13]
	s_setprio 0
	s_setprio 1
	v_mfma_f32_16x16x32_bf16 v[54:57], v[166:169], v[186:189], 0
	v_mfma_f32_16x16x32_bf16 v[50:53], v[174:177], v[186:189], 0
	v_mfma_f32_16x16x32_bf16 v[38:41], v[166:169], v[194:197], 0
	v_mfma_f32_16x16x32_bf16 v[34:37], v[174:177], v[194:197], 0
	v_mfma_f32_16x16x32_bf16 v[22:25], v[166:169], v[202:205], 0
	v_mfma_f32_16x16x32_bf16 v[18:21], v[174:177], v[202:205], 0
	v_mfma_f32_16x16x32_bf16 v[6:9], v[166:169], v[210:213], 0
	v_mfma_f32_16x16x32_bf16 v[2:5], v[174:177], v[210:213], 0
	v_mfma_f32_16x16x32_bf16 v[54:57], v[170:173], v[190:193], v[54:57]
	v_mfma_f32_16x16x32_bf16 v[50:53], v[180:183], v[190:193], v[50:53]
	v_mfma_f32_16x16x32_bf16 v[38:41], v[170:173], v[198:201], v[38:41]
	v_mfma_f32_16x16x32_bf16 v[34:37], v[180:183], v[198:201], v[34:37]
	v_mfma_f32_16x16x32_bf16 v[22:25], v[170:173], v[206:209], v[22:25]
	v_mfma_f32_16x16x32_bf16 v[18:21], v[180:183], v[206:209], v[18:21]
	v_mfma_f32_16x16x32_bf16 v[6:9], v[170:173], v[214:217], v[6:9]
	v_mfma_f32_16x16x32_bf16 v[2:5], v[180:183], v[214:217], v[2:5]
	s_setprio 0
	s_barrier
	s_add_i32 s50, 0, 0x18000
	v_add_u32_e32 v161, s50, v158
	s_add_i32 s51, 0, 0x1c000
	ds_read_b128 v[66:69], v161
	ds_read_b128 v[118:121], v161 offset:1024
	ds_read_b128 v[152:155], v161 offset:2048
	ds_read_b128 v[162:165], v161 offset:3072
	v_add_u32_e32 v161, s51, v158
	ds_read_b128 v[166:169], v161
	ds_read_b128 v[170:173], v161 offset:1024
	ds_read_b128 v[174:177], v161 offset:2048
	ds_read_b128 v[180:183], v161 offset:3072
	s_add_u32 s28, s28, 0x40000
	s_addc_u32 s29, s29, 0
	s_mov_b32 m0, s39
	v_lshl_add_u64 v[240:241], s[28:29], 0, v[144:145]
	ds_read_b128 v[186:189], v160 offset:32768
	ds_read_b128 v[190:193], v160 offset:33792
	ds_read_b128 v[194:197], v160 offset:34816
	ds_read_b128 v[198:201], v160 offset:35840
	ds_read_b128 v[202:205], v160 offset:36864
	ds_read_b128 v[206:209], v160 offset:37888
	ds_read_b128 v[210:213], v160 offset:38912
	ds_read_b128 v[214:217], v160 offset:39936
	global_load_lds_dwordx4 v[240:241], off
	v_lshl_add_u64 v[240:241], s[28:29], 0, v[140:141]
	s_mov_b32 m0, s40
	s_nop 0
	global_load_lds_dwordx4 v[240:241], off
	s_waitcnt vmcnt(8) lgkmcnt(0)
	s_barrier
	s_setprio 1
	v_mfma_f32_16x16x32_bf16 v[134:137], v[66:69], v[186:189], v[134:137]
	v_mfma_f32_16x16x32_bf16 v[126:129], v[152:155], v[186:189], v[126:129]
	v_mfma_f32_16x16x32_bf16 v[114:117], v[66:69], v[194:197], v[114:117]
	v_mfma_f32_16x16x32_bf16 v[110:113], v[152:155], v[194:197], v[110:113]
	v_mfma_f32_16x16x32_bf16 v[98:101], v[66:69], v[202:205], v[98:101]
	v_mfma_f32_16x16x32_bf16 v[94:97], v[152:155], v[202:205], v[94:97]
	v_mfma_f32_16x16x32_bf16 v[82:85], v[66:69], v[210:213], v[82:85]
	v_mfma_f32_16x16x32_bf16 v[78:81], v[152:155], v[210:213], v[78:81]
	v_mfma_f32_16x16x32_bf16 v[134:137], v[118:121], v[190:193], v[134:137]
	v_mfma_f32_16x16x32_bf16 v[126:129], v[162:165], v[190:193], v[126:129]
	v_mfma_f32_16x16x32_bf16 v[114:117], v[118:121], v[198:201], v[114:117]
	v_mfma_f32_16x16x32_bf16 v[110:113], v[162:165], v[198:201], v[110:113]
	v_mfma_f32_16x16x32_bf16 v[98:101], v[118:121], v[206:209], v[98:101]
	v_mfma_f32_16x16x32_bf16 v[94:97], v[162:165], v[206:209], v[94:97]
	v_mfma_f32_16x16x32_bf16 v[82:85], v[118:121], v[214:217], v[82:85]
	v_mfma_f32_16x16x32_bf16 v[78:81], v[162:165], v[214:217], v[78:81]
	s_setprio 0
	s_setprio 1
	v_mfma_f32_16x16x32_bf16 v[130:133], v[166:169], v[186:189], v[130:133]
	v_mfma_f32_16x16x32_bf16 v[122:125], v[174:177], v[186:189], v[122:125]
	v_mfma_f32_16x16x32_bf16 v[106:109], v[166:169], v[194:197], v[106:109]
	v_mfma_f32_16x16x32_bf16 v[102:105], v[174:177], v[194:197], v[102:105]
	v_mfma_f32_16x16x32_bf16 v[90:93], v[166:169], v[202:205], v[90:93]
	v_mfma_f32_16x16x32_bf16 v[86:89], v[174:177], v[202:205], v[86:89]
	v_mfma_f32_16x16x32_bf16 v[74:77], v[166:169], v[210:213], v[74:77]
	v_mfma_f32_16x16x32_bf16 v[70:73], v[174:177], v[210:213], v[70:73]
	v_mfma_f32_16x16x32_bf16 v[130:133], v[170:173], v[190:193], v[130:133]
	v_mfma_f32_16x16x32_bf16 v[122:125], v[180:183], v[190:193], v[122:125]
	v_mfma_f32_16x16x32_bf16 v[106:109], v[170:173], v[198:201], v[106:109]
	v_mfma_f32_16x16x32_bf16 v[102:105], v[180:183], v[198:201], v[102:105]
	v_mfma_f32_16x16x32_bf16 v[90:93], v[170:173], v[206:209], v[90:93]
	v_mfma_f32_16x16x32_bf16 v[86:89], v[180:183], v[206:209], v[86:89]
	v_mfma_f32_16x16x32_bf16 v[74:77], v[170:173], v[214:217], v[74:77]
	v_mfma_f32_16x16x32_bf16 v[70:73], v[180:183], v[214:217], v[70:73]
	s_setprio 0
	s_barrier
; #define PG8_STAGE(bufoff, gbase, voff) do { _Pragma("unroll") for (int _i = 0; _i < 2; ++_i) \
;         __builtin_amdgcn_global_load_lds((const unsigned*)((const char*)(gbase) + (voff)[_i]), (PG8_LAS unsigned*)(lds + (bufoff) + ldsw + _i * 8192), 16, 0, 0); } while (0)
; #define PG8_LDA(dst, b, h) do { _Pragma("unroll") for (int m = 0; m < 4; ++m) _Pragma("unroll") for (int k = 0; k < 2; ++k) dst[m][k] = *(const PG8_LAS bf16x8*)(lds + PG8_SA(b, h) + aoff + m * 2048 + k * 1024); } while (0)
; #define PG8_LDB(dst, b, h) do { _Pragma("unroll") for (int n = 0; n < 2; ++n) _Pragma("unroll") for (int k = 0; k < 2; ++k) dst[n][k] = *(const PG8_LAS bf16x8*)(lds + PG8_SB(b, h) + boff + n * 2048 + k * 1024); } while (0)
; template <class Epi, class Sched, bool ALIGN_EPI = false, bool SP2 = false>
; __device__ __forceinline__ void gemm_phase(PG8_LAS unsigned char* lds, const Gemm g, const Sched& S, const Epi& E) {
;     ...
;         for (int t = 0; t < nt; t += 2) {
;             const bool last = (t == nt - 2);
;             const char* a1 = cA + (size_t)(t + 1) * kstep;
;             const char* a2 = last ? nA : cA + (size_t)(t + 2) * kstep; const char* b2 = last ? nB : cB + (size_t)(t + 2) * kstep;
;             const char* a3 = a2 + kstep; const char* b3 = b2 + kstep;
;             if (last && has_next) S.a_ready(nxt);
;             if constexpr (SP2) {
;             PG8_LDB(B0, 0, 0); PG8_LDB(B1, 0, 1); PG8_SCHED; PG8_LDA(At, 0, 0); PG8_STAGE(PG8_SA(1, 1), a1 + hstep, voffA);
;             PG8_WAIT_V(8); PG8_WAIT_L(0); PG8_BAR; PG8_MMA(0, 0, At, B0); PG8_MMA(0, 1, At, B1); PG8_BAR; PG8_SCHED;
;             PG8_LDA(At, 0, 1); PG8_STAGE(PG8_SB(0, 0), b2, voffB); PG8_STAGE(PG8_SB(0, 1), b2 + hstep, voffB); PG8_STAGE(PG8_SA(0, 0), a2, voffA);
;             PG8_WAIT_V(8); PG8_WAIT_L(0); PG8_BAR; PG8_MMA(1, 0, At, B0); PG8_MMA(1, 1, At, B1); PG8_BAR; PG8_SCHED;
;             PG8_LDB(B0, 1, 0); PG8_LDB(B1, 1, 1); PG8_SCHED; PG8_LDA(At, 1, 0); PG8_STAGE(PG8_SA(0, 1), a2 + hstep, voffA);
;             PG8_WAIT_V(8); PG8_WAIT_L(0); PG8_BAR; PG8_MMA(0, 0, At, B0); PG8_MMA(0, 1, At, B1); PG8_BAR; PG8_SCHED;
;             PG8_LDA(At, 1, 1); PG8_STAGE(PG8_SB(1, 0), b3, voffB); PG8_STAGE(PG8_SB(1, 1), b3 + hstep, voffB); PG8_STAGE(PG8_SA(1, 0), a3, voffA);
;             PG8_WAIT_V(8); PG8_WAIT_L(0); PG8_BAR; PG8_MMA(1, 0, At, B0); PG8_MMA(1, 1, At, B1); PG8_BAR; PG8_SCHED;
	s_add_i32 s28, s50, s36
	v_lshl_add_u64 v[156:157], v[156:157], 0, s[80:81]
	s_mov_b32 m0, s28
	ds_read_b128 v[186:189], v160 offset:49152
	ds_read_b128 v[190:193], v160 offset:50176
	ds_read_b128 v[194:197], v160 offset:51200
	ds_read_b128 v[198:201], v160 offset:52224
	ds_read_b128 v[202:205], v160 offset:53248
	ds_read_b128 v[206:209], v160 offset:54272
	ds_read_b128 v[210:213], v160 offset:55296
	ds_read_b128 v[214:217], v160 offset:56320
	global_load_lds_dwordx4 v[156:157], off
	s_add_i32 m0, s28, 0x2000
	s_add_u32 s26, s26, 0x40080
	v_lshl_add_u64 v[156:157], v[218:219], 0, s[80:81]
	s_addc_u32 s27, s27, 0
	s_add_i32 s28, s51, s36
	global_load_lds_dwordx4 v[156:157], off
	v_lshl_add_u64 v[156:157], s[26:27], 0, v[142:143]
	s_mov_b32 m0, s28
	s_nop 0
	global_load_lds_dwordx4 v[156:157], off
	v_lshl_add_u64 v[156:157], s[26:27], 0, v[138:139]
	s_add_i32 m0, s28, 0x2000
	s_nop 0
	global_load_lds_dwordx4 v[156:157], off
	v_lshl_add_u64 v[156:157], v[220:221], 0, s[80:81]
	s_mov_b32 m0, s41
	s_nop 0
	global_load_lds_dwordx4 v[156:157], off
	v_lshl_add_u64 v[156:157], v[222:223], 0, s[80:81]
	s_mov_b32 m0, s42
	s_nop 0
	global_load_lds_dwordx4 v[156:157], off
	s_waitcnt vmcnt(8) lgkmcnt(0)
	s_barrier
	s_setprio 1
	v_mfma_f32_16x16x32_bf16 v[62:65], v[66:69], v[186:189], v[62:65]
	v_mfma_f32_16x16x32_bf16 v[58:61], v[152:155], v[186:189], v[58:61]
	v_mfma_f32_16x16x32_bf16 v[46:49], v[66:69], v[194:197], v[46:49]
	v_mfma_f32_16x16x32_bf16 v[42:45], v[152:155], v[194:197], v[42:45]
	v_mfma_f32_16x16x32_bf16 v[30:33], v[66:69], v[202:205], v[30:33]
	v_mfma_f32_16x16x32_bf16 v[26:29], v[152:155], v[202:205], v[26:29]
	v_mfma_f32_16x16x32_bf16 v[14:17], v[66:69], v[210:213], v[14:17]
	v_mfma_f32_16x16x32_bf16 v[10:13], v[152:155], v[210:213], v[10:13]
	v_mfma_f32_16x16x32_bf16 v[62:65], v[118:121], v[190:193], v[62:65]
	v_mfma_f32_16x16x32_bf16 v[58:61], v[162:165], v[190:193], v[58:61]
	v_mfma_f32_16x16x32_bf16 v[46:49], v[118:121], v[198:201], v[46:49]
	v_mfma_f32_16x16x32_bf16 v[42:45], v[162:165], v[198:201], v[42:45]
	v_mfma_f32_16x16x32_bf16 v[30:33], v[118:121], v[206:209], v[30:33]
	v_mfma_f32_16x16x32_bf16 v[26:29], v[162:165], v[206:209], v[26:29]
	v_mfma_f32_16x16x32_bf16 v[14:17], v[118:121], v[214:217], v[14:17]
	v_mfma_f32_16x16x32_bf16 v[10:13], v[162:165], v[214:217], v[10:13]
	s_setprio 0
	s_setprio 1
	v_mfma_f32_16x16x32_bf16 v[54:57], v[166:169], v[186:189], v[54:57]
	v_mfma_f32_16x16x32_bf16 v[50:53], v[174:177], v[186:189], v[50:53]
	v_mfma_f32_16x16x32_bf16 v[38:41], v[166:169], v[194:197], v[38:41]
	v_mfma_f32_16x16x32_bf16 v[34:37], v[174:177], v[194:197], v[34:37]
	v_mfma_f32_16x16x32_bf16 v[22:25], v[166:169], v[202:205], v[22:25]
	v_mfma_f32_16x16x32_bf16 v[18:21], v[174:177], v[202:205], v[18:21]
	v_mfma_f32_16x16x32_bf16 v[6:9], v[166:169], v[210:213], v[6:9]
	v_mfma_f32_16x16x32_bf16 v[2:5], v[174:177], v[210:213], v[2:5]
	v_mfma_f32_16x16x32_bf16 v[54:57], v[170:173], v[190:193], v[54:57]
	v_mfma_f32_16x16x32_bf16 v[50:53], v[180:183], v[190:193], v[50:53]
	v_mfma_f32_16x16x32_bf16 v[38:41], v[170:173], v[198:201], v[38:41]
	v_mfma_f32_16x16x32_bf16 v[34:37], v[180:183], v[198:201], v[34:37]
	v_mfma_f32_16x16x32_bf16 v[22:25], v[170:173], v[206:209], v[22:25]
	v_mfma_f32_16x16x32_bf16 v[18:21], v[180:183], v[206:209], v[18:21]
	v_mfma_f32_16x16x32_bf16 v[6:9], v[170:173], v[214:217], v[6:9]
	v_mfma_f32_16x16x32_bf16 v[2:5], v[180:183], v[214:217], v[2:5]
	s_setprio 0
	s_barrier
	s_add_i32 s49, s49, 2
	s_add_u32 s24, s24, 0x100
	s_addc_u32 s25, s25, 0
	s_add_u32 s47, s47, 0x100
	s_addc_u32 s48, s48, 0
	s_cmp_gt_u32 s49, 13
	s_branch .LBB0_1249
.LBB0_1249:
	s_add_u32 s26, s24, 0xfffc0080
	s_addc_u32 s27, s25, -1
	s_add_i32 s50, 0, 0x10000
	s_cmp_eq_u32 s49, 12
	s_cselect_b32 s29, s17, s27
	s_cselect_b32 s28, s45, s26
	v_add_u32_e32 v156, s50, v158
	s_cselect_b32 s27, s15, s48
	s_cselect_b32 s26, s46, s47
	s_add_i32 s52, 0, 0x14000
	ds_read_b128 v[66:69], v156
	ds_read_b128 v[118:121], v156 offset:1024
	ds_read_b128 v[152:155], v156 offset:2048
	ds_read_b128 v[162:165], v156 offset:3072
	v_add_u32_e32 v156, s52, v158
	ds_read_b128 v[166:169], v156
	ds_read_b128 v[170:173], v156 offset:1024
	ds_read_b128 v[174:177], v156 offset:2048
	ds_read_b128 v[180:183], v156 offset:3072
	v_lshl_add_u64 v[156:157], s[24:25], 0, v[148:149]
	s_add_i32 m0, s33, 0xc000
	ds_read_b128 v[186:189], v160
	ds_read_b128 v[190:193], v160 offset:1024
	ds_read_b128 v[194:197], v160 offset:2048
	ds_read_b128 v[198:201], v160 offset:3072
	ds_read_b128 v[202:205], v160 offset:4096
	ds_read_b128 v[206:209], v160 offset:5120
	ds_read_b128 v[210:213], v160 offset:6144
	ds_read_b128 v[214:217], v160 offset:7168
	global_load_lds_dwordx4 v[156:157], off
	v_lshl_add_u64 v[156:157], s[24:25], 0, v[150:151]
	s_add_i32 m0, s33, 0xe000
	s_nop 0
	global_load_lds_dwordx4 v[156:157], off
	s_waitcnt vmcnt(8) lgkmcnt(0)
	s_barrier
; #define PG8_STAGE(bufoff, gbase, voff) do { _Pragma("unroll") for (int _i = 0; _i < 2; ++_i) \
;         __builtin_amdgcn_global_load_lds((const unsigned*)((const char*)(gbase) + (voff)[_i]), (PG8_LAS unsigned*)(lds + (bufoff) + ldsw + _i * 8192), 16, 0, 0); } while (0)
; #define PG8_LDA(dst, b, h) do { _Pragma("unroll") for (int m = 0; m < 4; ++m) _Pragma("unroll") for (int k = 0; k < 2; ++k) dst[m][k] = *(const PG8_LAS bf16x8*)(lds + PG8_SA(b, h) + aoff + m * 2048 + k * 1024); } while (0)
; #define PG8_MMA(ai, bj, At, Bt) do { __builtin_amdgcn_s_setprio(1); _Pragma("unroll") for (int m = 0; m < 4; ++m) _Pragma("unroll") for (int n = 0; n < 2; ++n) _Pragma("unroll") for (int k = 0; k < 2; ++k) \
;         acc[ai][bj][m][n] = __builtin_amdgcn_mfma_f32_16x16x32_bf16(Bt[n][k], At[m][k], acc[ai][bj][m][n], 0, 0, 0); __builtin_amdgcn_s_setprio(0); } while (0)
; #define PG8_WAIT_V(n) asm volatile("s_waitcnt vmcnt(" #n ")" ::: "memory")
; #define PG8_WAIT_L(n) asm volatile("s_waitcnt lgkmcnt(" #n ")" ::: "memory")
; #define PG8_BAR __builtin_amdgcn_s_barrier()
; #define PG8_SCHED __builtin_amdgcn_sched_barrier(0)
; template <class Epi, class Sched, bool ALIGN_EPI = false, bool SP2 = false>
; __device__ __forceinline__ void gemm_phase(PG8_LAS unsigned char* lds, const Gemm g, const Sched& S, const Epi& E) {
;     ...
;             PG8_WAIT_V(8); PG8_WAIT_L(0); PG8_BAR; PG8_MMA(0, 0, At, B0); PG8_MMA(0, 1, At, B1); PG8_BAR; PG8_SCHED;
;             PG8_LDA(At, 0, 1); PG8_STAGE(PG8_SB(0, 0), b2, voffB); PG8_STAGE(PG8_SB(0, 1), b2 + hstep, voffB); PG8_STAGE(PG8_SA(0, 0), a2, voffA);
;             PG8_WAIT_V(8); PG8_WAIT_L(0); PG8_BAR; PG8_MMA(1, 0, At, B0); PG8_MMA(1, 1, At, B1); PG8_BAR; PG8_SCHED;
	s_setprio 1
	v_mfma_f32_16x16x32_bf16 v[134:137], v[66:69], v[186:189], v[134:137]
	v_mfma_f32_16x16x32_bf16 v[126:129], v[152:155], v[186:189], v[126:129]
	v_mfma_f32_16x16x32_bf16 v[114:117], v[66:69], v[194:197], v[114:117]
	v_mfma_f32_16x16x32_bf16 v[110:113], v[152:155], v[194:197], v[110:113]
	v_mfma_f32_16x16x32_bf16 v[98:101], v[66:69], v[202:205], v[98:101]
	v_mfma_f32_16x16x32_bf16 v[94:97], v[152:155], v[202:205], v[94:97]
	v_mfma_f32_16x16x32_bf16 v[82:85], v[66:69], v[210:213], v[82:85]
	v_mfma_f32_16x16x32_bf16 v[78:81], v[152:155], v[210:213], v[78:81]
	v_mfma_f32_16x16x32_bf16 v[134:137], v[118:121], v[190:193], v[134:137]
	v_mfma_f32_16x16x32_bf16 v[126:129], v[162:165], v[190:193], v[126:129]
	v_mfma_f32_16x16x32_bf16 v[114:117], v[118:121], v[198:201], v[114:117]
	v_mfma_f32_16x16x32_bf16 v[110:113], v[162:165], v[198:201], v[110:113]
	v_mfma_f32_16x16x32_bf16 v[98:101], v[118:121], v[206:209], v[98:101]
	v_mfma_f32_16x16x32_bf16 v[94:97], v[162:165], v[206:209], v[94:97]
	v_mfma_f32_16x16x32_bf16 v[82:85], v[118:121], v[214:217], v[82:85]
	v_mfma_f32_16x16x32_bf16 v[78:81], v[162:165], v[214:217], v[78:81]
	s_setprio 0
	s_setprio 1
	v_mfma_f32_16x16x32_bf16 v[130:133], v[166:169], v[186:189], v[130:133]
	v_mfma_f32_16x16x32_bf16 v[122:125], v[174:177], v[186:189], v[122:125]
	v_mfma_f32_16x16x32_bf16 v[106:109], v[166:169], v[194:197], v[106:109]
	v_mfma_f32_16x16x32_bf16 v[102:105], v[174:177], v[194:197], v[102:105]
	v_mfma_f32_16x16x32_bf16 v[90:93], v[166:169], v[202:205], v[90:93]
	v_mfma_f32_16x16x32_bf16 v[86:89], v[174:177], v[202:205], v[86:89]
	v_mfma_f32_16x16x32_bf16 v[74:77], v[166:169], v[210:213], v[74:77]
	v_mfma_f32_16x16x32_bf16 v[70:73], v[174:177], v[210:213], v[70:73]
	v_mfma_f32_16x16x32_bf16 v[130:133], v[170:173], v[190:193], v[130:133]
	v_mfma_f32_16x16x32_bf16 v[122:125], v[180:183], v[190:193], v[122:125]
	v_mfma_f32_16x16x32_bf16 v[106:109], v[170:173], v[198:201], v[106:109]
	v_mfma_f32_16x16x32_bf16 v[102:105], v[180:183], v[198:201], v[102:105]
	v_mfma_f32_16x16x32_bf16 v[90:93], v[170:173], v[206:209], v[90:93]
	v_mfma_f32_16x16x32_bf16 v[86:89], v[180:183], v[206:209], v[86:89]
	v_mfma_f32_16x16x32_bf16 v[74:77], v[170:173], v[214:217], v[74:77]
	v_mfma_f32_16x16x32_bf16 v[70:73], v[180:183], v[214:217], v[70:73]
	s_setprio 0
	s_barrier
	s_add_i32 s50, s50, s36
	v_lshl_add_u64 v[156:157], s[26:27], 0, v[142:143]
	s_mov_b32 m0, s50
	ds_read_b128 v[186:189], v160 offset:16384
	ds_read_b128 v[190:193], v160 offset:17408
	ds_read_b128 v[194:197], v160 offset:18432
	ds_read_b128 v[198:201], v160 offset:19456
	ds_read_b128 v[202:205], v160 offset:20480
	ds_read_b128 v[206:209], v160 offset:21504
	ds_read_b128 v[210:213], v160 offset:22528
	ds_read_b128 v[214:217], v160 offset:23552
	global_load_lds_dwordx4 v[156:157], off
	s_add_i32 m0, s50, 0x2000
	s_add_u32 s50, s26, 0x40000
	v_lshl_add_u64 v[218:219], s[26:27], 0, v[138:139]
	s_addc_u32 s51, s27, 0
	s_add_i32 s52, s52, s36
	global_load_lds_dwordx4 v[218:219], off
	v_lshl_add_u64 v[220:221], s[50:51], 0, v[142:143]
	s_mov_b32 m0, s52
	v_lshl_add_u64 v[222:223], s[28:29], 0, v[140:141]
	global_load_lds_dwordx4 v[220:221], off
	v_lshl_add_u64 v[220:221], s[50:51], 0, v[138:139]
	s_add_i32 m0, s52, 0x2000
	s_nop 0
	global_load_lds_dwordx4 v[220:221], off
	v_lshl_add_u64 v[220:221], s[28:29], 0, v[144:145]
	s_mov_b32 m0, s33
	s_nop 0
	global_load_lds_dwordx4 v[220:221], off
	s_mov_b32 m0, s38
	s_nop 0
	global_load_lds_dwordx4 v[222:223], off
	s_waitcnt vmcnt(8) lgkmcnt(0)
	s_barrier
	s_setprio 1
	v_mfma_f32_16x16x32_bf16 v[62:65], v[66:69], v[186:189], v[62:65]
	v_mfma_f32_16x16x32_bf16 v[58:61], v[152:155], v[186:189], v[58:61]
	v_mfma_f32_16x16x32_bf16 v[46:49], v[66:69], v[194:197], v[46:49]
	v_mfma_f32_16x16x32_bf16 v[42:45], v[152:155], v[194:197], v[42:45]
	v_mfma_f32_16x16x32_bf16 v[30:33], v[66:69], v[202:205], v[30:33]
	v_mfma_f32_16x16x32_bf16 v[26:29], v[152:155], v[202:205], v[26:29]
	v_mfma_f32_16x16x32_bf16 v[14:17], v[66:69], v[210:213], v[14:17]
	v_mfma_f32_16x16x32_bf16 v[10:13], v[152:155], v[210:213], v[10:13]
	v_mfma_f32_16x16x32_bf16 v[62:65], v[118:121], v[190:193], v[62:65]
	v_mfma_f32_16x16x32_bf16 v[58:61], v[162:165], v[190:193], v[58:61]
	v_mfma_f32_16x16x32_bf16 v[46:49], v[118:121], v[198:201], v[46:49]
	v_mfma_f32_16x16x32_bf16 v[42:45], v[162:165], v[198:201], v[42:45]
	v_mfma_f32_16x16x32_bf16 v[30:33], v[118:121], v[206:209], v[30:33]
	v_mfma_f32_16x16x32_bf16 v[26:29], v[162:165], v[206:209], v[26:29]
	v_mfma_f32_16x16x32_bf16 v[14:17], v[118:121], v[214:217], v[14:17]
	v_mfma_f32_16x16x32_bf16 v[10:13], v[162:165], v[214:217], v[10:13]
	s_setprio 0
	s_setprio 1
	v_mfma_f32_16x16x32_bf16 v[54:57], v[166:169], v[186:189], v[54:57]
	v_mfma_f32_16x16x32_bf16 v[50:53], v[174:177], v[186:189], v[50:53]
	v_mfma_f32_16x16x32_bf16 v[38:41], v[166:169], v[194:197], v[38:41]
	v_mfma_f32_16x16x32_bf16 v[34:37], v[174:177], v[194:197], v[34:37]
	v_mfma_f32_16x16x32_bf16 v[22:25], v[166:169], v[202:205], v[22:25]
	v_mfma_f32_16x16x32_bf16 v[18:21], v[174:177], v[202:205], v[18:21]
	v_mfma_f32_16x16x32_bf16 v[6:9], v[166:169], v[210:213], v[6:9]
	v_mfma_f32_16x16x32_bf16 v[2:5], v[174:177], v[210:213], v[2:5]
	v_mfma_f32_16x16x32_bf16 v[54:57], v[170:173], v[190:193], v[54:57]
	v_mfma_f32_16x16x32_bf16 v[50:53], v[180:183], v[190:193], v[50:53]
	v_mfma_f32_16x16x32_bf16 v[38:41], v[170:173], v[198:201], v[38:41]
	v_mfma_f32_16x16x32_bf16 v[34:37], v[180:183], v[198:201], v[34:37]
	v_mfma_f32_16x16x32_bf16 v[22:25], v[170:173], v[206:209], v[22:25]
	v_mfma_f32_16x16x32_bf16 v[18:21], v[180:183], v[206:209], v[18:21]
	v_mfma_f32_16x16x32_bf16 v[6:9], v[170:173], v[214:217], v[6:9]
	v_mfma_f32_16x16x32_bf16 v[2:5], v[180:183], v[214:217], v[2:5]
	s_setprio 0
	s_barrier
; #define PG8_STAGE(bufoff, gbase, voff) do { _Pragma("unroll") for (int _i = 0; _i < 2; ++_i) \
;         __builtin_amdgcn_global_load_lds((const unsigned*)((const char*)(gbase) + (voff)[_i]), (PG8_LAS unsigned*)(lds + (bufoff) + ldsw + _i * 8192), 16, 0, 0); } while (0)
; #define PG8_LDA(dst, b, h) do { _Pragma("unroll") for (int m = 0; m < 4; ++m) _Pragma("unroll") for (int k = 0; k < 2; ++k) dst[m][k] = *(const PG8_LAS bf16x8*)(lds + PG8_SA(b, h) + aoff + m * 2048 + k * 1024); } while (0)
; #define PG8_LDB(dst, b, h) do { _Pragma("unroll") for (int n = 0; n < 2; ++n) _Pragma("unroll") for (int k = 0; k < 2; ++k) dst[n][k] = *(const PG8_LAS bf16x8*)(lds + PG8_SB(b, h) + boff + n * 2048 + k * 1024); } while (0)
; #define PG8_MMA(ai, bj, At, Bt) do { __builtin_amdgcn_s_setprio(1); _Pragma("unroll") for (int m = 0; m < 4; ++m) _Pragma("unroll") for (int n = 0; n < 2; ++n) _Pragma("unroll") for (int k = 0; k < 2; ++k) \
;         acc[ai][bj][m][n] = __builtin_amdgcn_mfma_f32_16x16x32_bf16(Bt[n][k], At[m][k], acc[ai][bj][m][n], 0, 0, 0); __builtin_amdgcn_s_setprio(0); } while (0)
; #define PG8_WAIT_V(n) asm volatile("s_waitcnt vmcnt(" #n ")" ::: "memory")
; #define PG8_WAIT_L(n) asm volatile("s_waitcnt lgkmcnt(" #n ")" ::: "memory")
; #define PG8_BAR __builtin_amdgcn_s_barrier()
; #define PG8_SCHED __builtin_amdgcn_sched_barrier(0)
; template <class Epi, class Sched, bool ALIGN_EPI = false, bool SP2 = false>
; __device__ __forceinline__ void gemm_phase(PG8_LAS unsigned char* lds, const Gemm g, const Sched& S, const Epi& E) {
;     ...
;             PG8_LDB(B0, 1, 0); PG8_LDB(B1, 1, 1); PG8_SCHED; PG8_LDA(At, 1, 0); PG8_STAGE(PG8_SA(0, 1), a2 + hstep, voffA);
;             PG8_WAIT_V(8); PG8_WAIT_L(0); PG8_BAR; PG8_MMA(0, 0, At, B0); PG8_MMA(0, 1, At, B1); PG8_BAR; PG8_SCHED;
	s_add_i32 s50, 0, 0x18000
	v_add_u32_e32 v161, s50, v158
	s_add_i32 s51, 0, 0x1c000
	ds_read_b128 v[66:69], v161
	ds_read_b128 v[118:121], v161 offset:1024
	ds_read_b128 v[152:155], v161 offset:2048
	ds_read_b128 v[162:165], v161 offset:3072
	v_add_u32_e32 v161, s51, v158
	ds_read_b128 v[166:169], v161
	ds_read_b128 v[170:173], v161 offset:1024
	ds_read_b128 v[174:177], v161 offset:2048
	ds_read_b128 v[180:183], v161 offset:3072
	s_add_u32 s28, s28, 0x40000
	s_addc_u32 s29, s29, 0
	s_mov_b32 m0, s39
	v_lshl_add_u64 v[240:241], s[28:29], 0, v[144:145]
	ds_read_b128 v[186:189], v160 offset:32768
	ds_read_b128 v[190:193], v160 offset:33792
	ds_read_b128 v[194:197], v160 offset:34816
	ds_read_b128 v[198:201], v160 offset:35840
	ds_read_b128 v[202:205], v160 offset:36864
	ds_read_b128 v[206:209], v160 offset:37888
	ds_read_b128 v[210:213], v160 offset:38912
	ds_read_b128 v[214:217], v160 offset:39936
	global_load_lds_dwordx4 v[240:241], off
	v_lshl_add_u64 v[240:241], s[28:29], 0, v[140:141]
	s_mov_b32 m0, s40
	s_nop 0
	global_load_lds_dwordx4 v[240:241], off
	s_waitcnt vmcnt(8) lgkmcnt(0)
	s_barrier
	s_setprio 1
	v_mfma_f32_16x16x32_bf16 v[134:137], v[66:69], v[186:189], v[134:137]
	v_mfma_f32_16x16x32_bf16 v[126:129], v[152:155], v[186:189], v[126:129]
	v_mfma_f32_16x16x32_bf16 v[114:117], v[66:69], v[194:197], v[114:117]
	v_mfma_f32_16x16x32_bf16 v[110:113], v[152:155], v[194:197], v[110:113]
	v_mfma_f32_16x16x32_bf16 v[98:101], v[66:69], v[202:205], v[98:101]
	v_mfma_f32_16x16x32_bf16 v[94:97], v[152:155], v[202:205], v[94:97]
	v_mfma_f32_16x16x32_bf16 v[82:85], v[66:69], v[210:213], v[82:85]
	v_mfma_f32_16x16x32_bf16 v[78:81], v[152:155], v[210:213], v[78:81]
	v_mfma_f32_16x16x32_bf16 v[134:137], v[118:121], v[190:193], v[134:137]
	v_mfma_f32_16x16x32_bf16 v[126:129], v[162:165], v[190:193], v[126:129]
	v_mfma_f32_16x16x32_bf16 v[114:117], v[118:121], v[198:201], v[114:117]
	v_mfma_f32_16x16x32_bf16 v[110:113], v[162:165], v[198:201], v[110:113]
	v_mfma_f32_16x16x32_bf16 v[98:101], v[118:121], v[206:209], v[98:101]
	v_mfma_f32_16x16x32_bf16 v[94:97], v[162:165], v[206:209], v[94:97]
	v_mfma_f32_16x16x32_bf16 v[82:85], v[118:121], v[214:217], v[82:85]
	v_mfma_f32_16x16x32_bf16 v[78:81], v[162:165], v[214:217], v[78:81]
	s_setprio 0
	s_setprio 1
	v_mfma_f32_16x16x32_bf16 v[130:133], v[166:169], v[186:189], v[130:133]
	v_mfma_f32_16x16x32_bf16 v[122:125], v[174:177], v[186:189], v[122:125]
	v_mfma_f32_16x16x32_bf16 v[106:109], v[166:169], v[194:197], v[106:109]
	v_mfma_f32_16x16x32_bf16 v[102:105], v[174:177], v[194:197], v[102:105]
	v_mfma_f32_16x16x32_bf16 v[90:93], v[166:169], v[202:205], v[90:93]
	v_mfma_f32_16x16x32_bf16 v[86:89], v[174:177], v[202:205], v[86:89]
	v_mfma_f32_16x16x32_bf16 v[74:77], v[166:169], v[210:213], v[74:77]
	v_mfma_f32_16x16x32_bf16 v[70:73], v[174:177], v[210:213], v[70:73]
	v_mfma_f32_16x16x32_bf16 v[130:133], v[170:173], v[190:193], v[130:133]
	v_mfma_f32_16x16x32_bf16 v[122:125], v[180:183], v[190:193], v[122:125]
	v_mfma_f32_16x16x32_bf16 v[106:109], v[170:173], v[198:201], v[106:109]
	v_mfma_f32_16x16x32_bf16 v[102:105], v[180:183], v[198:201], v[102:105]
	v_mfma_f32_16x16x32_bf16 v[90:93], v[170:173], v[206:209], v[90:93]
	v_mfma_f32_16x16x32_bf16 v[86:89], v[180:183], v[206:209], v[86:89]
	v_mfma_f32_16x16x32_bf16 v[74:77], v[170:173], v[214:217], v[74:77]
	v_mfma_f32_16x16x32_bf16 v[70:73], v[180:183], v[214:217], v[70:73]
	s_setprio 0
	s_barrier
; #define PG8_STAGE(bufoff, gbase, voff) do { _Pragma("unroll") for (int _i = 0; _i < 2; ++_i) \
;         __builtin_amdgcn_global_load_lds((const unsigned*)((const char*)(gbase) + (voff)[_i]), (PG8_LAS unsigned*)(lds + (bufoff) + ldsw + _i * 8192), 16, 0, 0); } while (0)
; #define PG8_LDA(dst, b, h) do { _Pragma("unroll") for (int m = 0; m < 4; ++m) _Pragma("unroll") for (int k = 0; k < 2; ++k) dst[m][k] = *(const PG8_LAS bf16x8*)(lds + PG8_SA(b, h) + aoff + m * 2048 + k * 1024); } while (0)
; #define PG8_MMA(ai, bj, At, Bt) do { __builtin_amdgcn_s_setprio(1); _Pragma("unroll") for (int m = 0; m < 4; ++m) _Pragma("unroll") for (int n = 0; n < 2; ++n) _Pragma("unroll") for (int k = 0; k < 2; ++k) \
;         acc[ai][bj][m][n] = __builtin_amdgcn_mfma_f32_16x16x32_bf16(Bt[n][k], At[m][k], acc[ai][bj][m][n], 0, 0, 0); __builtin_amdgcn_s_setprio(0); } while (0)
; #define PG8_WAIT_V(n) asm volatile("s_waitcnt vmcnt(" #n ")" ::: "memory")
; #define PG8_WAIT_L(n) asm volatile("s_waitcnt lgkmcnt(" #n ")" ::: "memory")
; #define PG8_BAR __builtin_amdgcn_s_barrier()
; #define PG8_SCHED __builtin_amdgcn_sched_barrier(0)
; template <class Epi, class Sched, bool ALIGN_EPI = false, bool SP2 = false>
; __device__ __forceinline__ void gemm_phase(PG8_LAS unsigned char* lds, const Gemm g, const Sched& S, const Epi& E) {
;     ...
;             PG8_LDA(At, 1, 1); PG8_STAGE(PG8_SB(1, 0), b3, voffB); PG8_STAGE(PG8_SB(1, 1), b3 + hstep, voffB); PG8_STAGE(PG8_SA(1, 0), a3, voffA);
;             PG8_WAIT_V(8); PG8_WAIT_L(0); PG8_BAR; PG8_MMA(1, 0, At, B0); PG8_MMA(1, 1, At, B1); PG8_BAR; PG8_SCHED;
;     ...
;         if constexpr (ALIGN_EPI) { if (wr == 0) PG8_BAR; }
	s_add_i32 s28, s50, s36
	v_lshl_add_u64 v[156:157], v[156:157], 0, s[80:81]
	s_mov_b32 m0, s28
	ds_read_b128 v[186:189], v160 offset:49152
	ds_read_b128 v[190:193], v160 offset:50176
	ds_read_b128 v[194:197], v160 offset:51200
	ds_read_b128 v[198:201], v160 offset:52224
	ds_read_b128 v[202:205], v160 offset:53248
	ds_read_b128 v[206:209], v160 offset:54272
	ds_read_b128 v[210:213], v160 offset:55296
	ds_read_b128 v[214:217], v160 offset:56320
	global_load_lds_dwordx4 v[156:157], off
	s_add_i32 m0, s28, 0x2000
	s_add_u32 s26, s26, 0x40080
	v_lshl_add_u64 v[156:157], v[218:219], 0, s[80:81]
	s_addc_u32 s27, s27, 0
	s_add_i32 s28, s51, s36
	global_load_lds_dwordx4 v[156:157], off
	v_lshl_add_u64 v[156:157], s[26:27], 0, v[142:143]
	s_mov_b32 m0, s28
	s_nop 0
	global_load_lds_dwordx4 v[156:157], off
	v_lshl_add_u64 v[156:157], s[26:27], 0, v[138:139]
	s_add_i32 m0, s28, 0x2000
	s_nop 0
	global_load_lds_dwordx4 v[156:157], off
	v_lshl_add_u64 v[156:157], v[220:221], 0, s[80:81]
	s_mov_b32 m0, s41
	s_nop 0
	global_load_lds_dwordx4 v[156:157], off
	v_lshl_add_u64 v[156:157], v[222:223], 0, s[80:81]
	s_mov_b32 m0, s42
	s_nop 0
	global_load_lds_dwordx4 v[156:157], off
	s_waitcnt vmcnt(8) lgkmcnt(0)
	s_barrier
	s_setprio 1
	v_mfma_f32_16x16x32_bf16 v[62:65], v[66:69], v[186:189], v[62:65]
	v_mfma_f32_16x16x32_bf16 v[58:61], v[152:155], v[186:189], v[58:61]
	v_mfma_f32_16x16x32_bf16 v[46:49], v[66:69], v[194:197], v[46:49]
	v_mfma_f32_16x16x32_bf16 v[42:45], v[152:155], v[194:197], v[42:45]
	v_mfma_f32_16x16x32_bf16 v[30:33], v[66:69], v[202:205], v[30:33]
	v_mfma_f32_16x16x32_bf16 v[26:29], v[152:155], v[202:205], v[26:29]
	v_mfma_f32_16x16x32_bf16 v[14:17], v[66:69], v[210:213], v[14:17]
	v_mfma_f32_16x16x32_bf16 v[10:13], v[152:155], v[210:213], v[10:13]
	v_mfma_f32_16x16x32_bf16 v[62:65], v[118:121], v[190:193], v[62:65]
	v_mfma_f32_16x16x32_bf16 v[58:61], v[162:165], v[190:193], v[58:61]
	v_mfma_f32_16x16x32_bf16 v[46:49], v[118:121], v[198:201], v[46:49]
	v_mfma_f32_16x16x32_bf16 v[42:45], v[162:165], v[198:201], v[42:45]
	v_mfma_f32_16x16x32_bf16 v[30:33], v[118:121], v[206:209], v[30:33]
	v_mfma_f32_16x16x32_bf16 v[26:29], v[162:165], v[206:209], v[26:29]
	v_mfma_f32_16x16x32_bf16 v[14:17], v[118:121], v[214:217], v[14:17]
	v_mfma_f32_16x16x32_bf16 v[10:13], v[162:165], v[214:217], v[10:13]
	s_setprio 0
	s_setprio 1
	v_mfma_f32_16x16x32_bf16 v[54:57], v[166:169], v[186:189], v[54:57]
	v_mfma_f32_16x16x32_bf16 v[50:53], v[174:177], v[186:189], v[50:53]
	v_mfma_f32_16x16x32_bf16 v[38:41], v[166:169], v[194:197], v[38:41]
	v_mfma_f32_16x16x32_bf16 v[34:37], v[174:177], v[194:197], v[34:37]
	v_mfma_f32_16x16x32_bf16 v[22:25], v[166:169], v[202:205], v[22:25]
	v_mfma_f32_16x16x32_bf16 v[18:21], v[174:177], v[202:205], v[18:21]
	v_mfma_f32_16x16x32_bf16 v[6:9], v[166:169], v[210:213], v[6:9]
	v_mfma_f32_16x16x32_bf16 v[2:5], v[174:177], v[210:213], v[2:5]
	v_mfma_f32_16x16x32_bf16 v[54:57], v[170:173], v[190:193], v[54:57]
	v_mfma_f32_16x16x32_bf16 v[50:53], v[180:183], v[190:193], v[50:53]
	v_mfma_f32_16x16x32_bf16 v[38:41], v[170:173], v[198:201], v[38:41]
	v_mfma_f32_16x16x32_bf16 v[34:37], v[180:183], v[198:201], v[34:37]
	v_mfma_f32_16x16x32_bf16 v[22:25], v[170:173], v[206:209], v[22:25]
	v_mfma_f32_16x16x32_bf16 v[18:21], v[180:183], v[206:209], v[18:21]
	v_mfma_f32_16x16x32_bf16 v[6:9], v[170:173], v[214:217], v[6:9]
	v_mfma_f32_16x16x32_bf16 v[2:5], v[180:183], v[214:217], v[2:5]
	s_setprio 0
	s_barrier
	s_add_i32 s49, s49, 2
	s_add_u32 s24, s24, 0x100
	s_addc_u32 s25, s25, 0
	s_add_u32 s47, s47, 0x100
	s_addc_u32 s48, s48, 0
	s_cmp_gt_u32 s49, 13
	s_cbranch_scc0 .LBB0_1249
	s_and_b64 vcc, exec, s[12:13]
	s_cbranch_vccz .LBB0_1252
	s_barrier

; #define PG8_STAGE(bufoff, gbase, voff) do { _Pragma("unroll") for (int _i = 0; _i < 2; ++_i) \
;         __builtin_amdgcn_global_load_lds((const unsigned*)((const char*)(gbase) + (voff)[_i]), (PG8_LAS unsigned*)(lds + (bufoff) + ldsw + _i * 8192), 16, 0, 0); } while (0)
; #define PG8_LDA(dst, b, h) do { _Pragma("unroll") for (int m = 0; m < 4; ++m) _Pragma("unroll") for (int k = 0; k < 2; ++k) dst[m][k] = *(const PG8_LAS bf16x8*)(lds + PG8_SA(b, h) + aoff + m * 2048 + k * 1024); } while (0)
; #define PG8_LDB(dst, b, h) do { _Pragma("unroll") for (int n = 0; n < 2; ++n) _Pragma("unroll") for (int k = 0; k < 2; ++k) dst[n][k] = *(const PG8_LAS bf16x8*)(lds + PG8_SB(b, h) + boff + n * 2048 + k * 1024); } while (0)
; #define PG8_WAIT_V(n) asm volatile("s_waitcnt vmcnt(" #n ")" ::: "memory")
; #define PG8_WAIT_L(n) asm volatile("s_waitcnt lgkmcnt(" #n ")" ::: "memory")
; #define PG8_BAR __builtin_amdgcn_s_barrier()
; #define PG8_SCHED __builtin_amdgcn_sched_barrier(0)
; template <class Epi, class Sched, bool ALIGN_EPI = false, bool SP2 = false>
; __device__ __forceinline__ void gemm_phase(PG8_LAS unsigned char* lds, const Gemm g, const Sched& S, const Epi& E) {
;     ...
;     for (;;) {
;         const bool has_next = S.next(ui + 1, nxt);
;         const char* nA = has_next ? (const char*)g.A + (size_t)nxt.pm * tstep : cA; const char* nB = has_next ? (const char*)g.Bt + (size_t)nxt.pn * tstep : cB;
;         for (int t = 0; t < nt; t += 2) {
;             const bool last = (t == nt - 2);
;             const char* a1 = cA + (size_t)(t + 1) * kstep;
;             const char* a2 = last ? nA : cA + (size_t)(t + 2) * kstep; const char* b2 = last ? nB : cB + (size_t)(t + 2) * kstep;
;             const char* a3 = a2 + kstep; const char* b3 = b2 + kstep;
;             if (last && has_next) S.a_ready(nxt);
;             if constexpr (SP2) {
;             PG8_LDB(B0, 0, 0); PG8_LDB(B1, 0, 1); PG8_SCHED; PG8_LDA(At, 0, 0); PG8_STAGE(PG8_SA(1, 1), a1 + hstep, voffA);
;             PG8_WAIT_V(8); PG8_WAIT_L(0); PG8_BAR; PG8_MMA(0, 0, At, B0); PG8_MMA(0, 1, At, B1); PG8_BAR; PG8_SCHED;
;             PG8_LDA(At, 0, 1); PG8_STAGE(PG8_SB(0, 0), b2, voffB); PG8_STAGE(PG8_SB(0, 1), b2 + hstep, voffB); PG8_STAGE(PG8_SA(0, 0), a2, voffA);
;             PG8_WAIT_V(8); PG8_WAIT_L(0); PG8_BAR; PG8_MMA(1, 0, At, B0); PG8_MMA(1, 1, At, B1); PG8_BAR; PG8_SCHED;
.LBB0_1329:
	s_add_u32 s49, s22, 0x100
	s_addc_u32 s50, s23, 0
	s_mov_b32 s51, -2
	s_add_u32 s22, s20, 0x100
	s_addc_u32 s23, s21, 0
	s_add_i32 s52, 0, 0x10000
	s_cmp_eq_u32 s51, 40
	s_cselect_b32 s27, s7, s23
	s_cselect_b32 s26, s6, s22
	v_add_u32_e32 v157, s52, v154
	s_cselect_b32 s25, s19, s50
	s_cselect_b32 s24, s18, s49
	s_add_i32 s53, 0, 0x14000
	ds_read_b128 v[142:145], v157
	ds_read_b128 v[146:149], v157 offset:1024
	ds_read_b128 v[150:153], v157 offset:2048
	ds_read_b128 v[158:161], v157 offset:3072
	v_add_u32_e32 v157, s53, v154
	ds_read_b128 v[162:165], v157
	ds_read_b128 v[166:169], v157 offset:1024
	ds_read_b128 v[170:173], v157 offset:2048
	ds_read_b128 v[174:177], v157 offset:3072
	v_lshl_add_u64 v[214:215], s[20:21], 0, v[138:139]
	s_add_i32 m0, s37, 0xc000
	ds_read_b128 v[180:183], v156
	ds_read_b128 v[186:189], v156 offset:1024
	ds_read_b128 v[190:193], v156 offset:2048
	ds_read_b128 v[194:197], v156 offset:3072
	ds_read_b128 v[198:201], v156 offset:4096
	ds_read_b128 v[202:205], v156 offset:5120
	ds_read_b128 v[206:209], v156 offset:6144
	ds_read_b128 v[210:213], v156 offset:7168
	global_load_lds_dwordx4 v[214:215], off
	v_lshl_add_u64 v[214:215], s[20:21], 0, v[140:141]
	s_add_i32 m0, s37, 0xe000
	s_nop 0
	global_load_lds_dwordx4 v[214:215], off
	s_waitcnt vmcnt(8) lgkmcnt(0)
	s_barrier
	s_setprio 1
	v_mfma_f32_16x16x32_bf16 v[126:129], v[142:145], v[180:183], 0
	v_mfma_f32_16x16x32_bf16 v[122:125], v[150:153], v[180:183], 0
	v_mfma_f32_16x16x32_bf16 v[114:117], v[142:145], v[190:193], 0
	v_mfma_f32_16x16x32_bf16 v[106:109], v[150:153], v[190:193], 0
	v_mfma_f32_16x16x32_bf16 v[98:101], v[142:145], v[198:201], 0
	v_mfma_f32_16x16x32_bf16 v[90:93], v[150:153], v[198:201], 0
	v_mfma_f32_16x16x32_bf16 v[82:85], v[142:145], v[206:209], 0
	v_mfma_f32_16x16x32_bf16 v[74:77], v[150:153], v[206:209], 0
	v_mfma_f32_16x16x32_bf16 v[126:129], v[146:149], v[186:189], v[126:129]
	v_mfma_f32_16x16x32_bf16 v[122:125], v[158:161], v[186:189], v[122:125]
	v_mfma_f32_16x16x32_bf16 v[114:117], v[146:149], v[194:197], v[114:117]
	v_mfma_f32_16x16x32_bf16 v[106:109], v[158:161], v[194:197], v[106:109]
	v_mfma_f32_16x16x32_bf16 v[98:101], v[146:149], v[202:205], v[98:101]
	v_mfma_f32_16x16x32_bf16 v[90:93], v[158:161], v[202:205], v[90:93]
	v_mfma_f32_16x16x32_bf16 v[82:85], v[146:149], v[210:213], v[82:85]
	v_mfma_f32_16x16x32_bf16 v[74:77], v[158:161], v[210:213], v[74:77]
	s_setprio 0
	s_setprio 1
	v_mfma_f32_16x16x32_bf16 v[118:121], v[162:165], v[180:183], 0
	v_mfma_f32_16x16x32_bf16 v[110:113], v[170:173], v[180:183], 0
	v_mfma_f32_16x16x32_bf16 v[102:105], v[162:165], v[190:193], 0
	v_mfma_f32_16x16x32_bf16 v[94:97], v[170:173], v[190:193], 0
	v_mfma_f32_16x16x32_bf16 v[86:89], v[162:165], v[198:201], 0
	v_mfma_f32_16x16x32_bf16 v[78:81], v[170:173], v[198:201], 0
	v_mfma_f32_16x16x32_bf16 v[70:73], v[162:165], v[206:209], 0
	v_mfma_f32_16x16x32_bf16 v[66:69], v[170:173], v[206:209], 0
	v_mfma_f32_16x16x32_bf16 v[118:121], v[166:169], v[186:189], v[118:121]
	v_mfma_f32_16x16x32_bf16 v[110:113], v[174:177], v[186:189], v[110:113]
	v_mfma_f32_16x16x32_bf16 v[102:105], v[166:169], v[194:197], v[102:105]
	v_mfma_f32_16x16x32_bf16 v[94:97], v[174:177], v[194:197], v[94:97]
	v_mfma_f32_16x16x32_bf16 v[86:89], v[166:169], v[202:205], v[86:89]
	v_mfma_f32_16x16x32_bf16 v[78:81], v[174:177], v[202:205], v[78:81]
	v_mfma_f32_16x16x32_bf16 v[70:73], v[166:169], v[210:213], v[70:73]
	v_mfma_f32_16x16x32_bf16 v[66:69], v[174:177], v[210:213], v[66:69]
	s_setprio 0
	s_barrier
	s_add_i32 s20, s52, s36
	v_lshl_add_u64 v[214:215], s[24:25], 0, v[132:133]
	s_mov_b32 m0, s20
	ds_read_b128 v[180:183], v156 offset:16384
	ds_read_b128 v[186:189], v156 offset:17408
	ds_read_b128 v[190:193], v156 offset:18432
	ds_read_b128 v[194:197], v156 offset:19456
	ds_read_b128 v[198:201], v156 offset:20480
	ds_read_b128 v[202:205], v156 offset:21504
	ds_read_b128 v[206:209], v156 offset:22528
	ds_read_b128 v[210:213], v156 offset:23552
	global_load_lds_dwordx4 v[214:215], off
	s_add_i32 m0, s20, 0x2000
	s_add_u32 s20, s24, 0xb0000
	v_lshl_add_u64 v[216:217], s[24:25], 0, v[136:137]
	s_addc_u32 s21, s25, 0
	s_add_i32 s52, s53, s36
	global_load_lds_dwordx4 v[216:217], off
	v_lshl_add_u64 v[218:219], s[20:21], 0, v[132:133]
	s_mov_b32 m0, s52
	v_lshl_add_u64 v[220:221], s[26:27], 0, v[134:135]
	global_load_lds_dwordx4 v[218:219], off
	v_lshl_add_u64 v[218:219], s[20:21], 0, v[136:137]
	s_add_i32 m0, s52, 0x2000
	s_nop 0
	global_load_lds_dwordx4 v[218:219], off
	v_lshl_add_u64 v[218:219], s[26:27], 0, v[130:131]
	s_mov_b32 m0, s37
	s_nop 0
	global_load_lds_dwordx4 v[218:219], off
	s_mov_b32 m0, s38
	s_nop 0
	global_load_lds_dwordx4 v[220:221], off
	s_waitcnt vmcnt(8) lgkmcnt(0)
	s_barrier
; #define PG8_STAGE(bufoff, gbase, voff) do { _Pragma("unroll") for (int _i = 0; _i < 2; ++_i) \
;         __builtin_amdgcn_global_load_lds((const unsigned*)((const char*)(gbase) + (voff)[_i]), (PG8_LAS unsigned*)(lds + (bufoff) + ldsw + _i * 8192), 16, 0, 0); } while (0)
; #define PG8_LDA(dst, b, h) do { _Pragma("unroll") for (int m = 0; m < 4; ++m) _Pragma("unroll") for (int k = 0; k < 2; ++k) dst[m][k] = *(const PG8_LAS bf16x8*)(lds + PG8_SA(b, h) + aoff + m * 2048 + k * 1024); } while (0)
; #define PG8_LDB(dst, b, h) do { _Pragma("unroll") for (int n = 0; n < 2; ++n) _Pragma("unroll") for (int k = 0; k < 2; ++k) dst[n][k] = *(const PG8_LAS bf16x8*)(lds + PG8_SB(b, h) + boff + n * 2048 + k * 1024); } while (0)
; #define PG8_MMA(ai, bj, At, Bt) do { __builtin_amdgcn_s_setprio(1); _Pragma("unroll") for (int m = 0; m < 4; ++m) _Pragma("unroll") for (int n = 0; n < 2; ++n) _Pragma("unroll") for (int k = 0; k < 2; ++k) \
;         acc[ai][bj][m][n] = __builtin_amdgcn_mfma_f32_16x16x32_bf16(Bt[n][k], At[m][k], acc[ai][bj][m][n], 0, 0, 0); __builtin_amdgcn_s_setprio(0); } while (0)
; #define PG8_BAR __builtin_amdgcn_s_barrier()
; template <class Epi, class Sched, bool ALIGN_EPI = false, bool SP2 = false>
; __device__ __forceinline__ void gemm_phase(PG8_LAS unsigned char* lds, const Gemm g, const Sched& S, const Epi& E) {
;     ...
;             if constexpr (SP2) {
;             PG8_LDB(B0, 0, 0); PG8_LDB(B1, 0, 1); PG8_SCHED; PG8_LDA(At, 0, 0); PG8_STAGE(PG8_SA(1, 1), a1 + hstep, voffA);
;             PG8_WAIT_V(8); PG8_WAIT_L(0); PG8_BAR; PG8_MMA(0, 0, At, B0); PG8_MMA(0, 1, At, B1); PG8_BAR; PG8_SCHED;
;             PG8_LDA(At, 0, 1); PG8_STAGE(PG8_SB(0, 0), b2, voffB); PG8_STAGE(PG8_SB(0, 1), b2 + hstep, voffB); PG8_STAGE(PG8_SA(0, 0), a2, voffA);
;             PG8_WAIT_V(8); PG8_WAIT_L(0); PG8_BAR; PG8_MMA(1, 0, At, B0); PG8_MMA(1, 1, At, B1); PG8_BAR; PG8_SCHED;
;             PG8_LDB(B0, 1, 0); PG8_LDB(B1, 1, 1); PG8_SCHED; PG8_LDA(At, 1, 0); PG8_STAGE(PG8_SA(0, 1), a2 + hstep, voffA);
;             PG8_WAIT_V(8); PG8_WAIT_L(0); PG8_BAR; PG8_MMA(0, 0, At, B0); PG8_MMA(0, 1, At, B1); PG8_BAR; PG8_SCHED;
;             PG8_LDA(At, 1, 1); PG8_STAGE(PG8_SB(1, 0), b3, voffB); PG8_STAGE(PG8_SB(1, 1), b3 + hstep, voffB); PG8_STAGE(PG8_SA(1, 0), a3, voffA);
;             PG8_WAIT_V(8); PG8_WAIT_L(0); PG8_BAR; PG8_MMA(1, 0, At, B0); PG8_MMA(1, 1, At, B1); PG8_BAR; PG8_SCHED;
	s_setprio 1
	v_mfma_f32_16x16x32_bf16 v[62:65], v[142:145], v[180:183], 0
	v_mfma_f32_16x16x32_bf16 v[58:61], v[150:153], v[180:183], 0
	v_mfma_f32_16x16x32_bf16 v[50:53], v[142:145], v[190:193], 0
	v_mfma_f32_16x16x32_bf16 v[42:45], v[150:153], v[190:193], 0
	v_mfma_f32_16x16x32_bf16 v[34:37], v[142:145], v[198:201], 0
	v_mfma_f32_16x16x32_bf16 v[26:29], v[150:153], v[198:201], 0
	v_mfma_f32_16x16x32_bf16 v[18:21], v[142:145], v[206:209], 0
	v_mfma_f32_16x16x32_bf16 v[10:13], v[150:153], v[206:209], 0
	v_mfma_f32_16x16x32_bf16 v[62:65], v[146:149], v[186:189], v[62:65]
	v_mfma_f32_16x16x32_bf16 v[58:61], v[158:161], v[186:189], v[58:61]
	v_mfma_f32_16x16x32_bf16 v[50:53], v[146:149], v[194:197], v[50:53]
	v_mfma_f32_16x16x32_bf16 v[42:45], v[158:161], v[194:197], v[42:45]
	v_mfma_f32_16x16x32_bf16 v[34:37], v[146:149], v[202:205], v[34:37]
	v_mfma_f32_16x16x32_bf16 v[26:29], v[158:161], v[202:205], v[26:29]
	v_mfma_f32_16x16x32_bf16 v[18:21], v[146:149], v[210:213], v[18:21]
	v_mfma_f32_16x16x32_bf16 v[10:13], v[158:161], v[210:213], v[10:13]
	s_setprio 0
	s_setprio 1
	v_mfma_f32_16x16x32_bf16 v[54:57], v[162:165], v[180:183], 0
	v_mfma_f32_16x16x32_bf16 v[46:49], v[170:173], v[180:183], 0
	v_mfma_f32_16x16x32_bf16 v[38:41], v[162:165], v[190:193], 0
	v_mfma_f32_16x16x32_bf16 v[30:33], v[170:173], v[190:193], 0
	v_mfma_f32_16x16x32_bf16 v[22:25], v[162:165], v[198:201], 0
	v_mfma_f32_16x16x32_bf16 v[14:17], v[170:173], v[198:201], 0
	v_mfma_f32_16x16x32_bf16 v[6:9], v[162:165], v[206:209], 0
	v_mfma_f32_16x16x32_bf16 v[2:5], v[170:173], v[206:209], 0
	v_mfma_f32_16x16x32_bf16 v[54:57], v[166:169], v[186:189], v[54:57]
	v_mfma_f32_16x16x32_bf16 v[46:49], v[174:177], v[186:189], v[46:49]
	v_mfma_f32_16x16x32_bf16 v[38:41], v[166:169], v[194:197], v[38:41]
	v_mfma_f32_16x16x32_bf16 v[30:33], v[174:177], v[194:197], v[30:33]
	v_mfma_f32_16x16x32_bf16 v[22:25], v[166:169], v[202:205], v[22:25]
	v_mfma_f32_16x16x32_bf16 v[14:17], v[174:177], v[202:205], v[14:17]
	v_mfma_f32_16x16x32_bf16 v[6:9], v[166:169], v[210:213], v[6:9]
	v_mfma_f32_16x16x32_bf16 v[2:5], v[174:177], v[210:213], v[2:5]
	s_setprio 0
	s_barrier
	s_add_i32 s52, 0, 0x18000
	v_add_u32_e32 v157, s52, v154
	s_add_i32 s53, 0, 0x1c000
	ds_read_b128 v[142:145], v157
	ds_read_b128 v[146:149], v157 offset:1024
	ds_read_b128 v[150:153], v157 offset:2048
	ds_read_b128 v[158:161], v157 offset:3072
	v_add_u32_e32 v157, s53, v154
	ds_read_b128 v[162:165], v157
	ds_read_b128 v[166:169], v157 offset:1024
	ds_read_b128 v[170:173], v157 offset:2048
	ds_read_b128 v[174:177], v157 offset:3072
	s_add_u32 s20, s26, 0xb0000
	s_addc_u32 s21, s27, 0
	s_mov_b32 m0, s39
	v_lshl_add_u64 v[222:223], s[20:21], 0, v[130:131]
	ds_read_b128 v[180:183], v156 offset:32768
	ds_read_b128 v[186:189], v156 offset:33792
	ds_read_b128 v[190:193], v156 offset:34816
	ds_read_b128 v[194:197], v156 offset:35840
	ds_read_b128 v[198:201], v156 offset:36864
	ds_read_b128 v[202:205], v156 offset:37888
	ds_read_b128 v[206:209], v156 offset:38912
	ds_read_b128 v[210:213], v156 offset:39936
	global_load_lds_dwordx4 v[222:223], off
	v_lshl_add_u64 v[222:223], s[20:21], 0, v[134:135]
	s_mov_b32 m0, s40
	s_nop 0
	global_load_lds_dwordx4 v[222:223], off
	s_waitcnt vmcnt(8) lgkmcnt(0)
	s_barrier
	s_setprio 1
	v_mfma_f32_16x16x32_bf16 v[126:129], v[142:145], v[180:183], v[126:129]
	v_mfma_f32_16x16x32_bf16 v[122:125], v[150:153], v[180:183], v[122:125]
	v_mfma_f32_16x16x32_bf16 v[114:117], v[142:145], v[190:193], v[114:117]
	v_mfma_f32_16x16x32_bf16 v[106:109], v[150:153], v[190:193], v[106:109]
	v_mfma_f32_16x16x32_bf16 v[98:101], v[142:145], v[198:201], v[98:101]
	v_mfma_f32_16x16x32_bf16 v[90:93], v[150:153], v[198:201], v[90:93]
	v_mfma_f32_16x16x32_bf16 v[82:85], v[142:145], v[206:209], v[82:85]
	v_mfma_f32_16x16x32_bf16 v[74:77], v[150:153], v[206:209], v[74:77]
	v_mfma_f32_16x16x32_bf16 v[126:129], v[146:149], v[186:189], v[126:129]
	v_mfma_f32_16x16x32_bf16 v[122:125], v[158:161], v[186:189], v[122:125]
	v_mfma_f32_16x16x32_bf16 v[114:117], v[146:149], v[194:197], v[114:117]
	v_mfma_f32_16x16x32_bf16 v[106:109], v[158:161], v[194:197], v[106:109]
	v_mfma_f32_16x16x32_bf16 v[98:101], v[146:149], v[202:205], v[98:101]
	v_mfma_f32_16x16x32_bf16 v[90:93], v[158:161], v[202:205], v[90:93]
	v_mfma_f32_16x16x32_bf16 v[82:85], v[146:149], v[210:213], v[82:85]
	v_mfma_f32_16x16x32_bf16 v[74:77], v[158:161], v[210:213], v[74:77]
	s_setprio 0
	s_setprio 1
	v_mfma_f32_16x16x32_bf16 v[118:121], v[162:165], v[180:183], v[118:121]
	v_mfma_f32_16x16x32_bf16 v[110:113], v[170:173], v[180:183], v[110:113]
	v_mfma_f32_16x16x32_bf16 v[102:105], v[162:165], v[190:193], v[102:105]
	v_mfma_f32_16x16x32_bf16 v[94:97], v[170:173], v[190:193], v[94:97]
	v_mfma_f32_16x16x32_bf16 v[86:89], v[162:165], v[198:201], v[86:89]
	v_mfma_f32_16x16x32_bf16 v[78:81], v[170:173], v[198:201], v[78:81]
	v_mfma_f32_16x16x32_bf16 v[70:73], v[162:165], v[206:209], v[70:73]
	v_mfma_f32_16x16x32_bf16 v[66:69], v[170:173], v[206:209], v[66:69]
	v_mfma_f32_16x16x32_bf16 v[118:121], v[166:169], v[186:189], v[118:121]
	v_mfma_f32_16x16x32_bf16 v[110:113], v[174:177], v[186:189], v[110:113]
	v_mfma_f32_16x16x32_bf16 v[102:105], v[166:169], v[194:197], v[102:105]
	v_mfma_f32_16x16x32_bf16 v[94:97], v[174:177], v[194:197], v[94:97]
	v_mfma_f32_16x16x32_bf16 v[86:89], v[166:169], v[202:205], v[86:89]
	v_mfma_f32_16x16x32_bf16 v[78:81], v[174:177], v[202:205], v[78:81]
	v_mfma_f32_16x16x32_bf16 v[70:73], v[166:169], v[210:213], v[70:73]
	v_mfma_f32_16x16x32_bf16 v[66:69], v[174:177], v[210:213], v[66:69]
	s_setprio 0
	s_barrier
; #define PG8_STAGE(bufoff, gbase, voff) do { _Pragma("unroll") for (int _i = 0; _i < 2; ++_i) \
;         __builtin_amdgcn_global_load_lds((const unsigned*)((const char*)(gbase) + (voff)[_i]), (PG8_LAS unsigned*)(lds + (bufoff) + ldsw + _i * 8192), 16, 0, 0); } while (0)
; #define PG8_LDA(dst, b, h) do { _Pragma("unroll") for (int m = 0; m < 4; ++m) _Pragma("unroll") for (int k = 0; k < 2; ++k) dst[m][k] = *(const PG8_LAS bf16x8*)(lds + PG8_SA(b, h) + aoff + m * 2048 + k * 1024); } while (0)
; #define PG8_LDB(dst, b, h) do { _Pragma("unroll") for (int n = 0; n < 2; ++n) _Pragma("unroll") for (int k = 0; k < 2; ++k) dst[n][k] = *(const PG8_LAS bf16x8*)(lds + PG8_SB(b, h) + boff + n * 2048 + k * 1024); } while (0)
; template <class Epi, class Sched, bool ALIGN_EPI = false, bool SP2 = false>
; __device__ __forceinline__ void gemm_phase(PG8_LAS unsigned char* lds, const Gemm g, const Sched& S, const Epi& E) {
;     ...
;         for (int t = 0; t < nt; t += 2) {
;             const bool last = (t == nt - 2);
;             const char* a1 = cA + (size_t)(t + 1) * kstep;
;             const char* a2 = last ? nA : cA + (size_t)(t + 2) * kstep; const char* b2 = last ? nB : cB + (size_t)(t + 2) * kstep;
;             const char* a3 = a2 + kstep; const char* b3 = b2 + kstep;
;             if (last && has_next) S.a_ready(nxt);
;             if constexpr (SP2) {
;             PG8_LDB(B0, 0, 0); PG8_LDB(B1, 0, 1); PG8_SCHED; PG8_LDA(At, 0, 0); PG8_STAGE(PG8_SA(1, 1), a1 + hstep, voffA);
;             PG8_WAIT_V(8); PG8_WAIT_L(0); PG8_BAR; PG8_MMA(0, 0, At, B0); PG8_MMA(0, 1, At, B1); PG8_BAR; PG8_SCHED;
;             PG8_LDA(At, 0, 1); PG8_STAGE(PG8_SB(0, 0), b2, voffB); PG8_STAGE(PG8_SB(0, 1), b2 + hstep, voffB); PG8_STAGE(PG8_SA(0, 0), a2, voffA);
;             PG8_WAIT_V(8); PG8_WAIT_L(0); PG8_BAR; PG8_MMA(1, 0, At, B0); PG8_MMA(1, 1, At, B1); PG8_BAR; PG8_SCHED;
;             PG8_LDB(B0, 1, 0); PG8_LDB(B1, 1, 1); PG8_SCHED; PG8_LDA(At, 1, 0); PG8_STAGE(PG8_SA(0, 1), a2 + hstep, voffA);
;             PG8_WAIT_V(8); PG8_WAIT_L(0); PG8_BAR; PG8_MMA(0, 0, At, B0); PG8_MMA(0, 1, At, B1); PG8_BAR; PG8_SCHED;
;             PG8_LDA(At, 1, 1); PG8_STAGE(PG8_SB(1, 0), b3, voffB); PG8_STAGE(PG8_SB(1, 1), b3 + hstep, voffB); PG8_STAGE(PG8_SA(1, 0), a3, voffA);
;             PG8_WAIT_V(8); PG8_WAIT_L(0); PG8_BAR; PG8_MMA(1, 0, At, B0); PG8_MMA(1, 1, At, B1); PG8_BAR; PG8_SCHED;
	s_add_i32 s20, s52, s36
	v_lshl_add_u64 v[214:215], v[214:215], 0, s[80:81]
	s_mov_b32 m0, s20
	ds_read_b128 v[180:183], v156 offset:49152
	ds_read_b128 v[186:189], v156 offset:50176
	ds_read_b128 v[190:193], v156 offset:51200
	ds_read_b128 v[194:197], v156 offset:52224
	ds_read_b128 v[198:201], v156 offset:53248
	ds_read_b128 v[202:205], v156 offset:54272
	ds_read_b128 v[206:209], v156 offset:55296
	ds_read_b128 v[210:213], v156 offset:56320
	global_load_lds_dwordx4 v[214:215], off
	s_add_i32 m0, s20, 0x2000
	s_add_u32 s20, s24, 0xb0080
	v_lshl_add_u64 v[214:215], v[216:217], 0, s[80:81]
	s_addc_u32 s21, s25, 0
	s_add_i32 s24, s53, s36
	global_load_lds_dwordx4 v[214:215], off
	v_lshl_add_u64 v[214:215], s[20:21], 0, v[132:133]
	s_mov_b32 m0, s24
	s_nop 0
	global_load_lds_dwordx4 v[214:215], off
	v_lshl_add_u64 v[214:215], s[20:21], 0, v[136:137]
	s_add_i32 m0, s24, 0x2000
	s_nop 0
	global_load_lds_dwordx4 v[214:215], off
	v_lshl_add_u64 v[214:215], v[218:219], 0, s[80:81]
	s_mov_b32 m0, s41
	s_nop 0
	global_load_lds_dwordx4 v[214:215], off
	v_lshl_add_u64 v[214:215], v[220:221], 0, s[80:81]
	s_mov_b32 m0, s42
	s_nop 0
	global_load_lds_dwordx4 v[214:215], off
	s_waitcnt vmcnt(8) lgkmcnt(0)
	s_barrier
	s_setprio 1
	v_mfma_f32_16x16x32_bf16 v[62:65], v[142:145], v[180:183], v[62:65]
	v_mfma_f32_16x16x32_bf16 v[58:61], v[150:153], v[180:183], v[58:61]
	v_mfma_f32_16x16x32_bf16 v[50:53], v[142:145], v[190:193], v[50:53]
	v_mfma_f32_16x16x32_bf16 v[42:45], v[150:153], v[190:193], v[42:45]
	v_mfma_f32_16x16x32_bf16 v[34:37], v[142:145], v[198:201], v[34:37]
	v_mfma_f32_16x16x32_bf16 v[26:29], v[150:153], v[198:201], v[26:29]
	v_mfma_f32_16x16x32_bf16 v[18:21], v[142:145], v[206:209], v[18:21]
	v_mfma_f32_16x16x32_bf16 v[10:13], v[150:153], v[206:209], v[10:13]
	v_mfma_f32_16x16x32_bf16 v[62:65], v[146:149], v[186:189], v[62:65]
	v_mfma_f32_16x16x32_bf16 v[58:61], v[158:161], v[186:189], v[58:61]
	v_mfma_f32_16x16x32_bf16 v[50:53], v[146:149], v[194:197], v[50:53]
	v_mfma_f32_16x16x32_bf16 v[42:45], v[158:161], v[194:197], v[42:45]
	v_mfma_f32_16x16x32_bf16 v[34:37], v[146:149], v[202:205], v[34:37]
	v_mfma_f32_16x16x32_bf16 v[26:29], v[158:161], v[202:205], v[26:29]
	v_mfma_f32_16x16x32_bf16 v[18:21], v[146:149], v[210:213], v[18:21]
	v_mfma_f32_16x16x32_bf16 v[10:13], v[158:161], v[210:213], v[10:13]
	s_setprio 0
	s_setprio 1
	v_mfma_f32_16x16x32_bf16 v[54:57], v[162:165], v[180:183], v[54:57]
	v_mfma_f32_16x16x32_bf16 v[46:49], v[170:173], v[180:183], v[46:49]
	v_mfma_f32_16x16x32_bf16 v[38:41], v[162:165], v[190:193], v[38:41]
	v_mfma_f32_16x16x32_bf16 v[30:33], v[170:173], v[190:193], v[30:33]
	v_mfma_f32_16x16x32_bf16 v[22:25], v[162:165], v[198:201], v[22:25]
	v_mfma_f32_16x16x32_bf16 v[14:17], v[170:173], v[198:201], v[14:17]
	v_mfma_f32_16x16x32_bf16 v[6:9], v[162:165], v[206:209], v[6:9]
	v_mfma_f32_16x16x32_bf16 v[2:5], v[170:173], v[206:209], v[2:5]
	v_mfma_f32_16x16x32_bf16 v[54:57], v[166:169], v[186:189], v[54:57]
	v_mfma_f32_16x16x32_bf16 v[46:49], v[174:177], v[186:189], v[46:49]
	v_mfma_f32_16x16x32_bf16 v[38:41], v[166:169], v[194:197], v[38:41]
	v_mfma_f32_16x16x32_bf16 v[30:33], v[174:177], v[194:197], v[30:33]
	v_mfma_f32_16x16x32_bf16 v[22:25], v[166:169], v[202:205], v[22:25]
	v_mfma_f32_16x16x32_bf16 v[14:17], v[174:177], v[202:205], v[14:17]
	v_mfma_f32_16x16x32_bf16 v[6:9], v[166:169], v[210:213], v[6:9]
	v_mfma_f32_16x16x32_bf16 v[2:5], v[174:177], v[210:213], v[2:5]
	s_setprio 0
	s_barrier
	s_add_i32 s51, s51, 2
	s_add_u32 s49, s49, 0x100
	s_addc_u32 s50, s50, 0
	s_cmp_gt_u32 s51, 41
	s_mov_b64 s[20:21], s[22:23]
	s_branch .LBB0_1330
.LBB0_1330:
	s_add_u32 s22, s20, 0x100
	s_addc_u32 s23, s21, 0
	s_add_i32 s52, 0, 0x10000
	s_cmp_eq_u32 s51, 40
	s_cselect_b32 s27, s7, s23
	s_cselect_b32 s26, s6, s22
	v_add_u32_e32 v157, s52, v154
	s_cselect_b32 s25, s19, s50
	s_cselect_b32 s24, s18, s49
	s_add_i32 s53, 0, 0x14000
	ds_read_b128 v[142:145], v157
	ds_read_b128 v[146:149], v157 offset:1024
	ds_read_b128 v[150:153], v157 offset:2048
	ds_read_b128 v[158:161], v157 offset:3072
	v_add_u32_e32 v157, s53, v154
	ds_read_b128 v[162:165], v157
	ds_read_b128 v[166:169], v157 offset:1024
	ds_read_b128 v[170:173], v157 offset:2048
	ds_read_b128 v[174:177], v157 offset:3072
	v_lshl_add_u64 v[214:215], s[20:21], 0, v[138:139]
	s_add_i32 m0, s37, 0xc000
	ds_read_b128 v[180:183], v156
	ds_read_b128 v[186:189], v156 offset:1024
	ds_read_b128 v[190:193], v156 offset:2048
	ds_read_b128 v[194:197], v156 offset:3072
	ds_read_b128 v[198:201], v156 offset:4096
	ds_read_b128 v[202:205], v156 offset:5120
	ds_read_b128 v[206:209], v156 offset:6144
	ds_read_b128 v[210:213], v156 offset:7168
	global_load_lds_dwordx4 v[214:215], off
	v_lshl_add_u64 v[214:215], s[20:21], 0, v[140:141]
	s_add_i32 m0, s37, 0xe000
	s_nop 0
	global_load_lds_dwordx4 v[214:215], off
	s_waitcnt vmcnt(8) lgkmcnt(0)
	s_barrier
; #define PG8_STAGE(bufoff, gbase, voff) do { _Pragma("unroll") for (int _i = 0; _i < 2; ++_i) \
;         __builtin_amdgcn_global_load_lds((const unsigned*)((const char*)(gbase) + (voff)[_i]), (PG8_LAS unsigned*)(lds + (bufoff) + ldsw + _i * 8192), 16, 0, 0); } while (0)
; #define PG8_LDA(dst, b, h) do { _Pragma("unroll") for (int m = 0; m < 4; ++m) _Pragma("unroll") for (int k = 0; k < 2; ++k) dst[m][k] = *(const PG8_LAS bf16x8*)(lds + PG8_SA(b, h) + aoff + m * 2048 + k * 1024); } while (0)
; #define PG8_LDB(dst, b, h) do { _Pragma("unroll") for (int n = 0; n < 2; ++n) _Pragma("unroll") for (int k = 0; k < 2; ++k) dst[n][k] = *(const PG8_LAS bf16x8*)(lds + PG8_SB(b, h) + boff + n * 2048 + k * 1024); } while (0)
; #define PG8_MMA(ai, bj, At, Bt) do { __builtin_amdgcn_s_setprio(1); _Pragma("unroll") for (int m = 0; m < 4; ++m) _Pragma("unroll") for (int n = 0; n < 2; ++n) _Pragma("unroll") for (int k = 0; k < 2; ++k) \
;         acc[ai][bj][m][n] = __builtin_amdgcn_mfma_f32_16x16x32_bf16(Bt[n][k], At[m][k], acc[ai][bj][m][n], 0, 0, 0); __builtin_amdgcn_s_setprio(0); } while (0)
; #define PG8_BAR __builtin_amdgcn_s_barrier()
; template <class Epi, class Sched, bool ALIGN_EPI = false, bool SP2 = false>
; __device__ __forceinline__ void gemm_phase(PG8_LAS unsigned char* lds, const Gemm g, const Sched& S, const Epi& E) {
;     ...
;             if constexpr (SP2) {
;             PG8_LDB(B0, 0, 0); PG8_LDB(B1, 0, 1); PG8_SCHED; PG8_LDA(At, 0, 0); PG8_STAGE(PG8_SA(1, 1), a1 + hstep, voffA);
;             PG8_WAIT_V(8); PG8_WAIT_L(0); PG8_BAR; PG8_MMA(0, 0, At, B0); PG8_MMA(0, 1, At, B1); PG8_BAR; PG8_SCHED;
;             PG8_LDA(At, 0, 1); PG8_STAGE(PG8_SB(0, 0), b2, voffB); PG8_STAGE(PG8_SB(0, 1), b2 + hstep, voffB); PG8_STAGE(PG8_SA(0, 0), a2, voffA);
;             PG8_WAIT_V(8); PG8_WAIT_L(0); PG8_BAR; PG8_MMA(1, 0, At, B0); PG8_MMA(1, 1, At, B1); PG8_BAR; PG8_SCHED;
;             PG8_LDB(B0, 1, 0); PG8_LDB(B1, 1, 1); PG8_SCHED; PG8_LDA(At, 1, 0); PG8_STAGE(PG8_SA(0, 1), a2 + hstep, voffA);
;             PG8_WAIT_V(8); PG8_WAIT_L(0); PG8_BAR; PG8_MMA(0, 0, At, B0); PG8_MMA(0, 1, At, B1); PG8_BAR; PG8_SCHED;
;             PG8_LDA(At, 1, 1); PG8_STAGE(PG8_SB(1, 0), b3, voffB); PG8_STAGE(PG8_SB(1, 1), b3 + hstep, voffB); PG8_STAGE(PG8_SA(1, 0), a3, voffA);
;             PG8_WAIT_V(8); PG8_WAIT_L(0); PG8_BAR; PG8_MMA(1, 0, At, B0); PG8_MMA(1, 1, At, B1); PG8_BAR; PG8_SCHED;
	s_setprio 1
	v_mfma_f32_16x16x32_bf16 v[126:129], v[142:145], v[180:183], v[126:129]
	v_mfma_f32_16x16x32_bf16 v[122:125], v[150:153], v[180:183], v[122:125]
	v_mfma_f32_16x16x32_bf16 v[114:117], v[142:145], v[190:193], v[114:117]
	v_mfma_f32_16x16x32_bf16 v[106:109], v[150:153], v[190:193], v[106:109]
	v_mfma_f32_16x16x32_bf16 v[98:101], v[142:145], v[198:201], v[98:101]
	v_mfma_f32_16x16x32_bf16 v[90:93], v[150:153], v[198:201], v[90:93]
	v_mfma_f32_16x16x32_bf16 v[82:85], v[142:145], v[206:209], v[82:85]
	v_mfma_f32_16x16x32_bf16 v[74:77], v[150:153], v[206:209], v[74:77]
	v_mfma_f32_16x16x32_bf16 v[126:129], v[146:149], v[186:189], v[126:129]
	v_mfma_f32_16x16x32_bf16 v[122:125], v[158:161], v[186:189], v[122:125]
	v_mfma_f32_16x16x32_bf16 v[114:117], v[146:149], v[194:197], v[114:117]
	v_mfma_f32_16x16x32_bf16 v[106:109], v[158:161], v[194:197], v[106:109]
	v_mfma_f32_16x16x32_bf16 v[98:101], v[146:149], v[202:205], v[98:101]
	v_mfma_f32_16x16x32_bf16 v[90:93], v[158:161], v[202:205], v[90:93]
	v_mfma_f32_16x16x32_bf16 v[82:85], v[146:149], v[210:213], v[82:85]
	v_mfma_f32_16x16x32_bf16 v[74:77], v[158:161], v[210:213], v[74:77]
	s_setprio 0
	s_setprio 1
	v_mfma_f32_16x16x32_bf16 v[118:121], v[162:165], v[180:183], v[118:121]
	v_mfma_f32_16x16x32_bf16 v[110:113], v[170:173], v[180:183], v[110:113]
	v_mfma_f32_16x16x32_bf16 v[102:105], v[162:165], v[190:193], v[102:105]
	v_mfma_f32_16x16x32_bf16 v[94:97], v[170:173], v[190:193], v[94:97]
	v_mfma_f32_16x16x32_bf16 v[86:89], v[162:165], v[198:201], v[86:89]
	v_mfma_f32_16x16x32_bf16 v[78:81], v[170:173], v[198:201], v[78:81]
	v_mfma_f32_16x16x32_bf16 v[70:73], v[162:165], v[206:209], v[70:73]
	v_mfma_f32_16x16x32_bf16 v[66:69], v[170:173], v[206:209], v[66:69]
	v_mfma_f32_16x16x32_bf16 v[118:121], v[166:169], v[186:189], v[118:121]
	v_mfma_f32_16x16x32_bf16 v[110:113], v[174:177], v[186:189], v[110:113]
	v_mfma_f32_16x16x32_bf16 v[102:105], v[166:169], v[194:197], v[102:105]
	v_mfma_f32_16x16x32_bf16 v[94:97], v[174:177], v[194:197], v[94:97]
	v_mfma_f32_16x16x32_bf16 v[86:89], v[166:169], v[202:205], v[86:89]
	v_mfma_f32_16x16x32_bf16 v[78:81], v[174:177], v[202:205], v[78:81]
	v_mfma_f32_16x16x32_bf16 v[70:73], v[166:169], v[210:213], v[70:73]
	v_mfma_f32_16x16x32_bf16 v[66:69], v[174:177], v[210:213], v[66:69]
	s_setprio 0
	s_barrier
	s_add_i32 s20, s52, s36
	v_lshl_add_u64 v[214:215], s[24:25], 0, v[132:133]
	s_mov_b32 m0, s20
	ds_read_b128 v[180:183], v156 offset:16384
	ds_read_b128 v[186:189], v156 offset:17408
	ds_read_b128 v[190:193], v156 offset:18432
	ds_read_b128 v[194:197], v156 offset:19456
	ds_read_b128 v[198:201], v156 offset:20480
	ds_read_b128 v[202:205], v156 offset:21504
	ds_read_b128 v[206:209], v156 offset:22528
	ds_read_b128 v[210:213], v156 offset:23552
	global_load_lds_dwordx4 v[214:215], off
	s_add_i32 m0, s20, 0x2000
	s_add_u32 s20, s24, 0xb0000
	v_lshl_add_u64 v[216:217], s[24:25], 0, v[136:137]
	s_addc_u32 s21, s25, 0
	s_add_i32 s52, s53, s36
	global_load_lds_dwordx4 v[216:217], off
	v_lshl_add_u64 v[218:219], s[20:21], 0, v[132:133]
	s_mov_b32 m0, s52
	v_lshl_add_u64 v[220:221], s[26:27], 0, v[134:135]
	global_load_lds_dwordx4 v[218:219], off
	v_lshl_add_u64 v[218:219], s[20:21], 0, v[136:137]
	s_add_i32 m0, s52, 0x2000
	s_nop 0
	global_load_lds_dwordx4 v[218:219], off
	v_lshl_add_u64 v[218:219], s[26:27], 0, v[130:131]
	s_mov_b32 m0, s37
	s_nop 0
	global_load_lds_dwordx4 v[218:219], off
	s_mov_b32 m0, s38
	s_nop 0
	global_load_lds_dwordx4 v[220:221], off
	s_waitcnt vmcnt(8) lgkmcnt(0)
	s_barrier
	s_setprio 1
	v_mfma_f32_16x16x32_bf16 v[62:65], v[142:145], v[180:183], v[62:65]
	v_mfma_f32_16x16x32_bf16 v[58:61], v[150:153], v[180:183], v[58:61]
	v_mfma_f32_16x16x32_bf16 v[50:53], v[142:145], v[190:193], v[50:53]
	v_mfma_f32_16x16x32_bf16 v[42:45], v[150:153], v[190:193], v[42:45]
	v_mfma_f32_16x16x32_bf16 v[34:37], v[142:145], v[198:201], v[34:37]
	v_mfma_f32_16x16x32_bf16 v[26:29], v[150:153], v[198:201], v[26:29]
	v_mfma_f32_16x16x32_bf16 v[18:21], v[142:145], v[206:209], v[18:21]
	v_mfma_f32_16x16x32_bf16 v[10:13], v[150:153], v[206:209], v[10:13]
	v_mfma_f32_16x16x32_bf16 v[62:65], v[146:149], v[186:189], v[62:65]
	v_mfma_f32_16x16x32_bf16 v[58:61], v[158:161], v[186:189], v[58:61]
	v_mfma_f32_16x16x32_bf16 v[50:53], v[146:149], v[194:197], v[50:53]
	v_mfma_f32_16x16x32_bf16 v[42:45], v[158:161], v[194:197], v[42:45]
	v_mfma_f32_16x16x32_bf16 v[34:37], v[146:149], v[202:205], v[34:37]
	v_mfma_f32_16x16x32_bf16 v[26:29], v[158:161], v[202:205], v[26:29]
	v_mfma_f32_16x16x32_bf16 v[18:21], v[146:149], v[210:213], v[18:21]
	v_mfma_f32_16x16x32_bf16 v[10:13], v[158:161], v[210:213], v[10:13]
	s_setprio 0
	s_setprio 1
	v_mfma_f32_16x16x32_bf16 v[54:57], v[162:165], v[180:183], v[54:57]
	v_mfma_f32_16x16x32_bf16 v[46:49], v[170:173], v[180:183], v[46:49]
	v_mfma_f32_16x16x32_bf16 v[38:41], v[162:165], v[190:193], v[38:41]
	v_mfma_f32_16x16x32_bf16 v[30:33], v[170:173], v[190:193], v[30:33]
	v_mfma_f32_16x16x32_bf16 v[22:25], v[162:165], v[198:201], v[22:25]
	v_mfma_f32_16x16x32_bf16 v[14:17], v[170:173], v[198:201], v[14:17]
	v_mfma_f32_16x16x32_bf16 v[6:9], v[162:165], v[206:209], v[6:9]
	v_mfma_f32_16x16x32_bf16 v[2:5], v[170:173], v[206:209], v[2:5]
	v_mfma_f32_16x16x32_bf16 v[54:57], v[166:169], v[186:189], v[54:57]
	v_mfma_f32_16x16x32_bf16 v[46:49], v[174:177], v[186:189], v[46:49]
	v_mfma_f32_16x16x32_bf16 v[38:41], v[166:169], v[194:197], v[38:41]
	v_mfma_f32_16x16x32_bf16 v[30:33], v[174:177], v[194:197], v[30:33]
	v_mfma_f32_16x16x32_bf16 v[22:25], v[166:169], v[202:205], v[22:25]
	v_mfma_f32_16x16x32_bf16 v[14:17], v[174:177], v[202:205], v[14:17]
	v_mfma_f32_16x16x32_bf16 v[6:9], v[166:169], v[210:213], v[6:9]
	v_mfma_f32_16x16x32_bf16 v[2:5], v[174:177], v[210:213], v[2:5]
	s_setprio 0
	s_barrier
; #define PG8_STAGE(bufoff, gbase, voff) do { _Pragma("unroll") for (int _i = 0; _i < 2; ++_i) \
;         __builtin_amdgcn_global_load_lds((const unsigned*)((const char*)(gbase) + (voff)[_i]), (PG8_LAS unsigned*)(lds + (bufoff) + ldsw + _i * 8192), 16, 0, 0); } while (0)
; #define PG8_LDA(dst, b, h) do { _Pragma("unroll") for (int m = 0; m < 4; ++m) _Pragma("unroll") for (int k = 0; k < 2; ++k) dst[m][k] = *(const PG8_LAS bf16x8*)(lds + PG8_SA(b, h) + aoff + m * 2048 + k * 1024); } while (0)
; #define PG8_LDB(dst, b, h) do { _Pragma("unroll") for (int n = 0; n < 2; ++n) _Pragma("unroll") for (int k = 0; k < 2; ++k) dst[n][k] = *(const PG8_LAS bf16x8*)(lds + PG8_SB(b, h) + boff + n * 2048 + k * 1024); } while (0)
; #define PG8_MMA(ai, bj, At, Bt) do { __builtin_amdgcn_s_setprio(1); _Pragma("unroll") for (int m = 0; m < 4; ++m) _Pragma("unroll") for (int n = 0; n < 2; ++n) _Pragma("unroll") for (int k = 0; k < 2; ++k) \
;         acc[ai][bj][m][n] = __builtin_amdgcn_mfma_f32_16x16x32_bf16(Bt[n][k], At[m][k], acc[ai][bj][m][n], 0, 0, 0); __builtin_amdgcn_s_setprio(0); } while (0)
; #define PG8_WAIT_V(n) asm volatile("s_waitcnt vmcnt(" #n ")" ::: "memory")
; #define PG8_WAIT_L(n) asm volatile("s_waitcnt lgkmcnt(" #n ")" ::: "memory")
; #define PG8_BAR __builtin_amdgcn_s_barrier()
; #define PG8_SCHED __builtin_amdgcn_sched_barrier(0)
; template <class Epi, class Sched, bool ALIGN_EPI = false, bool SP2 = false>
; __device__ __forceinline__ void gemm_phase(PG8_LAS unsigned char* lds, const Gemm g, const Sched& S, const Epi& E) {
;     ...
;             PG8_LDB(B0, 1, 0); PG8_LDB(B1, 1, 1); PG8_SCHED; PG8_LDA(At, 1, 0); PG8_STAGE(PG8_SA(0, 1), a2 + hstep, voffA);
;             PG8_WAIT_V(8); PG8_WAIT_L(0); PG8_BAR; PG8_MMA(0, 0, At, B0); PG8_MMA(0, 1, At, B1); PG8_BAR; PG8_SCHED;
	s_add_i32 s52, 0, 0x18000
	v_add_u32_e32 v157, s52, v154
	s_add_i32 s53, 0, 0x1c000
	ds_read_b128 v[142:145], v157
	ds_read_b128 v[146:149], v157 offset:1024
	ds_read_b128 v[150:153], v157 offset:2048
	ds_read_b128 v[158:161], v157 offset:3072
	v_add_u32_e32 v157, s53, v154
	ds_read_b128 v[162:165], v157
	ds_read_b128 v[166:169], v157 offset:1024
	ds_read_b128 v[170:173], v157 offset:2048
	ds_read_b128 v[174:177], v157 offset:3072
	s_add_u32 s20, s26, 0xb0000
	s_addc_u32 s21, s27, 0
	s_mov_b32 m0, s39
	v_lshl_add_u64 v[222:223], s[20:21], 0, v[130:131]
	ds_read_b128 v[180:183], v156 offset:32768
	ds_read_b128 v[186:189], v156 offset:33792
	ds_read_b128 v[190:193], v156 offset:34816
	ds_read_b128 v[194:197], v156 offset:35840
	ds_read_b128 v[198:201], v156 offset:36864
	ds_read_b128 v[202:205], v156 offset:37888
	ds_read_b128 v[206:209], v156 offset:38912
	ds_read_b128 v[210:213], v156 offset:39936
	global_load_lds_dwordx4 v[222:223], off
	v_lshl_add_u64 v[222:223], s[20:21], 0, v[134:135]
	s_mov_b32 m0, s40
	s_nop 0
	global_load_lds_dwordx4 v[222:223], off
	s_waitcnt vmcnt(8) lgkmcnt(0)
	s_barrier
	s_setprio 1
	v_mfma_f32_16x16x32_bf16 v[126:129], v[142:145], v[180:183], v[126:129]
	v_mfma_f32_16x16x32_bf16 v[122:125], v[150:153], v[180:183], v[122:125]
	v_mfma_f32_16x16x32_bf16 v[114:117], v[142:145], v[190:193], v[114:117]
	v_mfma_f32_16x16x32_bf16 v[106:109], v[150:153], v[190:193], v[106:109]
	v_mfma_f32_16x16x32_bf16 v[98:101], v[142:145], v[198:201], v[98:101]
	v_mfma_f32_16x16x32_bf16 v[90:93], v[150:153], v[198:201], v[90:93]
	v_mfma_f32_16x16x32_bf16 v[82:85], v[142:145], v[206:209], v[82:85]
	v_mfma_f32_16x16x32_bf16 v[74:77], v[150:153], v[206:209], v[74:77]
	v_mfma_f32_16x16x32_bf16 v[126:129], v[146:149], v[186:189], v[126:129]
	v_mfma_f32_16x16x32_bf16 v[122:125], v[158:161], v[186:189], v[122:125]
	v_mfma_f32_16x16x32_bf16 v[114:117], v[146:149], v[194:197], v[114:117]
	v_mfma_f32_16x16x32_bf16 v[106:109], v[158:161], v[194:197], v[106:109]
	v_mfma_f32_16x16x32_bf16 v[98:101], v[146:149], v[202:205], v[98:101]
	v_mfma_f32_16x16x32_bf16 v[90:93], v[158:161], v[202:205], v[90:93]
	v_mfma_f32_16x16x32_bf16 v[82:85], v[146:149], v[210:213], v[82:85]
	v_mfma_f32_16x16x32_bf16 v[74:77], v[158:161], v[210:213], v[74:77]
	s_setprio 0
	s_setprio 1
	v_mfma_f32_16x16x32_bf16 v[118:121], v[162:165], v[180:183], v[118:121]
	v_mfma_f32_16x16x32_bf16 v[110:113], v[170:173], v[180:183], v[110:113]
	v_mfma_f32_16x16x32_bf16 v[102:105], v[162:165], v[190:193], v[102:105]
	v_mfma_f32_16x16x32_bf16 v[94:97], v[170:173], v[190:193], v[94:97]
	v_mfma_f32_16x16x32_bf16 v[86:89], v[162:165], v[198:201], v[86:89]
	v_mfma_f32_16x16x32_bf16 v[78:81], v[170:173], v[198:201], v[78:81]
	v_mfma_f32_16x16x32_bf16 v[70:73], v[162:165], v[206:209], v[70:73]
	v_mfma_f32_16x16x32_bf16 v[66:69], v[170:173], v[206:209], v[66:69]
	v_mfma_f32_16x16x32_bf16 v[118:121], v[166:169], v[186:189], v[118:121]
	v_mfma_f32_16x16x32_bf16 v[110:113], v[174:177], v[186:189], v[110:113]
	v_mfma_f32_16x16x32_bf16 v[102:105], v[166:169], v[194:197], v[102:105]
	v_mfma_f32_16x16x32_bf16 v[94:97], v[174:177], v[194:197], v[94:97]
	v_mfma_f32_16x16x32_bf16 v[86:89], v[166:169], v[202:205], v[86:89]
	v_mfma_f32_16x16x32_bf16 v[78:81], v[174:177], v[202:205], v[78:81]
	v_mfma_f32_16x16x32_bf16 v[70:73], v[166:169], v[210:213], v[70:73]
	v_mfma_f32_16x16x32_bf16 v[66:69], v[174:177], v[210:213], v[66:69]
	s_setprio 0
	s_barrier
; #define PG8_STAGE(bufoff, gbase, voff) do { _Pragma("unroll") for (int _i = 0; _i < 2; ++_i) \
;         __builtin_amdgcn_global_load_lds((const unsigned*)((const char*)(gbase) + (voff)[_i]), (PG8_LAS unsigned*)(lds + (bufoff) + ldsw + _i * 8192), 16, 0, 0); } while (0)
; #define PG8_LDA(dst, b, h) do { _Pragma("unroll") for (int m = 0; m < 4; ++m) _Pragma("unroll") for (int k = 0; k < 2; ++k) dst[m][k] = *(const PG8_LAS bf16x8*)(lds + PG8_SA(b, h) + aoff + m * 2048 + k * 1024); } while (0)
; #define PG8_WAIT_V(n) asm volatile("s_waitcnt vmcnt(" #n ")" ::: "memory")
; #define PG8_WAIT_L(n) asm volatile("s_waitcnt lgkmcnt(" #n ")" ::: "memory")
; template <class Epi, class Sched, bool ALIGN_EPI = false, bool SP2 = false>
; __device__ __forceinline__ void gemm_phase(PG8_LAS unsigned char* lds, const Gemm g, const Sched& S, const Epi& E) {
;     ...
;         for (int t = 0; t < nt; t += 2) {
;             const bool last = (t == nt - 2);
;             const char* a1 = cA + (size_t)(t + 1) * kstep;
;             const char* a2 = last ? nA : cA + (size_t)(t + 2) * kstep; const char* b2 = last ? nB : cB + (size_t)(t + 2) * kstep;
;             const char* a3 = a2 + kstep; const char* b3 = b2 + kstep;
;             if (last && has_next) S.a_ready(nxt);
;             if constexpr (SP2) {
;             PG8_LDB(B0, 0, 0); PG8_LDB(B1, 0, 1); PG8_SCHED; PG8_LDA(At, 0, 0); PG8_STAGE(PG8_SA(1, 1), a1 + hstep, voffA);
;             PG8_WAIT_V(8); PG8_WAIT_L(0); PG8_BAR; PG8_MMA(0, 0, At, B0); PG8_MMA(0, 1, At, B1); PG8_BAR; PG8_SCHED;
;             PG8_LDA(At, 0, 1); PG8_STAGE(PG8_SB(0, 0), b2, voffB); PG8_STAGE(PG8_SB(0, 1), b2 + hstep, voffB); PG8_STAGE(PG8_SA(0, 0), a2, voffA);
;             PG8_WAIT_V(8); PG8_WAIT_L(0); PG8_BAR; PG8_MMA(1, 0, At, B0); PG8_MMA(1, 1, At, B1); PG8_BAR; PG8_SCHED;
;             PG8_LDB(B0, 1, 0); PG8_LDB(B1, 1, 1); PG8_SCHED; PG8_LDA(At, 1, 0); PG8_STAGE(PG8_SA(0, 1), a2 + hstep, voffA);
;             PG8_WAIT_V(8); PG8_WAIT_L(0); PG8_BAR; PG8_MMA(0, 0, At, B0); PG8_MMA(0, 1, At, B1); PG8_BAR; PG8_SCHED;
;             PG8_LDA(At, 1, 1); PG8_STAGE(PG8_SB(1, 0), b3, voffB); PG8_STAGE(PG8_SB(1, 1), b3 + hstep, voffB); PG8_STAGE(PG8_SA(1, 0), a3, voffA);
;             PG8_WAIT_V(8); PG8_WAIT_L(0); PG8_BAR; PG8_MMA(1, 0, At, B0); PG8_MMA(1, 1, At, B1); PG8_BAR; PG8_SCHED;
;     ...
;         if constexpr (ALIGN_EPI) { if (wr == 0) PG8_BAR; }
	s_add_i32 s20, s52, s36
	v_lshl_add_u64 v[214:215], v[214:215], 0, s[80:81]
	s_mov_b32 m0, s20
	ds_read_b128 v[180:183], v156 offset:49152
	ds_read_b128 v[186:189], v156 offset:50176
	ds_read_b128 v[190:193], v156 offset:51200
	ds_read_b128 v[194:197], v156 offset:52224
	ds_read_b128 v[198:201], v156 offset:53248
	ds_read_b128 v[202:205], v156 offset:54272
	ds_read_b128 v[206:209], v156 offset:55296
	ds_read_b128 v[210:213], v156 offset:56320
	global_load_lds_dwordx4 v[214:215], off
	s_add_i32 m0, s20, 0x2000
	s_add_u32 s20, s24, 0xb0080
	v_lshl_add_u64 v[214:215], v[216:217], 0, s[80:81]
	s_addc_u32 s21, s25, 0
	s_add_i32 s24, s53, s36
	global_load_lds_dwordx4 v[214:215], off
	v_lshl_add_u64 v[214:215], s[20:21], 0, v[132:133]
	s_mov_b32 m0, s24
	s_nop 0
	global_load_lds_dwordx4 v[214:215], off
	v_lshl_add_u64 v[214:215], s[20:21], 0, v[136:137]
	s_add_i32 m0, s24, 0x2000
	s_nop 0
	global_load_lds_dwordx4 v[214:215], off
	v_lshl_add_u64 v[214:215], v[218:219], 0, s[80:81]
	s_mov_b32 m0, s41
	s_nop 0
	global_load_lds_dwordx4 v[214:215], off
	v_lshl_add_u64 v[214:215], v[220:221], 0, s[80:81]
	s_mov_b32 m0, s42
	s_nop 0
	global_load_lds_dwordx4 v[214:215], off
	s_waitcnt vmcnt(8) lgkmcnt(0)
	s_barrier
	s_setprio 1
	v_mfma_f32_16x16x32_bf16 v[62:65], v[142:145], v[180:183], v[62:65]
	v_mfma_f32_16x16x32_bf16 v[58:61], v[150:153], v[180:183], v[58:61]
	v_mfma_f32_16x16x32_bf16 v[50:53], v[142:145], v[190:193], v[50:53]
	v_mfma_f32_16x16x32_bf16 v[42:45], v[150:153], v[190:193], v[42:45]
	v_mfma_f32_16x16x32_bf16 v[34:37], v[142:145], v[198:201], v[34:37]
	v_mfma_f32_16x16x32_bf16 v[26:29], v[150:153], v[198:201], v[26:29]
	v_mfma_f32_16x16x32_bf16 v[18:21], v[142:145], v[206:209], v[18:21]
	v_mfma_f32_16x16x32_bf16 v[10:13], v[150:153], v[206:209], v[10:13]
	v_mfma_f32_16x16x32_bf16 v[62:65], v[146:149], v[186:189], v[62:65]
	v_mfma_f32_16x16x32_bf16 v[58:61], v[158:161], v[186:189], v[58:61]
	v_mfma_f32_16x16x32_bf16 v[50:53], v[146:149], v[194:197], v[50:53]
	v_mfma_f32_16x16x32_bf16 v[42:45], v[158:161], v[194:197], v[42:45]
	v_mfma_f32_16x16x32_bf16 v[34:37], v[146:149], v[202:205], v[34:37]
	v_mfma_f32_16x16x32_bf16 v[26:29], v[158:161], v[202:205], v[26:29]
	v_mfma_f32_16x16x32_bf16 v[18:21], v[146:149], v[210:213], v[18:21]
	v_mfma_f32_16x16x32_bf16 v[10:13], v[158:161], v[210:213], v[10:13]
	s_setprio 0
	s_setprio 1
	v_mfma_f32_16x16x32_bf16 v[54:57], v[162:165], v[180:183], v[54:57]
	v_mfma_f32_16x16x32_bf16 v[46:49], v[170:173], v[180:183], v[46:49]
	v_mfma_f32_16x16x32_bf16 v[38:41], v[162:165], v[190:193], v[38:41]
	v_mfma_f32_16x16x32_bf16 v[30:33], v[170:173], v[190:193], v[30:33]
	v_mfma_f32_16x16x32_bf16 v[22:25], v[162:165], v[198:201], v[22:25]
	v_mfma_f32_16x16x32_bf16 v[14:17], v[170:173], v[198:201], v[14:17]
	v_mfma_f32_16x16x32_bf16 v[6:9], v[162:165], v[206:209], v[6:9]
	v_mfma_f32_16x16x32_bf16 v[2:5], v[170:173], v[206:209], v[2:5]
	v_mfma_f32_16x16x32_bf16 v[54:57], v[166:169], v[186:189], v[54:57]
	v_mfma_f32_16x16x32_bf16 v[46:49], v[174:177], v[186:189], v[46:49]
	v_mfma_f32_16x16x32_bf16 v[38:41], v[166:169], v[194:197], v[38:41]
	v_mfma_f32_16x16x32_bf16 v[30:33], v[174:177], v[194:197], v[30:33]
	v_mfma_f32_16x16x32_bf16 v[22:25], v[166:169], v[202:205], v[22:25]
	v_mfma_f32_16x16x32_bf16 v[14:17], v[174:177], v[202:205], v[14:17]
	v_mfma_f32_16x16x32_bf16 v[6:9], v[166:169], v[210:213], v[6:9]
	v_mfma_f32_16x16x32_bf16 v[2:5], v[174:177], v[210:213], v[2:5]
	s_setprio 0
	s_barrier
	s_add_i32 s51, s51, 2
	s_add_u32 s49, s49, 0x100
	s_addc_u32 s50, s50, 0
	s_cmp_gt_u32 s51, 41
	s_mov_b64 s[20:21], s[22:23]
	s_cbranch_scc0 .LBB0_1330
	s_and_b64 vcc, exec, s[16:17]
	s_cbranch_vccz .LBB0_1333
	s_barrier

; #define PG8_STAGE(bufoff, gbase, voff) do { _Pragma("unroll") for (int _i = 0; _i < 2; ++_i) \
;         __builtin_amdgcn_global_load_lds((const unsigned*)((const char*)(gbase) + (voff)[_i]), (PG8_LAS unsigned*)(lds + (bufoff) + ldsw + _i * 8192), 16, 0, 0); } while (0)
; #define PG8_LDA(dst, b, h) do { _Pragma("unroll") for (int m = 0; m < 4; ++m) _Pragma("unroll") for (int k = 0; k < 2; ++k) dst[m][k] = *(const PG8_LAS bf16x8*)(lds + PG8_SA(b, h) + aoff + m * 2048 + k * 1024); } while (0)
; template <class Epi, class Sched, bool ALIGN_EPI = false, bool SP2 = false>
; __device__ __forceinline__ void gemm_phase(PG8_LAS unsigned char* lds, const Gemm g, const Sched& S, const Epi& E) {
;     ...
;         const bool has_next = S.next(ui + 1, nxt);
;         const char* nA = has_next ? (const char*)g.A + (size_t)nxt.pm * tstep : cA; const char* nB = has_next ? (const char*)g.Bt + (size_t)nxt.pn * tstep : cB;
;         for (int t = 0; t < nt; t += 2) {
;             const bool last = (t == nt - 2);
;             const char* a1 = cA + (size_t)(t + 1) * kstep;
;             const char* a2 = last ? nA : cA + (size_t)(t + 2) * kstep; const char* b2 = last ? nB : cB + (size_t)(t + 2) * kstep;
;             const char* a3 = a2 + kstep; const char* b3 = b2 + kstep;
;             if (last && has_next) S.a_ready(nxt);
;             if constexpr (SP2) {
;             PG8_LDB(B0, 0, 0); PG8_LDB(B1, 0, 1); PG8_SCHED; PG8_LDA(At, 0, 0); PG8_STAGE(PG8_SA(1, 1), a1 + hstep, voffA);
;             PG8_WAIT_V(8); PG8_WAIT_L(0); PG8_BAR; PG8_MMA(0, 0, At, B0); PG8_MMA(0, 1, At, B1); PG8_BAR; PG8_SCHED;
;             PG8_LDA(At, 0, 1); PG8_STAGE(PG8_SB(0, 0), b2, voffB); PG8_STAGE(PG8_SB(0, 1), b2 + hstep, voffB); PG8_STAGE(PG8_SA(0, 0), a2, voffA);
;             PG8_WAIT_V(8); PG8_WAIT_L(0); PG8_BAR; PG8_MMA(1, 0, At, B0); PG8_MMA(1, 1, At, B1); PG8_BAR; PG8_SCHED;
;             PG8_LDB(B0, 1, 0); PG8_LDB(B1, 1, 1); PG8_SCHED; PG8_LDA(At, 1, 0); PG8_STAGE(PG8_SA(0, 1), a2 + hstep, voffA);
;             PG8_WAIT_V(8); PG8_WAIT_L(0); PG8_BAR; PG8_MMA(0, 0, At, B0); PG8_MMA(0, 1, At, B1); PG8_BAR; PG8_SCHED;
;             PG8_LDA(At, 1, 1); PG8_STAGE(PG8_SB(1, 0), b3, voffB); PG8_STAGE(PG8_SB(1, 1), b3 + hstep, voffB); PG8_STAGE(PG8_SA(1, 0), a3, voffA);
;             PG8_WAIT_V(8); PG8_WAIT_L(0); PG8_BAR; PG8_MMA(1, 0, At, B0); PG8_MMA(1, 1, At, B1); PG8_BAR; PG8_SCHED;
.LBB0_1359:
	s_add_u32 s47, s20, 0x100
	s_addc_u32 s48, s21, 0
	s_mov_b32 s49, -2
	s_add_u32 s20, s18, 0x100
	s_addc_u32 s21, s19, 0
	s_add_i32 s50, 0, 0x10000
	s_cmp_eq_u32 s49, 40
	s_cselect_b32 s25, s7, s21
	s_cselect_b32 s24, s6, s20
	v_add_u32_e32 v146, s50, v148
	s_cselect_b32 s23, s17, s48
	s_cselect_b32 s22, s16, s47
	s_add_i32 s51, 0, 0x14000
	ds_read_b128 v[142:145], v146
	ds_read_b128 v[152:155], v146 offset:1024
	ds_read_b128 v[156:159], v146 offset:2048
	ds_read_b128 v[160:163], v146 offset:3072
	v_add_u32_e32 v146, s51, v148
	ds_read_b128 v[164:167], v146
	ds_read_b128 v[168:171], v146 offset:1024
	ds_read_b128 v[172:175], v146 offset:2048
	ds_read_b128 v[180:183], v146 offset:3072
	v_lshl_add_u64 v[146:147], s[18:19], 0, v[138:139]
	s_add_i32 m0, s33, 0xc000
	ds_read_b128 v[186:189], v150
	ds_read_b128 v[190:193], v150 offset:1024
	ds_read_b128 v[194:197], v150 offset:2048
	ds_read_b128 v[198:201], v150 offset:3072
	ds_read_b128 v[202:205], v150 offset:4096
	ds_read_b128 v[206:209], v150 offset:5120
	ds_read_b128 v[210:213], v150 offset:6144
	ds_read_b128 v[214:217], v150 offset:7168
	global_load_lds_dwordx4 v[146:147], off
	v_lshl_add_u64 v[146:147], s[18:19], 0, v[140:141]
	s_add_i32 m0, s33, 0xe000
	s_nop 0
	global_load_lds_dwordx4 v[146:147], off
	s_waitcnt vmcnt(8) lgkmcnt(0)
	s_barrier
	s_setprio 1
	v_mfma_f32_16x16x32_bf16 v[126:129], v[142:145], v[186:189], 0
	v_mfma_f32_16x16x32_bf16 v[122:125], v[156:159], v[186:189], 0
	v_mfma_f32_16x16x32_bf16 v[114:117], v[142:145], v[194:197], 0
	v_mfma_f32_16x16x32_bf16 v[106:109], v[156:159], v[194:197], 0
	v_mfma_f32_16x16x32_bf16 v[98:101], v[142:145], v[202:205], 0
	v_mfma_f32_16x16x32_bf16 v[90:93], v[156:159], v[202:205], 0
	v_mfma_f32_16x16x32_bf16 v[82:85], v[142:145], v[210:213], 0
	v_mfma_f32_16x16x32_bf16 v[74:77], v[156:159], v[210:213], 0
	v_mfma_f32_16x16x32_bf16 v[126:129], v[152:155], v[190:193], v[126:129]
	v_mfma_f32_16x16x32_bf16 v[122:125], v[160:163], v[190:193], v[122:125]
	v_mfma_f32_16x16x32_bf16 v[114:117], v[152:155], v[198:201], v[114:117]
	v_mfma_f32_16x16x32_bf16 v[106:109], v[160:163], v[198:201], v[106:109]
	v_mfma_f32_16x16x32_bf16 v[98:101], v[152:155], v[206:209], v[98:101]
	v_mfma_f32_16x16x32_bf16 v[90:93], v[160:163], v[206:209], v[90:93]
	v_mfma_f32_16x16x32_bf16 v[82:85], v[152:155], v[214:217], v[82:85]
	v_mfma_f32_16x16x32_bf16 v[74:77], v[160:163], v[214:217], v[74:77]
	s_setprio 0
	s_setprio 1
	v_mfma_f32_16x16x32_bf16 v[118:121], v[164:167], v[186:189], 0
	v_mfma_f32_16x16x32_bf16 v[110:113], v[172:175], v[186:189], 0
	v_mfma_f32_16x16x32_bf16 v[102:105], v[164:167], v[194:197], 0
	v_mfma_f32_16x16x32_bf16 v[94:97], v[172:175], v[194:197], 0
	v_mfma_f32_16x16x32_bf16 v[86:89], v[164:167], v[202:205], 0
	v_mfma_f32_16x16x32_bf16 v[78:81], v[172:175], v[202:205], 0
	v_mfma_f32_16x16x32_bf16 v[70:73], v[164:167], v[210:213], 0
	v_mfma_f32_16x16x32_bf16 v[66:69], v[172:175], v[210:213], 0
	v_mfma_f32_16x16x32_bf16 v[118:121], v[168:171], v[190:193], v[118:121]
	v_mfma_f32_16x16x32_bf16 v[110:113], v[180:183], v[190:193], v[110:113]
	v_mfma_f32_16x16x32_bf16 v[102:105], v[168:171], v[198:201], v[102:105]
	v_mfma_f32_16x16x32_bf16 v[94:97], v[180:183], v[198:201], v[94:97]
	v_mfma_f32_16x16x32_bf16 v[86:89], v[168:171], v[206:209], v[86:89]
	v_mfma_f32_16x16x32_bf16 v[78:81], v[180:183], v[206:209], v[78:81]
	v_mfma_f32_16x16x32_bf16 v[70:73], v[168:171], v[214:217], v[70:73]
	v_mfma_f32_16x16x32_bf16 v[66:69], v[180:183], v[214:217], v[66:69]
	s_setprio 0
	s_barrier
	s_add_i32 s18, s50, s27
	v_lshl_add_u64 v[146:147], s[22:23], 0, v[132:133]
	s_mov_b32 m0, s18
	ds_read_b128 v[186:189], v150 offset:16384
	ds_read_b128 v[190:193], v150 offset:17408
	ds_read_b128 v[194:197], v150 offset:18432
	ds_read_b128 v[198:201], v150 offset:19456
	ds_read_b128 v[202:205], v150 offset:20480
	ds_read_b128 v[206:209], v150 offset:21504
	ds_read_b128 v[210:213], v150 offset:22528
	ds_read_b128 v[214:217], v150 offset:23552
	global_load_lds_dwordx4 v[146:147], off
	s_add_i32 m0, s18, 0x2000
	s_add_u32 s18, s22, 0xb0000
	v_lshl_add_u64 v[176:177], s[22:23], 0, v[136:137]
	s_addc_u32 s19, s23, 0
	s_add_i32 s50, s51, s27
	global_load_lds_dwordx4 v[176:177], off
	v_lshl_add_u64 v[218:219], s[18:19], 0, v[132:133]
	s_mov_b32 m0, s50
	v_lshl_add_u64 v[220:221], s[24:25], 0, v[134:135]
	global_load_lds_dwordx4 v[218:219], off
	v_lshl_add_u64 v[218:219], s[18:19], 0, v[136:137]
	s_add_i32 m0, s50, 0x2000
	s_nop 0
	global_load_lds_dwordx4 v[218:219], off
	v_lshl_add_u64 v[218:219], s[24:25], 0, v[130:131]
	s_mov_b32 m0, s33
	s_nop 0
	global_load_lds_dwordx4 v[218:219], off
	s_mov_b32 m0, s36
	s_nop 0
	global_load_lds_dwordx4 v[220:221], off
	s_waitcnt vmcnt(8) lgkmcnt(0)
	s_barrier
; #define PG8_STAGE(bufoff, gbase, voff) do { _Pragma("unroll") for (int _i = 0; _i < 2; ++_i) \
;         __builtin_amdgcn_global_load_lds((const unsigned*)((const char*)(gbase) + (voff)[_i]), (PG8_LAS unsigned*)(lds + (bufoff) + ldsw + _i * 8192), 16, 0, 0); } while (0)
; #define PG8_LDA(dst, b, h) do { _Pragma("unroll") for (int m = 0; m < 4; ++m) _Pragma("unroll") for (int k = 0; k < 2; ++k) dst[m][k] = *(const PG8_LAS bf16x8*)(lds + PG8_SA(b, h) + aoff + m * 2048 + k * 1024); } while (0)
; #define PG8_LDB(dst, b, h) do { _Pragma("unroll") for (int n = 0; n < 2; ++n) _Pragma("unroll") for (int k = 0; k < 2; ++k) dst[n][k] = *(const PG8_LAS bf16x8*)(lds + PG8_SB(b, h) + boff + n * 2048 + k * 1024); } while (0)
; #define PG8_MMA(ai, bj, At, Bt) do { __builtin_amdgcn_s_setprio(1); _Pragma("unroll") for (int m = 0; m < 4; ++m) _Pragma("unroll") for (int n = 0; n < 2; ++n) _Pragma("unroll") for (int k = 0; k < 2; ++k) \
;         acc[ai][bj][m][n] = __builtin_amdgcn_mfma_f32_16x16x32_bf16(Bt[n][k], At[m][k], acc[ai][bj][m][n], 0, 0, 0); __builtin_amdgcn_s_setprio(0); } while (0)
; #define PG8_WAIT_V(n) asm volatile("s_waitcnt vmcnt(" #n ")" ::: "memory")
; #define PG8_WAIT_L(n) asm volatile("s_waitcnt lgkmcnt(" #n ")" ::: "memory")
; #define PG8_BAR __builtin_amdgcn_s_barrier()
; #define PG8_SCHED __builtin_amdgcn_sched_barrier(0)
; template <class Epi, class Sched, bool ALIGN_EPI = false, bool SP2 = false>
; __device__ __forceinline__ void gemm_phase(PG8_LAS unsigned char* lds, const Gemm g, const Sched& S, const Epi& E) {
;     ...
;             if constexpr (SP2) {
;             PG8_LDB(B0, 0, 0); PG8_LDB(B1, 0, 1); PG8_SCHED; PG8_LDA(At, 0, 0); PG8_STAGE(PG8_SA(1, 1), a1 + hstep, voffA);
;             PG8_WAIT_V(8); PG8_WAIT_L(0); PG8_BAR; PG8_MMA(0, 0, At, B0); PG8_MMA(0, 1, At, B1); PG8_BAR; PG8_SCHED;
;             PG8_LDA(At, 0, 1); PG8_STAGE(PG8_SB(0, 0), b2, voffB); PG8_STAGE(PG8_SB(0, 1), b2 + hstep, voffB); PG8_STAGE(PG8_SA(0, 0), a2, voffA);
;             PG8_WAIT_V(8); PG8_WAIT_L(0); PG8_BAR; PG8_MMA(1, 0, At, B0); PG8_MMA(1, 1, At, B1); PG8_BAR; PG8_SCHED;
;             PG8_LDB(B0, 1, 0); PG8_LDB(B1, 1, 1); PG8_SCHED; PG8_LDA(At, 1, 0); PG8_STAGE(PG8_SA(0, 1), a2 + hstep, voffA);
;             PG8_WAIT_V(8); PG8_WAIT_L(0); PG8_BAR; PG8_MMA(0, 0, At, B0); PG8_MMA(0, 1, At, B1); PG8_BAR; PG8_SCHED;
	s_setprio 1
	v_mfma_f32_16x16x32_bf16 v[62:65], v[142:145], v[186:189], 0
	v_mfma_f32_16x16x32_bf16 v[58:61], v[156:159], v[186:189], 0
	v_mfma_f32_16x16x32_bf16 v[50:53], v[142:145], v[194:197], 0
	v_mfma_f32_16x16x32_bf16 v[42:45], v[156:159], v[194:197], 0
	v_mfma_f32_16x16x32_bf16 v[34:37], v[142:145], v[202:205], 0
	v_mfma_f32_16x16x32_bf16 v[26:29], v[156:159], v[202:205], 0
	v_mfma_f32_16x16x32_bf16 v[18:21], v[142:145], v[210:213], 0
	v_mfma_f32_16x16x32_bf16 v[10:13], v[156:159], v[210:213], 0
	v_mfma_f32_16x16x32_bf16 v[62:65], v[152:155], v[190:193], v[62:65]
	v_mfma_f32_16x16x32_bf16 v[58:61], v[160:163], v[190:193], v[58:61]
	v_mfma_f32_16x16x32_bf16 v[50:53], v[152:155], v[198:201], v[50:53]
	v_mfma_f32_16x16x32_bf16 v[42:45], v[160:163], v[198:201], v[42:45]
	v_mfma_f32_16x16x32_bf16 v[34:37], v[152:155], v[206:209], v[34:37]
	v_mfma_f32_16x16x32_bf16 v[26:29], v[160:163], v[206:209], v[26:29]
	v_mfma_f32_16x16x32_bf16 v[18:21], v[152:155], v[214:217], v[18:21]
	v_mfma_f32_16x16x32_bf16 v[10:13], v[160:163], v[214:217], v[10:13]
	s_setprio 0
	s_setprio 1
	v_mfma_f32_16x16x32_bf16 v[54:57], v[164:167], v[186:189], 0
	v_mfma_f32_16x16x32_bf16 v[46:49], v[172:175], v[186:189], 0
	v_mfma_f32_16x16x32_bf16 v[38:41], v[164:167], v[194:197], 0
	v_mfma_f32_16x16x32_bf16 v[30:33], v[172:175], v[194:197], 0
	v_mfma_f32_16x16x32_bf16 v[22:25], v[164:167], v[202:205], 0
	v_mfma_f32_16x16x32_bf16 v[14:17], v[172:175], v[202:205], 0
	v_mfma_f32_16x16x32_bf16 v[6:9], v[164:167], v[210:213], 0
	v_mfma_f32_16x16x32_bf16 v[2:5], v[172:175], v[210:213], 0
	v_mfma_f32_16x16x32_bf16 v[54:57], v[168:171], v[190:193], v[54:57]
	v_mfma_f32_16x16x32_bf16 v[46:49], v[180:183], v[190:193], v[46:49]
	v_mfma_f32_16x16x32_bf16 v[38:41], v[168:171], v[198:201], v[38:41]
	v_mfma_f32_16x16x32_bf16 v[30:33], v[180:183], v[198:201], v[30:33]
	v_mfma_f32_16x16x32_bf16 v[22:25], v[168:171], v[206:209], v[22:25]
	v_mfma_f32_16x16x32_bf16 v[14:17], v[180:183], v[206:209], v[14:17]
	v_mfma_f32_16x16x32_bf16 v[6:9], v[168:171], v[214:217], v[6:9]
	v_mfma_f32_16x16x32_bf16 v[2:5], v[180:183], v[214:217], v[2:5]
	s_setprio 0
	s_barrier
	s_add_i32 s50, 0, 0x18000
	v_add_u32_e32 v151, s50, v148
	s_add_i32 s51, 0, 0x1c000
	ds_read_b128 v[142:145], v151
	ds_read_b128 v[152:155], v151 offset:1024
	ds_read_b128 v[156:159], v151 offset:2048
	ds_read_b128 v[160:163], v151 offset:3072
	v_add_u32_e32 v151, s51, v148
	ds_read_b128 v[164:167], v151
	ds_read_b128 v[168:171], v151 offset:1024
	ds_read_b128 v[172:175], v151 offset:2048
	ds_read_b128 v[180:183], v151 offset:3072
	s_add_u32 s18, s24, 0xb0000
	s_addc_u32 s19, s25, 0
	s_mov_b32 m0, s37
	v_lshl_add_u64 v[222:223], s[18:19], 0, v[130:131]
	ds_read_b128 v[186:189], v150 offset:32768
	ds_read_b128 v[190:193], v150 offset:33792
	ds_read_b128 v[194:197], v150 offset:34816
	ds_read_b128 v[198:201], v150 offset:35840
	ds_read_b128 v[202:205], v150 offset:36864
	ds_read_b128 v[206:209], v150 offset:37888
	ds_read_b128 v[210:213], v150 offset:38912
	ds_read_b128 v[214:217], v150 offset:39936
	global_load_lds_dwordx4 v[222:223], off
	v_lshl_add_u64 v[222:223], s[18:19], 0, v[134:135]
	s_mov_b32 m0, s38
	s_nop 0
	global_load_lds_dwordx4 v[222:223], off
	s_waitcnt vmcnt(8) lgkmcnt(0)
	s_barrier
	s_setprio 1
	v_mfma_f32_16x16x32_bf16 v[126:129], v[142:145], v[186:189], v[126:129]
	v_mfma_f32_16x16x32_bf16 v[122:125], v[156:159], v[186:189], v[122:125]
	v_mfma_f32_16x16x32_bf16 v[114:117], v[142:145], v[194:197], v[114:117]
	v_mfma_f32_16x16x32_bf16 v[106:109], v[156:159], v[194:197], v[106:109]
	v_mfma_f32_16x16x32_bf16 v[98:101], v[142:145], v[202:205], v[98:101]
	v_mfma_f32_16x16x32_bf16 v[90:93], v[156:159], v[202:205], v[90:93]
	v_mfma_f32_16x16x32_bf16 v[82:85], v[142:145], v[210:213], v[82:85]
	v_mfma_f32_16x16x32_bf16 v[74:77], v[156:159], v[210:213], v[74:77]
	v_mfma_f32_16x16x32_bf16 v[126:129], v[152:155], v[190:193], v[126:129]
	v_mfma_f32_16x16x32_bf16 v[122:125], v[160:163], v[190:193], v[122:125]
	v_mfma_f32_16x16x32_bf16 v[114:117], v[152:155], v[198:201], v[114:117]
	v_mfma_f32_16x16x32_bf16 v[106:109], v[160:163], v[198:201], v[106:109]
	v_mfma_f32_16x16x32_bf16 v[98:101], v[152:155], v[206:209], v[98:101]
	v_mfma_f32_16x16x32_bf16 v[90:93], v[160:163], v[206:209], v[90:93]
	v_mfma_f32_16x16x32_bf16 v[82:85], v[152:155], v[214:217], v[82:85]
	v_mfma_f32_16x16x32_bf16 v[74:77], v[160:163], v[214:217], v[74:77]
	s_setprio 0
	s_setprio 1
	v_mfma_f32_16x16x32_bf16 v[118:121], v[164:167], v[186:189], v[118:121]
	v_mfma_f32_16x16x32_bf16 v[110:113], v[172:175], v[186:189], v[110:113]
	v_mfma_f32_16x16x32_bf16 v[102:105], v[164:167], v[194:197], v[102:105]
	v_mfma_f32_16x16x32_bf16 v[94:97], v[172:175], v[194:197], v[94:97]
	v_mfma_f32_16x16x32_bf16 v[86:89], v[164:167], v[202:205], v[86:89]
	v_mfma_f32_16x16x32_bf16 v[78:81], v[172:175], v[202:205], v[78:81]
	v_mfma_f32_16x16x32_bf16 v[70:73], v[164:167], v[210:213], v[70:73]
	v_mfma_f32_16x16x32_bf16 v[66:69], v[172:175], v[210:213], v[66:69]
	v_mfma_f32_16x16x32_bf16 v[118:121], v[168:171], v[190:193], v[118:121]
	v_mfma_f32_16x16x32_bf16 v[110:113], v[180:183], v[190:193], v[110:113]
	v_mfma_f32_16x16x32_bf16 v[102:105], v[168:171], v[198:201], v[102:105]
	v_mfma_f32_16x16x32_bf16 v[94:97], v[180:183], v[198:201], v[94:97]
	v_mfma_f32_16x16x32_bf16 v[86:89], v[168:171], v[206:209], v[86:89]
	v_mfma_f32_16x16x32_bf16 v[78:81], v[180:183], v[206:209], v[78:81]
	v_mfma_f32_16x16x32_bf16 v[70:73], v[168:171], v[214:217], v[70:73]
	v_mfma_f32_16x16x32_bf16 v[66:69], v[180:183], v[214:217], v[66:69]
	s_setprio 0
	s_barrier
; #define PG8_STAGE(bufoff, gbase, voff) do { _Pragma("unroll") for (int _i = 0; _i < 2; ++_i) \
;         __builtin_amdgcn_global_load_lds((const unsigned*)((const char*)(gbase) + (voff)[_i]), (PG8_LAS unsigned*)(lds + (bufoff) + ldsw + _i * 8192), 16, 0, 0); } while (0)
; #define PG8_LDA(dst, b, h) do { _Pragma("unroll") for (int m = 0; m < 4; ++m) _Pragma("unroll") for (int k = 0; k < 2; ++k) dst[m][k] = *(const PG8_LAS bf16x8*)(lds + PG8_SA(b, h) + aoff + m * 2048 + k * 1024); } while (0)
; #define PG8_LDB(dst, b, h) do { _Pragma("unroll") for (int n = 0; n < 2; ++n) _Pragma("unroll") for (int k = 0; k < 2; ++k) dst[n][k] = *(const PG8_LAS bf16x8*)(lds + PG8_SB(b, h) + boff + n * 2048 + k * 1024); } while (0)
; template <class Epi, class Sched, bool ALIGN_EPI = false, bool SP2 = false>
; __device__ __forceinline__ void gemm_phase(PG8_LAS unsigned char* lds, const Gemm g, const Sched& S, const Epi& E) {
;     ...
;         for (int t = 0; t < nt; t += 2) {
;             const bool last = (t == nt - 2);
;             const char* a1 = cA + (size_t)(t + 1) * kstep;
;             const char* a2 = last ? nA : cA + (size_t)(t + 2) * kstep; const char* b2 = last ? nB : cB + (size_t)(t + 2) * kstep;
;             const char* a3 = a2 + kstep; const char* b3 = b2 + kstep;
;             if (last && has_next) S.a_ready(nxt);
;             if constexpr (SP2) {
;             PG8_LDB(B0, 0, 0); PG8_LDB(B1, 0, 1); PG8_SCHED; PG8_LDA(At, 0, 0); PG8_STAGE(PG8_SA(1, 1), a1 + hstep, voffA);
;             PG8_WAIT_V(8); PG8_WAIT_L(0); PG8_BAR; PG8_MMA(0, 0, At, B0); PG8_MMA(0, 1, At, B1); PG8_BAR; PG8_SCHED;
;             PG8_LDA(At, 0, 1); PG8_STAGE(PG8_SB(0, 0), b2, voffB); PG8_STAGE(PG8_SB(0, 1), b2 + hstep, voffB); PG8_STAGE(PG8_SA(0, 0), a2, voffA);
;             PG8_WAIT_V(8); PG8_WAIT_L(0); PG8_BAR; PG8_MMA(1, 0, At, B0); PG8_MMA(1, 1, At, B1); PG8_BAR; PG8_SCHED;
;             PG8_LDB(B0, 1, 0); PG8_LDB(B1, 1, 1); PG8_SCHED; PG8_LDA(At, 1, 0); PG8_STAGE(PG8_SA(0, 1), a2 + hstep, voffA);
;             PG8_WAIT_V(8); PG8_WAIT_L(0); PG8_BAR; PG8_MMA(0, 0, At, B0); PG8_MMA(0, 1, At, B1); PG8_BAR; PG8_SCHED;
;             PG8_LDA(At, 1, 1); PG8_STAGE(PG8_SB(1, 0), b3, voffB); PG8_STAGE(PG8_SB(1, 1), b3 + hstep, voffB); PG8_STAGE(PG8_SA(1, 0), a3, voffA);
;             PG8_WAIT_V(8); PG8_WAIT_L(0); PG8_BAR; PG8_MMA(1, 0, At, B0); PG8_MMA(1, 1, At, B1); PG8_BAR; PG8_SCHED;
	s_add_i32 s18, s50, s27
	v_lshl_add_u64 v[146:147], v[146:147], 0, s[80:81]
	s_mov_b32 m0, s18
	ds_read_b128 v[186:189], v150 offset:49152
	ds_read_b128 v[190:193], v150 offset:50176
	ds_read_b128 v[194:197], v150 offset:51200
	ds_read_b128 v[198:201], v150 offset:52224
	ds_read_b128 v[202:205], v150 offset:53248
	ds_read_b128 v[206:209], v150 offset:54272
	ds_read_b128 v[210:213], v150 offset:55296
	ds_read_b128 v[214:217], v150 offset:56320
	global_load_lds_dwordx4 v[146:147], off
	s_add_i32 m0, s18, 0x2000
	s_add_u32 s18, s22, 0xb0080
	v_lshl_add_u64 v[146:147], v[176:177], 0, s[80:81]
	s_addc_u32 s19, s23, 0
	s_add_i32 s22, s51, s27
	global_load_lds_dwordx4 v[146:147], off
	v_lshl_add_u64 v[146:147], s[18:19], 0, v[132:133]
	s_mov_b32 m0, s22
	s_nop 0
	global_load_lds_dwordx4 v[146:147], off
	v_lshl_add_u64 v[146:147], s[18:19], 0, v[136:137]
	s_add_i32 m0, s22, 0x2000
	s_nop 0
	global_load_lds_dwordx4 v[146:147], off
	v_lshl_add_u64 v[146:147], v[218:219], 0, s[80:81]
	s_mov_b32 m0, s39
	s_nop 0
	global_load_lds_dwordx4 v[146:147], off
	v_lshl_add_u64 v[146:147], v[220:221], 0, s[80:81]
	s_mov_b32 m0, s40
	s_nop 0
	global_load_lds_dwordx4 v[146:147], off
	s_waitcnt vmcnt(8) lgkmcnt(0)
	s_barrier
	s_setprio 1
	v_mfma_f32_16x16x32_bf16 v[62:65], v[142:145], v[186:189], v[62:65]
	v_mfma_f32_16x16x32_bf16 v[58:61], v[156:159], v[186:189], v[58:61]
	v_mfma_f32_16x16x32_bf16 v[50:53], v[142:145], v[194:197], v[50:53]
	v_mfma_f32_16x16x32_bf16 v[42:45], v[156:159], v[194:197], v[42:45]
	v_mfma_f32_16x16x32_bf16 v[34:37], v[142:145], v[202:205], v[34:37]
	v_mfma_f32_16x16x32_bf16 v[26:29], v[156:159], v[202:205], v[26:29]
	v_mfma_f32_16x16x32_bf16 v[18:21], v[142:145], v[210:213], v[18:21]
	v_mfma_f32_16x16x32_bf16 v[10:13], v[156:159], v[210:213], v[10:13]
	v_mfma_f32_16x16x32_bf16 v[62:65], v[152:155], v[190:193], v[62:65]
	v_mfma_f32_16x16x32_bf16 v[58:61], v[160:163], v[190:193], v[58:61]
	v_mfma_f32_16x16x32_bf16 v[50:53], v[152:155], v[198:201], v[50:53]
	v_mfma_f32_16x16x32_bf16 v[42:45], v[160:163], v[198:201], v[42:45]
	v_mfma_f32_16x16x32_bf16 v[34:37], v[152:155], v[206:209], v[34:37]
	v_mfma_f32_16x16x32_bf16 v[26:29], v[160:163], v[206:209], v[26:29]
	v_mfma_f32_16x16x32_bf16 v[18:21], v[152:155], v[214:217], v[18:21]
	v_mfma_f32_16x16x32_bf16 v[10:13], v[160:163], v[214:217], v[10:13]
	s_setprio 0
	s_setprio 1
	v_mfma_f32_16x16x32_bf16 v[54:57], v[164:167], v[186:189], v[54:57]
	v_mfma_f32_16x16x32_bf16 v[46:49], v[172:175], v[186:189], v[46:49]
	v_mfma_f32_16x16x32_bf16 v[38:41], v[164:167], v[194:197], v[38:41]
	v_mfma_f32_16x16x32_bf16 v[30:33], v[172:175], v[194:197], v[30:33]
	v_mfma_f32_16x16x32_bf16 v[22:25], v[164:167], v[202:205], v[22:25]
	v_mfma_f32_16x16x32_bf16 v[14:17], v[172:175], v[202:205], v[14:17]
	v_mfma_f32_16x16x32_bf16 v[6:9], v[164:167], v[210:213], v[6:9]
	v_mfma_f32_16x16x32_bf16 v[2:5], v[172:175], v[210:213], v[2:5]
	v_mfma_f32_16x16x32_bf16 v[54:57], v[168:171], v[190:193], v[54:57]
	v_mfma_f32_16x16x32_bf16 v[46:49], v[180:183], v[190:193], v[46:49]
	v_mfma_f32_16x16x32_bf16 v[38:41], v[168:171], v[198:201], v[38:41]
	v_mfma_f32_16x16x32_bf16 v[30:33], v[180:183], v[198:201], v[30:33]
	v_mfma_f32_16x16x32_bf16 v[22:25], v[168:171], v[206:209], v[22:25]
	v_mfma_f32_16x16x32_bf16 v[14:17], v[180:183], v[206:209], v[14:17]
	v_mfma_f32_16x16x32_bf16 v[6:9], v[168:171], v[214:217], v[6:9]
	v_mfma_f32_16x16x32_bf16 v[2:5], v[180:183], v[214:217], v[2:5]
	s_setprio 0
	s_barrier
	s_add_i32 s49, s49, 2
	s_add_u32 s47, s47, 0x100
	s_addc_u32 s48, s48, 0
	s_cmp_gt_u32 s49, 41
	s_mov_b64 s[18:19], s[20:21]
	s_branch .LBB0_1360
.LBB0_1360:
	s_add_u32 s20, s18, 0x100
	s_addc_u32 s21, s19, 0
	s_add_i32 s50, 0, 0x10000
	s_cmp_eq_u32 s49, 40
	s_cselect_b32 s25, s7, s21
	s_cselect_b32 s24, s6, s20
	v_add_u32_e32 v146, s50, v148
	s_cselect_b32 s23, s17, s48
	s_cselect_b32 s22, s16, s47
	s_add_i32 s51, 0, 0x14000
	ds_read_b128 v[142:145], v146
	ds_read_b128 v[152:155], v146 offset:1024
	ds_read_b128 v[156:159], v146 offset:2048
	ds_read_b128 v[160:163], v146 offset:3072
	v_add_u32_e32 v146, s51, v148
	ds_read_b128 v[164:167], v146
	ds_read_b128 v[168:171], v146 offset:1024
	ds_read_b128 v[172:175], v146 offset:2048
	ds_read_b128 v[180:183], v146 offset:3072
	v_lshl_add_u64 v[146:147], s[18:19], 0, v[138:139]
	s_add_i32 m0, s33, 0xc000
	ds_read_b128 v[186:189], v150
	ds_read_b128 v[190:193], v150 offset:1024
	ds_read_b128 v[194:197], v150 offset:2048
	ds_read_b128 v[198:201], v150 offset:3072
	ds_read_b128 v[202:205], v150 offset:4096
	ds_read_b128 v[206:209], v150 offset:5120
	ds_read_b128 v[210:213], v150 offset:6144
	ds_read_b128 v[214:217], v150 offset:7168
	global_load_lds_dwordx4 v[146:147], off
	v_lshl_add_u64 v[146:147], s[18:19], 0, v[140:141]
	s_add_i32 m0, s33, 0xe000
	s_nop 0
	global_load_lds_dwordx4 v[146:147], off
	s_waitcnt vmcnt(8) lgkmcnt(0)
	s_barrier
; #define PG8_STAGE(bufoff, gbase, voff) do { _Pragma("unroll") for (int _i = 0; _i < 2; ++_i) \
;         __builtin_amdgcn_global_load_lds((const unsigned*)((const char*)(gbase) + (voff)[_i]), (PG8_LAS unsigned*)(lds + (bufoff) + ldsw + _i * 8192), 16, 0, 0); } while (0)
; #define PG8_LDA(dst, b, h) do { _Pragma("unroll") for (int m = 0; m < 4; ++m) _Pragma("unroll") for (int k = 0; k < 2; ++k) dst[m][k] = *(const PG8_LAS bf16x8*)(lds + PG8_SA(b, h) + aoff + m * 2048 + k * 1024); } while (0)
; #define PG8_LDB(dst, b, h) do { _Pragma("unroll") for (int n = 0; n < 2; ++n) _Pragma("unroll") for (int k = 0; k < 2; ++k) dst[n][k] = *(const PG8_LAS bf16x8*)(lds + PG8_SB(b, h) + boff + n * 2048 + k * 1024); } while (0)
; #define PG8_MMA(ai, bj, At, Bt) do { __builtin_amdgcn_s_setprio(1); _Pragma("unroll") for (int m = 0; m < 4; ++m) _Pragma("unroll") for (int n = 0; n < 2; ++n) _Pragma("unroll") for (int k = 0; k < 2; ++k) \
;         acc[ai][bj][m][n] = __builtin_amdgcn_mfma_f32_16x16x32_bf16(Bt[n][k], At[m][k], acc[ai][bj][m][n], 0, 0, 0); __builtin_amdgcn_s_setprio(0); } while (0)
; #define PG8_BAR __builtin_amdgcn_s_barrier()
; template <class Epi, class Sched, bool ALIGN_EPI = false, bool SP2 = false>
; __device__ __forceinline__ void gemm_phase(PG8_LAS unsigned char* lds, const Gemm g, const Sched& S, const Epi& E) {
;     ...
;             if constexpr (SP2) {
;             PG8_LDB(B0, 0, 0); PG8_LDB(B1, 0, 1); PG8_SCHED; PG8_LDA(At, 0, 0); PG8_STAGE(PG8_SA(1, 1), a1 + hstep, voffA);
;             PG8_WAIT_V(8); PG8_WAIT_L(0); PG8_BAR; PG8_MMA(0, 0, At, B0); PG8_MMA(0, 1, At, B1); PG8_BAR; PG8_SCHED;
;             PG8_LDA(At, 0, 1); PG8_STAGE(PG8_SB(0, 0), b2, voffB); PG8_STAGE(PG8_SB(0, 1), b2 + hstep, voffB); PG8_STAGE(PG8_SA(0, 0), a2, voffA);
;             PG8_WAIT_V(8); PG8_WAIT_L(0); PG8_BAR; PG8_MMA(1, 0, At, B0); PG8_MMA(1, 1, At, B1); PG8_BAR; PG8_SCHED;
;             PG8_LDB(B0, 1, 0); PG8_LDB(B1, 1, 1); PG8_SCHED; PG8_LDA(At, 1, 0); PG8_STAGE(PG8_SA(0, 1), a2 + hstep, voffA);
;             PG8_WAIT_V(8); PG8_WAIT_L(0); PG8_BAR; PG8_MMA(0, 0, At, B0); PG8_MMA(0, 1, At, B1); PG8_BAR; PG8_SCHED;
;             PG8_LDA(At, 1, 1); PG8_STAGE(PG8_SB(1, 0), b3, voffB); PG8_STAGE(PG8_SB(1, 1), b3 + hstep, voffB); PG8_STAGE(PG8_SA(1, 0), a3, voffA);
;             PG8_WAIT_V(8); PG8_WAIT_L(0); PG8_BAR; PG8_MMA(1, 0, At, B0); PG8_MMA(1, 1, At, B1); PG8_BAR; PG8_SCHED;
	s_setprio 1
	v_mfma_f32_16x16x32_bf16 v[126:129], v[142:145], v[186:189], v[126:129]
	v_mfma_f32_16x16x32_bf16 v[122:125], v[156:159], v[186:189], v[122:125]
	v_mfma_f32_16x16x32_bf16 v[114:117], v[142:145], v[194:197], v[114:117]
	v_mfma_f32_16x16x32_bf16 v[106:109], v[156:159], v[194:197], v[106:109]
	v_mfma_f32_16x16x32_bf16 v[98:101], v[142:145], v[202:205], v[98:101]
	v_mfma_f32_16x16x32_bf16 v[90:93], v[156:159], v[202:205], v[90:93]
	v_mfma_f32_16x16x32_bf16 v[82:85], v[142:145], v[210:213], v[82:85]
	v_mfma_f32_16x16x32_bf16 v[74:77], v[156:159], v[210:213], v[74:77]
	v_mfma_f32_16x16x32_bf16 v[126:129], v[152:155], v[190:193], v[126:129]
	v_mfma_f32_16x16x32_bf16 v[122:125], v[160:163], v[190:193], v[122:125]
	v_mfma_f32_16x16x32_bf16 v[114:117], v[152:155], v[198:201], v[114:117]
	v_mfma_f32_16x16x32_bf16 v[106:109], v[160:163], v[198:201], v[106:109]
	v_mfma_f32_16x16x32_bf16 v[98:101], v[152:155], v[206:209], v[98:101]
	v_mfma_f32_16x16x32_bf16 v[90:93], v[160:163], v[206:209], v[90:93]
	v_mfma_f32_16x16x32_bf16 v[82:85], v[152:155], v[214:217], v[82:85]
	v_mfma_f32_16x16x32_bf16 v[74:77], v[160:163], v[214:217], v[74:77]
	s_setprio 0
	s_setprio 1
	v_mfma_f32_16x16x32_bf16 v[118:121], v[164:167], v[186:189], v[118:121]
	v_mfma_f32_16x16x32_bf16 v[110:113], v[172:175], v[186:189], v[110:113]
	v_mfma_f32_16x16x32_bf16 v[102:105], v[164:167], v[194:197], v[102:105]
	v_mfma_f32_16x16x32_bf16 v[94:97], v[172:175], v[194:197], v[94:97]
	v_mfma_f32_16x16x32_bf16 v[86:89], v[164:167], v[202:205], v[86:89]
	v_mfma_f32_16x16x32_bf16 v[78:81], v[172:175], v[202:205], v[78:81]
	v_mfma_f32_16x16x32_bf16 v[70:73], v[164:167], v[210:213], v[70:73]
	v_mfma_f32_16x16x32_bf16 v[66:69], v[172:175], v[210:213], v[66:69]
	v_mfma_f32_16x16x32_bf16 v[118:121], v[168:171], v[190:193], v[118:121]
	v_mfma_f32_16x16x32_bf16 v[110:113], v[180:183], v[190:193], v[110:113]
	v_mfma_f32_16x16x32_bf16 v[102:105], v[168:171], v[198:201], v[102:105]
	v_mfma_f32_16x16x32_bf16 v[94:97], v[180:183], v[198:201], v[94:97]
	v_mfma_f32_16x16x32_bf16 v[86:89], v[168:171], v[206:209], v[86:89]
	v_mfma_f32_16x16x32_bf16 v[78:81], v[180:183], v[206:209], v[78:81]
	v_mfma_f32_16x16x32_bf16 v[70:73], v[168:171], v[214:217], v[70:73]
	v_mfma_f32_16x16x32_bf16 v[66:69], v[180:183], v[214:217], v[66:69]
	s_setprio 0
	s_barrier
	s_add_i32 s18, s50, s27
	v_lshl_add_u64 v[146:147], s[22:23], 0, v[132:133]
	s_mov_b32 m0, s18
	ds_read_b128 v[186:189], v150 offset:16384
	ds_read_b128 v[190:193], v150 offset:17408
	ds_read_b128 v[194:197], v150 offset:18432
	ds_read_b128 v[198:201], v150 offset:19456
	ds_read_b128 v[202:205], v150 offset:20480
	ds_read_b128 v[206:209], v150 offset:21504
	ds_read_b128 v[210:213], v150 offset:22528
	ds_read_b128 v[214:217], v150 offset:23552
	global_load_lds_dwordx4 v[146:147], off
	s_add_i32 m0, s18, 0x2000
	s_add_u32 s18, s22, 0xb0000
	v_lshl_add_u64 v[176:177], s[22:23], 0, v[136:137]
	s_addc_u32 s19, s23, 0
	s_add_i32 s50, s51, s27
	global_load_lds_dwordx4 v[176:177], off
	v_lshl_add_u64 v[218:219], s[18:19], 0, v[132:133]
	s_mov_b32 m0, s50
	v_lshl_add_u64 v[220:221], s[24:25], 0, v[134:135]
	global_load_lds_dwordx4 v[218:219], off
	v_lshl_add_u64 v[218:219], s[18:19], 0, v[136:137]
	s_add_i32 m0, s50, 0x2000
	s_nop 0
	global_load_lds_dwordx4 v[218:219], off
	v_lshl_add_u64 v[218:219], s[24:25], 0, v[130:131]
	s_mov_b32 m0, s33
	s_nop 0
	global_load_lds_dwordx4 v[218:219], off
	s_mov_b32 m0, s36
	s_nop 0
	global_load_lds_dwordx4 v[220:221], off
	s_waitcnt vmcnt(8) lgkmcnt(0)
	s_barrier
	s_setprio 1
	v_mfma_f32_16x16x32_bf16 v[62:65], v[142:145], v[186:189], v[62:65]
	v_mfma_f32_16x16x32_bf16 v[58:61], v[156:159], v[186:189], v[58:61]
	v_mfma_f32_16x16x32_bf16 v[50:53], v[142:145], v[194:197], v[50:53]
	v_mfma_f32_16x16x32_bf16 v[42:45], v[156:159], v[194:197], v[42:45]
	v_mfma_f32_16x16x32_bf16 v[34:37], v[142:145], v[202:205], v[34:37]
	v_mfma_f32_16x16x32_bf16 v[26:29], v[156:159], v[202:205], v[26:29]
	v_mfma_f32_16x16x32_bf16 v[18:21], v[142:145], v[210:213], v[18:21]
	v_mfma_f32_16x16x32_bf16 v[10:13], v[156:159], v[210:213], v[10:13]
	v_mfma_f32_16x16x32_bf16 v[62:65], v[152:155], v[190:193], v[62:65]
	v_mfma_f32_16x16x32_bf16 v[58:61], v[160:163], v[190:193], v[58:61]
	v_mfma_f32_16x16x32_bf16 v[50:53], v[152:155], v[198:201], v[50:53]
	v_mfma_f32_16x16x32_bf16 v[42:45], v[160:163], v[198:201], v[42:45]
	v_mfma_f32_16x16x32_bf16 v[34:37], v[152:155], v[206:209], v[34:37]
	v_mfma_f32_16x16x32_bf16 v[26:29], v[160:163], v[206:209], v[26:29]
	v_mfma_f32_16x16x32_bf16 v[18:21], v[152:155], v[214:217], v[18:21]
	v_mfma_f32_16x16x32_bf16 v[10:13], v[160:163], v[214:217], v[10:13]
	s_setprio 0
	s_setprio 1
	v_mfma_f32_16x16x32_bf16 v[54:57], v[164:167], v[186:189], v[54:57]
	v_mfma_f32_16x16x32_bf16 v[46:49], v[172:175], v[186:189], v[46:49]
	v_mfma_f32_16x16x32_bf16 v[38:41], v[164:167], v[194:197], v[38:41]
	v_mfma_f32_16x16x32_bf16 v[30:33], v[172:175], v[194:197], v[30:33]
	v_mfma_f32_16x16x32_bf16 v[22:25], v[164:167], v[202:205], v[22:25]
	v_mfma_f32_16x16x32_bf16 v[14:17], v[172:175], v[202:205], v[14:17]
	v_mfma_f32_16x16x32_bf16 v[6:9], v[164:167], v[210:213], v[6:9]
	v_mfma_f32_16x16x32_bf16 v[2:5], v[172:175], v[210:213], v[2:5]
	v_mfma_f32_16x16x32_bf16 v[54:57], v[168:171], v[190:193], v[54:57]
	v_mfma_f32_16x16x32_bf16 v[46:49], v[180:183], v[190:193], v[46:49]
	v_mfma_f32_16x16x32_bf16 v[38:41], v[168:171], v[198:201], v[38:41]
	v_mfma_f32_16x16x32_bf16 v[30:33], v[180:183], v[198:201], v[30:33]
	v_mfma_f32_16x16x32_bf16 v[22:25], v[168:171], v[206:209], v[22:25]
	v_mfma_f32_16x16x32_bf16 v[14:17], v[180:183], v[206:209], v[14:17]
	v_mfma_f32_16x16x32_bf16 v[6:9], v[168:171], v[214:217], v[6:9]
	v_mfma_f32_16x16x32_bf16 v[2:5], v[180:183], v[214:217], v[2:5]
	s_setprio 0
	s_barrier
; #define PG8_STAGE(bufoff, gbase, voff) do { _Pragma("unroll") for (int _i = 0; _i < 2; ++_i) \
;         __builtin_amdgcn_global_load_lds((const unsigned*)((const char*)(gbase) + (voff)[_i]), (PG8_LAS unsigned*)(lds + (bufoff) + ldsw + _i * 8192), 16, 0, 0); } while (0)
; #define PG8_LDA(dst, b, h) do { _Pragma("unroll") for (int m = 0; m < 4; ++m) _Pragma("unroll") for (int k = 0; k < 2; ++k) dst[m][k] = *(const PG8_LAS bf16x8*)(lds + PG8_SA(b, h) + aoff + m * 2048 + k * 1024); } while (0)
; #define PG8_LDB(dst, b, h) do { _Pragma("unroll") for (int n = 0; n < 2; ++n) _Pragma("unroll") for (int k = 0; k < 2; ++k) dst[n][k] = *(const PG8_LAS bf16x8*)(lds + PG8_SB(b, h) + boff + n * 2048 + k * 1024); } while (0)
; #define PG8_MMA(ai, bj, At, Bt) do { __builtin_amdgcn_s_setprio(1); _Pragma("unroll") for (int m = 0; m < 4; ++m) _Pragma("unroll") for (int n = 0; n < 2; ++n) _Pragma("unroll") for (int k = 0; k < 2; ++k) \
;         acc[ai][bj][m][n] = __builtin_amdgcn_mfma_f32_16x16x32_bf16(Bt[n][k], At[m][k], acc[ai][bj][m][n], 0, 0, 0); __builtin_amdgcn_s_setprio(0); } while (0)
; #define PG8_WAIT_V(n) asm volatile("s_waitcnt vmcnt(" #n ")" ::: "memory")
; #define PG8_WAIT_L(n) asm volatile("s_waitcnt lgkmcnt(" #n ")" ::: "memory")
; #define PG8_BAR __builtin_amdgcn_s_barrier()
; #define PG8_SCHED __builtin_amdgcn_sched_barrier(0)
; template <class Epi, class Sched, bool ALIGN_EPI = false, bool SP2 = false>
; __device__ __forceinline__ void gemm_phase(PG8_LAS unsigned char* lds, const Gemm g, const Sched& S, const Epi& E) {
;     ...
;             PG8_LDB(B0, 1, 0); PG8_LDB(B1, 1, 1); PG8_SCHED; PG8_LDA(At, 1, 0); PG8_STAGE(PG8_SA(0, 1), a2 + hstep, voffA);
;             PG8_WAIT_V(8); PG8_WAIT_L(0); PG8_BAR; PG8_MMA(0, 0, At, B0); PG8_MMA(0, 1, At, B1); PG8_BAR; PG8_SCHED;
	s_add_i32 s50, 0, 0x18000
	v_add_u32_e32 v151, s50, v148
	s_add_i32 s51, 0, 0x1c000
	ds_read_b128 v[142:145], v151
	ds_read_b128 v[152:155], v151 offset:1024
	ds_read_b128 v[156:159], v151 offset:2048
	ds_read_b128 v[160:163], v151 offset:3072
	v_add_u32_e32 v151, s51, v148
	ds_read_b128 v[164:167], v151
	ds_read_b128 v[168:171], v151 offset:1024
	ds_read_b128 v[172:175], v151 offset:2048
	ds_read_b128 v[180:183], v151 offset:3072
	s_add_u32 s18, s24, 0xb0000
	s_addc_u32 s19, s25, 0
	s_mov_b32 m0, s37
	v_lshl_add_u64 v[222:223], s[18:19], 0, v[130:131]
	ds_read_b128 v[186:189], v150 offset:32768
	ds_read_b128 v[190:193], v150 offset:33792
	ds_read_b128 v[194:197], v150 offset:34816
	ds_read_b128 v[198:201], v150 offset:35840
	ds_read_b128 v[202:205], v150 offset:36864
	ds_read_b128 v[206:209], v150 offset:37888
	ds_read_b128 v[210:213], v150 offset:38912
	ds_read_b128 v[214:217], v150 offset:39936
	global_load_lds_dwordx4 v[222:223], off
	v_lshl_add_u64 v[222:223], s[18:19], 0, v[134:135]
	s_mov_b32 m0, s38
	s_nop 0
	global_load_lds_dwordx4 v[222:223], off
	s_waitcnt vmcnt(8) lgkmcnt(0)
	s_barrier
	s_setprio 1
	v_mfma_f32_16x16x32_bf16 v[126:129], v[142:145], v[186:189], v[126:129]
	v_mfma_f32_16x16x32_bf16 v[122:125], v[156:159], v[186:189], v[122:125]
	v_mfma_f32_16x16x32_bf16 v[114:117], v[142:145], v[194:197], v[114:117]
	v_mfma_f32_16x16x32_bf16 v[106:109], v[156:159], v[194:197], v[106:109]
	v_mfma_f32_16x16x32_bf16 v[98:101], v[142:145], v[202:205], v[98:101]
	v_mfma_f32_16x16x32_bf16 v[90:93], v[156:159], v[202:205], v[90:93]
	v_mfma_f32_16x16x32_bf16 v[82:85], v[142:145], v[210:213], v[82:85]
	v_mfma_f32_16x16x32_bf16 v[74:77], v[156:159], v[210:213], v[74:77]
	v_mfma_f32_16x16x32_bf16 v[126:129], v[152:155], v[190:193], v[126:129]
	v_mfma_f32_16x16x32_bf16 v[122:125], v[160:163], v[190:193], v[122:125]
	v_mfma_f32_16x16x32_bf16 v[114:117], v[152:155], v[198:201], v[114:117]
	v_mfma_f32_16x16x32_bf16 v[106:109], v[160:163], v[198:201], v[106:109]
	v_mfma_f32_16x16x32_bf16 v[98:101], v[152:155], v[206:209], v[98:101]
	v_mfma_f32_16x16x32_bf16 v[90:93], v[160:163], v[206:209], v[90:93]
	v_mfma_f32_16x16x32_bf16 v[82:85], v[152:155], v[214:217], v[82:85]
	v_mfma_f32_16x16x32_bf16 v[74:77], v[160:163], v[214:217], v[74:77]
	s_setprio 0
	s_setprio 1
	v_mfma_f32_16x16x32_bf16 v[118:121], v[164:167], v[186:189], v[118:121]
	v_mfma_f32_16x16x32_bf16 v[110:113], v[172:175], v[186:189], v[110:113]
	v_mfma_f32_16x16x32_bf16 v[102:105], v[164:167], v[194:197], v[102:105]
	v_mfma_f32_16x16x32_bf16 v[94:97], v[172:175], v[194:197], v[94:97]
	v_mfma_f32_16x16x32_bf16 v[86:89], v[164:167], v[202:205], v[86:89]
	v_mfma_f32_16x16x32_bf16 v[78:81], v[172:175], v[202:205], v[78:81]
	v_mfma_f32_16x16x32_bf16 v[70:73], v[164:167], v[210:213], v[70:73]
	v_mfma_f32_16x16x32_bf16 v[66:69], v[172:175], v[210:213], v[66:69]
	v_mfma_f32_16x16x32_bf16 v[118:121], v[168:171], v[190:193], v[118:121]
	v_mfma_f32_16x16x32_bf16 v[110:113], v[180:183], v[190:193], v[110:113]
	v_mfma_f32_16x16x32_bf16 v[102:105], v[168:171], v[198:201], v[102:105]
	v_mfma_f32_16x16x32_bf16 v[94:97], v[180:183], v[198:201], v[94:97]
	v_mfma_f32_16x16x32_bf16 v[86:89], v[168:171], v[206:209], v[86:89]
	v_mfma_f32_16x16x32_bf16 v[78:81], v[180:183], v[206:209], v[78:81]
	v_mfma_f32_16x16x32_bf16 v[70:73], v[168:171], v[214:217], v[70:73]
	v_mfma_f32_16x16x32_bf16 v[66:69], v[180:183], v[214:217], v[66:69]
	s_setprio 0
	s_barrier
; #define PG8_STAGE(bufoff, gbase, voff) do { _Pragma("unroll") for (int _i = 0; _i < 2; ++_i) \
;         __builtin_amdgcn_global_load_lds((const unsigned*)((const char*)(gbase) + (voff)[_i]), (PG8_LAS unsigned*)(lds + (bufoff) + ldsw + _i * 8192), 16, 0, 0); } while (0)
; #define PG8_LDA(dst, b, h) do { _Pragma("unroll") for (int m = 0; m < 4; ++m) _Pragma("unroll") for (int k = 0; k < 2; ++k) dst[m][k] = *(const PG8_LAS bf16x8*)(lds + PG8_SA(b, h) + aoff + m * 2048 + k * 1024); } while (0)
; #define PG8_WAIT_V(n) asm volatile("s_waitcnt vmcnt(" #n ")" ::: "memory")
; #define PG8_WAIT_L(n) asm volatile("s_waitcnt lgkmcnt(" #n ")" ::: "memory")
; template <class Epi, class Sched, bool ALIGN_EPI = false, bool SP2 = false>
; __device__ __forceinline__ void gemm_phase(PG8_LAS unsigned char* lds, const Gemm g, const Sched& S, const Epi& E) {
;     ...
;         for (int t = 0; t < nt; t += 2) {
;             const bool last = (t == nt - 2);
;             const char* a1 = cA + (size_t)(t + 1) * kstep;
;             const char* a2 = last ? nA : cA + (size_t)(t + 2) * kstep; const char* b2 = last ? nB : cB + (size_t)(t + 2) * kstep;
;             const char* a3 = a2 + kstep; const char* b3 = b2 + kstep;
;             if (last && has_next) S.a_ready(nxt);
;             if constexpr (SP2) {
;             PG8_LDB(B0, 0, 0); PG8_LDB(B1, 0, 1); PG8_SCHED; PG8_LDA(At, 0, 0); PG8_STAGE(PG8_SA(1, 1), a1 + hstep, voffA);
;             PG8_WAIT_V(8); PG8_WAIT_L(0); PG8_BAR; PG8_MMA(0, 0, At, B0); PG8_MMA(0, 1, At, B1); PG8_BAR; PG8_SCHED;
;             PG8_LDA(At, 0, 1); PG8_STAGE(PG8_SB(0, 0), b2, voffB); PG8_STAGE(PG8_SB(0, 1), b2 + hstep, voffB); PG8_STAGE(PG8_SA(0, 0), a2, voffA);
;             PG8_WAIT_V(8); PG8_WAIT_L(0); PG8_BAR; PG8_MMA(1, 0, At, B0); PG8_MMA(1, 1, At, B1); PG8_BAR; PG8_SCHED;
;             PG8_LDB(B0, 1, 0); PG8_LDB(B1, 1, 1); PG8_SCHED; PG8_LDA(At, 1, 0); PG8_STAGE(PG8_SA(0, 1), a2 + hstep, voffA);
;             PG8_WAIT_V(8); PG8_WAIT_L(0); PG8_BAR; PG8_MMA(0, 0, At, B0); PG8_MMA(0, 1, At, B1); PG8_BAR; PG8_SCHED;
;             PG8_LDA(At, 1, 1); PG8_STAGE(PG8_SB(1, 0), b3, voffB); PG8_STAGE(PG8_SB(1, 1), b3 + hstep, voffB); PG8_STAGE(PG8_SA(1, 0), a3, voffA);
;             PG8_WAIT_V(8); PG8_WAIT_L(0); PG8_BAR; PG8_MMA(1, 0, At, B0); PG8_MMA(1, 1, At, B1); PG8_BAR; PG8_SCHED;
;     ...
;         if constexpr (ALIGN_EPI) { if (wr == 0) PG8_BAR; }
	s_add_i32 s18, s50, s27
	v_lshl_add_u64 v[146:147], v[146:147], 0, s[80:81]
	s_mov_b32 m0, s18
	ds_read_b128 v[186:189], v150 offset:49152
	ds_read_b128 v[190:193], v150 offset:50176
	ds_read_b128 v[194:197], v150 offset:51200
	ds_read_b128 v[198:201], v150 offset:52224
	ds_read_b128 v[202:205], v150 offset:53248
	ds_read_b128 v[206:209], v150 offset:54272
	ds_read_b128 v[210:213], v150 offset:55296
	ds_read_b128 v[214:217], v150 offset:56320
	global_load_lds_dwordx4 v[146:147], off
	s_add_i32 m0, s18, 0x2000
	s_add_u32 s18, s22, 0xb0080
	v_lshl_add_u64 v[146:147], v[176:177], 0, s[80:81]
	s_addc_u32 s19, s23, 0
	s_add_i32 s22, s51, s27
	global_load_lds_dwordx4 v[146:147], off
	v_lshl_add_u64 v[146:147], s[18:19], 0, v[132:133]
	s_mov_b32 m0, s22
	s_nop 0
	global_load_lds_dwordx4 v[146:147], off
	v_lshl_add_u64 v[146:147], s[18:19], 0, v[136:137]
	s_add_i32 m0, s22, 0x2000
	s_nop 0
	global_load_lds_dwordx4 v[146:147], off
	v_lshl_add_u64 v[146:147], v[218:219], 0, s[80:81]
	s_mov_b32 m0, s39
	s_nop 0
	global_load_lds_dwordx4 v[146:147], off
	v_lshl_add_u64 v[146:147], v[220:221], 0, s[80:81]
	s_mov_b32 m0, s40
	s_nop 0
	global_load_lds_dwordx4 v[146:147], off
	s_waitcnt vmcnt(8) lgkmcnt(0)
	s_barrier
	s_setprio 1
	v_mfma_f32_16x16x32_bf16 v[62:65], v[142:145], v[186:189], v[62:65]
	v_mfma_f32_16x16x32_bf16 v[58:61], v[156:159], v[186:189], v[58:61]
	v_mfma_f32_16x16x32_bf16 v[50:53], v[142:145], v[194:197], v[50:53]
	v_mfma_f32_16x16x32_bf16 v[42:45], v[156:159], v[194:197], v[42:45]
	v_mfma_f32_16x16x32_bf16 v[34:37], v[142:145], v[202:205], v[34:37]
	v_mfma_f32_16x16x32_bf16 v[26:29], v[156:159], v[202:205], v[26:29]
	v_mfma_f32_16x16x32_bf16 v[18:21], v[142:145], v[210:213], v[18:21]
	v_mfma_f32_16x16x32_bf16 v[10:13], v[156:159], v[210:213], v[10:13]
	v_mfma_f32_16x16x32_bf16 v[62:65], v[152:155], v[190:193], v[62:65]
	v_mfma_f32_16x16x32_bf16 v[58:61], v[160:163], v[190:193], v[58:61]
	v_mfma_f32_16x16x32_bf16 v[50:53], v[152:155], v[198:201], v[50:53]
	v_mfma_f32_16x16x32_bf16 v[42:45], v[160:163], v[198:201], v[42:45]
	v_mfma_f32_16x16x32_bf16 v[34:37], v[152:155], v[206:209], v[34:37]
	v_mfma_f32_16x16x32_bf16 v[26:29], v[160:163], v[206:209], v[26:29]
	v_mfma_f32_16x16x32_bf16 v[18:21], v[152:155], v[214:217], v[18:21]
	v_mfma_f32_16x16x32_bf16 v[10:13], v[160:163], v[214:217], v[10:13]
	s_setprio 0
	s_setprio 1
	v_mfma_f32_16x16x32_bf16 v[54:57], v[164:167], v[186:189], v[54:57]
	v_mfma_f32_16x16x32_bf16 v[46:49], v[172:175], v[186:189], v[46:49]
	v_mfma_f32_16x16x32_bf16 v[38:41], v[164:167], v[194:197], v[38:41]
	v_mfma_f32_16x16x32_bf16 v[30:33], v[172:175], v[194:197], v[30:33]
	v_mfma_f32_16x16x32_bf16 v[22:25], v[164:167], v[202:205], v[22:25]
	v_mfma_f32_16x16x32_bf16 v[14:17], v[172:175], v[202:205], v[14:17]
	v_mfma_f32_16x16x32_bf16 v[6:9], v[164:167], v[210:213], v[6:9]
	v_mfma_f32_16x16x32_bf16 v[2:5], v[172:175], v[210:213], v[2:5]
	v_mfma_f32_16x16x32_bf16 v[54:57], v[168:171], v[190:193], v[54:57]
	v_mfma_f32_16x16x32_bf16 v[46:49], v[180:183], v[190:193], v[46:49]
	v_mfma_f32_16x16x32_bf16 v[38:41], v[168:171], v[198:201], v[38:41]
	v_mfma_f32_16x16x32_bf16 v[30:33], v[180:183], v[198:201], v[30:33]
	v_mfma_f32_16x16x32_bf16 v[22:25], v[168:171], v[206:209], v[22:25]
	v_mfma_f32_16x16x32_bf16 v[14:17], v[180:183], v[206:209], v[14:17]
	v_mfma_f32_16x16x32_bf16 v[6:9], v[168:171], v[214:217], v[6:9]
	v_mfma_f32_16x16x32_bf16 v[2:5], v[180:183], v[214:217], v[2:5]
	s_setprio 0
	s_barrier
	s_add_i32 s49, s49, 2
	s_add_u32 s47, s47, 0x100
	s_addc_u32 s48, s48, 0
	s_cmp_gt_u32 s49, 41
	s_mov_b64 s[18:19], s[20:21]
	s_cbranch_scc0 .LBB0_1360
	s_and_b64 vcc, exec, s[14:15]
	s_cbranch_vccz .LBB0_1363
	s_barrier
